# conv2d only: hoist the 4 per-row UV loads of each column step above the first store (1 wait per step instead of 4)
# speedup vs baseline: 1.0157x; 1.0157x over previous
.LBB0_8:
	s_cmpk_gt_i32 s53, 0x67f
	s_mov_b64 s[48:49], -1
	s_cbranch_scc0 .LBB0_26
	s_cmpk_gt_u32 s53, 0x7bf
	s_cbranch_scc0 .LBB0_23
	s_cmpk_gt_u32 s53, 0x8bf
	s_cbranch_scc0 .LBB0_20
	s_cmpk_gt_u32 s53, 0x9bf
	s_cbranch_scc0 .LBB0_17
	s_cmpk_gt_u32 s53, 0xf3f
	s_cbranch_scc0 .LBB0_14
	s_and_b32 s4, s50, 0x7fffffc0
	s_addk_i32 s4, 0xc300
	s_and_b32 s33, s3, 0x3c0
	s_lshl_b32 s28, s33, 2
	v_or_b32_e32 v24, s4, v1
	v_mov_b32_e32 v25, v3
	v_lshl_add_u64 v[28:29], v[4:5], 0, s[28:29]
	v_lshlrev_b64 v[24:25], 12, v[24:25]
	v_lshl_add_u64 v[24:25], v[28:29], 0, v[24:25]
	v_add_u32_e32 v30, s4, v16
	v_mov_b32_e32 v31, v3
	flat_load_dwordx4 v[24:27], v[24:25]
	v_lshlrev_b64 v[30:31], 12, v[30:31]
	v_lshl_add_u64 v[28:29], v[28:29], 0, v[30:31]
	flat_load_dwordx4 v[28:31], v[28:29]
	v_add_u32_e32 v23, s33, v17
	v_mul_u32_u24_e32 v23, 0xb00, v23
	v_mov_b32_e32 v33, v3
	v_lshlrev_b32_e32 v32, 1, v23
	s_mov_b32 s5, s29
	v_lshl_add_u64 v[32:33], s[30:31], 0, v[32:33]
	v_lshl_add_u64 v[32:33], s[4:5], 1, v[32:33]
	v_lshl_add_u64 v[32:33], v[32:33], 0, v[2:3]
	s_mov_b64 s[48:49], 0
	s_waitcnt vmcnt(0) lgkmcnt(0)
	ds_write2_b32 v18, v24, v25 offset1:1
	ds_write2_b32 v18, v26, v27 offset0:2 offset1:3
	ds_write2_b32 v19, v28, v29 offset1:1
	ds_write2_b32 v20, v30, v31 offset1:1
	s_waitcnt lgkmcnt(0)
	s_barrier
	ds_read2_b32 v[24:25], v21 offset1:65
	ds_read2_b32 v[26:27], v21 offset0:130 offset1:195
	ds_read2_b32 v[28:29], v22 offset0:4 offset1:69
	ds_read2_b32 v[30:31], v22 offset0:134 offset1:199
	s_waitcnt lgkmcnt(3)
	v_cvt_pk_bf16_f32 v24, v24, v25
	s_waitcnt lgkmcnt(2)
	v_cvt_pk_bf16_f32 v25, v26, v27
	s_waitcnt lgkmcnt(1)
	v_cvt_pk_bf16_f32 v26, v28, v29
	s_waitcnt lgkmcnt(0)
	v_cvt_pk_bf16_f32 v27, v30, v31
	flat_store_dwordx4 v[32:33], v[24:27]
	s_waitcnt lgkmcnt(0)
	s_barrier
.LBB0_14:
	s_andn2_b64 vcc, exec, s[48:49]
	s_cbranch_vccnz .LBB0_16
	s_add_i32 s4, s53, 0xf640
	s_and_b32 s5, s4, 0xffff
	s_mul_i32 s5, s5, 0xba2f
	s_lshr_b32 s28, s5, 16
	s_lshr_b32 s5, s5, 22
	s_mulk_i32 s5, 0x58
	s_sub_i32 s4, s4, s5
	s_and_b32 s5, s28, 0xffc0
	s_lshl_b32 s4, s4, 6
	s_and_b32 s4, s4, 0xffc0
	v_or_b32_e32 v23, s5, v1
	s_lshl_b32 s28, s4, 2
	v_mul_u32_u24_e32 v23, 0x1600, v23
	v_lshl_add_u64 v[28:29], v[6:7], 0, s[28:29]
	v_lshlrev_b32_e32 v24, 2, v23
	v_mov_b32_e32 v25, v3
	v_add_u32_e32 v23, s5, v16
	v_lshl_add_u64 v[24:25], v[28:29], 0, v[24:25]
	v_mul_u32_u24_e32 v23, 0x1600, v23
	flat_load_dwordx4 v[24:27], v[24:25]
	v_lshlrev_b32_e32 v30, 2, v23
	v_mov_b32_e32 v31, v3
	v_lshl_add_u64 v[28:29], v[28:29], 0, v[30:31]
	flat_load_dwordx4 v[28:31], v[28:29]
	v_mov_b32_e32 v33, v3
	v_add_lshl_u32 v32, v17, s4, 11
	v_lshl_add_u64 v[32:33], s[34:35], 0, v[32:33]
	s_lshl_b32 s28, s5, 1
	v_lshl_add_u64 v[32:33], v[32:33], 0, s[28:29]
	v_lshl_add_u64 v[32:33], v[32:33], 0, v[2:3]
	s_waitcnt vmcnt(0) lgkmcnt(0)
	ds_write2_b32 v18, v24, v25 offset1:1
	ds_write2_b32 v18, v26, v27 offset0:2 offset1:3
	ds_write2_b32 v19, v28, v29 offset1:1
	ds_write2_b32 v20, v30, v31 offset1:1
	s_waitcnt lgkmcnt(0)
	s_barrier
	ds_read2_b32 v[24:25], v21 offset1:65
	ds_read2_b32 v[26:27], v21 offset0:130 offset1:195
	ds_read2_b32 v[28:29], v22 offset0:4 offset1:69
	ds_read2_b32 v[30:31], v22 offset0:134 offset1:199
	s_waitcnt lgkmcnt(3)
	v_cvt_pk_bf16_f32 v24, v24, v25
	s_waitcnt lgkmcnt(2)
	v_cvt_pk_bf16_f32 v25, v26, v27
	s_waitcnt lgkmcnt(1)
	v_cvt_pk_bf16_f32 v26, v28, v29
	s_waitcnt lgkmcnt(0)
	v_cvt_pk_bf16_f32 v27, v30, v31
	flat_store_dwordx4 v[32:33], v[24:27]
	s_waitcnt lgkmcnt(0)
	s_barrier

.LBB0_17:
	s_andn2_b64 vcc, exec, s[48:49]
	s_cbranch_vccnz .LBB0_19
	s_and_b32 s4, s50, 0x3fc0
	s_addk_i32 s4, 0xdd00
	s_and_b32 s33, s3, 0x3c0
	s_lshl_b32 s28, s33, 2
	v_or_b32_e32 v24, s4, v1
	v_mov_b32_e32 v25, v3
	v_lshl_add_u64 v[28:29], v[8:9], 0, s[28:29]
	v_lshlrev_b64 v[24:25], 12, v[24:25]
	v_lshl_add_u64 v[24:25], v[28:29], 0, v[24:25]
	v_add_u32_e32 v30, s4, v16
	v_mov_b32_e32 v31, v3
	flat_load_dwordx4 v[24:27], v[24:25]
	v_lshlrev_b64 v[30:31], 12, v[30:31]
	v_lshl_add_u64 v[28:29], v[28:29], 0, v[30:31]
	flat_load_dwordx4 v[28:31], v[28:29]
	v_mov_b32_e32 v33, v3
	v_add_lshl_u32 v32, s33, v17, 11
	s_mov_b32 s5, s29
	v_lshl_add_u64 v[32:33], s[36:37], 0, v[32:33]
	v_lshl_add_u64 v[32:33], s[4:5], 1, v[32:33]
	v_lshl_add_u64 v[32:33], v[32:33], 0, v[2:3]
	s_waitcnt vmcnt(0) lgkmcnt(0)
	ds_write2_b32 v18, v24, v25 offset1:1
	ds_write2_b32 v18, v26, v27 offset0:2 offset1:3
	ds_write2_b32 v19, v28, v29 offset1:1
	ds_write2_b32 v20, v30, v31 offset1:1
	s_waitcnt lgkmcnt(0)
	s_barrier
	ds_read2_b32 v[24:25], v21 offset1:65
	ds_read2_b32 v[26:27], v21 offset0:130 offset1:195
	ds_read2_b32 v[28:29], v22 offset0:4 offset1:69
	ds_read2_b32 v[30:31], v22 offset0:134 offset1:199
	s_waitcnt lgkmcnt(3)
	v_cvt_pk_bf16_f32 v24, v24, v25
	s_waitcnt lgkmcnt(2)
	v_cvt_pk_bf16_f32 v25, v26, v27
	s_waitcnt lgkmcnt(1)
	v_cvt_pk_bf16_f32 v26, v28, v29
	s_waitcnt lgkmcnt(0)
	v_cvt_pk_bf16_f32 v27, v30, v31
	flat_store_dwordx4 v[32:33], v[24:27]
	s_waitcnt lgkmcnt(0)
	s_barrier

.LBB0_20:
	s_andn2_b64 vcc, exec, s[48:49]
	s_cbranch_vccnz .LBB0_22
	s_and_b32 s4, s50, 0x3fc0
	s_addk_i32 s4, 0xe100
	s_and_b32 s33, s3, 0x3c0
	s_lshl_b32 s28, s33, 2
	v_or_b32_e32 v24, s4, v1
	v_mov_b32_e32 v25, v3
	v_lshl_add_u64 v[28:29], v[10:11], 0, s[28:29]
	v_lshlrev_b64 v[24:25], 12, v[24:25]
	v_lshl_add_u64 v[24:25], v[28:29], 0, v[24:25]
	v_add_u32_e32 v30, s4, v16
	v_mov_b32_e32 v31, v3
	flat_load_dwordx4 v[24:27], v[24:25]
	v_lshlrev_b64 v[30:31], 12, v[30:31]
	v_lshl_add_u64 v[28:29], v[28:29], 0, v[30:31]
	flat_load_dwordx4 v[28:31], v[28:29]
	v_add_u32_e32 v23, s33, v17
	v_mul_u32_u24_e32 v23, 0x900, v23
	v_mov_b32_e32 v33, v3
	v_lshlrev_b32_e32 v32, 1, v23
	s_mov_b32 s5, s29
	v_lshl_add_u64 v[32:33], s[6:7], 0, v[32:33]
	v_lshl_add_u64 v[32:33], s[4:5], 1, v[32:33]
	v_lshl_add_u64 v[32:33], v[32:33], 0, v[2:3]
	v_add_co_u32_e32 v32, vcc, 0xf80000, v32
	s_waitcnt vmcnt(0) lgkmcnt(0)
	ds_write2_b32 v18, v24, v25 offset1:1
	ds_write2_b32 v18, v26, v27 offset0:2 offset1:3
	ds_write2_b32 v19, v28, v29 offset1:1
	ds_write2_b32 v20, v30, v31 offset1:1
	s_waitcnt lgkmcnt(0)
	s_barrier
	ds_read2_b32 v[24:25], v21 offset1:65
	ds_read2_b32 v[26:27], v21 offset0:130 offset1:195
	ds_read2_b32 v[28:29], v22 offset0:4 offset1:69
	ds_read2_b32 v[30:31], v22 offset0:134 offset1:199
	v_addc_co_u32_e32 v33, vcc, 0, v33, vcc
	s_waitcnt lgkmcnt(3)
	v_cvt_pk_bf16_f32 v24, v24, v25
	s_waitcnt lgkmcnt(2)
	v_cvt_pk_bf16_f32 v25, v26, v27
	s_waitcnt lgkmcnt(1)
	v_cvt_pk_bf16_f32 v26, v28, v29
	s_waitcnt lgkmcnt(0)
	v_cvt_pk_bf16_f32 v27, v30, v31
	flat_store_dwordx4 v[32:33], v[24:27] offset:2560
	s_waitcnt lgkmcnt(0)
	s_barrier

.LBB0_23:
	s_andn2_b64 vcc, exec, s[48:49]
	s_cbranch_vccnz .LBB0_25
	s_and_b32 s4, s50, 0x1fc0
	s_addk_i32 s4, 0xe600
	s_and_b32 s33, s3, 0x3c0
	s_lshl_b32 s28, s33, 2
	v_or_b32_e32 v24, s4, v1
	v_mov_b32_e32 v25, v3
	v_lshl_add_u64 v[28:29], v[12:13], 0, s[28:29]
	v_lshlrev_b64 v[24:25], 12, v[24:25]
	v_lshl_add_u64 v[24:25], v[28:29], 0, v[24:25]
	v_add_u32_e32 v30, s4, v16
	v_mov_b32_e32 v31, v3
	flat_load_dwordx4 v[24:27], v[24:25]
	v_lshlrev_b64 v[30:31], 12, v[30:31]
	v_lshl_add_u64 v[28:29], v[28:29], 0, v[30:31]
	flat_load_dwordx4 v[28:31], v[28:29]
	v_add_u32_e32 v23, s33, v17
	v_mul_u32_u24_e32 v23, 0x900, v23
	v_mov_b32_e32 v33, v3
	v_lshlrev_b32_e32 v32, 1, v23
	s_mov_b32 s5, s29
	v_lshl_add_u64 v[32:33], s[46:47], 0, v[32:33]
	v_lshl_add_u64 v[32:33], s[4:5], 1, v[32:33]
	v_lshl_add_u64 v[32:33], v[32:33], 0, v[2:3]
	s_waitcnt vmcnt(0) lgkmcnt(0)
	ds_write2_b32 v18, v24, v25 offset1:1
	ds_write2_b32 v18, v26, v27 offset0:2 offset1:3
	ds_write2_b32 v19, v28, v29 offset1:1
	ds_write2_b32 v20, v30, v31 offset1:1
	s_waitcnt lgkmcnt(0)
	s_barrier
	ds_read2_b32 v[24:25], v21 offset1:65
	ds_read2_b32 v[26:27], v21 offset0:130 offset1:195
	ds_read2_b32 v[28:29], v22 offset0:4 offset1:69
	ds_read2_b32 v[30:31], v22 offset0:134 offset1:199
	s_waitcnt lgkmcnt(3)
	v_cvt_pk_bf16_f32 v24, v24, v25
	s_waitcnt lgkmcnt(2)
	v_cvt_pk_bf16_f32 v25, v26, v27
	s_waitcnt lgkmcnt(1)
	v_cvt_pk_bf16_f32 v26, v28, v29
	s_waitcnt lgkmcnt(0)
	v_cvt_pk_bf16_f32 v27, v30, v31
	flat_store_dwordx4 v[32:33], v[24:27]
	s_waitcnt lgkmcnt(0)
	s_barrier

.LBB0_26:
	s_andn2_b64 vcc, exec, s[48:49]
	s_cbranch_vccnz .LBB0_7
	s_mul_hi_i32 s4, s53, 0x4ec4ec4f
	s_lshr_b32 s5, s4, 31
	s_ashr_i32 s4, s4, 5
	s_add_i32 s5, s4, s5
	s_lshl_b32 s4, s5, 6
	s_mulk_i32 s5, 0xe600
	s_add_i32 s44, s3, s5
	s_ashr_i32 s45, s44, 31
	v_lshl_add_u64 v[28:29], s[44:45], 2, v[14:15]
	v_or_b32_e32 v23, s4, v1
	v_mad_i64_i32 v[24:25], s[48:49], v23, s52, v[28:29]
	flat_load_dwordx4 v[24:27], v[24:25]
	v_add_u32_e32 v23, s4, v16
	v_mad_i64_i32 v[28:29], s[48:49], v23, s52, v[28:29]
	flat_load_dwordx4 v[28:31], v[28:29]
	v_add_u32_e32 v32, s44, v17
	v_ashrrev_i32_e32 v33, 31, v32
	v_lshlrev_b64 v[32:33], 11, v[32:33]
	s_ashr_i32 s5, s4, 31
	v_lshl_add_u64 v[32:33], s[6:7], 0, v[32:33]
	v_lshl_add_u64 v[32:33], s[4:5], 1, v[32:33]
	v_lshl_add_u64 v[32:33], v[32:33], 0, v[2:3]
	s_waitcnt vmcnt(0) lgkmcnt(0)
	ds_write2_b32 v18, v24, v25 offset1:1
	ds_write2_b32 v18, v26, v27 offset0:2 offset1:3
	ds_write2_b32 v19, v28, v29 offset1:1
	ds_write2_b32 v20, v30, v31 offset1:1
	s_waitcnt lgkmcnt(0)
	s_barrier
	ds_read2_b32 v[24:25], v21 offset1:65
	ds_read2_b32 v[26:27], v21 offset0:130 offset1:195
	ds_read2_b32 v[28:29], v22 offset0:4 offset1:69
	ds_read2_b32 v[30:31], v22 offset0:134 offset1:199
	s_waitcnt lgkmcnt(3)
	v_cvt_pk_bf16_f32 v24, v24, v25
	s_waitcnt lgkmcnt(2)
	v_cvt_pk_bf16_f32 v25, v26, v27
	s_waitcnt lgkmcnt(1)
	v_cvt_pk_bf16_f32 v26, v28, v29
	s_waitcnt lgkmcnt(0)
	v_cvt_pk_bf16_f32 v27, v30, v31
	flat_store_dwordx4 v[32:33], v[24:27]
	s_waitcnt lgkmcnt(0)
	s_barrier
	s_branch .LBB0_7

.LBB0_30:
	v_bfe_u32 v22, v14, 15, 1
	v_ashrrev_i32_e32 v4, 18, v14
	v_bfe_u32 v17, v14, 14, 1
	v_mad_u32_u24 v20, v22, 5, v4
	v_cmp_eq_u32_e32 vcc, 0, v17
	v_ashrrev_i32_e32 v21, 31, v20
	v_bfe_u32 v15, v14, 6, 8
	v_ashrrev_i32_e32 v16, 16, v14
	v_cndmask_b32_e32 v19, v10, v11, vcc
	v_cndmask_b32_e32 v18, v12, v13, vcc
	v_lshlrev_b64 v[20:21], 18, v[20:21]
	v_lshlrev_b32_e32 v4, 10, v15
	v_lshlrev_b32_e32 v23, 8, v16
	v_lshl_add_u64 v[18:19], v[18:19], 0, v[20:21]
	v_lshl_add_u64 v[18:19], v[18:19], 0, v[4:5]
	v_and_b32_e32 v4, 0x300, v23
	v_lshl_add_u64 v[18:19], v[18:19], 0, v[4:5]
	v_lshl_add_u64 v[18:19], v[18:19], 0, v[6:7]
	flat_load_dword v18, v[18:19]
	v_lshl_or_b32 v4, v22, 7, v9
	v_lshlrev_b32_e32 v19, 4, v17
	v_ashrrev_i32_e32 v17, 31, v16
	v_or3_b32 v4, v4, v19, v3
	v_lshlrev_b64 v[16:17], 17, v[16:17]
	v_add_u32_e32 v14, s28, v14
	v_lshl_or_b32 v16, v4, 9, v16
	v_cmp_lt_i32_e32 vcc, s3, v14
	v_lshl_add_u64 v[16:17], s[34:35], 0, v[16:17]
	v_lshlrev_b32_e32 v4, 1, v15
	s_or_b64 s[36:37], vcc, s[36:37]
	v_lshl_add_u64 v[16:17], v[16:17], 0, v[4:5]
	s_waitcnt vmcnt(0) lgkmcnt(0)
	v_cvt_pk_bf16_f32 v4, v18, v18
	flat_store_short v[16:17], v4
	s_andn2_b64 exec, exec, s[36:37]
	s_cbranch_execnz .LBB0_30

.LBB0_33:
	v_ashrrev_i32_e32 v7, 31, v6
	v_add_u32_e32 v8, s28, v8
	v_lshl_add_u64 v[10:11], v[6:7], 2, s[26:27]
	v_cmp_lt_i32_e32 vcc, s4, v8
	flat_load_dwordx2 v[10:11], v[10:11]
	v_add_u32_e32 v6, s3, v6
	s_or_b64 s[30:31], vcc, s[30:31]
	s_waitcnt vmcnt(0) lgkmcnt(0)
	v_cvt_pk_bf16_f32 v7, v10, v11
	flat_store_dword v[4:5], v7
	v_lshl_add_u64 v[4:5], v[4:5], 0, s[14:15]
	s_andn2_b64 exec, exec, s[30:31]
	s_cbranch_execnz .LBB0_33

.LBB0_36:
	v_lshl_add_u64 v[8:9], s[12:13], 0, v[4:5]
	flat_load_dword v7, v[8:9]
	v_lshl_add_u64 v[8:9], s[6:7], 0, v[4:5]
	v_add_co_u32_e32 v12, vcc, 0x51f6000, v8
	v_lshl_add_u64 v[10:11], s[24:25], 0, v[4:5]
	s_nop 0
	v_addc_co_u32_e32 v13, vcc, 0, v9, vcc
	v_add_u32_e32 v2, s28, v2
	s_waitcnt vmcnt(0) lgkmcnt(0)
	v_mul_f32_e32 v7, 0xbfb8aa3b, v7
	flat_store_dword v[12:13], v7
	flat_load_dword v7, v[10:11]
	v_add_co_u32_e32 v12, vcc, 0x51f8000, v8
	v_lshl_add_u64 v[10:11], s[8:9], 0, v[4:5]
	s_nop 0
	v_addc_co_u32_e32 v13, vcc, 0, v9, vcc
	v_cmp_lt_i32_e32 vcc, s37, v2
	s_or_b64 s[26:27], vcc, s[26:27]
	v_add_co_u32_e32 v8, vcc, 0x51fb000, v8
	v_lshl_add_u64 v[4:5], v[4:5], 0, s[14:15]
	s_nop 0
	v_addc_co_u32_e32 v9, vcc, 0, v9, vcc
	s_waitcnt vmcnt(0) lgkmcnt(0)
	v_mul_f32_e32 v7, 0xbfb8aa3b, v7
	flat_store_dword v[12:13], v7 offset:2048
	flat_load_dword v7, v[10:11]
	s_waitcnt vmcnt(0) lgkmcnt(0)
	v_mul_f32_e32 v10, 0xbfb8aa3b, v7
	v_fma_f32 v11, v7, s3, -v10
	v_rndne_f32_e32 v12, v10
	v_fmac_f32_e32 v11, 0xb2a5705f, v7
	v_sub_f32_e32 v10, v10, v12
	v_add_f32_e32 v10, v10, v11
	v_cvt_i32_f32_e32 v12, v12
	v_exp_f32_e32 v10, v10
	v_cmp_nlt_f32_e32 vcc, s29, v7
	v_ldexp_f32 v10, v10, v12
	s_nop 0
	v_cndmask_b32_e32 v10, 0, v10, vcc
	v_cmp_ngt_f32_e32 vcc, s30, v7
	s_nop 1
	v_cndmask_b32_e32 v7, v3, v10, vcc
	v_add_f32_e32 v12, 1.0, v7
	v_add_f32_e32 v13, -1.0, v12
	v_frexp_mant_f32_e32 v14, v12
	v_cvt_f64_f32_e32 v[10:11], v12
	v_sub_f32_e32 v15, v13, v12
	v_frexp_exp_i32_f64_e32 v10, v[10:11]
	v_cmp_gt_f32_e32 vcc, s34, v14
	v_sub_f32_e32 v13, v7, v13
	v_add_f32_e32 v11, 1.0, v15
	v_subbrev_co_u32_e32 v10, vcc, 0, v10, vcc
	v_add_f32_e32 v11, v13, v11
	v_sub_u32_e32 v13, 0, v10
	v_cvt_f32_i32_e32 v10, v10
	v_ldexp_f32 v12, v12, v13
	v_ldexp_f32 v11, v11, v13
	v_add_f32_e32 v13, -1.0, v12
	v_add_f32_e32 v14, 1.0, v12
	v_add_f32_e32 v15, 1.0, v13
	v_add_f32_e32 v16, -1.0, v14
	v_sub_f32_e32 v15, v12, v15
	v_sub_f32_e32 v12, v12, v16
	v_mul_f32_e32 v16, 0x3f317218, v10
	v_add_f32_e32 v15, v11, v15
	v_add_f32_e32 v11, v11, v12
	v_fma_f32 v12, v10, s35, -v16
	v_add_f32_e32 v17, v13, v15
	v_add_f32_e32 v18, v14, v11
	v_fmac_f32_e32 v12, 0xb102e308, v10
	v_sub_f32_e32 v10, v13, v17
	v_sub_f32_e32 v13, v14, v18
	v_rcp_f32_e32 v14, v18
	v_add_f32_e32 v19, v16, v12
	v_add_f32_e32 v11, v11, v13
	v_sub_f32_e32 v13, v19, v16
	v_sub_f32_e32 v12, v12, v13
	v_mul_f32_e32 v13, v17, v14
	v_add_f32_e32 v10, v15, v10
	v_mul_f32_e32 v15, v18, v13
	v_fma_f32 v16, v13, v18, -v15
	v_fmac_f32_e32 v16, v13, v11
	v_add_f32_e32 v20, v15, v16
	v_sub_f32_e32 v21, v17, v20
	v_sub_f32_e32 v15, v20, v15
	v_sub_f32_e32 v17, v17, v21
	v_sub_f32_e32 v15, v15, v16
	v_sub_f32_e32 v16, v17, v20
	v_add_f32_e32 v10, v10, v16
	v_add_f32_e32 v10, v15, v10
	v_add_f32_e32 v15, v21, v10
	v_mul_f32_e32 v16, v14, v15
	v_sub_f32_e32 v17, v21, v15
	v_mul_f32_e32 v20, v18, v16
	v_add_f32_e32 v10, v10, v17
	v_add_f32_e32 v17, v13, v16
	v_fma_f32 v18, v16, v18, -v20
	v_sub_f32_e32 v13, v17, v13
	v_fmac_f32_e32 v18, v16, v11
	v_sub_f32_e32 v11, v16, v13
	v_add_f32_e32 v13, v20, v18
	v_sub_f32_e32 v16, v13, v20
	v_sub_f32_e32 v20, v15, v13
	v_sub_f32_e32 v15, v15, v20
	v_sub_f32_e32 v13, v15, v13
	v_sub_f32_e32 v16, v16, v18
	v_add_f32_e32 v10, v10, v13
	v_add_f32_e32 v10, v16, v10
	v_add_f32_e32 v10, v20, v10
	v_mul_f32_e32 v10, v14, v10
	v_add_f32_e32 v10, v11, v10
	v_add_f32_e32 v11, v17, v10
	v_mul_f32_e32 v13, v11, v11
	v_fmamk_f32 v16, v13, 0x3e9b6dac, v6
	v_sub_f32_e32 v14, v11, v17
	v_ldexp_f32 v15, v11, 1
	v_mul_f32_e32 v11, v11, v13
	v_fmaak_f32 v13, v13, v16, 0x3f2aaada
	v_mul_f32_e32 v11, v11, v13
	v_add_f32_e32 v13, v15, v11
	v_sub_f32_e32 v10, v10, v14
	v_sub_f32_e32 v14, v13, v15
	v_ldexp_f32 v10, v10, 1
	v_sub_f32_e32 v11, v11, v14
	v_add_f32_e32 v10, v10, v11
	v_add_f32_e32 v11, v13, v10
	v_sub_f32_e32 v13, v11, v13
	v_add_f32_e32 v14, v19, v11
	v_sub_f32_e32 v10, v10, v13
	v_sub_f32_e32 v13, v14, v19
	v_sub_f32_e32 v15, v14, v13
	v_sub_f32_e32 v11, v11, v13
	v_add_f32_e32 v13, v12, v10
	v_sub_f32_e32 v15, v19, v15
	v_sub_f32_e32 v16, v13, v12
	v_add_f32_e32 v11, v11, v15
	v_sub_f32_e32 v15, v13, v16
	v_sub_f32_e32 v10, v10, v16
	v_sub_f32_e32 v12, v12, v15
	v_add_f32_e32 v11, v13, v11
	v_add_f32_e32 v10, v10, v12
	v_add_f32_e32 v12, v14, v11
	v_sub_f32_e32 v13, v12, v14
	v_sub_f32_e32 v11, v11, v13
	v_add_f32_e32 v10, v10, v11
	v_add_f32_e32 v10, v12, v10
	v_cmp_neq_f32_e32 vcc, s31, v7
	s_nop 1
	v_cndmask_b32_e32 v10, v3, v10, vcc
	v_cmp_lt_f32_e64 vcc, |v7|, s36
	s_nop 1
	v_cndmask_b32_e32 v7, v10, v7, vcc
	v_mul_f32_e32 v7, 0xc138aa3b, v7
	flat_store_dword v[8:9], v7
	s_andn2_b64 exec, exec, s[26:27]
	s_cbranch_execnz .LBB0_36

.LBB0_39:
	s_mov_b32 s4, 0x2aaaaaab
	v_mul_hi_i32 v2, v17, s4
	v_lshrrev_b32_e32 v3, 31, v2
	v_ashrrev_i32_e32 v2, 4, v2
	v_add_u32_e32 v26, v2, v3
	v_lshlrev_b32_e32 v14, 6, v26
	v_or_b32_e32 v2, v14, v1
	v_ashrrev_i32_e32 v3, 31, v2
	v_lshlrev_b64 v[4:5], 2, v[2:3]
	v_add_u32_e32 v6, v19, v14
	v_add_u32_e32 v8, v20, v14
	v_add_u32_e32 v10, v21, v14
	v_add_u32_e32 v12, v22, v14
	v_lshl_add_u64 v[2:3], s[22:23], 0, v[4:5]
	v_ashrrev_i32_e32 v7, 31, v6
	v_ashrrev_i32_e32 v9, 31, v8
	v_ashrrev_i32_e32 v11, 31, v10
	v_ashrrev_i32_e32 v13, 31, v12
	v_lshl_add_u64 v[6:7], v[6:7], 2, s[22:23]
	v_lshl_add_u64 v[8:9], v[8:9], 2, s[22:23]
	v_lshl_add_u64 v[10:11], v[10:11], 2, s[22:23]
	v_lshl_add_u64 v[12:13], v[12:13], 2, s[22:23]
	flat_load_dword v15, v[2:3]
	flat_load_dword v16, v[6:7]
	flat_load_dword v18, v[8:9]
	flat_load_dword v30, v[10:11]
	flat_load_dword v31, v[12:13]
	v_add_u32_e32 v6, v23, v14
	v_add_u32_e32 v8, v24, v14
	v_add_u32_e32 v10, v25, v14
	v_ashrrev_i32_e32 v7, 31, v6
	v_ashrrev_i32_e32 v9, 31, v8
	v_ashrrev_i32_e32 v11, 31, v10
	v_lshl_add_u64 v[6:7], v[6:7], 2, s[22:23]
	v_lshl_add_u64 v[8:9], v[8:9], 2, s[22:23]
	v_lshl_add_u64 v[10:11], v[10:11], 2, s[22:23]
	v_lshl_add_u64 v[4:5], s[16:17], 0, v[4:5]
	flat_load_dword v3, v[6:7]
	flat_load_dword v12, v[8:9]
	flat_load_dword v13, v[10:11]
	flat_load_dword v34, v[4:5]
	s_movk_i32 s4, 0x60
	v_mul_lo_u32 v2, v26, s4
	v_sub_u32_e32 v2, v17, v2
	v_lshl_or_b32 v2, v2, 6, v1
	s_mov_b32 s96, 0
	s_waitcnt vmcnt(0) lgkmcnt(0)
	v_mul_f32_e32 v4, 0xbfb8aa3b, v15
	v_mul_f32_e32 v5, 0xbfb8aa3b, v16
	v_exp_f32_e32 v4, v4
	v_mul_f32_e32 v6, 0xbfb8aa3b, v18
	v_exp_f32_e32 v5, v5
	v_exp_f32_e32 v6, v6
	v_add_f32_e32 v4, 1.0, v4
	v_div_scale_f32 v9, s[4:5], v4, v4, v15
	v_add_f32_e32 v5, 1.0, v5
	v_mul_f32_e32 v7, 0xbfb8aa3b, v30
	v_add_f32_e32 v6, 1.0, v6
	v_div_scale_f32 v11, s[4:5], v5, v5, v16
	v_rcp_f32_e32 v35, v9
	v_exp_f32_e32 v7, v7
	v_div_scale_f32 v28, s[4:5], v6, v6, v18
	v_rcp_f32_e32 v36, v11
	v_rcp_f32_e32 v37, v28
	v_fma_f32 v39, -v9, v35, 1.0
	v_add_f32_e32 v7, 1.0, v7
	v_div_scale_f32 v10, vcc, v15, v4, v15
	v_fma_f32 v40, -v11, v36, 1.0
	v_fmac_f32_e32 v35, v39, v35
	v_div_scale_f32 v27, s[6:7], v16, v5, v16
	v_div_scale_f32 v32, s[4:5], v7, v7, v30
	v_fma_f32 v41, -v28, v37, 1.0
	v_fmac_f32_e32 v36, v40, v36
	v_mul_f32_e32 v39, v10, v35
	v_mul_f32_e32 v8, 0xbfb8aa3b, v31
	v_div_scale_f32 v29, s[8:9], v18, v6, v18
	v_rcp_f32_e32 v38, v32
	v_fmac_f32_e32 v37, v41, v37
	v_mul_f32_e32 v40, v27, v36
	v_fma_f32 v43, -v9, v39, v10
	v_exp_f32_e32 v8, v8
	v_mul_f32_e32 v41, v29, v37
	v_fma_f32 v44, -v11, v40, v27
	v_fmac_f32_e32 v39, v43, v35
	v_fma_f32 v45, -v28, v41, v29
	v_fmac_f32_e32 v40, v44, v36
	v_fma_f32 v9, -v9, v39, v10
	v_fmac_f32_e32 v41, v45, v37
	v_fma_f32 v10, -v11, v40, v27
	v_div_fmas_f32 v9, v9, v35, v39
	s_mov_b64 vcc, s[6:7]
	v_fma_f32 v42, -v32, v38, 1.0
	v_fma_f32 v11, -v28, v41, v29
	v_div_fixup_f32 v27, v9, v4, v15
	v_div_fmas_f32 v4, v10, v36, v40
	s_mov_b64 vcc, s[8:9]
	v_div_scale_f32 v33, s[10:11], v30, v7, v30
	v_fmac_f32_e32 v38, v42, v38
	v_div_fixup_f32 v28, v4, v5, v16
	v_div_fmas_f32 v4, v11, v37, v41
	v_add_f32_e32 v5, 1.0, v8
	v_mul_f32_e32 v42, v33, v38
	v_div_fixup_f32 v29, v4, v6, v18
	v_div_scale_f32 v6, s[4:5], v5, v5, v31
	v_fma_f32 v46, -v32, v42, v33
	v_rcp_f32_e32 v8, v6
	v_fmac_f32_e32 v42, v46, v38
	v_fma_f32 v4, -v32, v42, v33
	s_mov_b64 vcc, s[10:11]
	v_div_fmas_f32 v4, v4, v38, v42
	v_div_fixup_f32 v30, v4, v7, v30
	v_fma_f32 v4, -v6, v8, 1.0
	v_mul_f32_e32 v9, 0xbfb8aa3b, v3
	v_fmac_f32_e32 v8, v4, v8
	v_div_scale_f32 v4, vcc, v31, v5, v31
	v_exp_f32_e32 v9, v9
	v_mul_f32_e32 v7, v4, v8
	v_fma_f32 v10, -v6, v7, v4
	v_fmac_f32_e32 v7, v10, v8
	v_fma_f32 v4, -v6, v7, v4
	v_add_f32_e32 v6, 1.0, v9
	v_div_scale_f32 v9, s[4:5], v6, v6, v3
	v_rcp_f32_e32 v10, v9
	v_div_fmas_f32 v4, v4, v8, v7
	v_mul_f32_e32 v7, 0xbfb8aa3b, v12
	v_exp_f32_e32 v7, v7
	v_div_fixup_f32 v31, v4, v5, v31
	v_fma_f32 v4, -v9, v10, 1.0
	v_fmac_f32_e32 v10, v4, v10
	v_div_scale_f32 v4, vcc, v3, v6, v3
	v_mul_f32_e32 v5, v4, v10
	v_fma_f32 v8, -v9, v5, v4
	v_add_f32_e32 v7, 1.0, v7
	v_fmac_f32_e32 v5, v8, v10
	v_div_scale_f32 v8, s[4:5], v7, v7, v12
	v_fma_f32 v4, -v9, v5, v4
	v_rcp_f32_e32 v9, v8
	v_div_fmas_f32 v4, v4, v10, v5
	v_mul_f32_e32 v5, 0xbfb8aa3b, v13
	v_exp_f32_e32 v5, v5
	v_div_fixup_f32 v32, v4, v6, v3
	v_fma_f32 v3, -v8, v9, 1.0
	v_fmac_f32_e32 v9, v3, v9
	v_div_scale_f32 v3, vcc, v12, v7, v12
	v_mul_f32_e32 v4, v3, v9
	v_fma_f32 v6, -v8, v4, v3
	v_add_f32_e32 v5, 1.0, v5
	v_fmac_f32_e32 v4, v6, v9
	v_div_scale_f32 v6, s[4:5], v5, v5, v13
	v_fma_f32 v3, -v8, v4, v3
	v_rcp_f32_e32 v8, v6
	v_div_fmas_f32 v3, v3, v9, v4
	v_div_fixup_f32 v33, v3, v7, v12
	v_mul_f32_e32 v7, 0xbfb8aa3b, v34
	v_fma_f32 v3, -v6, v8, 1.0
	v_fmac_f32_e32 v8, v3, v8
	v_div_scale_f32 v3, vcc, v13, v5, v13
	v_exp_f32_e32 v7, v7
	v_mul_f32_e32 v4, v3, v8
	v_fma_f32 v9, -v6, v4, v3
	v_fmac_f32_e32 v4, v9, v8
	v_fma_f32 v3, -v6, v4, v3
	v_add_f32_e32 v6, 1.0, v7
	v_div_scale_f32 v7, s[4:5], v6, v6, v34
	v_rcp_f32_e32 v9, v7
	v_div_fmas_f32 v3, v3, v8, v4
	v_div_fixup_f32 v35, v3, v5, v13
	v_mov_b32_e32 v8, 0
	v_fma_f32 v3, -v7, v9, 1.0
	v_fmac_f32_e32 v9, v3, v9
	v_div_scale_f32 v3, vcc, v34, v6, v34
	v_mul_f32_e32 v4, v3, v9
	v_fma_f32 v5, -v7, v4, v3
	v_fmac_f32_e32 v4, v5, v9
	v_fma_f32 v3, -v7, v4, v3
	v_div_fmas_f32 v3, v3, v9, v4
	v_div_fixup_f32 v36, v3, v6, v34
	v_ashrrev_i32_e32 v3, 31, v2
	v_lshlrev_b64 v[4:5], 2, v[2:3]
	v_mad_i64_i32 v[4:5], s[4:5], v14, s39, v[4:5]
	v_mov_b32_e32 v34, 0
	v_lshl_add_u64 v[6:7], s[18:19], 0, v[4:5]
	v_mov_b32_e32 v4, 0
	v_mov_b32_e32 v5, v34
	v_mov_b32_e32 v9, v34
	v_mov_b32_e32 v10, 0
	v_mov_b32_e32 v11, v34
	v_mov_b32_e32 v12, 0
	v_mov_b32_e32 v13, v34
.LBB0_40:
	s_mov_b32 s6, 0xfffdc000
	v_add_co_u32_e64 v38, s[6:7], s6, v6
	v_add_co_u32_e32 v14, vcc, 0xfffd6000, v6
	s_nop 0
	v_addc_co_u32_e64 v39, s[6:7], -1, v7, s[6:7]
	s_mov_b32 s6, 0xfffe2000
	s_nop 0
	v_add_co_u32_e64 v40, s[6:7], s6, v6
	flat_load_dword v16, v[6:7]
	s_nop 0
	v_addc_co_u32_e64 v41, s[6:7], -1, v7, s[6:7]
	s_mov_b32 s6, 0xfffe8000
	s_nop 0
	v_add_co_u32_e64 v42, s[6:7], s6, v6
	v_addc_co_u32_e32 v15, vcc, -1, v7, vcc
	s_nop 0
	v_addc_co_u32_e64 v43, s[6:7], -1, v7, s[6:7]
	s_mov_b32 s6, 0xfffee000
	s_nop 0
	v_add_co_u32_e64 v44, s[6:7], s6, v6
	v_readlane_b32 s9, v27, s96
	s_nop 0
	v_addc_co_u32_e64 v45, s[6:7], -1, v7, s[6:7]
	s_mov_b32 s6, 0xffff4000
	s_nop 0
	v_add_co_u32_e64 v46, s[6:7], s6, v6
	v_readlane_b32 s11, v28, s96
	s_nop 0
	v_addc_co_u32_e64 v47, s[6:7], -1, v7, s[6:7]
	s_movk_i32 s6, 0xa000
	s_nop 0
	v_add_co_u32_e64 v48, s[6:7], s6, v6
	v_readlane_b32 s26, v29, s96
	s_nop 0
	v_addc_co_u32_e64 v49, s[6:7], -1, v7, s[6:7]
	flat_load_dword v38, v[38:39]
	s_nop 0
	flat_load_dword v40, v[40:41]
	s_nop 0
	flat_load_dword v42, v[42:43]
	s_nop 0
	flat_load_dword v44, v[44:45]
	s_nop 0
	flat_load_dword v46, v[46:47]
	s_nop 0
	flat_load_dword v18, v[48:49]
	s_nop 0
	flat_load_dword v14, v[14:15]
	v_readlane_b32 s97, v30, s96
	v_readlane_b32 s27, v31, s96
	v_readlane_b32 s10, v32, s96
	v_readlane_b32 s8, v33, s96
	v_readlane_b32 s29, v35, s96
	v_readlane_b32 s28, v36, s96
	s_add_i32 s36, s96, 1
	s_add_i32 s52, s96, 2
	v_readlane_b32 s7, v27, s36
	v_readlane_b32 s31, v28, s36
	v_readlane_b32 s34, v29, s36
	v_readlane_b32 s94, v30, s36
	v_readlane_b32 s35, v31, s36
	v_readlane_b32 s30, v32, s36
	v_readlane_b32 s6, v33, s36
	v_readlane_b32 s47, v35, s36
	v_readlane_b32 s46, v36, s36
	s_add_i32 s33, s96, 3
	v_readlane_b32 s37, v27, s52
	v_readlane_b32 s49, v28, s52
	v_readlane_b32 s50, v29, s52
	v_readlane_b32 s44, v30, s52
	v_readlane_b32 s51, v31, s52
	v_readlane_b32 s48, v32, s52
	v_readlane_b32 s36, v33, s52
	v_readlane_b32 s53, v35, s52
	v_readlane_b32 s52, v36, s52
	s_add_i32 s68, s96, 4
	v_readlane_b32 s55, v27, s33
	v_readlane_b32 s57, v28, s33
	v_readlane_b32 s58, v29, s33
	v_readlane_b32 s45, v30, s33
	v_readlane_b32 s59, v31, s33
	v_readlane_b32 s56, v32, s33
	v_readlane_b32 s54, v33, s33
	v_readlane_b32 s63, v35, s33
	v_readlane_b32 s62, v36, s33
	s_add_i32 s4, s96, 5
	v_readlane_b32 s61, v27, s68
	v_readlane_b32 s65, v28, s68
	v_readlane_b32 s66, v29, s68
	v_readlane_b32 s33, v30, s68
	v_readlane_b32 s67, v31, s68
	v_readlane_b32 s64, v32, s68
	v_readlane_b32 s60, v33, s68
	v_readlane_b32 s71, v35, s68
	v_readlane_b32 s70, v36, s68
	s_add_i32 s5, s96, 6
	v_readlane_b32 s69, v27, s4
	v_readlane_b32 s73, v28, s4
	v_readlane_b32 s74, v29, s4
	v_readlane_b32 vcc_lo, v30, s4
	v_readlane_b32 s75, v31, s4
	v_readlane_b32 s72, v32, s4
	v_readlane_b32 s68, v33, s4
	v_readlane_b32 s79, v35, s4
	v_readlane_b32 s78, v36, s4
	s_add_i32 s40, s96, 7
	v_readlane_b32 s77, v27, s5
	v_readlane_b32 s81, v28, s5
	v_readlane_b32 s82, v29, s5
	v_readlane_b32 vcc_hi, v30, s5
	v_readlane_b32 s83, v31, s5
	v_readlane_b32 s80, v32, s5
	v_readlane_b32 s76, v33, s5
	v_readlane_b32 s87, v35, s5
	v_readlane_b32 s86, v36, s5
	s_add_i32 s96, s96, 8
	v_readlane_b32 s85, v27, s40
	v_readlane_b32 s89, v28, s40
	v_readlane_b32 s90, v29, s40
	v_readlane_b32 s91, v31, s40
	v_readlane_b32 s88, v32, s40
	v_readlane_b32 s84, v33, s40
	v_readlane_b32 s93, v35, s40
	v_readlane_b32 s92, v36, s40
	v_readlane_b32 s4, v30, s40
	s_mov_b64 s[40:41], 0x30000
	s_cmp_eq_u32 s96, 64
	s_waitcnt vmcnt(0) lgkmcnt(0)
	v_fmac_f32_e32 v34, s97, v14
	v_pk_fma_f32 v[12:13], v[14:15], s[26:27], v[12:13] op_sel_hi:[0,1,1]
	v_pk_fma_f32 v[10:11], v[14:15], s[10:11], v[10:11] op_sel_hi:[0,1,1]
	v_pk_fma_f32 v[8:9], v[14:15], s[8:9], v[8:9] op_sel_hi:[0,1,1]
	v_pk_fma_f32 v[4:5], v[14:15], s[28:29], v[4:5] op_sel_hi:[0,1,1]
	v_fmac_f32_e32 v34, s94, v38
	v_pk_fma_f32 v[12:13], v[38:39], s[34:35], v[12:13] op_sel_hi:[0,1,1]
	v_pk_fma_f32 v[10:11], v[38:39], s[30:31], v[10:11] op_sel_hi:[0,1,1]
	v_pk_fma_f32 v[8:9], v[38:39], s[6:7], v[8:9] op_sel_hi:[0,1,1]
	v_pk_fma_f32 v[4:5], v[38:39], s[46:47], v[4:5] op_sel_hi:[0,1,1]
	v_fmac_f32_e32 v34, s44, v40
	v_pk_fma_f32 v[12:13], v[40:41], s[50:51], v[12:13] op_sel_hi:[0,1,1]
	v_pk_fma_f32 v[10:11], v[40:41], s[48:49], v[10:11] op_sel_hi:[0,1,1]
	v_pk_fma_f32 v[8:9], v[40:41], s[36:37], v[8:9] op_sel_hi:[0,1,1]
	v_pk_fma_f32 v[4:5], v[40:41], s[52:53], v[4:5] op_sel_hi:[0,1,1]
	v_fmac_f32_e32 v34, s45, v42
	v_pk_fma_f32 v[12:13], v[42:43], s[58:59], v[12:13] op_sel_hi:[0,1,1]
	v_pk_fma_f32 v[10:11], v[42:43], s[56:57], v[10:11] op_sel_hi:[0,1,1]
	v_pk_fma_f32 v[8:9], v[42:43], s[54:55], v[8:9] op_sel_hi:[0,1,1]
	v_pk_fma_f32 v[4:5], v[42:43], s[62:63], v[4:5] op_sel_hi:[0,1,1]
	v_fmac_f32_e32 v34, s33, v44
	v_pk_fma_f32 v[12:13], v[44:45], s[66:67], v[12:13] op_sel_hi:[0,1,1]
	v_pk_fma_f32 v[10:11], v[44:45], s[64:65], v[10:11] op_sel_hi:[0,1,1]
	v_pk_fma_f32 v[8:9], v[44:45], s[60:61], v[8:9] op_sel_hi:[0,1,1]
	v_pk_fma_f32 v[4:5], v[44:45], s[70:71], v[4:5] op_sel_hi:[0,1,1]
	v_fmac_f32_e32 v34, vcc_lo, v46
	v_pk_fma_f32 v[12:13], v[46:47], s[74:75], v[12:13] op_sel_hi:[0,1,1]
	v_pk_fma_f32 v[10:11], v[46:47], s[72:73], v[10:11] op_sel_hi:[0,1,1]
	v_pk_fma_f32 v[8:9], v[46:47], s[68:69], v[8:9] op_sel_hi:[0,1,1]
	v_pk_fma_f32 v[4:5], v[46:47], s[78:79], v[4:5] op_sel_hi:[0,1,1]
	v_fmac_f32_e32 v34, vcc_hi, v18
	v_pk_fma_f32 v[12:13], v[18:19], s[82:83], v[12:13] op_sel_hi:[0,1,1]
	v_pk_fma_f32 v[10:11], v[18:19], s[80:81], v[10:11] op_sel_hi:[0,1,1]
	v_pk_fma_f32 v[8:9], v[18:19], s[76:77], v[8:9] op_sel_hi:[0,1,1]
	v_pk_fma_f32 v[4:5], v[18:19], s[86:87], v[4:5] op_sel_hi:[0,1,1]
	v_lshl_add_u64 v[6:7], v[6:7], 0, s[40:41]
	v_fmac_f32_e32 v34, s4, v16
	v_pk_fma_f32 v[12:13], v[16:17], s[90:91], v[12:13] op_sel_hi:[0,1,1]
	v_pk_fma_f32 v[10:11], v[16:17], s[88:89], v[10:11] op_sel_hi:[0,1,1]
	v_pk_fma_f32 v[8:9], v[16:17], s[84:85], v[8:9] op_sel_hi:[0,1,1]
	v_pk_fma_f32 v[4:5], v[16:17], s[92:93], v[4:5] op_sel_hi:[0,1,1]
	s_cbranch_scc0 .LBB0_40
	v_lshl_add_u32 v14, v26, 3, v26
	v_mov_b64_e32 v[6:7], s[14:15]
	v_mad_i64_i32 v[6:7], s[4:5], v14, s39, v[6:7]
	v_lshl_add_u64 v[2:3], v[2:3], 2, v[6:7]
	v_add_co_u32_e32 v6, vcc, 0x6000, v2
	flat_store_dword v[2:3], v9
	s_nop 0
	v_addc_co_u32_e32 v7, vcc, 0, v3, vcc
	flat_store_dword v[6:7], v11
	v_add_co_u32_e32 v6, vcc, 0xc000, v2
	v_add_u32_e32 v17, s3, v17
	s_nop 0
	v_addc_co_u32_e32 v7, vcc, 0, v3, vcc
	flat_store_dword v[6:7], v12
	v_add_co_u32_e32 v6, vcc, 0x12000, v2
	s_movk_i32 s4, 0x5ff
	s_nop 0
	v_addc_co_u32_e32 v7, vcc, 0, v3, vcc
	flat_store_dword v[6:7], v34
	v_add_co_u32_e32 v6, vcc, 0x18000, v2
	s_nop 1
	v_addc_co_u32_e32 v7, vcc, 0, v3, vcc
	flat_store_dword v[6:7], v13
	v_add_co_u32_e32 v6, vcc, 0x1e000, v2
	s_nop 1
	v_addc_co_u32_e32 v7, vcc, 0, v3, vcc
	flat_store_dword v[6:7], v10
	v_add_co_u32_e32 v6, vcc, 0x24000, v2
	s_nop 1
	v_addc_co_u32_e32 v7, vcc, 0, v3, vcc
	flat_store_dword v[6:7], v8
	v_add_co_u32_e32 v6, vcc, 0x2a000, v2
	s_nop 1
	v_addc_co_u32_e32 v7, vcc, 0, v3, vcc
	v_add_co_u32_e32 v2, vcc, 0x30000, v2
	flat_store_dword v[6:7], v5
	s_nop 0
	v_addc_co_u32_e32 v3, vcc, 0, v3, vcc
	v_cmp_lt_i32_e32 vcc, s4, v17
	s_or_b64 s[24:25], vcc, s[24:25]
	flat_store_dword v[2:3], v4
	s_andn2_b64 exec, exec, s[24:25]
	s_cbranch_execnz .LBB0_39

.LBB0_58:
	v_mul_hi_i32 v1, v0, s4
	v_lshrrev_b32_e32 v2, 31, v1
	v_ashrrev_i32_e32 v1, 10, v1
	v_add_u32_e32 v1, v1, v2
	v_mul_i32_i24_e32 v4, 0x1800, v1
	v_sub_u32_e32 v4, v0, v4
	v_ashrrev_i32_e32 v5, 31, v4
	v_lshlrev_b64 v[4:5], 2, v[4:5]
	v_mul_hi_i32_i24_e32 v3, 0x6000, v1
	v_mul_i32_i24_e32 v2, 0x6000, v1
	v_lshl_add_u64 v[6:7], s[8:9], 0, v[4:5]
	v_lshl_add_u64 v[4:5], s[22:23], 0, v[4:5]
	v_lshl_add_u64 v[2:3], v[4:5], 0, v[2:3]
	v_add_co_u32_e32 v4, vcc, s5, v2
	flat_load_dword v28, v[6:7]
	s_nop 0
	v_addc_co_u32_e32 v5, vcc, 0, v3, vcc
	v_add_co_u32_e32 v6, vcc, s28, v2
	v_ashrrev_i32_e32 v1, 31, v0
	s_nop 0
	v_addc_co_u32_e32 v7, vcc, 0, v3, vcc
	v_add_co_u32_e32 v8, vcc, s29, v2
	s_nop 1
	v_addc_co_u32_e32 v9, vcc, 0, v3, vcc
	v_add_co_u32_e32 v10, vcc, s30, v2
	s_nop 1
	v_addc_co_u32_e32 v11, vcc, 0, v3, vcc
	v_add_co_u32_e32 v12, vcc, s31, v2
	s_nop 1
	v_addc_co_u32_e32 v13, vcc, 0, v3, vcc
	v_add_co_u32_e32 v14, vcc, s33, v2
	s_nop 1
	v_addc_co_u32_e32 v15, vcc, 0, v3, vcc
	v_add_co_u32_e32 v16, vcc, s34, v2
	s_nop 1
	v_addc_co_u32_e32 v17, vcc, 0, v3, vcc
	v_add_co_u32_e32 v18, vcc, s35, v2
	s_nop 1
	v_addc_co_u32_e32 v19, vcc, 0, v3, vcc
	v_add_co_u32_e32 v20, vcc, s36, v2
	s_nop 1
	v_addc_co_u32_e32 v21, vcc, 0, v3, vcc
	v_add_co_u32_e32 v22, vcc, s37, v2
	s_nop 1
	v_addc_co_u32_e32 v23, vcc, 0, v3, vcc
	v_add_co_u32_e32 v24, vcc, s39, v2
	s_nop 1
	v_addc_co_u32_e32 v25, vcc, 0, v3, vcc
	v_add_co_u32_e32 v26, vcc, s44, v2
	flat_load_dword v29, v[2:3]
	flat_load_dword v30, v[4:5]
	flat_load_dword v31, v[6:7]
	s_nop 0
	flat_load_dword v8, v[8:9]
	s_nop 0
	flat_load_dword v9, v[10:11]
	s_nop 0
	flat_load_dword v10, v[12:13]
	flat_load_dword v11, v[14:15]
	s_nop 0
	flat_load_dword v12, v[16:17]
	flat_load_dword v13, v[18:19]
	flat_load_dword v14, v[20:21]
	flat_load_dword v15, v[22:23]
	s_nop 0
	flat_load_dword v16, v[24:25]
	v_addc_co_u32_e32 v27, vcc, 0, v3, vcc
	v_add_co_u32_e32 v4, vcc, s45, v2
	s_nop 1
	v_addc_co_u32_e32 v5, vcc, 0, v3, vcc
	v_add_co_u32_e32 v6, vcc, s46, v2
	flat_load_dword v17, v[26:27]
	s_nop 0
	flat_load_dword v4, v[4:5]
	v_addc_co_u32_e32 v7, vcc, 0, v3, vcc
	v_add_co_u32_e32 v2, vcc, 0x32a000, v2
	s_nop 1
	v_addc_co_u32_e32 v3, vcc, 0, v3, vcc
	flat_load_dword v5, v[6:7]
	s_nop 0
	flat_load_dword v6, v[2:3]
	v_lshl_add_u64 v[2:3], v[0:1], 2, s[24:25]
	v_add_u32_e32 v0, s3, v0
	v_cmp_lt_i32_e32 vcc, s47, v0
	s_or_b64 s[26:27], vcc, s[26:27]
	s_waitcnt vmcnt(0) lgkmcnt(0)
	v_add_f32_e32 v1, v28, v29
	v_add_f32_e32 v1, v1, v30
	v_add_f32_e32 v1, v1, v31
	v_add_f32_e32 v1, v1, v8
	v_add_f32_e32 v1, v1, v9
	v_add_f32_e32 v1, v1, v10
	v_add_f32_e32 v1, v1, v11
	v_add_f32_e32 v1, v1, v12
	v_add_f32_e32 v1, v1, v13
	v_add_f32_e32 v1, v1, v14
	v_add_f32_e32 v1, v1, v15
	v_add_f32_e32 v1, v1, v16
	v_add_f32_e32 v1, v1, v17
	v_add_f32_e32 v1, v1, v4
	v_add_f32_e32 v1, v1, v5
	v_add_f32_e32 v1, v1, v6
	flat_store_dword v[2:3], v1
	s_andn2_b64 exec, exec, s[26:27]
	s_cbranch_execnz .LBB0_58

.LBB0_63:
	v_lshl_add_u64 v[2:3], s[34:35], 0, v[22:23]
	flat_load_dword v8, v[2:3]
	v_lshl_add_u64 v[2:3], s[26:27], 0, v[22:23]
	v_add_co_u32_e32 v4, vcc, 0x26c0000, v2
	s_nop 1
	v_addc_co_u32_e32 v5, vcc, 0, v3, vcc
	flat_load_dword v9, v[4:5]
	v_lshl_add_u64 v[4:5], s[30:31], 0, v[22:23]
	v_add_co_u32_e32 v6, vcc, 0x26f0000, v4
	s_nop 1
	v_addc_co_u32_e32 v7, vcc, 0, v5, vcc
	flat_load_dword v10, v[6:7]
	v_add_co_u32_e32 v6, vcc, 0x26f6000, v2
	s_nop 1
	v_addc_co_u32_e32 v7, vcc, 0, v3, vcc
	flat_load_dword v11, v[6:7]
	v_add_co_u32_e32 v6, vcc, 0x2726000, v4
	s_nop 1
	v_addc_co_u32_e32 v7, vcc, 0, v5, vcc
	flat_load_dword v12, v[6:7]
	v_add_co_u32_e32 v6, vcc, 0x272c000, v2
	s_nop 1
	v_addc_co_u32_e32 v7, vcc, 0, v3, vcc
	flat_load_dword v13, v[6:7]
	v_add_co_u32_e32 v6, vcc, 0x275c000, v4
	s_nop 1
	v_addc_co_u32_e32 v7, vcc, 0, v5, vcc
	flat_load_dword v14, v[6:7]
	v_add_co_u32_e32 v6, vcc, 0x2762000, v2
	s_nop 1
	v_addc_co_u32_e32 v7, vcc, 0, v3, vcc
	flat_load_dword v15, v[6:7]
	v_add_co_u32_e32 v6, vcc, 0x2792000, v4
	s_nop 1
	v_addc_co_u32_e32 v7, vcc, 0, v5, vcc
	flat_load_dword v18, v[6:7]
	v_add_co_u32_e32 v6, vcc, 0x2798000, v2
	s_nop 1
	v_addc_co_u32_e32 v7, vcc, 0, v3, vcc
	flat_load_dword v29, v[6:7]
	v_add_co_u32_e32 v6, vcc, 0x27c8000, v4
	s_nop 1
	v_addc_co_u32_e32 v7, vcc, 0, v5, vcc
	flat_load_dword v31, v[6:7]
	v_add_co_u32_e32 v6, vcc, 0x27ce000, v2
	s_nop 1
	v_addc_co_u32_e32 v7, vcc, 0, v3, vcc
	flat_load_dword v32, v[6:7]
	v_add_co_u32_e32 v6, vcc, 0x27fe000, v4
	s_nop 1
	v_addc_co_u32_e32 v7, vcc, 0, v5, vcc
	flat_load_dword v33, v[6:7]
	v_add_co_u32_e32 v6, vcc, 0x2804000, v2
	s_nop 1
	v_addc_co_u32_e32 v7, vcc, 0, v3, vcc
	flat_load_dword v43, v[6:7]
	v_add_co_u32_e32 v6, vcc, 0x2834000, v4
	s_nop 1
	v_addc_co_u32_e32 v7, vcc, 0, v5, vcc
	flat_load_dword v44, v[6:7]
	v_add_co_u32_e32 v6, vcc, 0x283a000, v2
	s_nop 1
	v_addc_co_u32_e32 v7, vcc, 0, v3, vcc
	flat_load_dword v45, v[6:7]
	v_add_co_u32_e32 v6, vcc, 0x286a000, v4
	s_nop 1
	v_addc_co_u32_e32 v7, vcc, 0, v5, vcc
	flat_load_dword v46, v[6:7]
	v_add_co_u32_e32 v6, vcc, 0x2870000, v2
	s_nop 1
	v_addc_co_u32_e32 v7, vcc, 0, v3, vcc
	flat_load_dword v47, v[6:7]
	v_add_co_u32_e32 v6, vcc, 0x28a0000, v4
	s_nop 1
	v_addc_co_u32_e32 v7, vcc, 0, v5, vcc
	flat_load_dword v48, v[6:7]
	v_add_co_u32_e32 v6, vcc, 0x28a6000, v2
	s_nop 1
	v_addc_co_u32_e32 v7, vcc, 0, v3, vcc
	flat_load_dword v49, v[6:7]
	v_add_co_u32_e32 v6, vcc, 0x28d6000, v4
	s_nop 1
	v_addc_co_u32_e32 v7, vcc, 0, v5, vcc
	flat_load_dword v50, v[6:7]
	v_add_co_u32_e32 v6, vcc, 0x28dc000, v2
	s_nop 1
	v_addc_co_u32_e32 v7, vcc, 0, v3, vcc
	flat_load_dword v51, v[6:7]
	v_add_co_u32_e32 v6, vcc, 0x290c000, v4
	s_nop 1
	v_addc_co_u32_e32 v7, vcc, 0, v5, vcc
	flat_load_dword v52, v[6:7]
	v_add_co_u32_e32 v6, vcc, 0x2912000, v2
	s_nop 1
	v_addc_co_u32_e32 v7, vcc, 0, v3, vcc
	flat_load_dword v53, v[6:7]
	v_add_co_u32_e32 v6, vcc, 0x2942000, v4
	s_nop 1
	v_addc_co_u32_e32 v7, vcc, 0, v5, vcc
	flat_load_dword v54, v[6:7]
	v_add_co_u32_e32 v6, vcc, 0x2948000, v2
	s_nop 1
	v_addc_co_u32_e32 v7, vcc, 0, v3, vcc
	flat_load_dword v55, v[6:7]
	v_add_co_u32_e32 v6, vcc, 0x2978000, v4
	s_nop 1
	v_addc_co_u32_e32 v7, vcc, 0, v5, vcc
	flat_load_dword v56, v[6:7]
	v_add_co_u32_e32 v6, vcc, 0x297e000, v2
	s_nop 1
	v_addc_co_u32_e32 v7, vcc, 0, v3, vcc
	flat_load_dword v57, v[6:7]
	v_add_co_u32_e32 v6, vcc, 0x29ae000, v4
	s_nop 1
	v_addc_co_u32_e32 v7, vcc, 0, v5, vcc
	flat_load_dword v58, v[6:7]
	v_add_co_u32_e32 v6, vcc, 0x29b4000, v2
	s_nop 1
	v_addc_co_u32_e32 v7, vcc, 0, v3, vcc
	flat_load_dword v59, v[6:7]
	v_add_co_u32_e32 v6, vcc, 0x29e4000, v4
	s_nop 1
	v_addc_co_u32_e32 v7, vcc, 0, v5, vcc
	v_add_co_u32_e32 v2, vcc, 0x29ea000, v2
	flat_load_dword v6, v[6:7]
	s_nop 0
	v_addc_co_u32_e32 v3, vcc, 0, v3, vcc
	flat_load_dword v7, v[2:3]
	v_add_co_u32_e32 v2, vcc, 0x2a1a000, v4
	s_waitcnt vmcnt(0) lgkmcnt(0)
	v_add_f32_e32 v4, v8, v10
	v_addc_co_u32_e32 v3, vcc, 0, v5, vcc
	flat_load_dword v2, v[2:3]
	v_add_f32_e32 v3, v8, v9
	v_add_f32_e32 v3, v3, v11
	v_add_f32_e32 v4, v4, v12
	v_add_f32_e32 v3, v3, v13
	v_add_f32_e32 v4, v4, v14
	v_add_f32_e32 v3, v3, v15
	v_add_f32_e32 v4, v4, v18
	v_add_f32_e32 v3, v3, v29
	v_add_f32_e32 v4, v4, v31
	v_add_f32_e32 v3, v3, v32
	v_add_f32_e32 v4, v4, v33
	v_add_f32_e32 v3, v3, v43
	v_add_f32_e32 v4, v4, v44
	v_add_f32_e32 v3, v3, v45
	v_add_f32_e32 v4, v4, v46
	v_add_f32_e32 v3, v3, v47
	v_add_f32_e32 v4, v4, v48
	v_add_f32_e32 v3, v3, v49
	v_add_f32_e32 v4, v4, v50
	v_add_f32_e32 v3, v3, v51
	v_add_f32_e32 v4, v4, v52
	v_cmp_lt_u32_e32 vcc, s3, v1
	v_add_f32_e32 v3, v3, v53
	v_add_f32_e32 v4, v4, v54
	v_add_f32_e32 v3, v3, v55
	v_add_f32_e32 v4, v4, v56
	v_add_f32_e32 v3, v3, v57
	v_add_f32_e32 v4, v4, v58
	v_add_f32_e32 v3, v3, v59
	v_add_f32_e32 v4, v4, v6
	v_add_f32_e32 v3, v3, v7
	s_waitcnt vmcnt(0) lgkmcnt(0)
	v_add_f32_e32 v2, v4, v2
	s_and_saveexec_b64 s[4:5], vcc
	s_xor_b64 s[36:37], exec, s[4:5]
	s_cbranch_execz .LBB0_65
	v_add_u32_e32 v18, 0xfffffc00, v1
	v_lshl_add_u64 v[4:5], v[18:19], 2, s[10:11]
	flat_load_dword v6, v[4:5]
	v_add_f32_e32 v3, 1.0, v3
	v_add_f32_e32 v2, 1.0, v2
	s_waitcnt vmcnt(0) lgkmcnt(0)
	v_mul_f32_e32 v3, v3, v6
	ds_write_b32 v0, v3
	flat_load_dword v3, v[4:5]
	s_waitcnt vmcnt(0) lgkmcnt(0)
	v_mul_f32_e32 v2, v2, v3
	ds_write_b32 v0, v2 offset:8192

.LBB0_68:
	flat_load_dwordx4 v[44:47], v[32:33]
	flat_load_dwordx4 v[48:51], v[32:33] offset:16
	flat_load_dwordx4 v[52:55], v[32:33] offset:2048
	flat_load_dwordx4 v[56:59], v[32:33] offset:2064
	ds_read_b128 v[60:63], v34 offset:2048
	ds_read_b128 v[64:67], v34 offset:2064
	ds_read_b128 v[68:71], v34 offset:6144
	ds_read_b128 v[72:75], v34 offset:6160
	v_lshl_add_u64 v[76:77], v[24:25], 0, s[26:27]
	s_add_u32 s26, s26, 0x800
	s_addc_u32 s27, s27, 0
	v_lshl_add_u64 v[32:33], v[32:33], 0, s[20:21]
	s_cmp_eq_u32 s26, 0x10000
	s_waitcnt vmcnt(0) lgkmcnt(0)
	v_mov_b32_e32 v80, v45
	v_mov_b32_e32 v81, v49
	v_mov_b32_e32 v78, v44
	v_mov_b32_e32 v79, v48
	v_mov_b32_e32 v84, v53
	v_mov_b32_e32 v85, v57
	v_pk_mul_f32 v[80:81], v[80:81], v[80:81]
	v_mov_b32_e32 v82, v52
	v_mov_b32_e32 v83, v56
	v_mov_b32_e32 v86, v46
	v_mov_b32_e32 v87, v50
	v_pk_mul_f32 v[84:85], v[84:85], v[84:85]
	v_pk_fma_f32 v[78:79], v[78:79], v[78:79], v[80:81]
	v_mov_b32_e32 v88, v54
	v_mov_b32_e32 v89, v58
	v_mov_b32_e32 v90, v47
	v_mov_b32_e32 v91, v51
	v_pk_fma_f32 v[80:81], v[82:83], v[82:83], v[84:85]
	v_pk_fma_f32 v[78:79], v[86:87], v[86:87], v[78:79]
	v_mov_b32_e32 v92, v55
	v_mov_b32_e32 v93, v59
	v_pk_fma_f32 v[80:81], v[88:89], v[88:89], v[80:81]
	v_pk_fma_f32 v[78:79], v[90:91], v[90:91], v[78:79]
	v_pk_fma_f32 v[80:81], v[92:93], v[92:93], v[80:81]
	v_add_f32_e32 v18, v78, v79
	v_add_f32_e32 v18, v18, v80
	v_add_f32_e32 v18, v18, v81
	ds_bpermute_b32 v29, v35, v18
	s_waitcnt lgkmcnt(0)
	v_add_f32_e32 v18, v18, v29
	ds_bpermute_b32 v29, v36, v18
	s_waitcnt lgkmcnt(0)
	v_add_f32_e32 v18, v18, v29
	ds_bpermute_b32 v29, v37, v18
	s_waitcnt lgkmcnt(0)
	v_add_f32_e32 v18, v18, v29
	ds_bpermute_b32 v29, v38, v18
	s_waitcnt lgkmcnt(0)
	v_add_f32_e32 v18, v18, v29
	ds_bpermute_b32 v29, v39, v18
	s_waitcnt lgkmcnt(0)
	v_add_f32_e32 v18, v18, v29
	ds_bpermute_b32 v29, v40, v18
	s_waitcnt lgkmcnt(0)
	v_add_f32_e32 v18, v18, v29
	v_fmamk_f32 v18, v18, 0x3a800000, v42
	v_mul_f32_e32 v29, 0x4b800000, v18
	v_cmp_gt_f32_e32 vcc, s46, v18
	s_nop 1
	v_cndmask_b32_e32 v18, v18, v29, vcc
	v_rsq_f32_e32 v18, v18
	s_nop 0
	v_mul_f32_e32 v29, 0x45800000, v18
	v_cndmask_b32_e32 v18, v18, v29, vcc
	v_pk_mul_f32 v[44:45], v[44:45], v[18:19] op_sel_hi:[1,0]
	v_pk_mul_f32 v[46:47], v[46:47], v[18:19] op_sel_hi:[1,0]
	v_pk_mul_f32 v[48:49], v[48:49], v[18:19] op_sel_hi:[1,0]
	v_pk_mul_f32 v[50:51], v[50:51], v[18:19] op_sel_hi:[1,0]
	v_pk_fma_f32 v[46:47], v[2:3], v[46:47], v[10:11]
	v_pk_fma_f32 v[44:45], v[0:1], v[44:45], v[8:9]
	v_pk_mul_f32 v[52:53], v[52:53], v[18:19] op_sel_hi:[1,0]
	v_pk_mul_f32 v[54:55], v[54:55], v[18:19] op_sel_hi:[1,0]
	v_pk_mul_f32 v[56:57], v[56:57], v[18:19] op_sel_hi:[1,0]
	v_pk_mul_f32 v[58:59], v[58:59], v[18:19] op_sel_hi:[1,0]
	v_pk_fma_f32 v[50:51], v[6:7], v[50:51], v[14:15]
	v_pk_fma_f32 v[48:49], v[4:5], v[48:49], v[12:13]
	v_cvt_pk_bf16_f32 v44, v44, v45
	v_cvt_pk_bf16_f32 v45, v46, v47
	v_cvt_pk_bf16_f32 v47, v50, v51
	v_pk_fma_f32 v[54:55], v[62:63], v[54:55], v[70:71]
	v_cvt_pk_bf16_f32 v46, v48, v49
	v_pk_fma_f32 v[52:53], v[60:61], v[52:53], v[68:69]
	v_pk_fma_f32 v[58:59], v[66:67], v[58:59], v[74:75]
	v_pk_fma_f32 v[56:57], v[64:65], v[56:57], v[72:73]
	v_cvt_pk_bf16_f32 v48, v52, v53
	v_cvt_pk_bf16_f32 v49, v54, v55
	v_cvt_pk_bf16_f32 v51, v58, v59
	s_nop 0
	v_cvt_pk_bf16_f32 v50, v56, v57
	flat_store_dwordx4 v[76:77], v[44:47]
	flat_store_dwordx4 v[76:77], v[48:51] offset:1024
	s_cbranch_scc0 .LBB0_68
	s_ashr_i32 s25, s24, 31
	v_lshl_add_u64 v[32:33], s[24:25], 3, v[16:17]
	v_lshlrev_b64 v[0:1], 12, v[32:33]
	v_lshl_add_u64 v[44:45], v[20:21], 0, v[0:1]
	flat_load_dwordx4 v[0:3], v[44:45]
	flat_load_dwordx4 v[4:7], v[44:45] offset:16
	flat_load_dwordx4 v[8:11], v[44:45] offset:2048
	flat_load_dwordx4 v[12:15], v[44:45] offset:2064
	v_lshlrev_b64 v[32:33], 11, v[32:33]
	v_lshl_add_u64 v[32:33], s[12:13], 0, v[32:33]
	v_lshl_add_u64 v[32:33], v[32:33], 0, s[22:23]
	s_add_i32 s24, s24, s38
	v_lshl_add_u64 v[24:25], v[24:25], 0, s[16:17]
	s_cmpk_gt_i32 s24, 0xff
	v_lshl_add_u64 v[26:27], v[26:27], 0, s[18:19]
	s_waitcnt vmcnt(0) lgkmcnt(0)
	v_mov_b32_e32 v46, v1
	v_mov_b32_e32 v47, v5
	v_mov_b32_e32 v44, v0
	v_mov_b32_e32 v45, v4
	v_mov_b32_e32 v54, v9
	v_mov_b32_e32 v55, v13
	v_pk_mul_f32 v[46:47], v[46:47], v[46:47]
	v_mov_b32_e32 v48, v2
	v_mov_b32_e32 v49, v6
	v_mov_b32_e32 v52, v8
	v_mov_b32_e32 v53, v12
	v_pk_mul_f32 v[54:55], v[54:55], v[54:55]
	v_pk_fma_f32 v[44:45], v[44:45], v[44:45], v[46:47]
	v_mov_b32_e32 v50, v3
	v_mov_b32_e32 v51, v7
	v_mov_b32_e32 v56, v10
	v_mov_b32_e32 v57, v14
	v_pk_fma_f32 v[46:47], v[52:53], v[52:53], v[54:55]
	v_pk_fma_f32 v[44:45], v[48:49], v[48:49], v[44:45]
	v_mov_b32_e32 v58, v11
	v_mov_b32_e32 v59, v15
	v_pk_fma_f32 v[46:47], v[56:57], v[56:57], v[46:47]
	v_pk_fma_f32 v[44:45], v[50:51], v[50:51], v[44:45]
	v_pk_fma_f32 v[46:47], v[58:59], v[58:59], v[46:47]
	v_add_f32_e32 v18, v44, v45
	v_add_f32_e32 v18, v18, v46
	v_add_f32_e32 v18, v18, v47
	ds_bpermute_b32 v29, v35, v18
	ds_read_b128 v[44:47], v34 offset:8192
	ds_read_b128 v[48:51], v34 offset:8208
	ds_read_b128 v[52:55], v34 offset:12288
	ds_read_b128 v[56:59], v34 offset:12304
	ds_read_b128 v[60:63], v34 offset:10240
	ds_read_b128 v[64:67], v34 offset:10256
	ds_read_b128 v[68:71], v34 offset:14336
	ds_read_b128 v[72:75], v34 offset:14352
	s_waitcnt lgkmcnt(8)
	v_add_f32_e32 v18, v18, v29
	ds_bpermute_b32 v29, v36, v18
	s_waitcnt lgkmcnt(0)
	v_add_f32_e32 v18, v18, v29
	ds_bpermute_b32 v29, v37, v18
	s_waitcnt lgkmcnt(0)
	v_add_f32_e32 v18, v18, v29
	ds_bpermute_b32 v31, v38, v18
	v_mov_b32_e32 v29, v19
	v_lshl_add_u64 v[76:77], v[32:33], 0, v[28:29]
	s_waitcnt lgkmcnt(0)
	v_add_f32_e32 v18, v18, v31
	ds_bpermute_b32 v43, v39, v18
	v_mov_b32_e32 v31, v19
	v_lshl_add_u64 v[32:33], v[32:33], 0, v[30:31]
	s_waitcnt lgkmcnt(0)
	v_add_f32_e32 v18, v18, v43
	ds_bpermute_b32 v43, v40, v18
	s_waitcnt lgkmcnt(0)
	v_add_f32_e32 v18, v18, v43
	v_fmamk_f32 v18, v18, 0x3a800000, v42
	v_mul_f32_e32 v43, 0x4b800000, v18
	v_cmp_gt_f32_e32 vcc, s46, v18
	s_nop 1
	v_cndmask_b32_e32 v18, v18, v43, vcc
	v_rsq_f32_e32 v18, v18
	s_nop 0
	v_mul_f32_e32 v29, 0x45800000, v18
	v_cndmask_b32_e32 v18, v18, v29, vcc
	v_pk_mul_f32 v[0:1], v[0:1], v[18:19] op_sel_hi:[1,0]
	v_pk_mul_f32 v[2:3], v[2:3], v[18:19] op_sel_hi:[1,0]
	v_pk_mul_f32 v[4:5], v[4:5], v[18:19] op_sel_hi:[1,0]
	v_pk_mul_f32 v[6:7], v[6:7], v[18:19] op_sel_hi:[1,0]
	v_pk_fma_f32 v[2:3], v[46:47], v[2:3], v[54:55]
	v_pk_fma_f32 v[0:1], v[44:45], v[0:1], v[52:53]
	v_pk_mul_f32 v[8:9], v[8:9], v[18:19] op_sel_hi:[1,0]
	v_pk_mul_f32 v[10:11], v[10:11], v[18:19] op_sel_hi:[1,0]
	v_pk_mul_f32 v[12:13], v[12:13], v[18:19] op_sel_hi:[1,0]
	v_pk_mul_f32 v[14:15], v[14:15], v[18:19] op_sel_hi:[1,0]
	v_pk_fma_f32 v[6:7], v[50:51], v[6:7], v[58:59]
	v_pk_fma_f32 v[4:5], v[48:49], v[4:5], v[56:57]
	v_cvt_pk_bf16_f32 v0, v0, v1
	v_cvt_pk_bf16_f32 v1, v2, v3
	v_cvt_pk_bf16_f32 v3, v6, v7
	v_pk_fma_f32 v[10:11], v[62:63], v[10:11], v[70:71]
	v_cvt_pk_bf16_f32 v2, v4, v5
	v_pk_fma_f32 v[8:9], v[60:61], v[8:9], v[68:69]
	v_pk_fma_f32 v[14:15], v[66:67], v[14:15], v[74:75]
	v_pk_fma_f32 v[12:13], v[64:65], v[12:13], v[72:73]
	v_cvt_pk_bf16_f32 v4, v8, v9
	v_cvt_pk_bf16_f32 v5, v10, v11
	v_cvt_pk_bf16_f32 v7, v14, v15
	s_nop 0
	v_cvt_pk_bf16_f32 v6, v12, v13
	flat_store_dwordx4 v[76:77], v[0:3]
	flat_store_dwordx4 v[32:33], v[4:7]
	s_cbranch_scc0 .LBB0_61

.LBB0_140:
	s_lshl_b32 s4, s12, 8
	s_add_i32 s4, s4, s66
	v_add_u32_e32 v150, s4, v148
	s_lshl_b32 s4, s10, 8
	s_or_b32 s4, s4, s67
	s_cmpk_lt_i32 s12, 0x100
	v_add_u32_e32 v151, 0xffff0000, v150
	v_mov_b64_e32 v[152:153], s[28:29]
	v_mov_b64_e32 v[166:167], s[26:27]
	v_lshl_add_u32 v148, v160, 3, s4
	v_mad_i64_i32 v[152:153], s[4:5], v151, s72, v[152:153]
	v_mad_i64_i32 v[166:167], s[4:5], v150, s73, v[166:167]
	s_cselect_b64 s[12:13], -1, 0
	v_ashrrev_i32_e32 v149, 31, v148
	v_cndmask_b32_e64 v153, v153, v167, s[12:13]
	v_cndmask_b32_e64 v152, v152, v166, s[12:13]
	v_lshl_add_u64 v[152:153], v[148:149], 1, v[152:153]
	s_and_b64 vcc, exec, s[8:9]
	v_cvt_pk_bf16_f32 v162, v124, v125
	v_cvt_pk_bf16_f32 v163, v126, v127
	v_cvt_pk_bf16_f32 v164, v120, v121
	v_cvt_pk_bf16_f32 v165, v122, v123
	flat_store_dwordx4 v[152:153], v[162:165]
	s_cbranch_vccnz .LBB0_142
	s_nop 0
	v_pk_mul_f32 v[162:163], v[116:117], v[116:117]
	s_nop 0
	v_pk_fma_f32 v[162:163], v[162:163], s[46:47], v[146:147] op_sel_hi:[1,0,0]
	s_nop 0
	v_pk_mul_f32 v[162:163], v[116:117], v[162:163]
	s_nop 0
	v_exp_f32_e32 v162, v162
	v_exp_f32_e32 v163, v163
	s_nop 0
	v_pk_add_f32 v[162:163], v[162:163], 1.0 op_sel_hi:[1,0]
	s_nop 0
	v_rcp_f32_e32 v162, v162
	v_rcp_f32_e32 v163, v163
	s_nop 0
	v_pk_mul_f32 v[116:117], v[116:117], v[162:163]

.LBB0_148:
	s_cmp_eq_u32 s11, 2
	s_cselect_b64 s[58:59], -1, 0
	s_lshl_b32 s4, s10, 2
	s_sub_i32 s56, s4, 56
	s_ashr_i32 s57, s56, 31
	v_ashrrev_i32_e32 v151, 31, v150
	s_cmp_lg_u32 s11, 2
	v_cmp_eq_u32_e64 s[10:11], 0, v160
	v_cvt_pk_bf16_f32 v160, v116, v117
	v_cvt_pk_bf16_f32 v161, v118, v119
	v_cvt_pk_bf16_f32 v162, v112, v113
	v_cvt_pk_bf16_f32 v163, v114, v115
	flat_store_dwordx4 v[152:153], v[160:163] offset:256
	s_cbranch_scc1 .LBB0_152
	v_pk_mul_f32 v[124:125], v[124:125], v[124:125]
	v_pk_mul_f32 v[126:127], v[126:127], v[126:127]
	v_pk_mul_f32 v[120:121], v[120:121], v[120:121]
	v_add_f32_e32 v126, v126, v127
	v_add_f32_e32 v124, v124, v125
	v_pk_mul_f32 v[122:123], v[122:123], v[122:123]
	v_add_f32_e32 v124, v124, v126
	v_add_f32_e32 v120, v120, v121
	v_pk_mul_f32 v[116:117], v[116:117], v[116:117]
	v_add_f32_e32 v120, v124, v120
	v_add_f32_e32 v121, v122, v123
	v_pk_mul_f32 v[118:119], v[118:119], v[118:119]
	v_add_f32_e32 v120, v120, v121
	v_add_f32_e32 v116, v116, v117
	v_pk_mul_f32 v[112:113], v[112:113], v[112:113]
	v_add_f32_e32 v116, v120, v116
	v_add_f32_e32 v117, v118, v119
	v_pk_mul_f32 v[114:115], v[114:115], v[114:115]
	v_add_f32_e32 v116, v116, v117
	v_add_f32_e32 v112, v112, v113
	v_add_f32_e32 v112, v116, v112
	v_add_f32_e32 v113, v114, v115
	v_and_b32_e32 v114, 64, v159
	v_add_f32_e32 v112, v112, v113
	v_xor_b32_e32 v113, 16, v159
	v_add_u32_e32 v114, 64, v114
	v_cmp_lt_i32_e32 vcc, v113, v114
	s_nop 1
	v_cndmask_b32_e32 v113, v159, v113, vcc
	v_lshlrev_b32_e32 v113, 2, v113
	ds_bpermute_b32 v113, v113, v112
	s_waitcnt lgkmcnt(0)
	v_add_f32_e32 v112, v112, v113
	v_xor_b32_e32 v113, 32, v159
	v_cmp_lt_i32_e32 vcc, v113, v114
	s_nop 1
	v_cndmask_b32_e32 v113, v159, v113, vcc
	v_lshlrev_b32_e32 v113, 2, v113
	ds_bpermute_b32 v113, v113, v112
	s_and_saveexec_b64 s[14:15], s[10:11]
	s_cbranch_execz .LBB0_151
	v_lshlrev_b64 v[114:115], 6, v[150:151]
	v_lshl_add_u64 v[114:115], s[30:31], 0, v[114:115]
	v_lshl_add_u64 v[114:115], s[56:57], 2, v[114:115]
	s_lshl_b32 s22, s65, 2
	v_lshl_add_u64 v[114:115], v[114:115], 0, s[22:23]
	s_waitcnt lgkmcnt(0)
	v_add_f32_e32 v112, v112, v113
	flat_store_dword v[114:115], v112

.LBB0_160:
	v_add_u32_e32 v112, 16, v150
	s_waitcnt lgkmcnt(0)
	v_add_u32_e32 v113, 0xffff0010, v150
	v_mov_b64_e32 v[114:115], s[26:27]
	v_mov_b64_e32 v[120:121], s[28:29]
	v_mad_i64_i32 v[114:115], s[4:5], v112, s73, v[114:115]
	v_mad_i64_i32 v[120:121], s[4:5], v113, s72, v[120:121]
	v_cndmask_b32_e64 v115, v121, v115, s[12:13]
	v_cndmask_b32_e64 v114, v120, v114, s[12:13]
	v_lshl_add_u64 v[114:115], v[148:149], 1, v[114:115]
	s_and_b64 vcc, exec, s[8:9]
	v_cvt_pk_bf16_f32 v116, v108, v109
	v_cvt_pk_bf16_f32 v117, v110, v111
	v_cvt_pk_bf16_f32 v118, v104, v105
	v_cvt_pk_bf16_f32 v119, v106, v107
	flat_store_dwordx4 v[114:115], v[116:119]
	s_cbranch_vccnz .LBB0_162
	s_nop 0
	v_pk_mul_f32 v[116:117], v[100:101], v[100:101]
	s_nop 0
	v_pk_fma_f32 v[116:117], v[116:117], s[46:47], v[146:147] op_sel_hi:[1,0,0]
	s_nop 0
	v_pk_mul_f32 v[116:117], v[100:101], v[116:117]
	s_nop 0
	v_exp_f32_e32 v116, v116
	v_exp_f32_e32 v117, v117
	s_nop 0
	v_pk_add_f32 v[116:117], v[116:117], 1.0 op_sel_hi:[1,0]
	s_nop 0
	v_rcp_f32_e32 v116, v116
	v_rcp_f32_e32 v117, v117
	s_nop 0
	v_pk_mul_f32 v[100:101], v[100:101], v[116:117]

.LBB0_168:
	v_cndmask_b32_e64 v113, 0, 1, s[58:59]
	v_cmp_ne_u32_e64 s[14:15], 1, v113
	s_andn2_b64 vcc, exec, s[58:59]
	v_cvt_pk_bf16_f32 v116, v100, v101
	v_cvt_pk_bf16_f32 v117, v102, v103
	v_cvt_pk_bf16_f32 v118, v96, v97
	v_cvt_pk_bf16_f32 v119, v98, v99
	flat_store_dwordx4 v[114:115], v[116:119] offset:256
	s_cbranch_vccnz .LBB0_172
	v_pk_mul_f32 v[108:109], v[108:109], v[108:109]
	v_pk_mul_f32 v[110:111], v[110:111], v[110:111]
	v_pk_mul_f32 v[104:105], v[104:105], v[104:105]
	v_add_f32_e32 v110, v110, v111
	v_add_f32_e32 v108, v108, v109
	v_pk_mul_f32 v[106:107], v[106:107], v[106:107]
	v_add_f32_e32 v108, v108, v110
	v_add_f32_e32 v104, v104, v105
	v_pk_mul_f32 v[100:101], v[100:101], v[100:101]
	v_add_f32_e32 v104, v108, v104
	v_add_f32_e32 v105, v106, v107
	v_pk_mul_f32 v[102:103], v[102:103], v[102:103]
	v_add_f32_e32 v104, v104, v105
	v_add_f32_e32 v100, v100, v101
	v_pk_mul_f32 v[96:97], v[96:97], v[96:97]
	v_add_f32_e32 v100, v104, v100
	v_add_f32_e32 v101, v102, v103
	v_pk_mul_f32 v[98:99], v[98:99], v[98:99]
	v_add_f32_e32 v100, v100, v101
	v_add_f32_e32 v96, v96, v97
	v_add_f32_e32 v96, v100, v96
	v_add_f32_e32 v97, v98, v99
	v_and_b32_e32 v98, 64, v159
	v_add_f32_e32 v96, v96, v97
	v_xor_b32_e32 v97, 16, v159
	v_add_u32_e32 v98, 64, v98
	v_cmp_lt_i32_e32 vcc, v97, v98
	s_nop 1
	v_cndmask_b32_e32 v97, v159, v97, vcc
	v_lshlrev_b32_e32 v97, 2, v97
	ds_bpermute_b32 v97, v97, v96
	s_waitcnt lgkmcnt(0)
	v_add_f32_e32 v96, v96, v97
	v_xor_b32_e32 v97, 32, v159
	v_cmp_lt_i32_e32 vcc, v97, v98
	s_nop 1
	v_cndmask_b32_e32 v97, v159, v97, vcc
	v_lshlrev_b32_e32 v97, 2, v97
	ds_bpermute_b32 v97, v97, v96
	s_and_saveexec_b64 s[58:59], s[10:11]
	s_cbranch_execz .LBB0_171
	v_ashrrev_i32_e32 v113, 31, v112
	v_lshlrev_b64 v[98:99], 6, v[112:113]
	v_lshl_add_u64 v[98:99], s[30:31], 0, v[98:99]
	v_lshl_add_u64 v[98:99], s[56:57], 2, v[98:99]
	s_lshl_b32 s22, s65, 2
	v_lshl_add_u64 v[98:99], v[98:99], 0, s[22:23]
	s_waitcnt lgkmcnt(0)
	v_add_f32_e32 v96, v96, v97
	flat_store_dword v[98:99], v96

.LBB0_180:
	v_add_u32_e32 v96, 32, v150
	s_waitcnt lgkmcnt(0)
	v_add_u32_e32 v97, 0xffff0020, v150
	v_mov_b64_e32 v[98:99], s[26:27]
	v_mov_b64_e32 v[104:105], s[28:29]
	v_mad_i64_i32 v[98:99], s[4:5], v96, s73, v[98:99]
	v_mad_i64_i32 v[104:105], s[4:5], v97, s72, v[104:105]
	v_cndmask_b32_e64 v99, v105, v99, s[12:13]
	v_cndmask_b32_e64 v98, v104, v98, s[12:13]
	v_lshl_add_u64 v[98:99], v[148:149], 1, v[98:99]
	s_and_b64 vcc, exec, s[8:9]
	v_cvt_pk_bf16_f32 v100, v92, v93
	v_cvt_pk_bf16_f32 v101, v94, v95
	v_cvt_pk_bf16_f32 v102, v88, v89
	v_cvt_pk_bf16_f32 v103, v90, v91
	flat_store_dwordx4 v[98:99], v[100:103]
	s_cbranch_vccnz .LBB0_182
	s_nop 0
	v_pk_mul_f32 v[100:101], v[84:85], v[84:85]
	s_nop 0
	v_pk_fma_f32 v[100:101], v[100:101], s[46:47], v[146:147] op_sel_hi:[1,0,0]
	s_nop 0
	v_pk_mul_f32 v[100:101], v[84:85], v[100:101]
	s_nop 0
	v_exp_f32_e32 v100, v100
	v_exp_f32_e32 v101, v101
	s_nop 0
	v_pk_add_f32 v[100:101], v[100:101], 1.0 op_sel_hi:[1,0]
	s_nop 0
	v_rcp_f32_e32 v100, v100
	v_rcp_f32_e32 v101, v101
	s_nop 0
	v_pk_mul_f32 v[84:85], v[84:85], v[100:101]

.LBB0_188:
	s_and_b64 vcc, exec, s[14:15]
	v_cvt_pk_bf16_f32 v100, v84, v85
	v_cvt_pk_bf16_f32 v101, v86, v87
	v_cvt_pk_bf16_f32 v102, v80, v81
	v_cvt_pk_bf16_f32 v103, v82, v83
	flat_store_dwordx4 v[98:99], v[100:103] offset:256
	s_cbranch_vccnz .LBB0_192
	v_pk_mul_f32 v[92:93], v[92:93], v[92:93]
	v_pk_mul_f32 v[94:95], v[94:95], v[94:95]
	v_pk_mul_f32 v[88:89], v[88:89], v[88:89]
	v_add_f32_e32 v94, v94, v95
	v_add_f32_e32 v92, v92, v93
	v_pk_mul_f32 v[90:91], v[90:91], v[90:91]
	v_add_f32_e32 v92, v92, v94
	v_add_f32_e32 v88, v88, v89
	v_pk_mul_f32 v[84:85], v[84:85], v[84:85]
	v_add_f32_e32 v88, v92, v88
	v_add_f32_e32 v89, v90, v91
	v_pk_mul_f32 v[86:87], v[86:87], v[86:87]
	v_add_f32_e32 v88, v88, v89
	v_add_f32_e32 v84, v84, v85
	v_pk_mul_f32 v[80:81], v[80:81], v[80:81]
	v_add_f32_e32 v84, v88, v84
	v_add_f32_e32 v85, v86, v87
	v_pk_mul_f32 v[82:83], v[82:83], v[82:83]
	v_add_f32_e32 v84, v84, v85
	v_add_f32_e32 v80, v80, v81
	v_add_f32_e32 v80, v84, v80
	v_add_f32_e32 v81, v82, v83
	v_and_b32_e32 v82, 64, v159
	v_add_f32_e32 v80, v80, v81
	v_xor_b32_e32 v81, 16, v159
	v_add_u32_e32 v82, 64, v82
	v_cmp_lt_i32_e32 vcc, v81, v82
	s_nop 1
	v_cndmask_b32_e32 v81, v159, v81, vcc
	v_lshlrev_b32_e32 v81, 2, v81
	ds_bpermute_b32 v81, v81, v80
	s_waitcnt lgkmcnt(0)
	v_add_f32_e32 v80, v80, v81
	v_xor_b32_e32 v81, 32, v159
	v_cmp_lt_i32_e32 vcc, v81, v82
	s_nop 1
	v_cndmask_b32_e32 v81, v159, v81, vcc
	v_lshlrev_b32_e32 v81, 2, v81
	ds_bpermute_b32 v81, v81, v80
	s_and_saveexec_b64 s[58:59], s[10:11]
	s_cbranch_execz .LBB0_191
	v_ashrrev_i32_e32 v97, 31, v96
	v_lshlrev_b64 v[82:83], 6, v[96:97]
	v_lshl_add_u64 v[82:83], s[30:31], 0, v[82:83]
	v_lshl_add_u64 v[82:83], s[56:57], 2, v[82:83]
	s_lshl_b32 s22, s65, 2
	v_lshl_add_u64 v[82:83], v[82:83], 0, s[22:23]
	s_waitcnt lgkmcnt(0)
	v_add_f32_e32 v80, v80, v81
	flat_store_dword v[82:83], v80

.LBB0_200:
	v_add_u32_e32 v80, 48, v150
	s_waitcnt lgkmcnt(0)
	v_add_u32_e32 v81, 0xffff0030, v150
	v_mov_b64_e32 v[82:83], s[26:27]
	v_mov_b64_e32 v[88:89], s[28:29]
	v_mad_i64_i32 v[82:83], s[4:5], v80, s73, v[82:83]
	v_mad_i64_i32 v[88:89], s[4:5], v81, s72, v[88:89]
	v_cndmask_b32_e64 v83, v89, v83, s[12:13]
	v_cndmask_b32_e64 v82, v88, v82, s[12:13]
	v_lshl_add_u64 v[82:83], v[148:149], 1, v[82:83]
	s_and_b64 vcc, exec, s[8:9]
	v_cvt_pk_bf16_f32 v84, v76, v77
	v_cvt_pk_bf16_f32 v85, v78, v79
	v_cvt_pk_bf16_f32 v86, v72, v73
	v_cvt_pk_bf16_f32 v87, v74, v75
	flat_store_dwordx4 v[82:83], v[84:87]
	s_cbranch_vccnz .LBB0_202
	s_nop 0
	v_pk_mul_f32 v[84:85], v[68:69], v[68:69]
	s_nop 0
	v_pk_fma_f32 v[84:85], v[84:85], s[46:47], v[146:147] op_sel_hi:[1,0,0]
	s_nop 0
	v_pk_mul_f32 v[84:85], v[68:69], v[84:85]
	s_nop 0
	v_exp_f32_e32 v84, v84
	v_exp_f32_e32 v85, v85
	s_nop 0
	v_pk_add_f32 v[84:85], v[84:85], 1.0 op_sel_hi:[1,0]
	s_nop 0
	v_rcp_f32_e32 v84, v84
	v_rcp_f32_e32 v85, v85
	s_nop 0
	v_pk_mul_f32 v[68:69], v[68:69], v[84:85]

.LBB0_208:
	s_and_b64 vcc, exec, s[14:15]
	v_cvt_pk_bf16_f32 v84, v68, v69
	v_cvt_pk_bf16_f32 v85, v70, v71
	v_cvt_pk_bf16_f32 v86, v64, v65
	v_cvt_pk_bf16_f32 v87, v66, v67
	flat_store_dwordx4 v[82:83], v[84:87] offset:256
	s_cbranch_vccnz .LBB0_212
	v_pk_mul_f32 v[76:77], v[76:77], v[76:77]
	v_pk_mul_f32 v[78:79], v[78:79], v[78:79]
	v_pk_mul_f32 v[72:73], v[72:73], v[72:73]
	v_add_f32_e32 v78, v78, v79
	v_add_f32_e32 v76, v76, v77
	v_pk_mul_f32 v[74:75], v[74:75], v[74:75]
	v_add_f32_e32 v76, v76, v78
	v_add_f32_e32 v72, v72, v73
	v_pk_mul_f32 v[68:69], v[68:69], v[68:69]
	v_add_f32_e32 v72, v76, v72
	v_add_f32_e32 v73, v74, v75
	v_pk_mul_f32 v[70:71], v[70:71], v[70:71]
	v_add_f32_e32 v72, v72, v73
	v_add_f32_e32 v68, v68, v69
	v_pk_mul_f32 v[64:65], v[64:65], v[64:65]
	v_add_f32_e32 v68, v72, v68
	v_add_f32_e32 v69, v70, v71
	v_pk_mul_f32 v[66:67], v[66:67], v[66:67]
	v_add_f32_e32 v68, v68, v69
	v_add_f32_e32 v64, v64, v65
	v_add_f32_e32 v64, v68, v64
	v_add_f32_e32 v65, v66, v67
	v_and_b32_e32 v66, 64, v159
	v_add_f32_e32 v64, v64, v65
	v_xor_b32_e32 v65, 16, v159
	v_add_u32_e32 v66, 64, v66
	v_cmp_lt_i32_e32 vcc, v65, v66
	s_nop 1
	v_cndmask_b32_e32 v65, v159, v65, vcc
	v_lshlrev_b32_e32 v65, 2, v65
	ds_bpermute_b32 v65, v65, v64
	s_waitcnt lgkmcnt(0)
	v_add_f32_e32 v64, v64, v65
	v_xor_b32_e32 v65, 32, v159
	v_cmp_lt_i32_e32 vcc, v65, v66
	s_nop 1
	v_cndmask_b32_e32 v65, v159, v65, vcc
	v_lshlrev_b32_e32 v65, 2, v65
	ds_bpermute_b32 v65, v65, v64
	s_and_saveexec_b64 s[58:59], s[10:11]
	s_cbranch_execz .LBB0_211
	v_ashrrev_i32_e32 v81, 31, v80
	v_lshlrev_b64 v[66:67], 6, v[80:81]
	v_lshl_add_u64 v[66:67], s[30:31], 0, v[66:67]
	v_lshl_add_u64 v[66:67], s[56:57], 2, v[66:67]
	s_lshl_b32 s22, s65, 2
	v_lshl_add_u64 v[66:67], v[66:67], 0, s[22:23]
	s_waitcnt lgkmcnt(0)
	v_add_f32_e32 v64, v64, v65
	flat_store_dword v[66:67], v64

.LBB0_220:
	v_add_u32_e32 v64, 0x80, v150
	s_waitcnt lgkmcnt(0)
	v_add_u32_e32 v65, 0xffff0080, v150
	v_mov_b64_e32 v[66:67], s[26:27]
	v_mov_b64_e32 v[72:73], s[28:29]
	v_mad_i64_i32 v[66:67], s[4:5], v64, s73, v[66:67]
	v_mad_i64_i32 v[72:73], s[4:5], v65, s72, v[72:73]
	v_cndmask_b32_e64 v67, v73, v67, s[12:13]
	v_cndmask_b32_e64 v66, v72, v66, s[12:13]
	v_lshl_add_u64 v[66:67], v[148:149], 1, v[66:67]
	s_and_b64 vcc, exec, s[8:9]
	v_cvt_pk_bf16_f32 v68, v60, v61
	v_cvt_pk_bf16_f32 v69, v62, v63
	v_cvt_pk_bf16_f32 v70, v56, v57
	v_cvt_pk_bf16_f32 v71, v58, v59
	flat_store_dwordx4 v[66:67], v[68:71]
	s_cbranch_vccnz .LBB0_222
	s_nop 0
	v_pk_mul_f32 v[68:69], v[52:53], v[52:53]
	s_nop 0
	v_pk_fma_f32 v[68:69], v[68:69], s[46:47], v[146:147] op_sel_hi:[1,0,0]
	s_nop 0
	v_pk_mul_f32 v[68:69], v[52:53], v[68:69]
	s_nop 0
	v_exp_f32_e32 v68, v68
	v_exp_f32_e32 v69, v69
	s_nop 0
	v_pk_add_f32 v[68:69], v[68:69], 1.0 op_sel_hi:[1,0]
	s_nop 0
	v_rcp_f32_e32 v68, v68
	v_rcp_f32_e32 v69, v69
	s_nop 0
	v_pk_mul_f32 v[52:53], v[52:53], v[68:69]

.LBB0_228:
	s_and_b64 vcc, exec, s[14:15]
	v_cvt_pk_bf16_f32 v68, v52, v53
	v_cvt_pk_bf16_f32 v69, v54, v55
	v_cvt_pk_bf16_f32 v70, v48, v49
	v_cvt_pk_bf16_f32 v71, v50, v51
	flat_store_dwordx4 v[66:67], v[68:71] offset:256
	s_cbranch_vccnz .LBB0_232
	v_pk_mul_f32 v[60:61], v[60:61], v[60:61]
	v_pk_mul_f32 v[62:63], v[62:63], v[62:63]
	v_pk_mul_f32 v[56:57], v[56:57], v[56:57]
	v_add_f32_e32 v62, v62, v63
	v_add_f32_e32 v60, v60, v61
	v_pk_mul_f32 v[58:59], v[58:59], v[58:59]
	v_add_f32_e32 v60, v60, v62
	v_add_f32_e32 v56, v56, v57
	v_pk_mul_f32 v[52:53], v[52:53], v[52:53]
	v_add_f32_e32 v56, v60, v56
	v_add_f32_e32 v57, v58, v59
	v_pk_mul_f32 v[54:55], v[54:55], v[54:55]
	v_add_f32_e32 v56, v56, v57
	v_add_f32_e32 v52, v52, v53
	v_pk_mul_f32 v[48:49], v[48:49], v[48:49]
	v_add_f32_e32 v52, v56, v52
	v_add_f32_e32 v53, v54, v55
	v_pk_mul_f32 v[50:51], v[50:51], v[50:51]
	v_add_f32_e32 v52, v52, v53
	v_add_f32_e32 v48, v48, v49
	v_add_f32_e32 v48, v52, v48
	v_add_f32_e32 v49, v50, v51
	v_and_b32_e32 v50, 64, v159
	v_add_f32_e32 v48, v48, v49
	v_xor_b32_e32 v49, 16, v159
	v_add_u32_e32 v50, 64, v50
	v_cmp_lt_i32_e32 vcc, v49, v50
	s_nop 1
	v_cndmask_b32_e32 v49, v159, v49, vcc
	v_lshlrev_b32_e32 v49, 2, v49
	ds_bpermute_b32 v49, v49, v48
	s_waitcnt lgkmcnt(0)
	v_add_f32_e32 v48, v48, v49
	v_xor_b32_e32 v49, 32, v159
	v_cmp_lt_i32_e32 vcc, v49, v50
	s_nop 1
	v_cndmask_b32_e32 v49, v159, v49, vcc
	v_lshlrev_b32_e32 v49, 2, v49
	ds_bpermute_b32 v49, v49, v48
	s_and_saveexec_b64 s[58:59], s[10:11]
	s_cbranch_execz .LBB0_231
	v_ashrrev_i32_e32 v65, 31, v64
	v_lshlrev_b64 v[50:51], 6, v[64:65]
	v_lshl_add_u64 v[50:51], s[30:31], 0, v[50:51]
	v_lshl_add_u64 v[50:51], s[56:57], 2, v[50:51]
	s_lshl_b32 s22, s65, 2
	v_lshl_add_u64 v[50:51], v[50:51], 0, s[22:23]
	s_waitcnt lgkmcnt(0)
	v_add_f32_e32 v48, v48, v49
	flat_store_dword v[50:51], v48

.LBB0_240:
	v_add_u32_e32 v48, 0x90, v150
	s_waitcnt lgkmcnt(0)
	v_add_u32_e32 v49, 0xffff0090, v150
	v_mov_b64_e32 v[50:51], s[26:27]
	v_mov_b64_e32 v[56:57], s[28:29]
	v_mad_i64_i32 v[50:51], s[4:5], v48, s73, v[50:51]
	v_mad_i64_i32 v[56:57], s[4:5], v49, s72, v[56:57]
	v_cndmask_b32_e64 v51, v57, v51, s[12:13]
	v_cndmask_b32_e64 v50, v56, v50, s[12:13]
	v_lshl_add_u64 v[50:51], v[148:149], 1, v[50:51]
	s_and_b64 vcc, exec, s[8:9]
	v_cvt_pk_bf16_f32 v52, v44, v45
	v_cvt_pk_bf16_f32 v53, v46, v47
	v_cvt_pk_bf16_f32 v54, v40, v41
	v_cvt_pk_bf16_f32 v55, v42, v43
	flat_store_dwordx4 v[50:51], v[52:55]
	s_cbranch_vccnz .LBB0_242
	s_nop 0
	v_pk_mul_f32 v[52:53], v[36:37], v[36:37]
	s_nop 0
	v_pk_fma_f32 v[52:53], v[52:53], s[46:47], v[146:147] op_sel_hi:[1,0,0]
	s_nop 0
	v_pk_mul_f32 v[52:53], v[36:37], v[52:53]
	s_nop 0
	v_exp_f32_e32 v52, v52
	v_exp_f32_e32 v53, v53
	s_nop 0
	v_pk_add_f32 v[52:53], v[52:53], 1.0 op_sel_hi:[1,0]
	s_nop 0
	v_rcp_f32_e32 v52, v52
	v_rcp_f32_e32 v53, v53
	s_nop 0
	v_pk_mul_f32 v[36:37], v[36:37], v[52:53]

.LBB0_248:
	s_and_b64 vcc, exec, s[14:15]
	v_cvt_pk_bf16_f32 v52, v36, v37
	v_cvt_pk_bf16_f32 v53, v38, v39
	v_cvt_pk_bf16_f32 v54, v32, v33
	v_cvt_pk_bf16_f32 v55, v34, v35
	flat_store_dwordx4 v[50:51], v[52:55] offset:256
	s_cbranch_vccnz .LBB0_252
	v_pk_mul_f32 v[44:45], v[44:45], v[44:45]
	v_pk_mul_f32 v[46:47], v[46:47], v[46:47]
	v_pk_mul_f32 v[40:41], v[40:41], v[40:41]
	v_add_f32_e32 v46, v46, v47
	v_add_f32_e32 v44, v44, v45
	v_pk_mul_f32 v[42:43], v[42:43], v[42:43]
	v_add_f32_e32 v44, v44, v46
	v_add_f32_e32 v40, v40, v41
	v_pk_mul_f32 v[36:37], v[36:37], v[36:37]
	v_add_f32_e32 v40, v44, v40
	v_add_f32_e32 v41, v42, v43
	v_pk_mul_f32 v[38:39], v[38:39], v[38:39]
	v_add_f32_e32 v40, v40, v41
	v_add_f32_e32 v36, v36, v37
	v_pk_mul_f32 v[32:33], v[32:33], v[32:33]
	v_add_f32_e32 v36, v40, v36
	v_add_f32_e32 v37, v38, v39
	v_pk_mul_f32 v[34:35], v[34:35], v[34:35]
	v_add_f32_e32 v36, v36, v37
	v_add_f32_e32 v32, v32, v33
	v_add_f32_e32 v32, v36, v32
	v_add_f32_e32 v33, v34, v35
	v_and_b32_e32 v34, 64, v159
	v_add_f32_e32 v32, v32, v33
	v_xor_b32_e32 v33, 16, v159
	v_add_u32_e32 v34, 64, v34
	v_cmp_lt_i32_e32 vcc, v33, v34
	s_nop 1
	v_cndmask_b32_e32 v33, v159, v33, vcc
	v_lshlrev_b32_e32 v33, 2, v33
	ds_bpermute_b32 v33, v33, v32
	s_waitcnt lgkmcnt(0)
	v_add_f32_e32 v32, v32, v33
	v_xor_b32_e32 v33, 32, v159
	v_cmp_lt_i32_e32 vcc, v33, v34
	s_nop 1
	v_cndmask_b32_e32 v33, v159, v33, vcc
	v_lshlrev_b32_e32 v33, 2, v33
	ds_bpermute_b32 v33, v33, v32
	s_and_saveexec_b64 s[58:59], s[10:11]
	s_cbranch_execz .LBB0_251
	v_ashrrev_i32_e32 v49, 31, v48
	v_lshlrev_b64 v[34:35], 6, v[48:49]
	v_lshl_add_u64 v[34:35], s[30:31], 0, v[34:35]
	v_lshl_add_u64 v[34:35], s[56:57], 2, v[34:35]
	s_lshl_b32 s22, s65, 2
	v_lshl_add_u64 v[34:35], v[34:35], 0, s[22:23]
	s_waitcnt lgkmcnt(0)
	v_add_f32_e32 v32, v32, v33
	flat_store_dword v[34:35], v32

.LBB0_260:
	v_add_u32_e32 v32, 0xa0, v150
	s_waitcnt lgkmcnt(0)
	v_add_u32_e32 v33, 0xffff00a0, v150
	v_mov_b64_e32 v[34:35], s[26:27]
	v_mov_b64_e32 v[40:41], s[28:29]
	v_mad_i64_i32 v[34:35], s[4:5], v32, s73, v[34:35]
	v_mad_i64_i32 v[40:41], s[4:5], v33, s72, v[40:41]
	v_cndmask_b32_e64 v35, v41, v35, s[12:13]
	v_cndmask_b32_e64 v34, v40, v34, s[12:13]
	v_lshl_add_u64 v[34:35], v[148:149], 1, v[34:35]
	s_and_b64 vcc, exec, s[8:9]
	v_cvt_pk_bf16_f32 v36, v28, v29
	v_cvt_pk_bf16_f32 v37, v30, v31
	v_cvt_pk_bf16_f32 v38, v24, v25
	v_cvt_pk_bf16_f32 v39, v26, v27
	flat_store_dwordx4 v[34:35], v[36:39]
	s_cbranch_vccnz .LBB0_262
	s_nop 0
	v_pk_mul_f32 v[36:37], v[20:21], v[20:21]
	s_nop 0
	v_pk_fma_f32 v[36:37], v[36:37], s[46:47], v[146:147] op_sel_hi:[1,0,0]
	s_nop 0
	v_pk_mul_f32 v[36:37], v[20:21], v[36:37]
	s_nop 0
	v_exp_f32_e32 v36, v36
	v_exp_f32_e32 v37, v37
	s_nop 0
	v_pk_add_f32 v[36:37], v[36:37], 1.0 op_sel_hi:[1,0]
	s_nop 0
	v_rcp_f32_e32 v36, v36
	v_rcp_f32_e32 v37, v37
	s_nop 0
	v_pk_mul_f32 v[20:21], v[20:21], v[36:37]

.LBB0_268:
	s_and_b64 vcc, exec, s[14:15]
	v_cvt_pk_bf16_f32 v36, v20, v21
	v_cvt_pk_bf16_f32 v37, v22, v23
	v_cvt_pk_bf16_f32 v38, v16, v17
	v_cvt_pk_bf16_f32 v39, v18, v19
	flat_store_dwordx4 v[34:35], v[36:39] offset:256
	s_cbranch_vccnz .LBB0_272
	v_pk_mul_f32 v[28:29], v[28:29], v[28:29]
	v_pk_mul_f32 v[30:31], v[30:31], v[30:31]
	v_pk_mul_f32 v[24:25], v[24:25], v[24:25]
	v_add_f32_e32 v30, v30, v31
	v_add_f32_e32 v28, v28, v29
	v_pk_mul_f32 v[26:27], v[26:27], v[26:27]
	v_add_f32_e32 v28, v28, v30
	v_add_f32_e32 v24, v24, v25
	v_pk_mul_f32 v[20:21], v[20:21], v[20:21]
	v_add_f32_e32 v24, v28, v24
	v_add_f32_e32 v25, v26, v27
	v_pk_mul_f32 v[22:23], v[22:23], v[22:23]
	v_add_f32_e32 v24, v24, v25
	v_add_f32_e32 v20, v20, v21
	v_pk_mul_f32 v[16:17], v[16:17], v[16:17]
	v_add_f32_e32 v20, v24, v20
	v_add_f32_e32 v21, v22, v23
	v_pk_mul_f32 v[18:19], v[18:19], v[18:19]
	v_add_f32_e32 v20, v20, v21
	v_add_f32_e32 v16, v16, v17
	v_add_f32_e32 v16, v20, v16
	v_add_f32_e32 v17, v18, v19
	v_and_b32_e32 v18, 64, v159
	v_add_f32_e32 v16, v16, v17
	v_xor_b32_e32 v17, 16, v159
	v_add_u32_e32 v18, 64, v18
	v_cmp_lt_i32_e32 vcc, v17, v18
	s_nop 1
	v_cndmask_b32_e32 v17, v159, v17, vcc
	v_lshlrev_b32_e32 v17, 2, v17
	ds_bpermute_b32 v17, v17, v16
	s_waitcnt lgkmcnt(0)
	v_add_f32_e32 v16, v16, v17
	v_xor_b32_e32 v17, 32, v159
	v_cmp_lt_i32_e32 vcc, v17, v18
	s_nop 1
	v_cndmask_b32_e32 v17, v159, v17, vcc
	v_lshlrev_b32_e32 v17, 2, v17
	ds_bpermute_b32 v17, v17, v16
	s_and_saveexec_b64 s[58:59], s[10:11]
	s_cbranch_execz .LBB0_271
	v_ashrrev_i32_e32 v33, 31, v32
	v_lshlrev_b64 v[18:19], 6, v[32:33]
	v_lshl_add_u64 v[18:19], s[30:31], 0, v[18:19]
	v_lshl_add_u64 v[18:19], s[56:57], 2, v[18:19]
	s_lshl_b32 s22, s65, 2
	v_lshl_add_u64 v[18:19], v[18:19], 0, s[22:23]
	s_waitcnt lgkmcnt(0)
	v_add_f32_e32 v16, v16, v17
	flat_store_dword v[18:19], v16

.LBB0_280:
	v_add_u32_e32 v16, 0xb0, v150
	s_waitcnt lgkmcnt(0)
	v_add_u32_e32 v17, 0xffff00b0, v150
	v_mov_b64_e32 v[18:19], s[26:27]
	v_mov_b64_e32 v[24:25], s[28:29]
	v_mad_i64_i32 v[18:19], s[4:5], v16, s73, v[18:19]
	v_mad_i64_i32 v[24:25], s[4:5], v17, s72, v[24:25]
	v_cndmask_b32_e64 v19, v25, v19, s[12:13]
	v_cndmask_b32_e64 v18, v24, v18, s[12:13]
	v_lshl_add_u64 v[18:19], v[148:149], 1, v[18:19]
	s_and_b64 vcc, exec, s[8:9]
	v_cvt_pk_bf16_f32 v20, v12, v13
	v_cvt_pk_bf16_f32 v21, v14, v15
	v_cvt_pk_bf16_f32 v22, v8, v9
	v_cvt_pk_bf16_f32 v23, v10, v11
	flat_store_dwordx4 v[18:19], v[20:23]
	s_cbranch_vccnz .LBB0_282
	s_nop 0
	v_pk_mul_f32 v[20:21], v[4:5], v[4:5]
	s_nop 0
	v_pk_fma_f32 v[20:21], v[20:21], s[46:47], v[146:147] op_sel_hi:[1,0,0]
	s_nop 0
	v_pk_mul_f32 v[20:21], v[4:5], v[20:21]
	s_nop 0
	v_exp_f32_e32 v20, v20
	v_exp_f32_e32 v21, v21
	s_nop 0
	v_pk_add_f32 v[20:21], v[20:21], 1.0 op_sel_hi:[1,0]
	s_nop 0
	v_rcp_f32_e32 v20, v20
	v_rcp_f32_e32 v21, v21
	s_nop 0
	v_pk_mul_f32 v[4:5], v[4:5], v[20:21]

.LBB0_288:
	s_and_b64 vcc, exec, s[14:15]
	v_cvt_pk_bf16_f32 v20, v4, v5
	v_cvt_pk_bf16_f32 v21, v6, v7
	v_cvt_pk_bf16_f32 v22, v0, v1
	v_cvt_pk_bf16_f32 v23, v2, v3
	flat_store_dwordx4 v[18:19], v[20:23] offset:256
	s_cbranch_vccnz .LBB0_292
	v_pk_mul_f32 v[12:13], v[12:13], v[12:13]
	v_pk_mul_f32 v[14:15], v[14:15], v[14:15]
	v_pk_mul_f32 v[8:9], v[8:9], v[8:9]
	v_add_f32_e32 v14, v14, v15
	v_add_f32_e32 v12, v12, v13
	v_pk_mul_f32 v[10:11], v[10:11], v[10:11]
	v_add_f32_e32 v12, v12, v14
	v_add_f32_e32 v8, v8, v9
	v_pk_mul_f32 v[4:5], v[4:5], v[4:5]
	v_add_f32_e32 v8, v12, v8
	v_add_f32_e32 v9, v10, v11
	v_pk_mul_f32 v[6:7], v[6:7], v[6:7]
	v_add_f32_e32 v8, v8, v9
	v_add_f32_e32 v4, v4, v5
	v_pk_mul_f32 v[0:1], v[0:1], v[0:1]
	v_add_f32_e32 v4, v8, v4
	v_add_f32_e32 v5, v6, v7
	v_pk_mul_f32 v[2:3], v[2:3], v[2:3]
	v_add_f32_e32 v4, v4, v5
	v_add_f32_e32 v0, v0, v1
	v_add_f32_e32 v0, v4, v0
	v_add_f32_e32 v1, v2, v3
	v_and_b32_e32 v2, 64, v159
	v_add_f32_e32 v0, v0, v1
	v_xor_b32_e32 v1, 16, v159
	v_add_u32_e32 v2, 64, v2
	v_cmp_lt_i32_e32 vcc, v1, v2
	s_nop 1
	v_cndmask_b32_e32 v1, v159, v1, vcc
	v_lshlrev_b32_e32 v1, 2, v1
	ds_bpermute_b32 v1, v1, v0
	s_waitcnt lgkmcnt(0)
	v_add_f32_e32 v0, v0, v1
	v_xor_b32_e32 v1, 32, v159
	v_cmp_lt_i32_e32 vcc, v1, v2
	s_nop 1
	v_cndmask_b32_e32 v1, v159, v1, vcc
	v_lshlrev_b32_e32 v1, 2, v1
	ds_bpermute_b32 v1, v1, v0
	s_and_saveexec_b64 s[8:9], s[10:11]
	s_cbranch_execz .LBB0_291
	v_ashrrev_i32_e32 v17, 31, v16
	v_lshlrev_b64 v[2:3], 6, v[16:17]
	v_lshl_add_u64 v[2:3], s[30:31], 0, v[2:3]
	v_lshl_add_u64 v[2:3], s[56:57], 2, v[2:3]
	s_lshl_b32 s22, s65, 2
	v_lshl_add_u64 v[2:3], v[2:3], 0, s[22:23]
	s_waitcnt lgkmcnt(0)
	v_add_f32_e32 v0, v0, v1
	flat_store_dword v[2:3], v0

.LBB0_349:
	v_or_b32_e32 v0, s50, v20
	v_mov_b64_e32 v[54:55], s[46:47]
	s_mul_i32 s33, s51, 0x3400
	v_mad_u64_u32 v[0:1], s[4:5], v0, s54, v[54:55]
	v_add_u32_e32 v1, s33, v1
	s_lshl_b32 s16, s52, 8
	v_or_b32_e32 v2, s50, v28
	v_lshl_add_u64 v[0:1], v[0:1], 0, s[16:17]
	v_mad_u64_u32 v[2:3], s[4:5], v2, s54, v[54:55]
	v_lshl_add_u64 v[0:1], v[0:1], 0, v[22:23]
	v_add_u32_e32 v3, s33, v3
	v_add_co_u32_e32 v0, vcc, s27, v0
	v_lshl_add_u64 v[2:3], v[2:3], 0, s[16:17]
	s_nop 0
	v_addc_co_u32_e32 v1, vcc, 0, v1, vcc
	v_lshl_add_u64 v[2:3], v[2:3], 0, v[22:23]
	v_add_co_u32_e32 v2, vcc, s27, v2
	v_mov_b32_e32 v51, v23
	s_nop 0
	v_addc_co_u32_e32 v3, vcc, 0, v3, vcc
	flat_load_dwordx4 v[4:7], v[0:1] offset:3072
	flat_load_dwordx4 v[8:11], v[2:3] offset:3072
	v_lshl_add_u64 v[2:3], s[50:51], 0, v[32:33]
	v_mad_u64_u32 v[16:17], s[4:5], v2, s54, v[54:55]
	v_mov_b32_e32 v2, v17
	v_mad_u64_u32 v[2:3], s[4:5], v3, s54, v[2:3]
	v_or_b32_e32 v0, s50, v30
	v_mov_b32_e32 v17, v2
	v_mad_u64_u32 v[0:1], s[4:5], v0, s54, v[54:55]
	v_lshl_add_u64 v[2:3], v[16:17], 0, s[16:17]
	v_lshl_add_u64 v[16:17], s[50:51], 0, v[26:27]
	v_add_u32_e32 v1, s33, v1
	v_mad_u64_u32 v[18:19], s[4:5], v16, s54, v[54:55]
	v_lshl_add_u64 v[0:1], v[0:1], 0, s[16:17]
	v_mov_b32_e32 v16, v19
	v_lshl_add_u64 v[0:1], v[0:1], 0, v[22:23]
	v_mad_u64_u32 v[16:17], s[4:5], v17, s54, v[16:17]
	v_add_co_u32_e32 v0, vcc, s27, v0
	v_mov_b32_e32 v19, v16
	s_nop 0
	v_addc_co_u32_e32 v1, vcc, 0, v1, vcc
	v_lshl_add_u64 v[2:3], v[2:3], 0, v[22:23]
	v_lshl_add_u64 v[16:17], v[18:19], 0, s[16:17]
	v_add_co_u32_e32 v2, vcc, s27, v2
	v_mov_b32_e32 v53, v23
	v_lshl_add_u64 v[16:17], v[16:17], 0, v[50:51]
	v_addc_co_u32_e32 v3, vcc, 0, v3, vcc
	v_lshl_add_u64 v[16:17], v[16:17], 0, v[52:53]
	v_add_co_u32_e32 v62, vcc, s27, v16
	v_lshl_add_u64 v[60:61], v[16:17], 0, s[22:23]
	s_nop 0
	v_addc_co_u32_e32 v63, vcc, 0, v17, vcc
	v_lshl_add_u64 v[64:65], v[16:17], 0, s[24:25]
	v_add_co_u32_e32 v16, vcc, s57, v16
	s_lshl_b32 s4, s52, 9
	s_nop 0
	v_addc_co_u32_e32 v17, vcc, 0, v17, vcc
	s_mov_b32 s5, s17
	flat_load_dwordx4 v[112:115], v[0:1] offset:3072
	s_nop 0
	flat_load_dwordx4 v[0:3], v[2:3] offset:3072
	s_nop 0
	flat_load_dwordx2 v[72:73], v[62:63] offset:1024
	flat_load_dwordx2 v[70:71], v[60:61] offset:32
	flat_load_dwordx2 v[68:69], v[60:61] offset:64
	flat_load_dwordx2 v[66:67], v[60:61] offset:96
	flat_load_dwordx2 v[58:59], v[16:17] offset:1024
	flat_load_dwordx2 v[56:57], v[64:65] offset:32
	flat_load_dwordx2 v[18:19], v[64:65] offset:64
	s_nop 0
	flat_load_dwordx2 v[16:17], v[64:65] offset:96
	v_lshl_add_u64 v[64:65], v[14:15], 0, s[4:5]
	s_waitcnt lgkmcnt(0)
	s_barrier
	flat_load_dwordx4 v[116:119], v[64:65]
	flat_load_dwordx4 v[120:123], v[64:65] offset:16
	ds_read_b32 v43, v25
	ds_read_b32 v47, v94
	ds_read_b32 v49, v97
	ds_read_b32 v111, v100
	s_add_i32 s60, s60, s38
	s_add_i32 s59, s59, s39
	s_cmpk_lt_i32 s60, 0x1000
	s_waitcnt vmcnt(0)
	v_lshlrev_b32_e32 v45, 16, v4
	v_and_b32_e32 v4, 0xffff0000, v4
	s_waitcnt lgkmcnt(0)
	v_mul_f32_e32 v4, v43, v4
	v_mul_f32_e32 v45, v43, v45
	v_lshlrev_b32_e32 v74, 16, v5
	v_and_b32_e32 v5, 0xffff0000, v5
	v_mul_f32_e32 v74, v43, v74
	v_mul_f32_e32 v5, v43, v5
	v_lshlrev_b32_e32 v75, 16, v6
	v_and_b32_e32 v6, 0xffff0000, v6
	v_mul_f32_e32 v75, v43, v75
	v_mul_f32_e32 v6, v43, v6
	v_lshlrev_b32_e32 v176, 16, v70
	v_and_b32_e32 v177, 0xffff0000, v70
	v_lshlrev_b32_e32 v178, 16, v71
	v_and_b32_e32 v179, 0xffff0000, v71
	v_lshlrev_b32_e32 v182, 16, v69
	v_and_b32_e32 v183, 0xffff0000, v69
	v_lshlrev_b32_e32 v180, 16, v68
	v_mul_f32_e32 v4, v4, v117
	v_mul_f32_e32 v45, v45, v116
	v_cvt_pk_bf16_f32 v4, v45, v4
	v_mul_f32_e32 v74, v74, v118
	v_mul_f32_e32 v5, v5, v119
	v_lshlrev_b32_e32 v116, 16, v7
	v_and_b32_e32 v7, 0xffff0000, v7
	ds_write_b16 v29, v4 offset:34816
	ds_write_b16_d16_hi v31, v4 offset:35088
	v_cvt_pk_bf16_f32 v4, v74, v5
	v_mul_f32_e32 v75, v75, v120
	v_mul_f32_e32 v6, v6, v121
	v_mul_f32_e32 v116, v43, v116
	v_mul_f32_e32 v7, v43, v7
	ds_write_b16 v29, v4 offset:35360
	ds_write_b16_d16_hi v31, v4 offset:35632
	v_cvt_pk_bf16_f32 v4, v75, v6
	v_mul_f32_e32 v116, v116, v122
	v_mul_f32_e32 v7, v7, v123
	ds_write_b16 v29, v4 offset:35904
	ds_write_b16_d16_hi v31, v4 offset:36176
	v_cvt_pk_bf16_f32 v4, v116, v7
	ds_write_b16 v29, v4 offset:36448
	ds_write_b16_d16_hi v31, v4 offset:36720
	flat_load_dwordx4 v[4:7], v[64:65]
	flat_load_dwordx4 v[116:119], v[64:65] offset:16
	v_lshlrev_b32_e32 v43, 16, v8
	v_and_b32_e32 v8, 0xffff0000, v8
	v_lshlrev_b32_e32 v45, 16, v9
	v_and_b32_e32 v9, 0xffff0000, v9
	v_mul_f32_e32 v43, v47, v43
	v_lshlrev_b32_e32 v74, 16, v10
	v_and_b32_e32 v10, 0xffff0000, v10
	v_lshlrev_b32_e32 v75, 16, v11
	v_and_b32_e32 v11, 0xffff0000, v11
	v_mul_f32_e32 v8, v47, v8
	v_mul_f32_e32 v45, v47, v45
	v_mul_f32_e32 v9, v47, v9
	v_mul_f32_e32 v74, v47, v74
	v_mul_f32_e32 v10, v47, v10
	v_mul_f32_e32 v75, v47, v75
	v_mul_f32_e32 v11, v47, v11
	v_lshlrev_b32_e32 v47, 16, v113
	v_mul_f32_e32 v47, v49, v47
	v_lshlrev_b32_e32 v120, 16, v2
	v_and_b32_e32 v121, 0xffff0000, v2
	v_lshlrev_b32_e32 v122, 16, v3
	v_and_b32_e32 v123, 0xffff0000, v3
	v_mul_f32_e32 v124, v111, v120
	v_mul_f32_e32 v125, v111, v121
	v_mul_f32_e32 v122, v111, v122
	v_and_b32_e32 v181, 0xffff0000, v68
	v_lshlrev_b32_e32 v184, 16, v66
	v_and_b32_e32 v185, 0xffff0000, v66
	v_lshlrev_b32_e32 v186, 16, v67
	v_and_b32_e32 v187, 0xffff0000, v67
	v_pk_mul_f32 v[66:67], v[176:177], v[176:177]
	v_pk_mul_f32 v[68:69], v[178:179], v[178:179]
	v_pk_mul_f32 v[70:71], v[180:181], v[180:181]
	s_waitcnt vmcnt(0) lgkmcnt(0)
	v_mul_f32_e32 v4, v43, v4
	v_mul_f32_e32 v5, v8, v5
	v_mul_f32_e32 v6, v45, v6
	v_mul_f32_e32 v7, v9, v7
	v_cvt_pk_bf16_f32 v4, v4, v5
	v_mul_f32_e32 v8, v74, v116
	v_mul_f32_e32 v9, v10, v117
	v_mul_f32_e32 v10, v75, v118
	v_mul_f32_e32 v11, v11, v119
	v_cvt_pk_bf16_f32 v5, v6, v7
	v_cvt_pk_bf16_f32 v6, v8, v9
	v_cvt_pk_bf16_f32 v7, v10, v11
	ds_write_b16 v95, v4 offset:34816
	ds_write_b16_d16_hi v96, v4 offset:35088
	ds_write_b16 v95, v5 offset:35360
	ds_write_b16_d16_hi v96, v5 offset:35632
	ds_write_b16 v95, v6 offset:35904
	ds_write_b16_d16_hi v96, v6 offset:36176
	ds_write_b16 v95, v7 offset:36448
	ds_write_b16_d16_hi v96, v7 offset:36720
	flat_load_dwordx4 v[4:7], v[64:65]
	flat_load_dwordx4 v[8:11], v[64:65] offset:16
	v_lshlrev_b32_e32 v43, 16, v112
	v_and_b32_e32 v45, 0xffff0000, v112
	v_and_b32_e32 v74, 0xffff0000, v113
	v_mul_f32_e32 v43, v49, v43
	v_lshlrev_b32_e32 v75, 16, v114
	v_and_b32_e32 v112, 0xffff0000, v114
	v_lshlrev_b32_e32 v113, 16, v115
	v_and_b32_e32 v114, 0xffff0000, v115
	v_mul_f32_e32 v45, v49, v45
	v_mul_f32_e32 v74, v49, v74
	v_mul_f32_e32 v75, v49, v75
	v_mul_f32_e32 v112, v49, v112
	v_mul_f32_e32 v113, v49, v113
	v_mul_f32_e32 v49, v49, v114
	v_pk_mul_f32 v[114:115], v[182:183], v[182:183]
	v_pk_mul_f32 v[118:119], v[186:187], v[186:187]
	v_pk_mul_f32 v[116:117], v[184:185], v[184:185]
	s_waitcnt vmcnt(0) lgkmcnt(0)
	v_mul_f32_e32 v4, v43, v4
	v_mul_f32_e32 v5, v45, v5
	v_mul_f32_e32 v6, v47, v6
	v_mul_f32_e32 v7, v74, v7
	v_cvt_pk_bf16_f32 v4, v4, v5
	v_mul_f32_e32 v8, v75, v8
	v_mul_f32_e32 v9, v112, v9
	v_mul_f32_e32 v10, v113, v10
	v_mul_f32_e32 v11, v49, v11
	v_cvt_pk_bf16_f32 v5, v6, v7
	v_cvt_pk_bf16_f32 v6, v8, v9
	v_cvt_pk_bf16_f32 v7, v10, v11
	ds_write_b16 v98, v4 offset:34816
	ds_write_b16_d16_hi v99, v4 offset:35088
	ds_write_b16 v98, v5 offset:35360
	ds_write_b16_d16_hi v99, v5 offset:35632
	ds_write_b16 v98, v6 offset:35904
	ds_write_b16_d16_hi v99, v6 offset:36176
	ds_write_b16 v98, v7 offset:36448
	ds_write_b16_d16_hi v99, v7 offset:36720
	flat_load_dwordx4 v[8:11], v[64:65]
	flat_load_dwordx4 v[4:7], v[64:65] offset:16
	v_or_b32_e32 v43, s52, v92
	v_mov_b32_e32 v75, v23
	v_lshlrev_b32_e32 v74, 2, v43
	v_lshl_add_u64 v[112:113], s[36:37], 0, v[74:75]
	v_lshlrev_b32_e32 v74, 16, v72
	v_and_b32_e32 v75, 0xffff0000, v72
	v_lshlrev_b32_e32 v72, 16, v73
	v_and_b32_e32 v73, 0xffff0000, v73
	v_mov_b64_e32 v[64:65], s[28:29]
	v_pk_mul_f32 v[2:3], v[72:73], v[72:73]
	v_lshlrev_b32_e32 v43, 16, v0
	v_pk_fma_f32 v[2:3], v[2:3], s[26:27], v[64:65] op_sel_hi:[1,0,0] neg_lo:[1,0,0] neg_hi:[1,0,0]
	v_and_b32_e32 v45, 0xffff0000, v0
	v_mul_f32_e32 v43, v111, v43
	v_pk_mul_f32 v[2:3], v[2:3], v[72:73]
	v_lshlrev_b32_e32 v47, 16, v1
	v_and_b32_e32 v49, 0xffff0000, v1
	v_mul_f32_e32 v45, v111, v45
	v_exp_f32_e32 v120, v2
	v_mul_f32_e32 v47, v111, v47
	v_mul_f32_e32 v49, v111, v49
	v_mul_f32_e32 v111, v111, v123
	v_exp_f32_e32 v121, v3
	v_pk_mul_f32 v[0:1], v[74:75], v[74:75]
	v_pk_fma_f32 v[66:67], v[66:67], s[26:27], v[64:65] op_sel_hi:[1,0,0] neg_lo:[1,0,0] neg_hi:[1,0,0]
	v_pk_fma_f32 v[0:1], v[0:1], s[26:27], v[64:65] op_sel_hi:[1,0,0] neg_lo:[1,0,0] neg_hi:[1,0,0]
	v_pk_fma_f32 v[68:69], v[68:69], s[26:27], v[64:65] op_sel_hi:[1,0,0] neg_lo:[1,0,0] neg_hi:[1,0,0]
	v_pk_fma_f32 v[114:115], v[114:115], s[26:27], v[64:65] op_sel_hi:[1,0,0] neg_lo:[1,0,0] neg_hi:[1,0,0]
	v_pk_mul_f32 v[0:1], v[0:1], v[74:75]
	v_pk_mul_f32 v[66:67], v[66:67], v[176:177]
	v_pk_mul_f32 v[68:69], v[68:69], v[178:179]
	v_pk_mul_f32 v[114:115], v[114:115], v[182:183]
	v_exp_f32_e32 v0, v0
	v_exp_f32_e32 v1, v1
	v_exp_f32_e32 v66, v66
	v_exp_f32_e32 v67, v67
	v_exp_f32_e32 v68, v68
	v_exp_f32_e32 v69, v69
	v_exp_f32_e32 v123, v115
	v_pk_fma_f32 v[118:119], v[118:119], s[26:27], v[64:65] op_sel_hi:[1,0,0] neg_lo:[1,0,0] neg_hi:[1,0,0]
	v_pk_add_f32 v[136:137], v[0:1], 1.0 op_sel_hi:[1,0]
	v_pk_mul_f32 v[118:119], v[118:119], v[186:187]
	v_pk_add_f32 v[140:141], v[120:121], 1.0 op_sel_hi:[1,0]
	v_exp_f32_e32 v128, v118
	v_exp_f32_e32 v129, v119
	v_pk_add_f32 v[144:145], v[66:67], 1.0 op_sel_hi:[1,0]
	v_pk_add_f32 v[148:149], v[68:69], 1.0 op_sel_hi:[1,0]
	v_pk_fma_f32 v[116:117], v[116:117], s[26:27], v[64:65] op_sel_hi:[1,0,0] neg_lo:[1,0,0] neg_hi:[1,0,0]
	v_pk_add_f32 v[172:173], v[128:129], 1.0 op_sel_hi:[1,0]
	v_pk_mul_f32 v[116:117], v[116:117], v[184:185]
	v_rcp_f32_e32 v174, v136
	v_rcp_f32_e32 v175, v137
	v_rcp_f32_e32 v188, v140
	v_rcp_f32_e32 v189, v141
	v_rcp_f32_e32 v190, v144
	v_rcp_f32_e32 v191, v145
	v_rcp_f32_e32 v192, v148
	v_rcp_f32_e32 v193, v149
	v_pk_fma_f32 v[70:71], v[70:71], s[26:27], v[64:65] op_sel_hi:[1,0,0] neg_lo:[1,0,0] neg_hi:[1,0,0]
	v_rcp_f32_e32 v202, v172
	v_pk_mul_f32 v[70:71], v[70:71], v[180:181]
	v_rcp_f32_e32 v203, v173
	v_exp_f32_e32 v70, v70
	v_exp_f32_e32 v71, v71
	v_pk_mul_f32 v[74:75], v[174:175], v[74:75]
	v_pk_mul_f32 v[204:205], v[188:189], v[72:73]
	v_pk_mul_f32 v[206:207], v[190:191], v[176:177]
	v_pk_add_f32 v[70:71], v[70:71], 1.0 op_sel_hi:[1,0]
	v_pk_mul_f32 v[192:193], v[192:193], v[178:179]
	v_rcp_f32_e32 v194, v70
	v_rcp_f32_e32 v195, v71
	v_pk_mul_f32 v[202:203], v[202:203], v[186:187]
	v_pk_mul_f32 v[194:195], v[194:195], v[180:181]
	s_waitcnt vmcnt(0) lgkmcnt(0)
	v_mul_f32_e32 v2, v43, v8
	v_mul_f32_e32 v3, v45, v9
	v_mul_f32_e32 v4, v124, v4
	v_mul_f32_e32 v5, v125, v5
	v_cvt_pk_bf16_f32 v2, v2, v3
	v_mul_f32_e32 v8, v47, v10
	v_mul_f32_e32 v9, v49, v11
	v_mul_f32_e32 v6, v122, v6
	v_mul_f32_e32 v7, v111, v7
	v_cvt_pk_bf16_f32 v3, v8, v9
	v_cvt_pk_bf16_f32 v4, v4, v5
	v_cvt_pk_bf16_f32 v5, v6, v7
	ds_write_b16 v101, v2 offset:34816
	ds_write_b16_d16_hi v102, v2 offset:35088
	ds_write_b16 v101, v3 offset:35360
	ds_write_b16_d16_hi v102, v3 offset:35632
	ds_write_b16 v101, v4 offset:35904
	ds_write_b16_d16_hi v102, v4 offset:36176
	ds_write_b16 v101, v5 offset:36448
	ds_write_b16_d16_hi v102, v5 offset:36720
	s_waitcnt lgkmcnt(0)
	s_barrier
	flat_load_dword v43, v[112:113]
	v_exp_f32_e32 v122, v114
	ds_read_b128 v[0:3], v76 offset:34816
	ds_read_b128 v[4:7], v110
	ds_read_b128 v[8:11], v77 offset:34816
	ds_read_b128 v[66:69], v78 offset:34816
	ds_read_b128 v[112:115], v110 offset:64
	v_pk_add_f32 v[164:165], v[122:123], 1.0 op_sel_hi:[1,0]
	ds_read_b128 v[120:123], v79 offset:34816
	ds_read_b128 v[128:131], v80 offset:34816
	ds_read_b128 v[136:139], v81 offset:34816
	ds_read_b128 v[140:143], v82 offset:34816
	ds_read_b128 v[144:147], v83 offset:34816
	ds_read_b128 v[148:151], v84 offset:34816
	v_exp_f32_e32 v124, v116
	v_exp_f32_e32 v125, v117
	s_waitcnt lgkmcnt(0)
	v_mfma_f32_16x16x32_bf16 v[116:119], v[0:3], v[4:7], 0
	ds_read_b128 v[152:155], v110 offset:128
	ds_read_b128 v[156:159], v85 offset:34816
	v_rcp_f32_e32 v198, v164
	v_pk_add_f32 v[168:169], v[124:125], 1.0 op_sel_hi:[1,0]
	v_mfma_f32_16x16x32_bf16 v[124:127], v[8:11], v[4:7], 0
	v_rcp_f32_e32 v199, v165
	v_rcp_f32_e32 v200, v168
	v_rcp_f32_e32 v201, v169
	v_mfma_f32_16x16x32_bf16 v[132:135], v[66:69], v[4:7], 0
	v_mul_f32_e64 v198, v198, v182
	v_mul_f32_e64 v199, v199, v183
	v_pk_mul_f32 v[200:201], v[200:201], v[184:185]
	v_mfma_f32_16x16x32_bf16 v[4:7], v[120:123], v[4:7], 0
	v_mfma_f32_16x16x32_bf16 v[116:119], v[128:131], v[112:115], v[116:119]
	v_mfma_f32_16x16x32_bf16 v[124:127], v[136:139], v[112:115], v[124:127]
	v_mfma_f32_16x16x32_bf16 v[132:135], v[140:143], v[112:115], v[132:135]
	v_mfma_f32_16x16x32_bf16 v[4:7], v[144:147], v[112:115], v[4:7]
	ds_read_b128 v[112:115], v86 offset:34816
	ds_read_b128 v[160:163], v110 offset:192
	ds_read_b128 v[164:167], v87 offset:34816
	ds_read_b128 v[168:171], v88 offset:34816
	s_waitcnt lgkmcnt(0)
	v_mfma_f32_16x16x32_bf16 v[116:119], v[148:151], v[152:155], v[116:119]
	ds_read_b128 v[172:175], v89 offset:34816
	ds_read_b128 v[70:73], v90 offset:34816
	v_mfma_f32_16x16x32_bf16 v[124:127], v[156:159], v[152:155], v[124:127]
	v_mfma_f32_16x16x32_bf16 v[132:135], v[112:115], v[152:155], v[132:135]
	v_mfma_f32_16x16x32_bf16 v[4:7], v[164:167], v[152:155], v[4:7]
	ds_read_b128 v[152:155], v91 offset:34816
	ds_read_b128 v[176:179], v110 offset:4352
	ds_read_b128 v[180:183], v110 offset:4416
	ds_read_b128 v[184:187], v110 offset:4480
	ds_read_b128 v[188:191], v110 offset:4544
	v_mfma_f32_16x16x32_bf16 v[116:119], v[168:171], v[160:163], v[116:119]
	s_waitcnt lgkmcnt(0)
	v_mfma_f32_16x16x32_bf16 v[124:127], v[172:175], v[160:163], v[124:127]
	v_mfma_f32_16x16x32_bf16 v[132:135], v[70:73], v[160:163], v[132:135]
	s_waitcnt vmcnt(0)
	s_nop 3
	v_add_f32_e32 v45, v116, v43
	v_mfma_f32_16x16x32_bf16 v[4:7], v[152:155], v[160:163], v[4:7]
	v_add_f32_e32 v47, v117, v43
	v_add_f32_e32 v49, v118, v43
	v_add_f32_e32 v111, v119, v43
	v_add_f32_e32 v116, v124, v43
	v_add_f32_e32 v117, v125, v43
	v_add_f32_e32 v118, v126, v43
	v_add_f32_e32 v119, v127, v43
	v_add_f32_e32 v125, v133, v43
	v_add_f32_e32 v126, v134, v43
	v_add_f32_e32 v4, v4, v43
	v_add_f32_e32 v5, v5, v43
	v_add_f32_e32 v124, v132, v43
	v_add_f32_e32 v127, v135, v43
	v_add_f32_e32 v6, v6, v43
	v_add_f32_e32 v7, v7, v43
	v_mul_f32_e32 v43, v74, v45
	v_mul_f32_e32 v45, v75, v47
	v_mul_f32_e32 v47, v204, v49
	v_mul_f32_e32 v49, v205, v111
	v_mul_f32_e32 v74, v206, v116
	v_mul_f32_e32 v75, v207, v117
	v_mul_f32_e32 v111, v192, v118
	v_mul_f32_e32 v116, v193, v119
	v_mul_f32_e32 v118, v195, v125
	v_mul_f32_e32 v119, v198, v126
	v_mul_f32_e32 v125, v200, v4
	v_mul_f32_e32 v126, v201, v5
	v_cvt_pk_bf16_f32 v4, v43, v45
	v_cvt_pk_bf16_f32 v5, v47, v49
	v_mul_f32_e32 v117, v194, v124
	v_mul_f32_e32 v124, v199, v127
	v_mul_f32_e32 v127, v202, v6
	v_mul_f32_e32 v132, v203, v7
	v_cvt_pk_bf16_f32 v6, v74, v75
	v_cvt_pk_bf16_f32 v7, v111, v116
	v_cvt_pk_bf16_f32 v74, v117, v118
	v_cvt_pk_bf16_f32 v75, v119, v124
	flat_store_dwordx2 v[62:63], v[4:5] offset:1024
	flat_store_dwordx2 v[60:61], v[6:7] offset:32
	flat_store_dwordx2 v[60:61], v[74:75] offset:64
	v_or_b32_e32 v4, s52, v93
	v_lshlrev_b32_e32 v4, 2, v4
	v_mov_b32_e32 v5, v23
	v_cvt_pk_bf16_f32 v116, v125, v126
	v_cvt_pk_bf16_f32 v117, v127, v132
	flat_store_dwordx2 v[60:61], v[116:117] offset:96
	v_lshl_add_u64 v[4:5], s[36:37], 0, v[4:5]
	flat_load_dword v43, v[4:5]
	v_lshl_add_u64 v[6:7], s[50:51], 0, v[34:35]
	v_mfma_f32_16x16x32_bf16 v[2:5], v[0:3], v[176:179], 0
	v_mad_u64_u32 v[54:55], s[4:5], v6, s54, v[54:55]
	v_mov_b32_e32 v6, v55
	v_mfma_f32_16x16x32_bf16 v[60:63], v[66:69], v[176:179], 0
	v_mad_u64_u32 v[0:1], s[4:5], v7, s54, v[6:7]
	v_lshlrev_b32_e32 v74, 16, v58
	v_mfma_f32_16x16x32_bf16 v[66:69], v[120:123], v[176:179], 0
	v_and_b32_e32 v75, 0xffff0000, v58
	v_lshlrev_b32_e32 v116, 16, v59
	v_and_b32_e32 v117, 0xffff0000, v59
	v_mov_b32_e32 v55, v0
	v_mfma_f32_16x16x32_bf16 v[6:9], v[8:11], v[176:179], 0
	v_mul_f32_e64 v58, v74, v74
	v_mul_f32_e64 v59, v75, v75
	v_pk_mul_f32 v[122:123], v[116:117], v[116:117]
	v_lshl_add_u64 v[0:1], v[54:55], 0, s[16:17]
	v_mfma_f32_16x16x32_bf16 v[2:5], v[128:131], v[180:183], v[2:5]
	v_lshlrev_b32_e32 v118, 16, v56
	v_and_b32_e32 v119, 0xffff0000, v56
	v_lshlrev_b32_e32 v120, 16, v57
	v_and_b32_e32 v121, 0xffff0000, v57
	v_mfma_f32_16x16x32_bf16 v[54:57], v[140:143], v[180:183], v[60:63]
	v_fma_f32 v122, -v122, s26, v64
	v_fma_f32 v123, -v123, s26, v64
	v_pk_mul_f32 v[124:125], v[118:119], v[118:119]
	v_pk_mul_f32 v[126:127], v[120:121], v[120:121]
	v_pk_fma_f32 v[62:63], v[58:59], s[26:27], v[64:65] op_sel_hi:[1,0,0] neg_lo:[1,0,0] neg_hi:[1,0,0]
	v_mfma_f32_16x16x32_bf16 v[58:61], v[144:147], v[180:183], v[66:69]
	v_mul_f32_e64 v62, v62, v74
	v_mul_f32_e64 v63, v63, v75
	v_pk_fma_f32 v[124:125], v[124:125], s[26:27], v[64:65] op_sel_hi:[1,0,0] neg_lo:[1,0,0] neg_hi:[1,0,0]
	v_exp_f32_e32 v62, v62
	v_pk_mul_f32 v[68:69], v[122:123], v[116:117]
	v_exp_f32_e32 v63, v63
	v_exp_f32_e32 v68, v68
	v_exp_f32_e32 v69, v69
	v_mfma_f32_16x16x32_bf16 v[6:9], v[136:139], v[180:183], v[6:9]
	v_mul_f32_e64 v122, v124, v118
	v_mul_f32_e64 v123, v125, v119
	v_pk_add_f32 v[62:63], v[62:63], 1.0 op_sel_hi:[1,0]
	v_pk_add_f32 v[68:69], v[68:69], 1.0 op_sel_hi:[1,0]
	v_mfma_f32_16x16x32_bf16 v[2:5], v[148:151], v[184:187], v[2:5]
	v_fma_f32 v66, -v126, s26, v64
	v_fma_f32 v67, -v127, s26, v64
	v_rcp_f32_e32 v62, v62
	v_rcp_f32_e32 v63, v63
	v_mfma_f32_16x16x32_bf16 v[54:57], v[112:115], v[184:187], v[54:57]
	v_exp_f32_e32 v112, v122
	v_exp_f32_e32 v113, v123
	v_rcp_f32_e32 v68, v68
	v_mfma_f32_16x16x32_bf16 v[6:9], v[156:159], v[184:187], v[6:9]
	v_rcp_f32_e32 v69, v69
	v_pk_mul_f32 v[66:67], v[66:67], v[120:121]
	v_pk_add_f32 v[112:113], v[112:113], 1.0 op_sel_hi:[1,0]
	v_mfma_f32_16x16x32_bf16 v[2:5], v[168:171], v[188:191], v[2:5]
	v_exp_f32_e32 v66, v66
	v_exp_f32_e32 v67, v67
	v_lshl_add_u64 v[0:1], v[0:1], 0, v[50:51]
	v_mfma_f32_16x16x32_bf16 v[6:9], v[172:175], v[188:191], v[6:9]
	v_rcp_f32_e32 v112, v112
	v_rcp_f32_e32 v113, v113
	v_pk_mul_f32 v[62:63], v[62:63], v[74:75]
	v_pk_mul_f32 v[68:69], v[68:69], v[116:117]
	v_lshl_add_u64 v[10:11], v[0:1], 0, v[52:53]
	v_lshl_add_u64 v[0:1], v[10:11], 0, s[22:23]
	v_add_co_u32_e32 v10, vcc, s27, v10
	v_mfma_f32_16x16x32_bf16 v[54:57], v[70:73], v[188:191], v[54:57]
	s_nop 0
	v_addc_co_u32_e32 v11, vcc, 0, v11, vcc
	s_waitcnt vmcnt(0) lgkmcnt(0)
	v_add_f32_e32 v2, v2, v43
	v_add_f32_e32 v3, v3, v43
	v_add_f32_e32 v4, v4, v43
	v_add_f32_e32 v5, v5, v43
	v_mul_f32_e32 v2, v62, v2
	v_mul_f32_e32 v3, v63, v3
	v_mul_f32_e32 v4, v68, v4
	v_mul_f32_e32 v5, v69, v5
	v_cvt_pk_bf16_f32 v2, v2, v3
	v_cvt_pk_bf16_f32 v3, v4, v5
	v_pk_add_f32 v[4:5], v[66:67], 1.0 op_sel_hi:[1,0]
	flat_store_dwordx2 v[10:11], v[2:3] offset:1024
	v_rcp_f32_e32 v4, v4
	v_rcp_f32_e32 v5, v5
	v_pk_mul_f32 v[2:3], v[112:113], v[118:119]
	v_add_f32_e32 v6, v6, v43
	v_mul_f32_e32 v2, v2, v6
	v_add_f32_e32 v6, v7, v43
	v_mul_f32_e32 v3, v3, v6
	v_pk_mul_f32 v[4:5], v[4:5], v[120:121]
	v_cvt_pk_bf16_f32 v2, v2, v3
	v_add_f32_e32 v3, v8, v43
	v_mul_f32_e32 v3, v4, v3
	v_add_f32_e32 v4, v9, v43
	v_mul_f32_e32 v45, v5, v4
	v_lshlrev_b32_e32 v4, 16, v18
	v_and_b32_e32 v5, 0xffff0000, v18
	v_pk_mul_f32 v[6:7], v[4:5], v[4:5]
	v_lshlrev_b32_e32 v8, 16, v19
	v_pk_fma_f32 v[6:7], v[6:7], s[26:27], v[64:65] op_sel_hi:[1,0,0] neg_lo:[1,0,0] neg_hi:[1,0,0]
	v_and_b32_e32 v9, 0xffff0000, v19
	v_pk_mul_f32 v[6:7], v[6:7], v[4:5]
	v_pk_mul_f32 v[10:11], v[8:9], v[8:9]
	v_exp_f32_e32 v6, v6
	v_exp_f32_e32 v7, v7
	v_pk_fma_f32 v[10:11], v[10:11], s[26:27], v[64:65] op_sel_hi:[1,0,0] neg_lo:[1,0,0] neg_hi:[1,0,0]
	v_cvt_pk_bf16_f32 v3, v3, v45
	flat_store_dwordx2 v[0:1], v[2:3] offset:32
	v_pk_mul_f32 v[10:11], v[10:11], v[8:9]
	v_pk_add_f32 v[6:7], v[6:7], 1.0 op_sel_hi:[1,0]
	v_exp_f32_e32 v10, v10
	v_exp_f32_e32 v11, v11
	v_rcp_f32_e32 v6, v6
	v_rcp_f32_e32 v7, v7
	v_mfma_f32_16x16x32_bf16 v[58:61], v[164:167], v[184:187], v[58:61]
	v_add_f32_e64 v10, v10, 1.0
	v_add_f32_e64 v11, v11, 1.0
	v_pk_mul_f32 v[2:3], v[6:7], v[4:5]
	v_rcp_f32_e32 v10, v10
	v_rcp_f32_e32 v11, v11
	v_add_f32_e32 v6, v54, v43
	v_mul_f32_e32 v2, v2, v6
	v_add_f32_e32 v6, v55, v43
	v_mul_f32_e32 v3, v3, v6
	v_pk_mul_f32 v[4:5], v[10:11], v[8:9]
	v_cvt_pk_bf16_f32 v2, v2, v3
	v_add_f32_e32 v3, v56, v43
	v_mul_f32_e32 v3, v4, v3
	v_add_f32_e32 v4, v57, v43
	v_mul_f32_e32 v18, v5, v4
	v_lshlrev_b32_e32 v4, 16, v16
	v_and_b32_e32 v5, 0xffff0000, v16
	v_pk_mul_f32 v[6:7], v[4:5], v[4:5]
	v_lshlrev_b32_e32 v8, 16, v17
	v_pk_fma_f32 v[6:7], v[6:7], s[26:27], v[64:65] op_sel_hi:[1,0,0] neg_lo:[1,0,0] neg_hi:[1,0,0]
	v_and_b32_e32 v9, 0xffff0000, v17
	v_pk_mul_f32 v[6:7], v[6:7], v[4:5]
	v_pk_mul_f32 v[10:11], v[8:9], v[8:9]
	v_exp_f32_e32 v6, v6
	v_exp_f32_e32 v7, v7
	v_pk_fma_f32 v[10:11], v[10:11], s[26:27], v[64:65] op_sel_hi:[1,0,0] neg_lo:[1,0,0] neg_hi:[1,0,0]
	v_mfma_f32_16x16x32_bf16 v[58:61], v[152:155], v[188:191], v[58:61]
	v_mul_f32_e64 v10, v10, v8
	v_mul_f32_e64 v11, v11, v9
	v_pk_add_f32 v[6:7], v[6:7], 1.0 op_sel_hi:[1,0]
	v_exp_f32_e32 v10, v10
	v_exp_f32_e32 v11, v11
	v_rcp_f32_e32 v6, v6
	v_rcp_f32_e32 v7, v7
	v_cvt_pk_bf16_f32 v3, v3, v18
	v_pk_add_f32 v[10:11], v[10:11], 1.0 op_sel_hi:[1,0]
	flat_store_dwordx2 v[0:1], v[2:3] offset:64
	v_rcp_f32_e32 v10, v10
	v_rcp_f32_e32 v11, v11
	v_pk_mul_f32 v[2:3], v[6:7], v[4:5]
	v_add_f32_e32 v6, v58, v43
	v_mul_f32_e32 v2, v2, v6
	v_add_f32_e32 v6, v59, v43
	v_mul_f32_e32 v3, v3, v6
	v_pk_mul_f32 v[4:5], v[10:11], v[8:9]
	v_cvt_pk_bf16_f32 v2, v2, v3
	v_add_f32_e32 v3, v60, v43
	v_mul_f32_e32 v3, v4, v3
	v_add_f32_e32 v4, v61, v43
	v_mul_f32_e32 v4, v5, v4
	v_cvt_pk_bf16_f32 v3, v3, v4
	flat_store_dwordx2 v[0:1], v[2:3] offset:96
	s_cbranch_scc0 .LBB0_354
.LBB0_350:
	s_ashr_i32 s4, s60, 9
	s_ashr_i32 s5, s4, 31
	s_lshl_b64 s[50:51], s[4:5], 13
	s_and_b32 s4, s59, 0x1f80
	s_or_b32 s50, s50, s4
	s_waitcnt vmcnt(0)
	s_barrier
	s_and_saveexec_b64 s[52:53], s[6:7]
	s_cbranch_execz .LBB0_352
	v_mov_b32_e32 v1, s51
	v_or_b32_e32 v0, s50, v196
	v_lshlrev_b64 v[0:1], 6, v[0:1]
	v_lshl_add_u64 v[16:17], s[48:49], 0, v[0:1]
	flat_load_dwordx4 v[0:3], v[16:17]
	flat_load_dwordx4 v[4:7], v[16:17] offset:16
	flat_load_dwordx4 v[8:11], v[16:17] offset:32
	s_nop 0
	flat_load_dwordx4 v[16:19], v[16:17] offset:48
	s_waitcnt vmcnt(0) lgkmcnt(0)
	v_pk_add_f32 v[0:1], v[0:1], v[4:5]
	v_pk_add_f32 v[2:3], v[2:3], v[6:7]
	v_pk_add_f32 v[0:1], v[0:1], v[8:9]
	v_pk_add_f32 v[2:3], v[2:3], v[10:11]
	v_pk_add_f32 v[0:1], v[0:1], v[16:17]
	v_pk_add_f32 v[2:3], v[2:3], v[18:19]
	v_add_f32_e32 v0, v0, v1
	v_add_f32_e32 v0, v2, v0
	v_add_f32_e32 v0, v3, v0
	v_fmamk_f32 v0, v0, 0x3a800000, v105
	v_mul_f32_e32 v1, 0x4b800000, v0
	v_cmp_gt_f32_e32 vcc, s56, v0
	s_nop 1
	v_cndmask_b32_e32 v0, v0, v1, vcc
	v_rsq_f32_e32 v0, v0
	s_nop 0
	v_mul_f32_e32 v1, 0x45800000, v0
	v_cndmask_b32_e32 v0, v0, v1, vcc
	ds_write_b32 v21, v0
.LBB0_352:
	s_or_b64 exec, exec, s[52:53]
	s_and_b32 s52, s60, 7
	s_cmp_eq_u32 s52, s61
	s_cbranch_scc1 .LBB0_349
	s_lshl_b32 s16, s52, 15
	v_lshl_add_u64 v[4:5], v[12:13], 0, s[16:17]
	v_mov_b32_e32 v43, v23
	v_lshl_add_u64 v[0:1], v[4:5], 0, v[42:43]
	flat_load_dwordx4 v[0:3], v[0:1]
	v_mov_b32_e32 v45, v23
	v_lshl_add_u64 v[6:7], v[4:5], 0, v[44:45]
	v_mov_b32_e32 v47, v23
	v_mov_b32_e32 v49, v23
	s_mov_b32 s61, s52
	s_waitcnt vmcnt(0) lgkmcnt(0)
	ds_write_b128 v106, v[0:3]
	flat_load_dwordx4 v[0:3], v[6:7]
	v_lshl_add_u64 v[6:7], v[4:5], 0, v[46:47]
	v_lshl_add_u64 v[4:5], v[4:5], 0, v[48:49]
	s_waitcnt vmcnt(0) lgkmcnt(0)
	ds_write_b128 v107, v[0:3]
	flat_load_dwordx4 v[0:3], v[6:7]
	s_waitcnt vmcnt(0) lgkmcnt(0)
	ds_write_b128 v108, v[0:3]
	flat_load_dwordx4 v[0:3], v[4:5]
	s_waitcnt vmcnt(0) lgkmcnt(0)
	ds_write_b128 v109, v[0:3]
	s_branch .LBB0_349

.LBB0_355:
	s_andn2_b64 vcc, exec, s[36:37]
	s_cbranch_vccnz .LBB0_345
	s_mov_b64 s[46:47], s[0:1]
	s_and_saveexec_b64 s[36:37], s[8:9]
	s_cbranch_execz .LBB0_344
	s_and_b64 exec, exec, s[10:11]
	s_cbranch_execz .LBB0_344
	s_load_dwordx4 s[48:51], s[46:47], 0x40
	v_lshlrev_b64 v[16:17], 2, v[36:37]
	v_mov_b32_e32 v43, v103
	s_waitcnt lgkmcnt(0)
	v_lshl_add_u64 v[8:9], s[48:49], 0, v[16:17]
	v_add_co_u32_e32 v4, vcc, 0x1000, v8
	v_lshl_add_u64 v[16:17], s[50:51], 0, v[16:17]
	s_nop 0
	v_addc_co_u32_e32 v5, vcc, 0, v9, vcc
	v_add_co_u32_e32 v10, vcc, 0x2000, v8
	flat_load_dwordx4 v[0:3], v[8:9]
	s_nop 0
	flat_load_dwordx4 v[4:7], v[4:5] offset:1024
	v_addc_co_u32_e32 v11, vcc, 0, v9, vcc
	v_add_co_u32_e32 v12, vcc, 0x3000, v8
	s_nop 1
	v_addc_co_u32_e32 v13, vcc, 0, v9, vcc
	flat_load_dwordx4 v[8:11], v[10:11] offset:2048
	s_nop 0
	flat_load_dwordx4 v[12:15], v[12:13] offset:3072
	s_load_dwordx4 s[48:51], s[46:47], 0xd8
	flat_load_dwordx4 v[16:19], v[16:17]
	s_waitcnt lgkmcnt(0)
	s_add_u32 s46, s50, 0x4cf6000
	s_addc_u32 s47, s51, 0
	v_lshl_add_u64 v[54:55], s[50:51], 0, v[38:39]
	v_lshl_add_u64 v[56:57], s[48:49], 0, v[40:41]
	s_mov_b64 s[48:49], 0
	s_branch .LBB0_360
.LBB0_359:
	s_or_b64 exec, exec, s[50:51]
	s_waitcnt vmcnt(0) lgkmcnt(0)
	v_lshlrev_b32_e32 v62, 16, v60
	v_and_b32_e32 v63, 0xffff0000, v60
	v_lshlrev_b32_e32 v60, 16, v61
	v_and_b32_e32 v61, 0xffff0000, v61
	v_pk_fma_f32 v[62:63], v[0:1], v[62:63], v[16:17]
	v_pk_fma_f32 v[60:61], v[2:3], v[60:61], v[18:19]
	v_lshlrev_b32_e32 v68, 16, v58
	v_and_b32_e32 v69, 0xffff0000, v58
	v_lshlrev_b32_e32 v58, 16, v59
	v_and_b32_e32 v59, 0xffff0000, v59
	v_pk_fma_f32 v[58:59], v[6:7], v[58:59], v[60:61]
	v_pk_fma_f32 v[60:61], v[4:5], v[68:69], v[62:63]
	v_lshlrev_b32_e32 v62, 16, v66
	v_and_b32_e32 v63, 0xffff0000, v66
	v_lshlrev_b32_e32 v66, 16, v67
	v_and_b32_e32 v67, 0xffff0000, v67
	v_pk_fma_f32 v[60:61], v[8:9], v[62:63], v[60:61]
	v_lshlrev_b32_e32 v62, 16, v64
	v_and_b32_e32 v63, 0xffff0000, v64
	v_add_u32_e32 v43, 1, v43
	v_pk_fma_f32 v[58:59], v[10:11], v[66:67], v[58:59]
	v_lshlrev_b32_e32 v64, 16, v65
	v_and_b32_e32 v65, 0xffff0000, v65
	v_pk_fma_f32 v[60:61], v[12:13], v[62:63], v[60:61]
	v_cmp_ge_i32_e32 vcc, v43, v104
	v_pk_fma_f32 v[58:59], v[14:15], v[64:65], v[58:59]
	v_cvt_pk_bf16_f32 v60, v60, v61
	v_lshl_add_u64 v[54:55], v[54:55], 0, s[30:31]
	v_cvt_pk_bf16_f32 v61, v58, v59
	flat_store_dwordx2 v[56:57], v[60:61]
	s_or_b64 s[48:49], vcc, s[48:49]
	v_lshl_add_u64 v[56:57], v[56:57], 0, s[34:35]
	s_andn2_b64 exec, exec, s[48:49]
	s_cbranch_execz .LBB0_344
.LBB0_360:
	v_cmp_lt_i32_e32 vcc, s58, v43
	s_and_saveexec_b64 s[4:5], vcc
	s_xor_b64 s[50:51], exec, s[4:5]
	v_add_u32_e32 v22, 0xffff0000, v43
	v_mov_b64_e32 v[58:59], s[46:47]
	v_and_b32_e32 v45, 0xff, v43
	v_mad_u64_u32 v[58:59], s[4:5], v22, s55, v[58:59]
	s_or_saveexec_b64 s[50:51], s[50:51]
	v_mov_b64_e32 v[64:65], 0x500
	v_mov_b32_e32 v47, 0x100
	s_xor_b64 exec, exec, s[50:51]
	v_and_b32_e32 v45, 0x1fff, v43
	v_mov_b64_e32 v[64:65], 0x1a00
	v_mov_b32_e32 v47, 0x2000
	v_mov_b64_e32 v[58:59], v[54:55]
	s_or_b64 exec, exec, s[50:51]
	v_lshl_add_u64 v[62:63], v[36:37], 1, v[58:59]
	v_cmp_lt_u32_e32 vcc, 1, v45
	v_mov_b32_e32 v58, 0
	v_mov_b32_e32 v60, 0
	v_mov_b32_e32 v61, 0
	s_and_saveexec_b64 s[50:51], vcc
	s_cbranch_execz .LBB0_366
	v_mul_hi_i32_i24_e32 v61, -4, v64
	v_mul_i32_i24_e32 v60, -4, v64
	v_lshl_add_u64 v[60:61], v[62:63], 0, v[60:61]
	flat_load_dwordx2 v[60:61], v[60:61]
.LBB0_366:
	s_or_b64 exec, exec, s[50:51]
	v_cmp_ne_u32_e32 vcc, 0, v45
	v_lshlrev_b32_e32 v22, 1, v64
	v_mov_b32_e32 v59, 0
	s_and_saveexec_b64 s[50:51], vcc
	s_cbranch_execz .LBB0_368
	v_sub_co_u32_e32 v58, vcc, v62, v22
	s_nop 1
	v_subbrev_co_u32_e32 v59, vcc, 0, v63, vcc
	flat_load_dwordx2 v[58:59], v[58:59]
.LBB0_368:
	s_or_b64 exec, exec, s[50:51]
	flat_load_dwordx2 v[66:67], v[62:63]
	v_add_u32_e32 v45, 1, v45
	v_cmp_lt_u32_e32 vcc, v45, v47
	v_mov_b32_e32 v64, 0
	v_mov_b32_e32 v65, 0
	s_and_saveexec_b64 s[50:51], vcc
	s_cbranch_execz .LBB0_359
	v_lshl_add_u64 v[62:63], v[62:63], 0, v[22:23]
	flat_load_dwordx2 v[64:65], v[62:63]
	s_branch .LBB0_359

.LBB0_420:
	s_load_dwordx4 s[16:19], s[8:9], 0xd8
	v_lshlrev_b32_e32 v0, 4, v196
	v_add_u32_e32 v1, 0x2000, v0
	v_lshrrev_b32_e32 v2, 3, v196
	s_movk_i32 s3, 0x70
	v_lshrrev_b32_e32 v1, 7, v1
	s_movk_i32 s4, 0xf0
	v_and_b32_e32 v5, 32, v196
	s_waitcnt lgkmcnt(0)
	s_add_u32 s37, s18, 0xd00000
	v_and_or_b32 v2, v2, s3, v222
	v_and_or_b32 v1, v1, s4, v222
	v_bitop3_b32 v0, v0, v5, 48 bitop3:0x6c
	s_addc_u32 s39, s19, 0
	s_lshr_b32 s66, s34, 8
	v_mul_u32_u24_e32 v3, 0xa00, v2
	v_mul_u32_u24_e32 v4, 0xa00, v1
	v_and_or_b32 v0, v196, 64, v0
	v_and_b32_e32 v208, 15, v196
	v_bfe_u32 v209, v196, 4, 2
	s_lshl_b32 s68, s66, 6
	v_or_b32_e32 v152, v0, v3
	v_lshl_or_b32 v154, v2, 9, v0
	v_or_b32_e32 v156, v4, v0
	v_lshl_or_b32 v158, v1, 9, v0
	v_lshlrev_b32_e32 v0, 2, v209
	s_bfe_u32 s4, s34, 0x20006
	v_or_b32_e32 v8, s68, v208
	s_lshl_b32 s69, s4, 4
	v_lshl_or_b32 v0, s10, 6, v0
	v_lshl_add_u32 v9, s90, 8, v8
	s_movk_i32 s3, 0xa00
	v_or_b32_e32 v0, s69, v0
	v_or_b32_e32 v6, 16, v9
	v_mov_b64_e32 v[4:5], s[16:17]
	v_ashrrev_i32_e32 v1, 31, v0
	v_mov_b64_e32 v[2:3], s[16:17]
	v_mad_i64_i32 v[4:5], s[8:9], v6, s3, v[4:5]
	v_or_b32_e32 v10, 32, v9
	v_mov_b64_e32 v[6:7], s[16:17]
	v_mad_i64_i32 v[2:3], s[8:9], v9, s3, v[2:3]
	v_lshlrev_b64 v[0:1], 1, v[0:1]
	v_mad_i64_i32 v[6:7], s[8:9], v10, s3, v[6:7]
	v_or_b32_e32 v12, 48, v9
	v_mov_b64_e32 v[10:11], s[16:17]
	v_lshl_add_u64 v[2:3], v[2:3], 0, v[0:1]
	v_lshl_add_u64 v[4:5], v[4:5], 0, v[0:1]
	v_mad_i64_i32 v[10:11], s[8:9], v12, s3, v[10:11]
	v_lshl_add_u64 v[6:7], v[6:7], 0, v[0:1]
	v_lshl_add_u64 v[10:11], v[10:11], 0, v[0:1]
	flat_load_dwordx2 v[188:189], v[2:3]
	flat_load_dwordx2 v[186:187], v[4:5]
	flat_load_dwordx2 v[184:185], v[6:7]
	flat_load_dwordx2 v[182:183], v[10:11]
	v_add_u32_e32 v4, 0x80, v9
	v_mov_b64_e32 v[2:3], s[16:17]
	v_mad_i64_i32 v[2:3], s[8:9], v4, s3, v[2:3]
	v_add_u32_e32 v6, 0x90, v9
	v_mov_b64_e32 v[4:5], s[16:17]
	v_mad_i64_i32 v[4:5], s[8:9], v6, s3, v[4:5]
	v_add_u32_e32 v10, 0xa0, v9
	v_mov_b64_e32 v[6:7], s[16:17]
	v_mad_i64_i32 v[6:7], s[8:9], v10, s3, v[6:7]
	v_add_u32_e32 v9, 0xb0, v9
	v_mov_b64_e32 v[10:11], s[16:17]
	s_lshr_b32 s5, s34, 6
	v_mad_i64_i32 v[10:11], s[8:9], v9, s3, v[10:11]
	s_lshl_b32 s67, s5, 10
	s_mul_i32 s8, s90, 0xa0000
	s_mul_hi_i32 s5, s90, 0xa0000
	s_add_u32 s14, s16, s8
	s_addc_u32 s5, s17, s5
	s_ashr_i32 s11, s10, 31
	s_lshl_b64 s[8:9], s[10:11], 17
	s_add_u32 s12, s37, s8
	s_addc_u32 s13, s39, s9
	s_add_i32 s70, s67, 0
	v_lshl_add_u64 v[2:3], v[2:3], 0, v[0:1]
	s_add_i32 m0, s70, 0x10000
	v_lshl_add_u64 v[4:5], v[4:5], 0, v[0:1]
	v_lshl_add_u64 v[6:7], v[6:7], 0, v[0:1]
	v_lshl_add_u64 v[0:1], v[10:11], 0, v[0:1]
	flat_load_dwordx2 v[170:171], v[2:3]
	flat_load_dwordx2 v[168:169], v[4:5]
	flat_load_dwordx2 v[166:167], v[6:7]
	flat_load_dwordx2 v[164:165], v[0:1]
	v_writelane_b32 v254, s82, 4
	global_load_lds_dwordx4 v154, s[12:13]
	s_add_i32 m0, s70, 0x12000
	s_add_u32 s8, s12, 0x10000
	global_load_lds_dwordx4 v158, s[12:13]
	s_addc_u32 s9, s13, 0
	s_add_i32 m0, s70, 0x14000
	v_writelane_b32 v254, s83, 5
	global_load_lds_dwordx4 v154, s[8:9]
	s_add_i32 m0, s70, 0x16000
	s_add_u32 s14, s14, s6
	s_addc_u32 s15, s5, s7
	s_add_i32 s71, s70, 0x2000
	global_load_lds_dwordx4 v158, s[8:9]
	s_mov_b32 m0, s70
	s_add_u32 s6, s14, 0x50000
	global_load_lds_dwordx4 v152, s[14:15]
	s_mov_b32 m0, s71
	s_addc_u32 s7, s15, 0
	s_add_i32 s72, s70, 0x4000
	global_load_lds_dwordx4 v156, s[14:15]
	s_mov_b32 m0, s72
	s_add_i32 s73, s70, 0x6000
	global_load_lds_dwordx4 v152, s[6:7]
	s_mov_b32 m0, s73
	v_mov_b32_e32 v155, 0
	global_load_lds_dwordx4 v156, s[6:7]
	v_writelane_b32 v254, s80, 0
	v_mov_b32_e32 v159, v155
	v_mov_b32_e32 v153, v155
	v_mov_b32_e32 v157, v155
	s_cmp_eq_u32 s66, 1
	v_writelane_b32 v254, s81, 1
	s_mov_b32 s95, s78
	s_mov_b32 s45, s75
	s_mov_b32 s74, 0
	v_lshl_add_u64 v[6:7], s[12:13], 0, v[154:155]
	v_lshl_add_u64 v[4:5], s[12:13], 0, v[158:159]
	v_lshl_add_u64 v[2:3], s[14:15], 0, v[152:153]
	s_cselect_b64 s[22:23], -1, 0
	s_cmp_lg_u32 s66, 1
	v_lshl_add_u64 v[0:1], s[14:15], 0, v[156:157]
	v_writelane_b32 v254, s79, 2
	s_cbranch_scc1 .LBB0_422
	s_barrier

.LBB0_433:
	v_mov_b32_e32 v215, v208
	v_mov_b32_e32 v217, v209
	s_lshl_b32 s4, s10, 6
	s_or_b32 s4, s4, s69
	v_lshlrev_b32_e32 v216, 2, v217
	v_add_u32_e32 v176, s4, v216
	v_ashrrev_i32_e32 v177, 31, v176
	v_lshlrev_b64 v[64:65], 2, v[176:177]
	v_lshl_add_u64 v[66:67], s[26:27], 0, v[64:65]
	s_movk_i32 s4, 0x1000
	v_lshl_add_u64 v[68:69], s[28:29], 0, v[64:65]
	flat_load_dwordx4 v[92:95], v[66:67]
	flat_load_dwordx4 v[84:87], v[68:69]
	v_add_co_u32_e32 v66, vcc, s4, v66
	v_lshl_add_u64 v[64:65], s[30:31], 0, v[64:65]
	s_nop 0
	v_addc_co_u32_e32 v67, vcc, 0, v67, vcc
	flat_load_dwordx4 v[88:91], v[64:65]
	flat_load_dwordx4 v[72:75], v[66:67] offset:1024
	v_add_co_u32_e32 v66, vcc, 0x1000, v68
	s_cmpk_gt_i32 s90, 0xff
	s_nop 0
	v_addc_co_u32_e32 v67, vcc, 0, v69, vcc
	v_add_co_u32_e32 v64, vcc, 0x1000, v64
	s_cselect_b64 s[54:55], -1, 0
	s_nop 0
	v_addc_co_u32_e32 v65, vcc, 0, v65, vcc
	flat_load_dwordx4 v[68:71], v[66:67] offset:1024
	s_nop 0
	flat_load_dwordx4 v[64:67], v[64:65] offset:1024
	s_cmpk_lt_i32 s90, 0x100
	s_cselect_b64 s[56:57], -1, 0
	s_lshl_b32 s4, s90, 8
	s_add_i32 s4, s4, s68
	v_add_u32_e32 v218, s4, v215
	s_and_b64 vcc, exec, s[54:55]
	s_cbranch_vccnz .LBB0_435
	v_mov_b64_e32 v[172:173], s[24:25]
	v_add_u32_e32 v180, 16, v218
	v_add_u32_e32 v190, 32, v218
	v_mad_i64_i32 v[174:175], s[4:5], v218, s88, v[172:173]
	v_lshlrev_b64 v[178:179], 1, v[176:177]
	v_mad_i64_i32 v[180:181], s[4:5], v180, s88, v[172:173]
	v_mad_i64_i32 v[190:191], s[4:5], v190, s88, v[172:173]
	v_add_u32_e32 v192, 48, v218
	v_lshl_add_u64 v[174:175], v[174:175], 0, v[178:179]
	v_lshl_add_u64 v[180:181], v[180:181], 0, v[178:179]
	v_lshl_add_u64 v[190:191], v[190:191], 0, v[178:179]
	v_mad_i64_i32 v[192:193], s[4:5], v192, s88, v[172:173]
	v_lshl_add_u64 v[200:201], v[192:193], 0, v[178:179]
	flat_load_dwordx2 v[198:199], v[174:175] offset:2560
	flat_load_dwordx2 v[194:195], v[180:181] offset:2560
	flat_load_dwordx2 v[192:193], v[190:191] offset:2560
	s_nop 0
	flat_load_dwordx2 v[190:191], v[200:201] offset:2560
	v_add_u32_e32 v180, 0x90, v218
	v_mad_i64_i32 v[180:181], s[4:5], v180, s88, v[172:173]
	v_lshl_add_u64 v[200:201], v[180:181], 0, v[178:179]
	v_add_u32_e32 v180, 0xa0, v218
	v_mad_i64_i32 v[180:181], s[4:5], v180, s88, v[172:173]
	v_add_u32_e32 v174, 0x80, v218
	v_lshl_add_u64 v[202:203], v[180:181], 0, v[178:179]
	v_add_u32_e32 v180, 0xb0, v218
	v_mad_i64_i32 v[174:175], s[4:5], v174, s88, v[172:173]
	v_mad_i64_i32 v[172:173], s[4:5], v180, s88, v[172:173]
	v_lshl_add_u64 v[174:175], v[174:175], 0, v[178:179]
	v_lshl_add_u64 v[172:173], v[172:173], 0, v[178:179]
	flat_load_dwordx2 v[180:181], v[174:175] offset:2560
	flat_load_dwordx2 v[178:179], v[200:201] offset:2560
	s_nop 0
	flat_load_dwordx2 v[174:175], v[202:203] offset:2560
	s_nop 0
	flat_load_dwordx2 v[172:173], v[172:173] offset:2560
.LBB0_435:
	s_waitcnt vmcnt(0) lgkmcnt(0)
	v_pk_fma_f32 v[150:151], v[150:151], s[36:37], v[94:95] op_sel_hi:[1,0,1] neg_lo:[1,0,0] neg_hi:[1,0,0]
	v_pk_fma_f32 v[148:149], v[148:149], s[36:37], v[92:93] op_sel_hi:[1,0,1] neg_lo:[1,0,0] neg_hi:[1,0,0]
	v_exp_f32_e32 v150, v150
	v_exp_f32_e32 v151, v151
	v_exp_f32_e32 v148, v148
	v_exp_f32_e32 v149, v149
	v_pk_fma_f32 v[146:147], v[146:147], s[36:37], v[86:87] op_sel_hi:[1,0,1] neg_lo:[1,0,0] neg_hi:[1,0,0]
	v_pk_add_f32 v[150:151], v[150:151], 1.0 op_sel_hi:[1,0]
	v_exp_f32_e32 v146, v146
	v_exp_f32_e32 v147, v147
	v_rcp_f32_e32 v150, v150
	v_rcp_f32_e32 v151, v151
	v_pk_add_f32 v[148:149], v[148:149], 1.0 op_sel_hi:[1,0]
	v_pk_add_f32 v[146:147], v[146:147], 1.0 op_sel_hi:[1,0]
	v_rcp_f32_e32 v148, v148
	v_rcp_f32_e32 v149, v149
	v_rcp_f32_e32 v202, v146
	v_rcp_f32_e32 v203, v147
	v_pk_mul_f32 v[146:147], v[90:91], v[150:151]
	v_pk_fma_f32 v[144:145], v[144:145], s[36:37], v[84:85] op_sel_hi:[1,0,1] neg_lo:[1,0,0] neg_hi:[1,0,0]
	v_pk_fma_f32 v[140:141], v[140:141], s[36:37], v[92:93] op_sel_hi:[1,0,1] neg_lo:[1,0,0] neg_hi:[1,0,0]
	v_exp_f32_e32 v146, v146
	v_exp_f32_e32 v147, v147
	v_exp_f32_e32 v204, v144
	v_exp_f32_e32 v205, v145
	v_pk_mul_f32 v[144:145], v[88:89], v[148:149]
	v_exp_f32_e32 v140, v140
	v_exp_f32_e32 v141, v141
	v_exp_f32_e32 v144, v144
	v_exp_f32_e32 v145, v145
	v_pk_fma_f32 v[150:151], v[146:147], v[146:147], 1.0 op_sel_hi:[1,1,0] neg_lo:[1,0,0] neg_hi:[1,0,0]
	v_pk_add_f32 v[148:149], v[204:205], 1.0 op_sel_hi:[1,0]
	v_pk_add_f32 v[140:141], v[140:141], 1.0 op_sel_hi:[1,0]
	v_sqrt_f32_e32 v150, v150
	v_sqrt_f32_e32 v151, v151
	v_rcp_f32_e32 v204, v148
	v_rcp_f32_e32 v205, v149
	v_pk_fma_f32 v[148:149], v[144:145], v[144:145], 1.0 op_sel_hi:[1,1,0] neg_lo:[1,0,0] neg_hi:[1,0,0]
	v_rcp_f32_e32 v140, v140
	v_rcp_f32_e32 v141, v141
	v_lshl_add_u32 v200, v217, 4, v215
	v_sqrt_f32_e32 v206, v148
	v_sqrt_f32_e32 v207, v149
	v_pk_fma_f32 v[142:143], v[142:143], s[36:37], v[94:95] op_sel_hi:[1,0,1] neg_lo:[1,0,0] neg_hi:[1,0,0]
	v_and_b32_e32 v223, 48, v200
	v_lshlrev_b32_e32 v200, 16, v188
	v_and_b32_e32 v201, 0xffff0000, v188
	v_lshlrev_b32_e32 v188, 16, v189
	v_and_b32_e32 v189, 0xffff0000, v189
	v_exp_f32_e32 v142, v142
	v_exp_f32_e32 v143, v143
	v_pk_mul_f32 v[148:149], v[202:203], v[188:189]
	v_pk_fma_f32 v[138:139], v[138:139], s[36:37], v[86:87] op_sel_hi:[1,0,1] neg_lo:[1,0,0] neg_hi:[1,0,0]
	v_pk_fma_f32 v[136:137], v[136:137], s[36:37], v[84:85] op_sel_hi:[1,0,1] neg_lo:[1,0,0] neg_hi:[1,0,0]
	v_pk_fma_f32 v[134:135], v[134:135], s[36:37], v[94:95] op_sel_hi:[1,0,1] neg_lo:[1,0,0] neg_hi:[1,0,0]
	v_pk_mul_f32 v[148:149], v[148:149], v[150:151]
	v_pk_mul_f32 v[150:151], v[204:205], v[200:201]
	v_exp_f32_e32 v138, v138
	v_exp_f32_e32 v139, v139
	v_exp_f32_e32 v136, v136
	v_exp_f32_e32 v137, v137
	v_pk_mul_f32 v[140:141], v[88:89], v[140:141]
	v_exp_f32_e32 v134, v134
	v_exp_f32_e32 v135, v135
	v_pk_mul_f32 v[150:151], v[150:151], v[206:207]
	v_exp_f32_e32 v206, v140
	v_exp_f32_e32 v207, v141
	v_pk_add_f32 v[142:143], v[142:143], 1.0 op_sel_hi:[1,0]
	v_pk_fma_f32 v[132:133], v[132:133], s[36:37], v[92:93] op_sel_hi:[1,0,1] neg_lo:[1,0,0] neg_hi:[1,0,0]
	v_rcp_f32_e32 v142, v142
	v_rcp_f32_e32 v143, v143
	v_exp_f32_e32 v132, v132
	v_exp_f32_e32 v133, v133
	v_pk_add_f32 v[138:139], v[138:139], 1.0 op_sel_hi:[1,0]
	v_pk_add_f32 v[136:137], v[136:137], 1.0 op_sel_hi:[1,0]
	v_pk_add_f32 v[134:135], v[134:135], 1.0 op_sel_hi:[1,0]
	v_pk_fma_f32 v[124:125], v[124:125], s[36:37], v[92:93] op_sel_hi:[1,0,1] neg_lo:[1,0,0] neg_hi:[1,0,0]
	v_rcp_f32_e32 v138, v138
	v_rcp_f32_e32 v139, v139
	v_rcp_f32_e32 v140, v136
	v_rcp_f32_e32 v141, v137
	v_pk_fma_f32 v[136:137], v[206:207], v[206:207], 1.0 op_sel_hi:[1,1,0] neg_lo:[1,0,0] neg_hi:[1,0,0]
	v_rcp_f32_e32 v134, v134
	v_rcp_f32_e32 v135, v135
	v_exp_f32_e32 v124, v124
	v_exp_f32_e32 v125, v125
	v_sqrt_f32_e32 v220, v136
	v_sqrt_f32_e32 v221, v137
	v_pk_fma_f32 v[126:127], v[126:127], s[36:37], v[94:95] op_sel_hi:[1,0,1] neg_lo:[1,0,0] neg_hi:[1,0,0]
	v_pk_mul_f32 v[142:143], v[90:91], v[142:143]
	v_pk_add_f32 v[132:133], v[132:133], 1.0 op_sel_hi:[1,0]
	v_exp_f32_e32 v126, v126
	v_exp_f32_e32 v127, v127
	v_lshlrev_b32_e32 v202, 16, v186
	v_and_b32_e32 v203, 0xffff0000, v186
	v_lshlrev_b32_e32 v186, 16, v187
	v_and_b32_e32 v187, 0xffff0000, v187
	v_exp_f32_e32 v204, v142
	v_exp_f32_e32 v205, v143
	v_pk_fma_f32 v[130:131], v[130:131], s[36:37], v[86:87] op_sel_hi:[1,0,1] neg_lo:[1,0,0] neg_hi:[1,0,0]
	v_rcp_f32_e32 v132, v132
	v_rcp_f32_e32 v133, v133
	v_pk_mul_f32 v[136:137], v[138:139], v[186:187]
	v_pk_mul_f32 v[138:139], v[140:141], v[202:203]
	v_exp_f32_e32 v130, v130
	v_exp_f32_e32 v131, v131
	v_pk_mul_f32 v[134:135], v[90:91], v[134:135]
	v_pk_add_f32 v[124:125], v[124:125], 1.0 op_sel_hi:[1,0]
	v_pk_mul_f32 v[138:139], v[138:139], v[220:221]
	v_exp_f32_e32 v220, v134
	v_exp_f32_e32 v221, v135
	v_rcp_f32_e32 v124, v124
	v_rcp_f32_e32 v125, v125
	v_pk_fma_f32 v[128:129], v[128:129], s[36:37], v[84:85] op_sel_hi:[1,0,1] neg_lo:[1,0,0] neg_hi:[1,0,0]
	v_pk_add_f32 v[126:127], v[126:127], 1.0 op_sel_hi:[1,0]
	v_pk_fma_f32 v[142:143], v[204:205], v[204:205], 1.0 op_sel_hi:[1,1,0] neg_lo:[1,0,0] neg_hi:[1,0,0]
	v_exp_f32_e32 v128, v128
	v_exp_f32_e32 v129, v129
	v_pk_mul_f32 v[132:133], v[88:89], v[132:133]
	v_rcp_f32_e32 v126, v126
	v_rcp_f32_e32 v127, v127
	v_sqrt_f32_e32 v142, v142
	v_sqrt_f32_e32 v143, v143
	v_pk_add_f32 v[130:131], v[130:131], 1.0 op_sel_hi:[1,0]
	v_exp_f32_e32 v224, v132
	v_exp_f32_e32 v225, v133
	v_pk_fma_f32 v[120:121], v[120:121], s[36:37], v[84:85] op_sel_hi:[1,0,1] neg_lo:[1,0,0] neg_hi:[1,0,0]
	v_rcp_f32_e32 v130, v130
	v_rcp_f32_e32 v131, v131
	v_pk_fma_f32 v[134:135], v[220:221], v[220:221], 1.0 op_sel_hi:[1,1,0] neg_lo:[1,0,0] neg_hi:[1,0,0]
	v_exp_f32_e32 v120, v120
	v_exp_f32_e32 v121, v121
	v_pk_mul_f32 v[124:125], v[88:89], v[124:125]
	v_sqrt_f32_e32 v134, v134
	v_sqrt_f32_e32 v135, v135
	v_pk_fma_f32 v[122:123], v[122:123], s[36:37], v[86:87] op_sel_hi:[1,0,1] neg_lo:[1,0,0] neg_hi:[1,0,0]
	v_exp_f32_e32 v124, v124
	v_exp_f32_e32 v125, v125
	v_pk_add_f32 v[128:129], v[128:129], 1.0 op_sel_hi:[1,0]
	v_exp_f32_e32 v122, v122
	v_exp_f32_e32 v123, v123
	v_pk_mul_f32 v[126:127], v[90:91], v[126:127]
	v_pk_mul_f32 v[136:137], v[136:137], v[142:143]
	v_lshlrev_b32_e32 v142, 16, v185
	v_and_b32_e32 v143, 0xffff0000, v185
	v_rcp_f32_e32 v132, v128
	v_rcp_f32_e32 v133, v129
	v_pk_fma_f32 v[128:129], v[224:225], v[224:225], 1.0 op_sel_hi:[1,1,0] neg_lo:[1,0,0] neg_hi:[1,0,0]
	v_exp_f32_e32 v126, v126
	v_exp_f32_e32 v127, v127
	v_lshlrev_b32_e32 v140, 16, v184
	v_and_b32_e32 v141, 0xffff0000, v184
	v_sqrt_f32_e32 v184, v128
	v_sqrt_f32_e32 v185, v129
	v_pk_mul_f32 v[128:129], v[130:131], v[142:143]
	v_pk_add_f32 v[120:121], v[120:121], 1.0 op_sel_hi:[1,0]
	v_pk_mul_f32 v[128:129], v[128:129], v[134:135]
	v_rcp_f32_e32 v120, v120
	v_rcp_f32_e32 v121, v121
	v_pk_fma_f32 v[134:135], v[124:125], v[124:125], 1.0 op_sel_hi:[1,1,0] neg_lo:[1,0,0] neg_hi:[1,0,0]
	v_pk_add_f32 v[122:123], v[122:123], 1.0 op_sel_hi:[1,0]
	v_sqrt_f32_e32 v134, v134
	v_sqrt_f32_e32 v135, v135
	v_pk_mul_f32 v[130:131], v[132:133], v[140:141]
	v_rcp_f32_e32 v122, v122
	v_rcp_f32_e32 v123, v123
	v_pk_fma_f32 v[132:133], v[126:127], v[126:127], 1.0 op_sel_hi:[1,1,0] neg_lo:[1,0,0] neg_hi:[1,0,0]
	v_pk_mul_f32 v[130:131], v[130:131], v[184:185]
	v_lshlrev_b32_e32 v184, 16, v182
	v_and_b32_e32 v185, 0xffff0000, v182
	v_sqrt_f32_e32 v132, v132
	v_sqrt_f32_e32 v133, v133
	v_mov_b32_e32 v219, v144
	v_pk_mul_f32 v[120:121], v[120:121], v[184:185]
	s_nop 1
v_fmac_f32_dpp v150, v150, v219 row_shr:1 row_mask:0xf bank_mask:0xf
v_fmac_f32_dpp v151, v151, v145 row_shr:1 row_mask:0xf bank_mask:0xf
v_fmac_f32_dpp v148, v148, v146 row_shr:1 row_mask:0xf bank_mask:0xf
v_fmac_f32_dpp v149, v149, v147 row_shr:1 row_mask:0xf bank_mask:0xf
v_mul_f32_dpp v219, v219, v219 row_shr:1 row_mask:0xf bank_mask:0xf
v_mul_f32_dpp v145, v145, v145 row_shr:1 row_mask:0xf bank_mask:0xf
v_mul_f32_dpp v146, v146, v146 row_shr:1 row_mask:0xf bank_mask:0xf
v_mul_f32_dpp v147, v147, v147 row_shr:1 row_mask:0xf bank_mask:0xf
v_fmac_f32_dpp v150, v150, v219 row_shr:2 row_mask:0xf bank_mask:0xf
v_fmac_f32_dpp v151, v151, v145 row_shr:2 row_mask:0xf bank_mask:0xf
v_fmac_f32_dpp v148, v148, v146 row_shr:2 row_mask:0xf bank_mask:0xf
v_fmac_f32_dpp v149, v149, v147 row_shr:2 row_mask:0xf bank_mask:0xf
v_mul_f32_dpp v219, v219, v219 row_shr:2 row_mask:0xf bank_mask:0xf
v_mul_f32_dpp v145, v145, v145 row_shr:2 row_mask:0xf bank_mask:0xf
v_mul_f32_dpp v146, v146, v146 row_shr:2 row_mask:0xf bank_mask:0xf
v_mul_f32_dpp v147, v147, v147 row_shr:2 row_mask:0xf bank_mask:0xf
v_fmac_f32_dpp v150, v150, v219 row_shr:4 row_mask:0xf bank_mask:0xf
v_fmac_f32_dpp v151, v151, v145 row_shr:4 row_mask:0xf bank_mask:0xf
v_fmac_f32_dpp v148, v148, v146 row_shr:4 row_mask:0xf bank_mask:0xf
v_fmac_f32_dpp v149, v149, v147 row_shr:4 row_mask:0xf bank_mask:0xf
v_mul_f32_dpp v219, v219, v219 row_shr:4 row_mask:0xf bank_mask:0xf
v_mul_f32_dpp v145, v145, v145 row_shr:4 row_mask:0xf bank_mask:0xf
v_mul_f32_dpp v146, v146, v146 row_shr:4 row_mask:0xf bank_mask:0xf
v_mul_f32_dpp v147, v147, v147 row_shr:4 row_mask:0xf bank_mask:0xf
v_fmac_f32_dpp v150, v150, v219 row_shr:8 row_mask:0xf bank_mask:0xf
v_fmac_f32_dpp v151, v151, v145 row_shr:8 row_mask:0xf bank_mask:0xf
v_fmac_f32_dpp v148, v148, v146 row_shr:8 row_mask:0xf bank_mask:0xf
v_fmac_f32_dpp v149, v149, v147 row_shr:8 row_mask:0xf bank_mask:0xf
v_mul_f32_dpp v219, v219, v219 row_shr:8 row_mask:0xf bank_mask:0xf
v_mul_f32_dpp v145, v145, v145 row_shr:8 row_mask:0xf bank_mask:0xf
v_mul_f32_dpp v146, v146, v146 row_shr:8 row_mask:0xf bank_mask:0xf
v_mul_f32_dpp v147, v147, v147 row_shr:8 row_mask:0xf bank_mask:0xf

	v_lshlrev_b32_e32 v182, 16, v183
	v_and_b32_e32 v183, 0xffff0000, v183
	v_pk_mul_f32 v[134:135], v[120:121], v[134:135]
	v_and_or_b32 v121, v214, 64, v223
	v_pk_mul_f32 v[122:123], v[122:123], v[182:183]
	v_lshlrev_b32_e32 v144, 2, v121
	v_fmac_f32_e32 v150, 0, v219
	v_fmac_f32_e32 v151, 0, v145
	v_fmac_f32_e32 v148, 0, v146
	v_fmac_f32_e32 v149, 0, v147
	v_pk_mul_f32 v[132:133], v[122:123], v[132:133]
	v_mov_b32_e32 v120, v124
	v_mov_b32_e32 v124, v126
	ds_bpermute_b32 v121, v144, v150 offset:60
	ds_bpermute_b32 v122, v144, v219 offset:60
	ds_bpermute_b32 v123, v144, v151 offset:60
	ds_bpermute_b32 v126, v144, v145 offset:60
	ds_bpermute_b32 v223, v144, v148 offset:60
	ds_bpermute_b32 v227, v144, v146 offset:60
	ds_bpermute_b32 v228, v144, v149 offset:60
	ds_bpermute_b32 v230, v144, v147 offset:60
	s_nop 1
v_fmac_f32_dpp v138, v138, v206 row_shr:1 row_mask:0xf bank_mask:0xf
v_fmac_f32_dpp v139, v139, v207 row_shr:1 row_mask:0xf bank_mask:0xf
v_fmac_f32_dpp v136, v136, v204 row_shr:1 row_mask:0xf bank_mask:0xf
v_fmac_f32_dpp v137, v137, v205 row_shr:1 row_mask:0xf bank_mask:0xf
v_mul_f32_dpp v206, v206, v206 row_shr:1 row_mask:0xf bank_mask:0xf
v_mul_f32_dpp v207, v207, v207 row_shr:1 row_mask:0xf bank_mask:0xf
v_mul_f32_dpp v204, v204, v204 row_shr:1 row_mask:0xf bank_mask:0xf
v_mul_f32_dpp v205, v205, v205 row_shr:1 row_mask:0xf bank_mask:0xf
v_fmac_f32_dpp v138, v138, v206 row_shr:2 row_mask:0xf bank_mask:0xf
v_fmac_f32_dpp v139, v139, v207 row_shr:2 row_mask:0xf bank_mask:0xf
v_fmac_f32_dpp v136, v136, v204 row_shr:2 row_mask:0xf bank_mask:0xf
v_fmac_f32_dpp v137, v137, v205 row_shr:2 row_mask:0xf bank_mask:0xf
v_mul_f32_dpp v206, v206, v206 row_shr:2 row_mask:0xf bank_mask:0xf
v_mul_f32_dpp v207, v207, v207 row_shr:2 row_mask:0xf bank_mask:0xf
v_mul_f32_dpp v204, v204, v204 row_shr:2 row_mask:0xf bank_mask:0xf
v_mul_f32_dpp v205, v205, v205 row_shr:2 row_mask:0xf bank_mask:0xf
v_fmac_f32_dpp v138, v138, v206 row_shr:4 row_mask:0xf bank_mask:0xf
v_fmac_f32_dpp v139, v139, v207 row_shr:4 row_mask:0xf bank_mask:0xf
v_fmac_f32_dpp v136, v136, v204 row_shr:4 row_mask:0xf bank_mask:0xf
v_fmac_f32_dpp v137, v137, v205 row_shr:4 row_mask:0xf bank_mask:0xf
v_mul_f32_dpp v206, v206, v206 row_shr:4 row_mask:0xf bank_mask:0xf
v_mul_f32_dpp v207, v207, v207 row_shr:4 row_mask:0xf bank_mask:0xf
v_mul_f32_dpp v204, v204, v204 row_shr:4 row_mask:0xf bank_mask:0xf
v_mul_f32_dpp v205, v205, v205 row_shr:4 row_mask:0xf bank_mask:0xf
v_fmac_f32_dpp v138, v138, v206 row_shr:8 row_mask:0xf bank_mask:0xf
v_fmac_f32_dpp v139, v139, v207 row_shr:8 row_mask:0xf bank_mask:0xf
v_fmac_f32_dpp v136, v136, v204 row_shr:8 row_mask:0xf bank_mask:0xf
v_fmac_f32_dpp v137, v137, v205 row_shr:8 row_mask:0xf bank_mask:0xf
v_mul_f32_dpp v206, v206, v206 row_shr:8 row_mask:0xf bank_mask:0xf
v_mul_f32_dpp v207, v207, v207 row_shr:8 row_mask:0xf bank_mask:0xf
v_mul_f32_dpp v204, v204, v204 row_shr:8 row_mask:0xf bank_mask:0xf
v_mul_f32_dpp v205, v205, v205 row_shr:8 row_mask:0xf bank_mask:0xf

	v_mov_b32_e32 v229, v220
	v_mov_b32_e32 v220, v225
	s_waitcnt lgkmcnt(7)
	v_fmac_f32_e32 v138, v206, v121
	s_waitcnt lgkmcnt(6)
	v_mul_f32_e32 v225, v206, v122
	s_waitcnt lgkmcnt(5)
	v_fmac_f32_e32 v139, v207, v123
	s_waitcnt lgkmcnt(4)
	v_mul_f32_e32 v226, v207, v126
	s_waitcnt lgkmcnt(3)
	v_fmac_f32_e32 v136, v204, v223
	s_waitcnt lgkmcnt(2)
	v_mul_f32_e32 v227, v204, v227
	s_waitcnt lgkmcnt(1)
	v_fmac_f32_e32 v137, v205, v228
	s_waitcnt lgkmcnt(0)
	v_mul_f32_e32 v228, v205, v230
	ds_bpermute_b32 v121, v144, v138 offset:60
	ds_bpermute_b32 v122, v144, v225 offset:60
	ds_bpermute_b32 v123, v144, v139 offset:60
	ds_bpermute_b32 v126, v144, v226 offset:60
	ds_bpermute_b32 v204, v144, v136 offset:60
	ds_bpermute_b32 v207, v144, v227 offset:60
	ds_bpermute_b32 v205, v144, v137 offset:60
	ds_bpermute_b32 v230, v144, v228 offset:60
	s_nop 1
v_fmac_f32_dpp v130, v130, v224 row_shr:1 row_mask:0xf bank_mask:0xf
v_fmac_f32_dpp v131, v131, v220 row_shr:1 row_mask:0xf bank_mask:0xf
v_fmac_f32_dpp v128, v128, v229 row_shr:1 row_mask:0xf bank_mask:0xf
v_fmac_f32_dpp v129, v129, v221 row_shr:1 row_mask:0xf bank_mask:0xf
v_mul_f32_dpp v224, v224, v224 row_shr:1 row_mask:0xf bank_mask:0xf
v_mul_f32_dpp v220, v220, v220 row_shr:1 row_mask:0xf bank_mask:0xf
v_mul_f32_dpp v229, v229, v229 row_shr:1 row_mask:0xf bank_mask:0xf
v_mul_f32_dpp v221, v221, v221 row_shr:1 row_mask:0xf bank_mask:0xf
v_fmac_f32_dpp v130, v130, v224 row_shr:2 row_mask:0xf bank_mask:0xf
v_fmac_f32_dpp v131, v131, v220 row_shr:2 row_mask:0xf bank_mask:0xf
v_fmac_f32_dpp v128, v128, v229 row_shr:2 row_mask:0xf bank_mask:0xf
v_fmac_f32_dpp v129, v129, v221 row_shr:2 row_mask:0xf bank_mask:0xf
v_mul_f32_dpp v224, v224, v224 row_shr:2 row_mask:0xf bank_mask:0xf
v_mul_f32_dpp v220, v220, v220 row_shr:2 row_mask:0xf bank_mask:0xf
v_mul_f32_dpp v229, v229, v229 row_shr:2 row_mask:0xf bank_mask:0xf
v_mul_f32_dpp v221, v221, v221 row_shr:2 row_mask:0xf bank_mask:0xf
v_fmac_f32_dpp v130, v130, v224 row_shr:4 row_mask:0xf bank_mask:0xf
v_fmac_f32_dpp v131, v131, v220 row_shr:4 row_mask:0xf bank_mask:0xf
v_fmac_f32_dpp v128, v128, v229 row_shr:4 row_mask:0xf bank_mask:0xf
v_fmac_f32_dpp v129, v129, v221 row_shr:4 row_mask:0xf bank_mask:0xf
v_mul_f32_dpp v224, v224, v224 row_shr:4 row_mask:0xf bank_mask:0xf
v_mul_f32_dpp v220, v220, v220 row_shr:4 row_mask:0xf bank_mask:0xf
v_mul_f32_dpp v229, v229, v229 row_shr:4 row_mask:0xf bank_mask:0xf
v_mul_f32_dpp v221, v221, v221 row_shr:4 row_mask:0xf bank_mask:0xf
v_fmac_f32_dpp v130, v130, v224 row_shr:8 row_mask:0xf bank_mask:0xf
v_fmac_f32_dpp v131, v131, v220 row_shr:8 row_mask:0xf bank_mask:0xf
v_fmac_f32_dpp v128, v128, v229 row_shr:8 row_mask:0xf bank_mask:0xf
v_fmac_f32_dpp v129, v129, v221 row_shr:8 row_mask:0xf bank_mask:0xf
v_mul_f32_dpp v224, v224, v224 row_shr:8 row_mask:0xf bank_mask:0xf
v_mul_f32_dpp v220, v220, v220 row_shr:8 row_mask:0xf bank_mask:0xf
v_mul_f32_dpp v229, v229, v229 row_shr:8 row_mask:0xf bank_mask:0xf
v_mul_f32_dpp v221, v221, v221 row_shr:8 row_mask:0xf bank_mask:0xf

	s_ashr_i32 s8, s90, 5
	s_waitcnt lgkmcnt(7)
	v_fmac_f32_e32 v130, v224, v121
	s_waitcnt lgkmcnt(6)
	v_mul_f32_e32 v206, v224, v122
	s_waitcnt lgkmcnt(5)
	v_fmac_f32_e32 v131, v220, v123
	s_waitcnt lgkmcnt(4)
	v_mul_f32_e32 v220, v220, v126
	s_waitcnt lgkmcnt(3)
	v_fmac_f32_e32 v128, v229, v204
	s_waitcnt lgkmcnt(2)
	v_mul_f32_e32 v223, v229, v207
	s_waitcnt lgkmcnt(1)
	v_fmac_f32_e32 v129, v221, v205
	s_waitcnt lgkmcnt(0)
	v_mul_f32_e32 v224, v221, v230
	ds_bpermute_b32 v121, v144, v130 offset:60
	ds_bpermute_b32 v122, v144, v206 offset:60
	ds_bpermute_b32 v123, v144, v131 offset:60
	ds_bpermute_b32 v126, v144, v220 offset:60
	ds_bpermute_b32 v207, v144, v128 offset:60
	ds_bpermute_b32 v229, v144, v223 offset:60
	ds_bpermute_b32 v221, v144, v129 offset:60
	ds_bpermute_b32 v230, v144, v224 offset:60
	s_add_i32 s9, s90, 0xffffff00
	s_and_b64 s[4:5], exec, s[54:55]
	s_cselect_b32 s4, s9, s8
	s_nop 1
v_fmac_f32_dpp v134, v134, v120 row_shr:1 row_mask:0xf bank_mask:0xf
v_fmac_f32_dpp v135, v135, v125 row_shr:1 row_mask:0xf bank_mask:0xf
v_fmac_f32_dpp v132, v132, v124 row_shr:1 row_mask:0xf bank_mask:0xf
v_fmac_f32_dpp v133, v133, v127 row_shr:1 row_mask:0xf bank_mask:0xf
v_mul_f32_dpp v120, v120, v120 row_shr:1 row_mask:0xf bank_mask:0xf
v_mul_f32_dpp v125, v125, v125 row_shr:1 row_mask:0xf bank_mask:0xf
v_mul_f32_dpp v124, v124, v124 row_shr:1 row_mask:0xf bank_mask:0xf
v_mul_f32_dpp v127, v127, v127 row_shr:1 row_mask:0xf bank_mask:0xf
v_fmac_f32_dpp v134, v134, v120 row_shr:2 row_mask:0xf bank_mask:0xf
v_fmac_f32_dpp v135, v135, v125 row_shr:2 row_mask:0xf bank_mask:0xf
v_fmac_f32_dpp v132, v132, v124 row_shr:2 row_mask:0xf bank_mask:0xf
v_fmac_f32_dpp v133, v133, v127 row_shr:2 row_mask:0xf bank_mask:0xf
v_mul_f32_dpp v120, v120, v120 row_shr:2 row_mask:0xf bank_mask:0xf
v_mul_f32_dpp v125, v125, v125 row_shr:2 row_mask:0xf bank_mask:0xf
v_mul_f32_dpp v124, v124, v124 row_shr:2 row_mask:0xf bank_mask:0xf
v_mul_f32_dpp v127, v127, v127 row_shr:2 row_mask:0xf bank_mask:0xf
v_fmac_f32_dpp v134, v134, v120 row_shr:4 row_mask:0xf bank_mask:0xf
v_fmac_f32_dpp v135, v135, v125 row_shr:4 row_mask:0xf bank_mask:0xf
v_fmac_f32_dpp v132, v132, v124 row_shr:4 row_mask:0xf bank_mask:0xf
v_fmac_f32_dpp v133, v133, v127 row_shr:4 row_mask:0xf bank_mask:0xf
v_mul_f32_dpp v120, v120, v120 row_shr:4 row_mask:0xf bank_mask:0xf
v_mul_f32_dpp v125, v125, v125 row_shr:4 row_mask:0xf bank_mask:0xf
v_mul_f32_dpp v124, v124, v124 row_shr:4 row_mask:0xf bank_mask:0xf
v_mul_f32_dpp v127, v127, v127 row_shr:4 row_mask:0xf bank_mask:0xf
v_fmac_f32_dpp v134, v134, v120 row_shr:8 row_mask:0xf bank_mask:0xf
v_fmac_f32_dpp v135, v135, v125 row_shr:8 row_mask:0xf bank_mask:0xf
v_fmac_f32_dpp v132, v132, v124 row_shr:8 row_mask:0xf bank_mask:0xf
v_fmac_f32_dpp v133, v133, v127 row_shr:8 row_mask:0xf bank_mask:0xf
v_mul_f32_dpp v120, v120, v120 row_shr:8 row_mask:0xf bank_mask:0xf
v_mul_f32_dpp v125, v125, v125 row_shr:8 row_mask:0xf bank_mask:0xf
v_mul_f32_dpp v124, v124, v124 row_shr:8 row_mask:0xf bank_mask:0xf
v_mul_f32_dpp v127, v127, v127 row_shr:8 row_mask:0xf bank_mask:0xf

	s_lshl_b32 s47, s4, 1
	s_lshl_b32 s4, s90, 2
	s_waitcnt lgkmcnt(7)
	v_fmac_f32_e32 v134, v120, v121
	s_waitcnt lgkmcnt(6)
	v_mul_f32_e32 v204, v120, v122
	s_waitcnt lgkmcnt(5)
	v_fmac_f32_e32 v135, v125, v123
	s_waitcnt lgkmcnt(4)
	v_mul_f32_e32 v205, v125, v126
	s_waitcnt lgkmcnt(3)
	v_fmac_f32_e32 v132, v124, v207
	s_waitcnt lgkmcnt(2)
	v_mul_f32_e32 v207, v124, v229
	s_waitcnt lgkmcnt(1)
	v_fmac_f32_e32 v133, v127, v221
	s_waitcnt lgkmcnt(0)
	v_mul_f32_e32 v221, v127, v230
	s_and_b32 s49, s4, 0x7c
	ds_bpermute_b32 v121, v144, v134 offset:60
	ds_bpermute_b32 v120, v144, v204 offset:60
	ds_bpermute_b32 v123, v144, v135 offset:60
	ds_bpermute_b32 v122, v144, v205 offset:60
	ds_bpermute_b32 v125, v144, v132 offset:60
	ds_bpermute_b32 v124, v144, v207 offset:60
	ds_bpermute_b32 v127, v144, v133 offset:60
	ds_bpermute_b32 v126, v144, v221 offset:60
	s_add_i32 s8, s49, 4
	s_and_b64 s[4:5], exec, s[54:55]
	s_cselect_b32 s14, 0, s8
	s_add_i32 s14, s14, s66
	v_cmp_eq_u32_e64 s[10:11], 15, v215
	s_mul_hi_i32 s58, s47, 0x84
	s_mul_i32 s59, s47, 0x84
	s_and_saveexec_b64 s[8:9], s[10:11]
	s_cbranch_execz .LBB0_437
	s_add_u32 s4, s59, s14
	s_addc_u32 s5, s58, 0
	s_mulk_i32 s5, 0x2800
	s_mul_hi_u32 s12, s4, 0x2800
	s_add_i32 s12, s12, s5
	s_mulk_i32 s4, 0x2800
	s_add_u32 s4, s77, s4
	s_addc_u32 s5, s78, s12
	v_lshl_add_u64 v[230:231], v[176:177], 3, s[4:5]
	s_waitcnt lgkmcnt(4)
	flat_store_dwordx4 v[230:231], v[120:123]
	s_waitcnt lgkmcnt(0)
	flat_store_dwordx4 v[230:231], v[124:127] offset:16
.LBB0_437:
	s_or_b64 exec, exec, s[8:9]
	v_pk_fma_f32 v[116:117], v[116:117], s[36:37], v[72:73] op_sel_hi:[1,0,1] neg_lo:[1,0,0] neg_hi:[1,0,0]
	v_pk_fma_f32 v[108:109], v[108:109], s[36:37], v[72:73] op_sel_hi:[1,0,1] neg_lo:[1,0,0] neg_hi:[1,0,0]
	v_exp_f32_e32 v116, v116
	v_exp_f32_e32 v117, v117
	v_pk_fma_f32 v[114:115], v[114:115], s[36:37], v[70:71] op_sel_hi:[1,0,1] neg_lo:[1,0,0] neg_hi:[1,0,0]
	v_pk_fma_f32 v[112:113], v[112:113], s[36:37], v[68:69] op_sel_hi:[1,0,1] neg_lo:[1,0,0] neg_hi:[1,0,0]
	v_exp_f32_e32 v108, v108
	v_pk_add_f32 v[116:117], v[116:117], 1.0 op_sel_hi:[1,0]
	v_exp_f32_e32 v109, v109
	v_rcp_f32_e32 v116, v116
	v_rcp_f32_e32 v117, v117
	v_exp_f32_e32 v114, v114
	v_exp_f32_e32 v115, v115
	v_exp_f32_e32 v112, v112
	v_exp_f32_e32 v113, v113
	v_pk_mul_f32 v[116:117], v[64:65], v[116:117]
	v_pk_add_f32 v[108:109], v[108:109], 1.0 op_sel_hi:[1,0]
	v_pk_add_f32 v[114:115], v[114:115], 1.0 op_sel_hi:[1,0]
	v_exp_f32_e32 v116, v116
	v_exp_f32_e32 v117, v117
	v_pk_add_f32 v[112:113], v[112:113], 1.0 op_sel_hi:[1,0]
	v_rcp_f32_e32 v108, v108
	v_rcp_f32_e32 v109, v109
	v_rcp_f32_e32 v114, v114
	v_rcp_f32_e32 v115, v115
	s_waitcnt lgkmcnt(0)
	v_rcp_f32_e32 v122, v112
	v_rcp_f32_e32 v123, v113
	v_pk_fma_f32 v[106:107], v[106:107], s[36:37], v[70:71] op_sel_hi:[1,0,1] neg_lo:[1,0,0] neg_hi:[1,0,0]
	v_pk_fma_f32 v[104:105], v[104:105], s[36:37], v[68:69] op_sel_hi:[1,0,1] neg_lo:[1,0,0] neg_hi:[1,0,0]
	v_pk_fma_f32 v[102:103], v[102:103], s[36:37], v[74:75] op_sel_hi:[1,0,1] neg_lo:[1,0,0] neg_hi:[1,0,0]
	v_pk_fma_f32 v[112:113], v[116:117], v[116:117], 1.0 op_sel_hi:[1,1,0] neg_lo:[1,0,0] neg_hi:[1,0,0]
	v_exp_f32_e32 v106, v106
	v_exp_f32_e32 v107, v107
	v_exp_f32_e32 v104, v104
	v_exp_f32_e32 v105, v105
	v_pk_mul_f32 v[108:109], v[64:65], v[108:109]
	v_exp_f32_e32 v102, v102
	v_exp_f32_e32 v103, v103
	v_sqrt_f32_e32 v124, v112
	v_sqrt_f32_e32 v125, v113
	v_pk_mul_f32 v[112:113], v[114:115], v[188:189]
	v_pk_mul_f32 v[114:115], v[122:123], v[200:201]
	v_exp_f32_e32 v122, v108
	v_exp_f32_e32 v123, v109
	v_pk_fma_f32 v[100:101], v[100:101], s[36:37], v[72:73] op_sel_hi:[1,0,1] neg_lo:[1,0,0] neg_hi:[1,0,0]
	v_pk_fma_f32 v[118:119], v[118:119], s[36:37], v[74:75] op_sel_hi:[1,0,1] neg_lo:[1,0,0] neg_hi:[1,0,0]
	v_exp_f32_e32 v100, v100
	v_exp_f32_e32 v101, v101
	v_exp_f32_e32 v118, v118
	v_exp_f32_e32 v119, v119
	v_pk_add_f32 v[106:107], v[106:107], 1.0 op_sel_hi:[1,0]
	v_pk_add_f32 v[104:105], v[104:105], 1.0 op_sel_hi:[1,0]
	v_pk_add_f32 v[102:103], v[102:103], 1.0 op_sel_hi:[1,0]
	v_rcp_f32_e32 v106, v106
	v_rcp_f32_e32 v107, v107
	v_rcp_f32_e32 v108, v104
	v_rcp_f32_e32 v109, v105
	v_pk_fma_f32 v[104:105], v[122:123], v[122:123], 1.0 op_sel_hi:[1,1,0] neg_lo:[1,0,0] neg_hi:[1,0,0]
	v_rcp_f32_e32 v102, v102
	v_rcp_f32_e32 v103, v103
	v_pk_mul_f32 v[114:115], v[114:115], v[124:125]
	v_sqrt_f32_e32 v124, v104
	v_sqrt_f32_e32 v125, v105
	v_pk_add_f32 v[100:101], v[100:101], 1.0 op_sel_hi:[1,0]
	v_pk_add_f32 v[118:119], v[118:119], 1.0 op_sel_hi:[1,0]
	v_pk_fma_f32 v[110:111], v[110:111], s[36:37], v[74:75] op_sel_hi:[1,0,1] neg_lo:[1,0,0] neg_hi:[1,0,0]
	v_pk_fma_f32 v[98:99], v[98:99], s[36:37], v[70:71] op_sel_hi:[1,0,1] neg_lo:[1,0,0] neg_hi:[1,0,0]
	v_rcp_f32_e32 v100, v100
	v_rcp_f32_e32 v101, v101
	v_pk_fma_f32 v[82:83], v[82:83], s[36:37], v[74:75] op_sel_hi:[1,0,1] neg_lo:[1,0,0] neg_hi:[1,0,0]
	v_pk_fma_f32 v[80:81], v[80:81], s[36:37], v[72:73] op_sel_hi:[1,0,1] neg_lo:[1,0,0] neg_hi:[1,0,0]
	v_rcp_f32_e32 v118, v118
	v_rcp_f32_e32 v119, v119
	v_exp_f32_e32 v110, v110
	v_exp_f32_e32 v111, v111
	v_pk_mul_f32 v[104:105], v[106:107], v[186:187]
	v_pk_mul_f32 v[106:107], v[108:109], v[202:203]
	v_exp_f32_e32 v98, v98
	v_exp_f32_e32 v99, v99
	v_pk_mul_f32 v[102:103], v[66:67], v[102:103]
	v_pk_fma_f32 v[96:97], v[96:97], s[36:37], v[68:69] op_sel_hi:[1,0,1] neg_lo:[1,0,0] neg_hi:[1,0,0]
	v_exp_f32_e32 v82, v82
	v_exp_f32_e32 v83, v83
	v_exp_f32_e32 v80, v80
	v_exp_f32_e32 v81, v81
	v_pk_mul_f32 v[106:107], v[106:107], v[124:125]
	v_exp_f32_e32 v124, v102
	v_exp_f32_e32 v125, v103
	v_exp_f32_e32 v96, v96
	v_exp_f32_e32 v97, v97
	v_pk_mul_f32 v[100:101], v[64:65], v[100:101]
	v_pk_mul_f32 v[118:119], v[66:67], v[118:119]
	v_pk_add_f32 v[110:111], v[110:111], 1.0 op_sel_hi:[1,0]
	v_pk_add_f32 v[98:99], v[98:99], 1.0 op_sel_hi:[1,0]
	v_exp_f32_e32 v126, v100
	v_exp_f32_e32 v127, v101
	v_pk_add_f32 v[82:83], v[82:83], 1.0 op_sel_hi:[1,0]
	v_pk_add_f32 v[80:81], v[80:81], 1.0 op_sel_hi:[1,0]
	v_exp_f32_e32 v118, v118
	v_exp_f32_e32 v119, v119
	v_rcp_f32_e32 v110, v110
	v_rcp_f32_e32 v111, v111
	v_rcp_f32_e32 v98, v98
	v_rcp_f32_e32 v99, v99
	v_pk_fma_f32 v[102:103], v[124:125], v[124:125], 1.0 op_sel_hi:[1,1,0] neg_lo:[1,0,0] neg_hi:[1,0,0]
	v_pk_add_f32 v[96:97], v[96:97], 1.0 op_sel_hi:[1,0]
	v_rcp_f32_e32 v82, v82
	v_rcp_f32_e32 v83, v83
	v_rcp_f32_e32 v80, v80
	v_rcp_f32_e32 v81, v81
	v_sqrt_f32_e32 v102, v102
	v_sqrt_f32_e32 v103, v103
	v_rcp_f32_e32 v100, v96
	v_rcp_f32_e32 v101, v97
	v_pk_fma_f32 v[96:97], v[126:127], v[126:127], 1.0 op_sel_hi:[1,1,0] neg_lo:[1,0,0] neg_hi:[1,0,0]
	v_pk_fma_f32 v[78:79], v[78:79], s[36:37], v[70:71] op_sel_hi:[1,0,1] neg_lo:[1,0,0] neg_hi:[1,0,0]
	v_pk_fma_f32 v[76:77], v[76:77], s[36:37], v[68:69] op_sel_hi:[1,0,1] neg_lo:[1,0,0] neg_hi:[1,0,0]
	v_pk_fma_f32 v[120:121], v[118:119], v[118:119], 1.0 op_sel_hi:[1,1,0] neg_lo:[1,0,0] neg_hi:[1,0,0]
	v_pk_mul_f32 v[110:111], v[66:67], v[110:111]
	v_sqrt_f32_e32 v108, v96
	v_sqrt_f32_e32 v109, v97
	v_pk_mul_f32 v[96:97], v[98:99], v[142:143]
	v_exp_f32_e32 v78, v78
	v_exp_f32_e32 v79, v79
	v_pk_mul_f32 v[82:83], v[66:67], v[82:83]
	v_exp_f32_e32 v76, v76
	v_exp_f32_e32 v77, v77
	v_pk_mul_f32 v[80:81], v[64:65], v[80:81]
	v_sqrt_f32_e32 v120, v120
	v_sqrt_f32_e32 v121, v121
	v_exp_f32_e32 v110, v110
	v_exp_f32_e32 v111, v111
	v_pk_mul_f32 v[96:97], v[96:97], v[102:103]
	v_pk_mul_f32 v[98:99], v[100:101], v[140:141]
	v_exp_f32_e32 v100, v82
	v_exp_f32_e32 v101, v83
	v_exp_f32_e32 v102, v80
	v_exp_f32_e32 v103, v81
	v_pk_add_f32 v[78:79], v[78:79], 1.0 op_sel_hi:[1,0]
	v_pk_add_f32 v[76:77], v[76:77], 1.0 op_sel_hi:[1,0]
	v_pk_mul_f32 v[112:113], v[112:113], v[120:121]
	v_pk_fma_f32 v[120:121], v[110:111], v[110:111], 1.0 op_sel_hi:[1,1,0] neg_lo:[1,0,0] neg_hi:[1,0,0]
	v_rcp_f32_e32 v78, v78
	v_rcp_f32_e32 v79, v79
	v_pk_fma_f32 v[82:83], v[100:101], v[100:101], 1.0 op_sel_hi:[1,1,0] neg_lo:[1,0,0] neg_hi:[1,0,0]
	v_rcp_f32_e32 v76, v76
	v_rcp_f32_e32 v77, v77
	v_pk_fma_f32 v[80:81], v[102:103], v[102:103], 1.0 op_sel_hi:[1,1,0] neg_lo:[1,0,0] neg_hi:[1,0,0]
	v_sqrt_f32_e32 v120, v120
	v_sqrt_f32_e32 v121, v121
	v_sqrt_f32_e32 v82, v82
	v_sqrt_f32_e32 v83, v83
	v_sqrt_f32_e32 v80, v80
	v_sqrt_f32_e32 v81, v81
	v_pk_mul_f32 v[78:79], v[78:79], v[182:183]
	v_pk_mul_f32 v[76:77], v[76:77], v[184:185]
	v_mov_b32_e32 v188, v118
	v_mov_b32_e32 v189, v117
	v_pk_mul_f32 v[104:105], v[104:105], v[120:121]
	v_mov_b32_e32 v186, v122
	v_pk_mul_f32 v[98:99], v[98:99], v[108:109]
	v_mov_b32_e32 v117, v126
	v_mov_b32_e32 v122, v124
	v_pk_mul_f32 v[108:109], v[78:79], v[82:83]
	v_pk_mul_f32 v[120:121], v[76:77], v[80:81]
	s_nop 1
v_fmac_f32_dpp v114, v114, v116 row_shl:1 row_mask:0xf bank_mask:0xf
v_fmac_f32_dpp v115, v115, v189 row_shl:1 row_mask:0xf bank_mask:0xf
v_fmac_f32_dpp v112, v112, v188 row_shl:1 row_mask:0xf bank_mask:0xf
v_fmac_f32_dpp v113, v113, v119 row_shl:1 row_mask:0xf bank_mask:0xf
v_mul_f32_dpp v116, v116, v116 row_shl:1 row_mask:0xf bank_mask:0xf
v_mul_f32_dpp v189, v189, v189 row_shl:1 row_mask:0xf bank_mask:0xf
v_mul_f32_dpp v188, v188, v188 row_shl:1 row_mask:0xf bank_mask:0xf
v_mul_f32_dpp v119, v119, v119 row_shl:1 row_mask:0xf bank_mask:0xf
v_fmac_f32_dpp v114, v114, v116 row_shl:2 row_mask:0xf bank_mask:0xf
v_fmac_f32_dpp v115, v115, v189 row_shl:2 row_mask:0xf bank_mask:0xf
v_fmac_f32_dpp v112, v112, v188 row_shl:2 row_mask:0xf bank_mask:0xf
v_fmac_f32_dpp v113, v113, v119 row_shl:2 row_mask:0xf bank_mask:0xf
v_mul_f32_dpp v116, v116, v116 row_shl:2 row_mask:0xf bank_mask:0xf
v_mul_f32_dpp v189, v189, v189 row_shl:2 row_mask:0xf bank_mask:0xf
v_mul_f32_dpp v188, v188, v188 row_shl:2 row_mask:0xf bank_mask:0xf
v_mul_f32_dpp v119, v119, v119 row_shl:2 row_mask:0xf bank_mask:0xf
v_fmac_f32_dpp v114, v114, v116 row_shl:4 row_mask:0xf bank_mask:0xf
v_fmac_f32_dpp v115, v115, v189 row_shl:4 row_mask:0xf bank_mask:0xf
v_fmac_f32_dpp v112, v112, v188 row_shl:4 row_mask:0xf bank_mask:0xf
v_fmac_f32_dpp v113, v113, v119 row_shl:4 row_mask:0xf bank_mask:0xf
v_mul_f32_dpp v116, v116, v116 row_shl:4 row_mask:0xf bank_mask:0xf
v_mul_f32_dpp v189, v189, v189 row_shl:4 row_mask:0xf bank_mask:0xf
v_mul_f32_dpp v188, v188, v188 row_shl:4 row_mask:0xf bank_mask:0xf
v_mul_f32_dpp v119, v119, v119 row_shl:4 row_mask:0xf bank_mask:0xf
v_fmac_f32_dpp v114, v114, v116 row_shl:8 row_mask:0xf bank_mask:0xf
v_fmac_f32_dpp v115, v115, v189 row_shl:8 row_mask:0xf bank_mask:0xf
v_fmac_f32_dpp v112, v112, v188 row_shl:8 row_mask:0xf bank_mask:0xf
v_fmac_f32_dpp v113, v113, v119 row_shl:8 row_mask:0xf bank_mask:0xf
v_mul_f32_dpp v116, v116, v116 row_shl:8 row_mask:0xf bank_mask:0xf
v_mul_f32_dpp v189, v189, v189 row_shl:8 row_mask:0xf bank_mask:0xf
v_mul_f32_dpp v188, v188, v188 row_shl:8 row_mask:0xf bank_mask:0xf
v_mul_f32_dpp v119, v119, v119 row_shl:8 row_mask:0xf bank_mask:0xf

	s_nop 1
v_fmac_f32_dpp v106, v106, v186 row_shl:1 row_mask:0xf bank_mask:0xf
v_fmac_f32_dpp v107, v107, v123 row_shl:1 row_mask:0xf bank_mask:0xf
v_fmac_f32_dpp v104, v104, v110 row_shl:1 row_mask:0xf bank_mask:0xf
v_fmac_f32_dpp v105, v105, v111 row_shl:1 row_mask:0xf bank_mask:0xf
v_mul_f32_dpp v186, v186, v186 row_shl:1 row_mask:0xf bank_mask:0xf
v_mul_f32_dpp v123, v123, v123 row_shl:1 row_mask:0xf bank_mask:0xf
v_mul_f32_dpp v110, v110, v110 row_shl:1 row_mask:0xf bank_mask:0xf
v_mul_f32_dpp v111, v111, v111 row_shl:1 row_mask:0xf bank_mask:0xf
v_fmac_f32_dpp v106, v106, v186 row_shl:2 row_mask:0xf bank_mask:0xf
v_fmac_f32_dpp v107, v107, v123 row_shl:2 row_mask:0xf bank_mask:0xf
v_fmac_f32_dpp v104, v104, v110 row_shl:2 row_mask:0xf bank_mask:0xf
v_fmac_f32_dpp v105, v105, v111 row_shl:2 row_mask:0xf bank_mask:0xf
v_mul_f32_dpp v186, v186, v186 row_shl:2 row_mask:0xf bank_mask:0xf
v_mul_f32_dpp v123, v123, v123 row_shl:2 row_mask:0xf bank_mask:0xf
v_mul_f32_dpp v110, v110, v110 row_shl:2 row_mask:0xf bank_mask:0xf
v_mul_f32_dpp v111, v111, v111 row_shl:2 row_mask:0xf bank_mask:0xf
v_fmac_f32_dpp v106, v106, v186 row_shl:4 row_mask:0xf bank_mask:0xf
v_fmac_f32_dpp v107, v107, v123 row_shl:4 row_mask:0xf bank_mask:0xf
v_fmac_f32_dpp v104, v104, v110 row_shl:4 row_mask:0xf bank_mask:0xf
v_fmac_f32_dpp v105, v105, v111 row_shl:4 row_mask:0xf bank_mask:0xf
v_mul_f32_dpp v186, v186, v186 row_shl:4 row_mask:0xf bank_mask:0xf
v_mul_f32_dpp v123, v123, v123 row_shl:4 row_mask:0xf bank_mask:0xf
v_mul_f32_dpp v110, v110, v110 row_shl:4 row_mask:0xf bank_mask:0xf
v_mul_f32_dpp v111, v111, v111 row_shl:4 row_mask:0xf bank_mask:0xf
v_fmac_f32_dpp v106, v106, v186 row_shl:8 row_mask:0xf bank_mask:0xf
v_fmac_f32_dpp v107, v107, v123 row_shl:8 row_mask:0xf bank_mask:0xf
v_fmac_f32_dpp v104, v104, v110 row_shl:8 row_mask:0xf bank_mask:0xf
v_fmac_f32_dpp v105, v105, v111 row_shl:8 row_mask:0xf bank_mask:0xf
v_mul_f32_dpp v186, v186, v186 row_shl:8 row_mask:0xf bank_mask:0xf
v_mul_f32_dpp v123, v123, v123 row_shl:8 row_mask:0xf bank_mask:0xf
v_mul_f32_dpp v110, v110, v110 row_shl:8 row_mask:0xf bank_mask:0xf
v_mul_f32_dpp v111, v111, v111 row_shl:8 row_mask:0xf bank_mask:0xf

	s_nop 1
v_fmac_f32_dpp v98, v98, v117 row_shl:1 row_mask:0xf bank_mask:0xf
v_fmac_f32_dpp v99, v99, v127 row_shl:1 row_mask:0xf bank_mask:0xf
v_fmac_f32_dpp v96, v96, v122 row_shl:1 row_mask:0xf bank_mask:0xf
v_fmac_f32_dpp v97, v97, v125 row_shl:1 row_mask:0xf bank_mask:0xf
v_mul_f32_dpp v117, v117, v117 row_shl:1 row_mask:0xf bank_mask:0xf
v_mul_f32_dpp v127, v127, v127 row_shl:1 row_mask:0xf bank_mask:0xf
v_mul_f32_dpp v122, v122, v122 row_shl:1 row_mask:0xf bank_mask:0xf
v_mul_f32_dpp v125, v125, v125 row_shl:1 row_mask:0xf bank_mask:0xf
v_fmac_f32_dpp v98, v98, v117 row_shl:2 row_mask:0xf bank_mask:0xf
v_fmac_f32_dpp v99, v99, v127 row_shl:2 row_mask:0xf bank_mask:0xf
v_fmac_f32_dpp v96, v96, v122 row_shl:2 row_mask:0xf bank_mask:0xf
v_fmac_f32_dpp v97, v97, v125 row_shl:2 row_mask:0xf bank_mask:0xf
v_mul_f32_dpp v117, v117, v117 row_shl:2 row_mask:0xf bank_mask:0xf
v_mul_f32_dpp v127, v127, v127 row_shl:2 row_mask:0xf bank_mask:0xf
v_mul_f32_dpp v122, v122, v122 row_shl:2 row_mask:0xf bank_mask:0xf
v_mul_f32_dpp v125, v125, v125 row_shl:2 row_mask:0xf bank_mask:0xf
v_fmac_f32_dpp v98, v98, v117 row_shl:4 row_mask:0xf bank_mask:0xf
v_fmac_f32_dpp v99, v99, v127 row_shl:4 row_mask:0xf bank_mask:0xf
v_fmac_f32_dpp v96, v96, v122 row_shl:4 row_mask:0xf bank_mask:0xf
v_fmac_f32_dpp v97, v97, v125 row_shl:4 row_mask:0xf bank_mask:0xf
v_mul_f32_dpp v117, v117, v117 row_shl:4 row_mask:0xf bank_mask:0xf
v_mul_f32_dpp v127, v127, v127 row_shl:4 row_mask:0xf bank_mask:0xf
v_mul_f32_dpp v122, v122, v122 row_shl:4 row_mask:0xf bank_mask:0xf
v_mul_f32_dpp v125, v125, v125 row_shl:4 row_mask:0xf bank_mask:0xf
v_fmac_f32_dpp v98, v98, v117 row_shl:8 row_mask:0xf bank_mask:0xf
v_fmac_f32_dpp v99, v99, v127 row_shl:8 row_mask:0xf bank_mask:0xf
v_fmac_f32_dpp v96, v96, v122 row_shl:8 row_mask:0xf bank_mask:0xf
v_fmac_f32_dpp v97, v97, v125 row_shl:8 row_mask:0xf bank_mask:0xf
v_mul_f32_dpp v117, v117, v117 row_shl:8 row_mask:0xf bank_mask:0xf
v_mul_f32_dpp v127, v127, v127 row_shl:8 row_mask:0xf bank_mask:0xf
v_mul_f32_dpp v122, v122, v122 row_shl:8 row_mask:0xf bank_mask:0xf
v_mul_f32_dpp v125, v125, v125 row_shl:8 row_mask:0xf bank_mask:0xf

	v_cmp_eq_u32_e64 s[12:13], 0, v215
	s_nop 1
v_fmac_f32_dpp v120, v120, v102 row_shl:1 row_mask:0xf bank_mask:0xf
v_fmac_f32_dpp v121, v121, v103 row_shl:1 row_mask:0xf bank_mask:0xf
v_fmac_f32_dpp v108, v108, v100 row_shl:1 row_mask:0xf bank_mask:0xf
v_fmac_f32_dpp v109, v109, v101 row_shl:1 row_mask:0xf bank_mask:0xf
v_mul_f32_dpp v102, v102, v102 row_shl:1 row_mask:0xf bank_mask:0xf
v_mul_f32_dpp v103, v103, v103 row_shl:1 row_mask:0xf bank_mask:0xf
v_mul_f32_dpp v100, v100, v100 row_shl:1 row_mask:0xf bank_mask:0xf
v_mul_f32_dpp v101, v101, v101 row_shl:1 row_mask:0xf bank_mask:0xf
v_fmac_f32_dpp v120, v120, v102 row_shl:2 row_mask:0xf bank_mask:0xf
v_fmac_f32_dpp v121, v121, v103 row_shl:2 row_mask:0xf bank_mask:0xf
v_fmac_f32_dpp v108, v108, v100 row_shl:2 row_mask:0xf bank_mask:0xf
v_fmac_f32_dpp v109, v109, v101 row_shl:2 row_mask:0xf bank_mask:0xf
v_mul_f32_dpp v102, v102, v102 row_shl:2 row_mask:0xf bank_mask:0xf
v_mul_f32_dpp v103, v103, v103 row_shl:2 row_mask:0xf bank_mask:0xf
v_mul_f32_dpp v100, v100, v100 row_shl:2 row_mask:0xf bank_mask:0xf
v_mul_f32_dpp v101, v101, v101 row_shl:2 row_mask:0xf bank_mask:0xf
v_fmac_f32_dpp v120, v120, v102 row_shl:4 row_mask:0xf bank_mask:0xf
v_fmac_f32_dpp v121, v121, v103 row_shl:4 row_mask:0xf bank_mask:0xf
v_fmac_f32_dpp v108, v108, v100 row_shl:4 row_mask:0xf bank_mask:0xf
v_fmac_f32_dpp v109, v109, v101 row_shl:4 row_mask:0xf bank_mask:0xf
v_mul_f32_dpp v102, v102, v102 row_shl:4 row_mask:0xf bank_mask:0xf
v_mul_f32_dpp v103, v103, v103 row_shl:4 row_mask:0xf bank_mask:0xf
v_mul_f32_dpp v100, v100, v100 row_shl:4 row_mask:0xf bank_mask:0xf
v_mul_f32_dpp v101, v101, v101 row_shl:4 row_mask:0xf bank_mask:0xf
v_fmac_f32_dpp v120, v120, v102 row_shl:8 row_mask:0xf bank_mask:0xf
v_fmac_f32_dpp v121, v121, v103 row_shl:8 row_mask:0xf bank_mask:0xf
v_fmac_f32_dpp v108, v108, v100 row_shl:8 row_mask:0xf bank_mask:0xf
v_fmac_f32_dpp v109, v109, v101 row_shl:8 row_mask:0xf bank_mask:0xf
v_mul_f32_dpp v102, v102, v102 row_shl:8 row_mask:0xf bank_mask:0xf
v_mul_f32_dpp v103, v103, v103 row_shl:8 row_mask:0xf bank_mask:0xf
v_mul_f32_dpp v100, v100, v100 row_shl:8 row_mask:0xf bank_mask:0xf
v_mul_f32_dpp v101, v101, v101 row_shl:8 row_mask:0xf bank_mask:0xf

	ds_bpermute_b32 v77, v144, v102
	v_fmac_f32_e32 v120, 0, v102
	v_fmac_f32_e32 v121, 0, v103
	v_fmac_f32_e32 v108, 0, v100
	v_fmac_f32_e32 v109, 0, v101
	ds_bpermute_b32 v76, v144, v120
	ds_bpermute_b32 v78, v144, v121
	ds_bpermute_b32 v79, v144, v103
	ds_bpermute_b32 v80, v144, v108
	ds_bpermute_b32 v81, v144, v100
	ds_bpermute_b32 v82, v144, v109
	ds_bpermute_b32 v83, v144, v101
	s_waitcnt lgkmcnt(0)
	v_fmac_f32_e32 v98, v117, v76
	v_mul_f32_e32 v117, v117, v77
	v_fmac_f32_e32 v99, v127, v78
	v_mul_f32_e32 v118, v127, v79
	v_fmac_f32_e32 v96, v122, v80
	v_mul_f32_e32 v122, v122, v81
	v_fmac_f32_e32 v97, v125, v82
	v_mul_f32_e32 v124, v125, v83
	ds_bpermute_b32 v76, v144, v98
	ds_bpermute_b32 v77, v144, v117
	ds_bpermute_b32 v78, v144, v99
	ds_bpermute_b32 v79, v144, v118
	ds_bpermute_b32 v80, v144, v96
	ds_bpermute_b32 v81, v144, v122
	ds_bpermute_b32 v82, v144, v97
	ds_bpermute_b32 v83, v144, v124
	s_waitcnt lgkmcnt(0)
	v_fmac_f32_e32 v106, v186, v76
	v_mul_f32_e32 v125, v186, v77
	v_fmac_f32_e32 v107, v123, v78
	v_mul_f32_e32 v123, v123, v79
	v_fmac_f32_e32 v104, v110, v80
	v_mul_f32_e32 v126, v110, v81
	v_fmac_f32_e32 v105, v111, v82
	v_mul_f32_e32 v127, v111, v83
	ds_bpermute_b32 v76, v144, v106
	ds_bpermute_b32 v77, v144, v125
	ds_bpermute_b32 v78, v144, v107
	ds_bpermute_b32 v79, v144, v123
	ds_bpermute_b32 v80, v144, v104
	ds_bpermute_b32 v81, v144, v126
	ds_bpermute_b32 v82, v144, v105
	ds_bpermute_b32 v83, v144, v127
	s_waitcnt lgkmcnt(0)
	v_fmac_f32_e32 v114, v116, v76
	v_mul_f32_e32 v140, v116, v77
	v_fmac_f32_e32 v115, v189, v78
	v_mul_f32_e32 v141, v189, v79
	v_fmac_f32_e32 v112, v188, v80
	v_mul_f32_e32 v142, v188, v81
	v_fmac_f32_e32 v113, v119, v82
	v_mul_f32_e32 v119, v119, v83
	ds_bpermute_b32 v77, v144, v114
	ds_bpermute_b32 v76, v144, v140
	ds_bpermute_b32 v79, v144, v115
	ds_bpermute_b32 v78, v144, v141
	ds_bpermute_b32 v81, v144, v112
	ds_bpermute_b32 v80, v144, v142
	ds_bpermute_b32 v83, v144, v113
	ds_bpermute_b32 v82, v144, v119
	s_and_saveexec_b64 s[8:9], s[12:13]
	s_cbranch_execz .LBB0_439
	s_or_b32 s4, s47, 1
	s_mul_hi_i32 s5, s4, 0x84
	s_mulk_i32 s4, 0x84
	s_add_u32 s4, s4, s14
	s_addc_u32 s5, s5, 0
	s_mulk_i32 s5, 0x2800
	s_mul_hi_u32 s14, s4, 0x2800
	s_add_i32 s14, s14, s5
	s_mulk_i32 s4, 0x2800
	s_add_u32 s4, s77, s4
	s_addc_u32 s5, s78, s14
	v_lshl_add_u64 v[110:111], v[176:177], 3, s[4:5]
	s_waitcnt lgkmcnt(0)
	flat_store_dwordx4 v[110:111], v[76:79]
	flat_store_dwordx4 v[110:111], v[80:83] offset:16
.LBB0_439:
	s_or_b64 exec, exec, s[8:9]
	s_waitcnt lgkmcnt(0)
	v_and_b32_e32 v77, 1, v217
	v_and_b32_e32 v76, -8, v176
	v_cndmask_b32_e64 v78, 0, 1, s[56:57]
	v_cmp_eq_u32_e64 s[8:9], 0, v77
	v_lshl_add_u32 v110, v77, 4, v218
	v_ashrrev_i32_e32 v77, 31, v76
	v_cmp_ne_u32_e64 s[14:15], 1, v78
	v_and_b32_e32 v78, 64, v214
	s_andn2_b64 vcc, exec, s[56:57]
	v_xor_b32_e32 v111, 16, v214
	v_lshlrev_b64 v[76:77], 1, v[76:77]
	v_add_u32_e32 v116, 64, v78
	s_cbranch_vccnz .LBB0_441
	v_lshlrev_b32_e32 v78, 16, v198
	v_and_b32_e32 v79, 0xffff0000, v198
	v_add_f32_e32 v82, v150, v114
	v_add_f32_e32 v83, v151, v115
	v_mul_f32_e32 v82, v82, v78
	v_mul_f32_e32 v83, v83, v79
	v_lshlrev_b32_e32 v80, 16, v199
	v_and_b32_e32 v81, 0xffff0000, v199
	v_cvt_pk_bf16_f32 v82, v82, v83
	v_add_f32_e32 v83, v148, v112
	v_add_f32_e32 v112, v149, v113
	v_mul_f32_e32 v83, v83, v80
	v_mul_f32_e32 v112, v112, v81
	v_cvt_pk_bf16_f32 v83, v83, v112
	v_mul_f32_e32 v112, v219, v78
	v_mul_f32_e32 v113, v145, v79
	v_mul_f32_e32 v78, v140, v78
	v_mul_f32_e32 v79, v141, v79
	v_cvt_pk_bf16_f32 v112, v112, v113
	v_mul_f32_e32 v113, v146, v80
	v_mul_f32_e32 v114, v147, v81
	v_cvt_pk_bf16_f32 v78, v78, v79
	v_mul_f32_e32 v79, v142, v80
	v_mul_f32_e32 v80, v119, v81
	v_cvt_pk_bf16_f32 v113, v113, v114
	v_cvt_pk_bf16_f32 v79, v79, v80
	v_lshlrev_b32_e32 v80, 16, v194
	v_and_b32_e32 v81, 0xffff0000, v194
	v_lshlrev_b32_e32 v114, 16, v195
	v_and_b32_e32 v115, 0xffff0000, v195
	v_add_f32_e32 v106, v138, v106
	v_add_f32_e32 v107, v139, v107
	v_add_f32_e32 v104, v136, v104
	v_add_f32_e32 v105, v137, v105
	v_mul_f32_e32 v106, v106, v80
	v_mul_f32_e32 v107, v107, v81
	v_mul_f32_e32 v104, v104, v114
	v_mul_f32_e32 v105, v105, v115
	v_cvt_pk_bf16_f32 v106, v106, v107
	v_cvt_pk_bf16_f32 v104, v104, v105
	v_mul_f32_e32 v105, v225, v80
	v_mul_f32_e32 v107, v226, v81
	v_mul_f32_e32 v80, v125, v80
	v_mul_f32_e32 v81, v123, v81
	v_cvt_pk_bf16_f32 v105, v105, v107
	v_mul_f32_e32 v107, v227, v114
	v_cvt_pk_bf16_f32 v80, v80, v81
	v_mul_f32_e32 v81, v126, v114
	v_mul_f32_e32 v114, v127, v115
	v_cmp_lt_i32_e32 vcc, v111, v116
	v_cvt_pk_bf16_f32 v81, v81, v114
	v_cndmask_b32_e64 v114, v83, v104, s[8:9]
	v_cndmask_b32_e64 v123, v112, v105, s[8:9]
	v_cndmask_b32_e64 v126, v78, v80, s[8:9]
	v_cndmask_b32_e64 v83, v104, v83, s[8:9]
	v_cndmask_b32_e64 v104, v105, v112, s[8:9]
	v_cndmask_b32_e64 v112, v80, v78, s[8:9]
	v_cndmask_b32_e32 v78, v214, v111, vcc
	v_mul_f32_e32 v119, v228, v115
	v_cndmask_b32_e64 v115, v82, v106, s[8:9]
	v_lshlrev_b32_e32 v136, 2, v78
	v_cvt_pk_bf16_f32 v107, v107, v119
	v_cndmask_b32_e64 v125, v79, v81, s[8:9]
	v_cndmask_b32_e64 v119, v113, v107, s[8:9]
	v_cndmask_b32_e64 v105, v107, v113, s[8:9]
	v_cndmask_b32_e64 v113, v81, v79, s[8:9]
	ds_bpermute_b32 v78, v136, v115
	ds_bpermute_b32 v79, v136, v114
	ds_bpermute_b32 v114, v136, v123
	ds_bpermute_b32 v115, v136, v119
	v_cndmask_b32_e64 v82, v106, v82, s[8:9]
	ds_bpermute_b32 v119, v136, v126
	s_waitcnt lgkmcnt(0)
	v_cndmask_b32_e64 v81, v83, v79, s[8:9]
	v_cndmask_b32_e64 v80, v82, v78, s[8:9]
	v_cndmask_b32_e64 v79, v79, v83, s[8:9]
	v_cndmask_b32_e64 v78, v78, v82, s[8:9]
	v_mov_b64_e32 v[82:83], s[24:25]
	v_mad_i64_i32 v[126:127], s[4:5], v110, s88, v[82:83]
	ds_bpermute_b32 v123, v136, v125
	v_cndmask_b32_e64 v107, v105, v115, s[8:9]
	v_cndmask_b32_e64 v106, v104, v114, s[8:9]
	v_cndmask_b32_e64 v105, v115, v105, s[8:9]
	v_cndmask_b32_e64 v104, v114, v104, s[8:9]
	v_lshl_add_u64 v[126:127], v[126:127], 0, v[76:77]
	flat_store_dwordx4 v[126:127], v[78:81] offset:2560
	flat_store_dwordx4 v[126:127], v[104:107]
	v_cmp_gt_i32_e32 vcc, s85, v110
	v_add_u32_e32 v78, 0xffff8000, v110
	v_mov_b32_e32 v104, s82
	v_mov_b32_e32 v105, s80
	v_mov_b32_e32 v106, s81
	v_mov_b32_e32 v107, s79
	v_cndmask_b32_e64 v114, v112, v119, s[8:9]
	v_cndmask_b32_e64 v112, v119, v112, s[8:9]
	v_ashrrev_i32_e32 v119, 31, v110
	v_cndmask_b32_e32 v81, v78, v110, vcc
	v_cndmask_b32_e32 v79, v104, v105, vcc
	v_cndmask_b32_e32 v78, v106, v107, vcc
	v_cndmask_b32_e32 v80, 0, v119, vcc
	v_mad_u64_u32 v[78:79], s[4:5], v81, s3, v[78:79]
	v_mad_i32_i24 v79, v80, s3, v79
	s_waitcnt lgkmcnt(0)
	v_cndmask_b32_e64 v115, v113, v123, s[8:9]
	v_cndmask_b32_e64 v113, v123, v113, s[8:9]
	v_lshl_add_u64 v[78:79], v[78:79], 0, v[76:77]
	flat_store_dwordx4 v[78:79], v[112:115]
	v_lshlrev_b32_e32 v78, 16, v192
	v_and_b32_e32 v79, 0xffff0000, v192
	v_lshlrev_b32_e32 v80, 16, v193
	v_and_b32_e32 v81, 0xffff0000, v193
	v_add_f32_e32 v98, v130, v98
	v_add_f32_e32 v99, v131, v99
	v_add_f32_e32 v96, v128, v96
	v_add_f32_e32 v97, v129, v97
	v_mul_f32_e32 v98, v98, v78
	v_mul_f32_e32 v99, v99, v79
	v_mul_f32_e32 v96, v96, v80
	v_mul_f32_e32 v97, v97, v81
	v_cvt_pk_bf16_f32 v98, v98, v99
	v_cvt_pk_bf16_f32 v96, v96, v97
	v_mul_f32_e32 v97, v206, v78
	v_mul_f32_e32 v99, v220, v79
	v_mul_f32_e32 v78, v117, v78
	v_mul_f32_e32 v79, v118, v79
	v_cvt_pk_bf16_f32 v97, v97, v99
	v_mul_f32_e32 v99, v223, v80
	v_mul_f32_e32 v112, v224, v81
	v_cvt_pk_bf16_f32 v78, v78, v79
	v_mul_f32_e32 v79, v122, v80
	v_mul_f32_e32 v80, v124, v81
	v_cvt_pk_bf16_f32 v99, v99, v112
	v_cvt_pk_bf16_f32 v79, v79, v80
	v_lshlrev_b32_e32 v80, 16, v190
	v_and_b32_e32 v81, 0xffff0000, v190
	v_lshlrev_b32_e32 v112, 16, v191
	v_and_b32_e32 v113, 0xffff0000, v191
	v_add_f32_e32 v114, v134, v120
	v_add_f32_e32 v115, v135, v121
	v_add_f32_e32 v108, v132, v108
	v_add_f32_e32 v109, v133, v109
	v_mul_f32_e32 v114, v114, v80
	v_mul_f32_e32 v115, v115, v81
	v_mul_f32_e32 v108, v108, v112
	v_mul_f32_e32 v109, v109, v113
	v_cvt_pk_bf16_f32 v114, v114, v115
	v_cvt_pk_bf16_f32 v108, v108, v109
	v_mul_f32_e32 v109, v204, v80
	v_mul_f32_e32 v115, v205, v81
	v_mul_f32_e32 v80, v102, v80
	v_mul_f32_e32 v81, v103, v81
	v_cvt_pk_bf16_f32 v80, v80, v81
	v_mul_f32_e32 v81, v100, v112
	v_mul_f32_e32 v100, v101, v113
	v_cvt_pk_bf16_f32 v109, v109, v115
	v_mul_f32_e32 v115, v207, v112
	v_mul_f32_e32 v117, v221, v113
	v_cvt_pk_bf16_f32 v81, v81, v100
	v_cndmask_b32_e64 v100, v96, v108, s[8:9]
	v_cndmask_b32_e64 v101, v98, v114, s[8:9]
	v_cvt_pk_bf16_f32 v115, v115, v117
	v_cndmask_b32_e64 v103, v97, v109, s[8:9]
	v_cndmask_b32_e64 v102, v99, v115, s[8:9]
	v_cndmask_b32_e64 v113, v79, v81, s[8:9]
	v_cndmask_b32_e64 v117, v78, v80, s[8:9]
	v_cndmask_b32_e64 v98, v114, v98, s[8:9]
	v_cndmask_b32_e64 v96, v108, v96, s[8:9]
	v_cndmask_b32_e64 v108, v109, v97, s[8:9]
	v_cndmask_b32_e64 v109, v80, v78, s[8:9]
	v_cndmask_b32_e64 v114, v81, v79, s[8:9]
	ds_bpermute_b32 v78, v136, v101
	ds_bpermute_b32 v79, v136, v100
	ds_bpermute_b32 v100, v136, v103
	ds_bpermute_b32 v101, v136, v102
	v_add_u32_e32 v112, 32, v110
	v_mad_i64_i32 v[82:83], s[4:5], v112, s88, v[82:83]
	v_cndmask_b32_e64 v97, v115, v99, s[8:9]
	ds_bpermute_b32 v115, v136, v117
	ds_bpermute_b32 v113, v136, v113
	s_waitcnt lgkmcnt(0)
	v_cndmask_b32_e64 v81, v96, v79, s[8:9]
	v_cndmask_b32_e64 v80, v98, v78, s[8:9]
	v_cndmask_b32_e64 v79, v79, v96, s[8:9]
	v_cndmask_b32_e64 v78, v78, v98, s[8:9]
	v_lshl_add_u64 v[82:83], v[82:83], 0, v[76:77]
	v_cndmask_b32_e64 v99, v97, v101, s[8:9]
	v_cndmask_b32_e64 v98, v108, v100, s[8:9]
	v_cndmask_b32_e64 v97, v101, v97, s[8:9]
	v_cndmask_b32_e64 v96, v100, v108, s[8:9]
	flat_store_dwordx4 v[82:83], v[78:81] offset:2560
	flat_store_dwordx4 v[82:83], v[96:99]
	v_cmp_gt_i32_e32 vcc, s85, v112
	v_add_u32_e32 v78, 0xffff8020, v110
	v_ashrrev_i32_e32 v108, 31, v112
	v_cndmask_b32_e32 v81, v78, v112, vcc
	v_cndmask_b32_e32 v79, v104, v105, vcc
	v_cndmask_b32_e32 v78, v106, v107, vcc
	v_cndmask_b32_e32 v80, 0, v108, vcc
	v_mad_u64_u32 v[78:79], s[4:5], v81, s3, v[78:79]
	v_mad_i32_i24 v79, v80, s3, v79
	v_cndmask_b32_e64 v103, v114, v113, s[8:9]
	v_cndmask_b32_e64 v102, v109, v115, s[8:9]
	v_cndmask_b32_e64 v101, v113, v114, s[8:9]
	v_cndmask_b32_e64 v100, v115, v109, s[8:9]
	v_lshl_add_u64 v[78:79], v[78:79], 0, v[76:77]
	flat_store_dwordx4 v[78:79], v[100:103]
.LBB0_441:
	v_pk_fma_f32 v[62:63], v[62:63], s[36:37], v[94:95] op_sel_hi:[1,0,1] neg_lo:[1,0,0] neg_hi:[1,0,0]
	v_pk_fma_f32 v[60:61], v[60:61], s[36:37], v[92:93] op_sel_hi:[1,0,1] neg_lo:[1,0,0] neg_hi:[1,0,0]
	v_exp_f32_e32 v62, v62
	v_exp_f32_e32 v63, v63
	v_exp_f32_e32 v60, v60
	v_exp_f32_e32 v61, v61
	v_pk_fma_f32 v[58:59], v[58:59], s[36:37], v[86:87] op_sel_hi:[1,0,1] neg_lo:[1,0,0] neg_hi:[1,0,0]
	v_pk_fma_f32 v[54:55], v[54:55], s[36:37], v[94:95] op_sel_hi:[1,0,1] neg_lo:[1,0,0] neg_hi:[1,0,0]
	v_exp_f32_e32 v58, v58
	v_exp_f32_e32 v59, v59
	v_pk_add_f32 v[62:63], v[62:63], 1.0 op_sel_hi:[1,0]
	v_exp_f32_e32 v54, v54
	v_exp_f32_e32 v55, v55
	v_pk_fma_f32 v[52:53], v[52:53], s[36:37], v[92:93] op_sel_hi:[1,0,1] neg_lo:[1,0,0] neg_hi:[1,0,0]
	v_rcp_f32_e32 v62, v62
	v_rcp_f32_e32 v63, v63
	v_pk_add_f32 v[60:61], v[60:61], 1.0 op_sel_hi:[1,0]
	v_exp_f32_e32 v52, v52
	v_exp_f32_e32 v53, v53
	v_pk_fma_f32 v[46:47], v[46:47], s[36:37], v[94:95] op_sel_hi:[1,0,1] neg_lo:[1,0,0] neg_hi:[1,0,0]
	v_rcp_f32_e32 v60, v60
	v_rcp_f32_e32 v61, v61
	v_exp_f32_e32 v46, v46
	v_exp_f32_e32 v47, v47
	v_pk_add_f32 v[58:59], v[58:59], 1.0 op_sel_hi:[1,0]
	v_pk_add_f32 v[54:55], v[54:55], 1.0 op_sel_hi:[1,0]
	v_pk_fma_f32 v[44:45], v[44:45], s[36:37], v[92:93] op_sel_hi:[1,0,1] neg_lo:[1,0,0] neg_hi:[1,0,0]
	v_rcp_f32_e32 v82, v58
	v_rcp_f32_e32 v83, v59
	v_pk_mul_f32 v[58:59], v[90:91], v[62:63]
	v_pk_fma_f32 v[56:57], v[56:57], s[36:37], v[84:85] op_sel_hi:[1,0,1] neg_lo:[1,0,0] neg_hi:[1,0,0]
	v_rcp_f32_e32 v54, v54
	v_rcp_f32_e32 v55, v55
	v_pk_add_f32 v[52:53], v[52:53], 1.0 op_sel_hi:[1,0]
	v_exp_f32_e32 v44, v44
	v_exp_f32_e32 v45, v45
	v_exp_f32_e32 v58, v58
	v_exp_f32_e32 v59, v59
	v_exp_f32_e32 v96, v56
	v_exp_f32_e32 v97, v57
	v_pk_mul_f32 v[56:57], v[88:89], v[60:61]
	v_rcp_f32_e32 v52, v52
	v_rcp_f32_e32 v53, v53
	v_pk_add_f32 v[46:47], v[46:47], 1.0 op_sel_hi:[1,0]
	v_pk_fma_f32 v[38:39], v[38:39], s[36:37], v[94:95] op_sel_hi:[1,0,1] neg_lo:[1,0,0] neg_hi:[1,0,0]
	v_pk_fma_f32 v[36:37], v[36:37], s[36:37], v[92:93] op_sel_hi:[1,0,1] neg_lo:[1,0,0] neg_hi:[1,0,0]
	v_exp_f32_e32 v56, v56
	v_exp_f32_e32 v57, v57
	v_rcp_f32_e32 v46, v46
	v_rcp_f32_e32 v47, v47
	v_exp_f32_e32 v38, v38
	v_exp_f32_e32 v39, v39
	v_exp_f32_e32 v36, v36
	v_exp_f32_e32 v37, v37
	v_pk_fma_f32 v[50:51], v[50:51], s[36:37], v[86:87] op_sel_hi:[1,0,1] neg_lo:[1,0,0] neg_hi:[1,0,0]
	v_pk_mul_f32 v[54:55], v[90:91], v[54:55]
	v_exp_f32_e32 v50, v50
	v_exp_f32_e32 v51, v51
	v_pk_fma_f32 v[48:49], v[48:49], s[36:37], v[84:85] op_sel_hi:[1,0,1] neg_lo:[1,0,0] neg_hi:[1,0,0]
	v_pk_add_f32 v[44:45], v[44:45], 1.0 op_sel_hi:[1,0]
	v_pk_fma_f32 v[62:63], v[58:59], v[58:59], 1.0 op_sel_hi:[1,1,0] neg_lo:[1,0,0] neg_hi:[1,0,0]
	v_pk_add_f32 v[60:61], v[96:97], 1.0 op_sel_hi:[1,0]
	v_exp_f32_e32 v102, v54
	v_exp_f32_e32 v103, v55
	v_exp_f32_e32 v48, v48
	v_exp_f32_e32 v49, v49
	v_pk_mul_f32 v[52:53], v[88:89], v[52:53]
	v_pk_fma_f32 v[42:43], v[42:43], s[36:37], v[86:87] op_sel_hi:[1,0,1] neg_lo:[1,0,0] neg_hi:[1,0,0]
	v_rcp_f32_e32 v44, v44
	v_rcp_f32_e32 v45, v45
	v_sqrt_f32_e32 v62, v62
	v_sqrt_f32_e32 v63, v63
	v_rcp_f32_e32 v96, v60
	v_rcp_f32_e32 v97, v61
	v_pk_fma_f32 v[60:61], v[56:57], v[56:57], 1.0 op_sel_hi:[1,1,0] neg_lo:[1,0,0] neg_hi:[1,0,0]
	v_exp_f32_e32 v104, v52
	v_exp_f32_e32 v105, v53
	v_exp_f32_e32 v42, v42
	v_exp_f32_e32 v43, v43
	v_pk_mul_f32 v[46:47], v[90:91], v[46:47]
	v_pk_fma_f32 v[40:41], v[40:41], s[36:37], v[84:85] op_sel_hi:[1,0,1] neg_lo:[1,0,0] neg_hi:[1,0,0]
	v_pk_add_f32 v[38:39], v[38:39], 1.0 op_sel_hi:[1,0]
	v_pk_add_f32 v[36:37], v[36:37], 1.0 op_sel_hi:[1,0]
	v_sqrt_f32_e32 v98, v60
	v_sqrt_f32_e32 v99, v61
	v_exp_f32_e32 v106, v46
	v_exp_f32_e32 v107, v47
	v_exp_f32_e32 v40, v40
	v_exp_f32_e32 v41, v41
	v_rcp_f32_e32 v38, v38
	v_rcp_f32_e32 v39, v39
	v_rcp_f32_e32 v36, v36
	v_rcp_f32_e32 v37, v37
	v_lshlrev_b32_e32 v80, 16, v171
	v_and_b32_e32 v81, 0xffff0000, v171
	v_pk_add_f32 v[50:51], v[50:51], 1.0 op_sel_hi:[1,0]
	v_lshlrev_b32_e32 v78, 16, v170
	v_and_b32_e32 v79, 0xffff0000, v170
	v_pk_mul_f32 v[60:61], v[82:83], v[80:81]
	v_rcp_f32_e32 v50, v50
	v_rcp_f32_e32 v51, v51
	v_pk_fma_f32 v[54:55], v[102:103], v[102:103], 1.0 op_sel_hi:[1,1,0] neg_lo:[1,0,0] neg_hi:[1,0,0]
	v_pk_add_f32 v[48:49], v[48:49], 1.0 op_sel_hi:[1,0]
	v_pk_mul_f32 v[44:45], v[88:89], v[44:45]
	v_pk_mul_f32 v[60:61], v[60:61], v[62:63]
	v_pk_mul_f32 v[62:63], v[96:97], v[78:79]
	v_sqrt_f32_e32 v54, v54
	v_sqrt_f32_e32 v55, v55
	v_rcp_f32_e32 v52, v48
	v_rcp_f32_e32 v53, v49
	v_pk_fma_f32 v[48:49], v[104:105], v[104:105], 1.0 op_sel_hi:[1,1,0] neg_lo:[1,0,0] neg_hi:[1,0,0]
	v_pk_add_f32 v[42:43], v[42:43], 1.0 op_sel_hi:[1,0]
	v_exp_f32_e32 v108, v44
	v_exp_f32_e32 v109, v45
	v_pk_fma_f32 v[34:35], v[34:35], s[36:37], v[86:87] op_sel_hi:[1,0,1] neg_lo:[1,0,0] neg_hi:[1,0,0]
	v_pk_fma_f32 v[32:33], v[32:33], s[36:37], v[84:85] op_sel_hi:[1,0,1] neg_lo:[1,0,0] neg_hi:[1,0,0]
	v_pk_mul_f32 v[62:63], v[62:63], v[98:99]
	v_sqrt_f32_e32 v98, v48
	v_sqrt_f32_e32 v99, v49
	v_rcp_f32_e32 v42, v42
	v_rcp_f32_e32 v43, v43
	v_pk_fma_f32 v[46:47], v[106:107], v[106:107], 1.0 op_sel_hi:[1,1,0] neg_lo:[1,0,0] neg_hi:[1,0,0]
	v_pk_add_f32 v[40:41], v[40:41], 1.0 op_sel_hi:[1,0]
	v_exp_f32_e32 v34, v34
	v_exp_f32_e32 v35, v35
	v_pk_mul_f32 v[38:39], v[90:91], v[38:39]
	v_exp_f32_e32 v32, v32
	v_exp_f32_e32 v33, v33
	v_pk_mul_f32 v[36:37], v[88:89], v[36:37]
	v_lshlrev_b32_e32 v96, 16, v169
	v_and_b32_e32 v97, 0xffff0000, v169
	v_sqrt_f32_e32 v46, v46
	v_sqrt_f32_e32 v47, v47
	v_rcp_f32_e32 v44, v40
	v_rcp_f32_e32 v45, v41
	v_exp_f32_e32 v38, v38
	v_exp_f32_e32 v39, v39
	v_exp_f32_e32 v36, v36
	v_exp_f32_e32 v37, v37
	v_lshlrev_b32_e32 v82, 16, v168
	v_and_b32_e32 v83, 0xffff0000, v168
	v_pk_mul_f32 v[48:49], v[50:51], v[96:97]
	v_pk_mul_f32 v[50:51], v[52:53], v[82:83]
	v_pk_mul_f32 v[48:49], v[48:49], v[54:55]
	v_lshlrev_b32_e32 v54, 16, v167
	v_and_b32_e32 v55, 0xffff0000, v167
	v_pk_fma_f32 v[40:41], v[108:109], v[108:109], 1.0 op_sel_hi:[1,1,0] neg_lo:[1,0,0] neg_hi:[1,0,0]
	v_pk_mul_f32 v[50:51], v[50:51], v[98:99]
	v_lshlrev_b32_e32 v52, 16, v166
	v_and_b32_e32 v53, 0xffff0000, v166
	v_sqrt_f32_e32 v98, v40
	v_sqrt_f32_e32 v99, v41
	v_pk_mul_f32 v[40:41], v[42:43], v[54:55]
	v_pk_add_f32 v[34:35], v[34:35], 1.0 op_sel_hi:[1,0]
	v_pk_add_f32 v[32:33], v[32:33], 1.0 op_sel_hi:[1,0]
	v_pk_mul_f32 v[40:41], v[40:41], v[46:47]
	v_pk_mul_f32 v[42:43], v[44:45], v[52:53]
	v_rcp_f32_e32 v34, v34
	v_rcp_f32_e32 v35, v35
	v_pk_fma_f32 v[44:45], v[38:39], v[38:39], 1.0 op_sel_hi:[1,1,0] neg_lo:[1,0,0] neg_hi:[1,0,0]
	v_rcp_f32_e32 v32, v32
	v_rcp_f32_e32 v33, v33
	v_pk_fma_f32 v[46:47], v[36:37], v[36:37], 1.0 op_sel_hi:[1,1,0] neg_lo:[1,0,0] neg_hi:[1,0,0]
	v_sqrt_f32_e32 v44, v44
	v_sqrt_f32_e32 v45, v45
	v_sqrt_f32_e32 v46, v46
	v_sqrt_f32_e32 v47, v47
	s_nop 1
v_fmac_f32_dpp v62, v62, v56 row_shr:1 row_mask:0xf bank_mask:0xf
v_fmac_f32_dpp v63, v63, v57 row_shr:1 row_mask:0xf bank_mask:0xf
v_fmac_f32_dpp v60, v60, v58 row_shr:1 row_mask:0xf bank_mask:0xf
v_fmac_f32_dpp v61, v61, v59 row_shr:1 row_mask:0xf bank_mask:0xf
v_mul_f32_dpp v56, v56, v56 row_shr:1 row_mask:0xf bank_mask:0xf
v_mul_f32_dpp v57, v57, v57 row_shr:1 row_mask:0xf bank_mask:0xf
v_mul_f32_dpp v58, v58, v58 row_shr:1 row_mask:0xf bank_mask:0xf
v_mul_f32_dpp v59, v59, v59 row_shr:1 row_mask:0xf bank_mask:0xf
v_fmac_f32_dpp v62, v62, v56 row_shr:2 row_mask:0xf bank_mask:0xf
v_fmac_f32_dpp v63, v63, v57 row_shr:2 row_mask:0xf bank_mask:0xf
v_fmac_f32_dpp v60, v60, v58 row_shr:2 row_mask:0xf bank_mask:0xf
v_fmac_f32_dpp v61, v61, v59 row_shr:2 row_mask:0xf bank_mask:0xf
v_mul_f32_dpp v56, v56, v56 row_shr:2 row_mask:0xf bank_mask:0xf
v_mul_f32_dpp v57, v57, v57 row_shr:2 row_mask:0xf bank_mask:0xf
v_mul_f32_dpp v58, v58, v58 row_shr:2 row_mask:0xf bank_mask:0xf
v_mul_f32_dpp v59, v59, v59 row_shr:2 row_mask:0xf bank_mask:0xf
v_fmac_f32_dpp v62, v62, v56 row_shr:4 row_mask:0xf bank_mask:0xf
v_fmac_f32_dpp v63, v63, v57 row_shr:4 row_mask:0xf bank_mask:0xf
v_fmac_f32_dpp v60, v60, v58 row_shr:4 row_mask:0xf bank_mask:0xf
v_fmac_f32_dpp v61, v61, v59 row_shr:4 row_mask:0xf bank_mask:0xf
v_mul_f32_dpp v56, v56, v56 row_shr:4 row_mask:0xf bank_mask:0xf
v_mul_f32_dpp v57, v57, v57 row_shr:4 row_mask:0xf bank_mask:0xf
v_mul_f32_dpp v58, v58, v58 row_shr:4 row_mask:0xf bank_mask:0xf
v_mul_f32_dpp v59, v59, v59 row_shr:4 row_mask:0xf bank_mask:0xf
v_fmac_f32_dpp v62, v62, v56 row_shr:8 row_mask:0xf bank_mask:0xf
v_fmac_f32_dpp v63, v63, v57 row_shr:8 row_mask:0xf bank_mask:0xf
v_fmac_f32_dpp v60, v60, v58 row_shr:8 row_mask:0xf bank_mask:0xf
v_fmac_f32_dpp v61, v61, v59 row_shr:8 row_mask:0xf bank_mask:0xf
v_mul_f32_dpp v56, v56, v56 row_shr:8 row_mask:0xf bank_mask:0xf
v_mul_f32_dpp v57, v57, v57 row_shr:8 row_mask:0xf bank_mask:0xf
v_mul_f32_dpp v58, v58, v58 row_shr:8 row_mask:0xf bank_mask:0xf
v_mul_f32_dpp v59, v59, v59 row_shr:8 row_mask:0xf bank_mask:0xf

	v_pk_mul_f32 v[42:43], v[42:43], v[98:99]
	v_lshlrev_b32_e32 v98, 16, v164
	v_and_b32_e32 v99, 0xffff0000, v164
	v_lshlrev_b32_e32 v100, 16, v165
	v_and_b32_e32 v101, 0xffff0000, v165
	v_or_b32_e32 v112, 60, v144
	v_pk_mul_f32 v[34:35], v[34:35], v[100:101]
	v_pk_mul_f32 v[32:33], v[32:33], v[98:99]
	v_fmac_f32_e32 v62, 0, v56
	v_fmac_f32_e32 v63, 0, v57
	v_fmac_f32_e32 v60, 0, v58
	v_fmac_f32_e32 v61, 0, v59
	v_pk_mul_f32 v[44:45], v[34:35], v[44:45]
	v_pk_mul_f32 v[46:47], v[32:33], v[46:47]
	v_mov_b32_e32 v32, v36
	v_mov_b32_e32 v36, v38
	ds_bpermute_b32 v33, v112, v62
	ds_bpermute_b32 v34, v112, v56
	ds_bpermute_b32 v35, v112, v63
	ds_bpermute_b32 v38, v112, v57
	ds_bpermute_b32 v84, v112, v60
	ds_bpermute_b32 v85, v112, v58
	ds_bpermute_b32 v86, v112, v61
	ds_bpermute_b32 v87, v112, v59
	s_nop 1
v_fmac_f32_dpp v50, v50, v104 row_shr:1 row_mask:0xf bank_mask:0xf
v_fmac_f32_dpp v51, v51, v105 row_shr:1 row_mask:0xf bank_mask:0xf
v_fmac_f32_dpp v48, v48, v102 row_shr:1 row_mask:0xf bank_mask:0xf
v_fmac_f32_dpp v49, v49, v103 row_shr:1 row_mask:0xf bank_mask:0xf
v_mul_f32_dpp v104, v104, v104 row_shr:1 row_mask:0xf bank_mask:0xf
v_mul_f32_dpp v105, v105, v105 row_shr:1 row_mask:0xf bank_mask:0xf
v_mul_f32_dpp v102, v102, v102 row_shr:1 row_mask:0xf bank_mask:0xf
v_mul_f32_dpp v103, v103, v103 row_shr:1 row_mask:0xf bank_mask:0xf
v_fmac_f32_dpp v50, v50, v104 row_shr:2 row_mask:0xf bank_mask:0xf
v_fmac_f32_dpp v51, v51, v105 row_shr:2 row_mask:0xf bank_mask:0xf
v_fmac_f32_dpp v48, v48, v102 row_shr:2 row_mask:0xf bank_mask:0xf
v_fmac_f32_dpp v49, v49, v103 row_shr:2 row_mask:0xf bank_mask:0xf
v_mul_f32_dpp v104, v104, v104 row_shr:2 row_mask:0xf bank_mask:0xf
v_mul_f32_dpp v105, v105, v105 row_shr:2 row_mask:0xf bank_mask:0xf
v_mul_f32_dpp v102, v102, v102 row_shr:2 row_mask:0xf bank_mask:0xf
v_mul_f32_dpp v103, v103, v103 row_shr:2 row_mask:0xf bank_mask:0xf
v_fmac_f32_dpp v50, v50, v104 row_shr:4 row_mask:0xf bank_mask:0xf
v_fmac_f32_dpp v51, v51, v105 row_shr:4 row_mask:0xf bank_mask:0xf
v_fmac_f32_dpp v48, v48, v102 row_shr:4 row_mask:0xf bank_mask:0xf
v_fmac_f32_dpp v49, v49, v103 row_shr:4 row_mask:0xf bank_mask:0xf
v_mul_f32_dpp v104, v104, v104 row_shr:4 row_mask:0xf bank_mask:0xf
v_mul_f32_dpp v105, v105, v105 row_shr:4 row_mask:0xf bank_mask:0xf
v_mul_f32_dpp v102, v102, v102 row_shr:4 row_mask:0xf bank_mask:0xf
v_mul_f32_dpp v103, v103, v103 row_shr:4 row_mask:0xf bank_mask:0xf
v_fmac_f32_dpp v50, v50, v104 row_shr:8 row_mask:0xf bank_mask:0xf
v_fmac_f32_dpp v51, v51, v105 row_shr:8 row_mask:0xf bank_mask:0xf
v_fmac_f32_dpp v48, v48, v102 row_shr:8 row_mask:0xf bank_mask:0xf
v_fmac_f32_dpp v49, v49, v103 row_shr:8 row_mask:0xf bank_mask:0xf
v_mul_f32_dpp v104, v104, v104 row_shr:8 row_mask:0xf bank_mask:0xf
v_mul_f32_dpp v105, v105, v105 row_shr:8 row_mask:0xf bank_mask:0xf
v_mul_f32_dpp v102, v102, v102 row_shr:8 row_mask:0xf bank_mask:0xf
v_mul_f32_dpp v103, v103, v103 row_shr:8 row_mask:0xf bank_mask:0xf

	s_nop 1
v_fmac_f32_dpp v42, v42, v108 row_shr:1 row_mask:0xf bank_mask:0xf
v_fmac_f32_dpp v43, v43, v109 row_shr:1 row_mask:0xf bank_mask:0xf
v_fmac_f32_dpp v40, v40, v106 row_shr:1 row_mask:0xf bank_mask:0xf
v_fmac_f32_dpp v41, v41, v107 row_shr:1 row_mask:0xf bank_mask:0xf
v_mul_f32_dpp v108, v108, v108 row_shr:1 row_mask:0xf bank_mask:0xf
v_mul_f32_dpp v109, v109, v109 row_shr:1 row_mask:0xf bank_mask:0xf
v_mul_f32_dpp v106, v106, v106 row_shr:1 row_mask:0xf bank_mask:0xf
v_mul_f32_dpp v107, v107, v107 row_shr:1 row_mask:0xf bank_mask:0xf
v_fmac_f32_dpp v42, v42, v108 row_shr:2 row_mask:0xf bank_mask:0xf
v_fmac_f32_dpp v43, v43, v109 row_shr:2 row_mask:0xf bank_mask:0xf
v_fmac_f32_dpp v40, v40, v106 row_shr:2 row_mask:0xf bank_mask:0xf
v_fmac_f32_dpp v41, v41, v107 row_shr:2 row_mask:0xf bank_mask:0xf
v_mul_f32_dpp v108, v108, v108 row_shr:2 row_mask:0xf bank_mask:0xf
v_mul_f32_dpp v109, v109, v109 row_shr:2 row_mask:0xf bank_mask:0xf
v_mul_f32_dpp v106, v106, v106 row_shr:2 row_mask:0xf bank_mask:0xf
v_mul_f32_dpp v107, v107, v107 row_shr:2 row_mask:0xf bank_mask:0xf
v_fmac_f32_dpp v42, v42, v108 row_shr:4 row_mask:0xf bank_mask:0xf
v_fmac_f32_dpp v43, v43, v109 row_shr:4 row_mask:0xf bank_mask:0xf
v_fmac_f32_dpp v40, v40, v106 row_shr:4 row_mask:0xf bank_mask:0xf
v_fmac_f32_dpp v41, v41, v107 row_shr:4 row_mask:0xf bank_mask:0xf
v_mul_f32_dpp v108, v108, v108 row_shr:4 row_mask:0xf bank_mask:0xf
v_mul_f32_dpp v109, v109, v109 row_shr:4 row_mask:0xf bank_mask:0xf
v_mul_f32_dpp v106, v106, v106 row_shr:4 row_mask:0xf bank_mask:0xf
v_mul_f32_dpp v107, v107, v107 row_shr:4 row_mask:0xf bank_mask:0xf
v_fmac_f32_dpp v42, v42, v108 row_shr:8 row_mask:0xf bank_mask:0xf
v_fmac_f32_dpp v43, v43, v109 row_shr:8 row_mask:0xf bank_mask:0xf
v_fmac_f32_dpp v40, v40, v106 row_shr:8 row_mask:0xf bank_mask:0xf
v_fmac_f32_dpp v41, v41, v107 row_shr:8 row_mask:0xf bank_mask:0xf
v_mul_f32_dpp v108, v108, v108 row_shr:8 row_mask:0xf bank_mask:0xf
v_mul_f32_dpp v109, v109, v109 row_shr:8 row_mask:0xf bank_mask:0xf
v_mul_f32_dpp v106, v106, v106 row_shr:8 row_mask:0xf bank_mask:0xf
v_mul_f32_dpp v107, v107, v107 row_shr:8 row_mask:0xf bank_mask:0xf

	s_nop 1
v_fmac_f32_dpp v46, v46, v32 row_shr:1 row_mask:0xf bank_mask:0xf
v_fmac_f32_dpp v47, v47, v37 row_shr:1 row_mask:0xf bank_mask:0xf
v_fmac_f32_dpp v44, v44, v36 row_shr:1 row_mask:0xf bank_mask:0xf
v_fmac_f32_dpp v45, v45, v39 row_shr:1 row_mask:0xf bank_mask:0xf
v_mul_f32_dpp v32, v32, v32 row_shr:1 row_mask:0xf bank_mask:0xf
v_mul_f32_dpp v37, v37, v37 row_shr:1 row_mask:0xf bank_mask:0xf
v_mul_f32_dpp v36, v36, v36 row_shr:1 row_mask:0xf bank_mask:0xf
v_mul_f32_dpp v39, v39, v39 row_shr:1 row_mask:0xf bank_mask:0xf
v_fmac_f32_dpp v46, v46, v32 row_shr:2 row_mask:0xf bank_mask:0xf
v_fmac_f32_dpp v47, v47, v37 row_shr:2 row_mask:0xf bank_mask:0xf
v_fmac_f32_dpp v44, v44, v36 row_shr:2 row_mask:0xf bank_mask:0xf
v_fmac_f32_dpp v45, v45, v39 row_shr:2 row_mask:0xf bank_mask:0xf
v_mul_f32_dpp v32, v32, v32 row_shr:2 row_mask:0xf bank_mask:0xf
v_mul_f32_dpp v37, v37, v37 row_shr:2 row_mask:0xf bank_mask:0xf
v_mul_f32_dpp v36, v36, v36 row_shr:2 row_mask:0xf bank_mask:0xf
v_mul_f32_dpp v39, v39, v39 row_shr:2 row_mask:0xf bank_mask:0xf
v_fmac_f32_dpp v46, v46, v32 row_shr:4 row_mask:0xf bank_mask:0xf
v_fmac_f32_dpp v47, v47, v37 row_shr:4 row_mask:0xf bank_mask:0xf
v_fmac_f32_dpp v44, v44, v36 row_shr:4 row_mask:0xf bank_mask:0xf
v_fmac_f32_dpp v45, v45, v39 row_shr:4 row_mask:0xf bank_mask:0xf
v_mul_f32_dpp v32, v32, v32 row_shr:4 row_mask:0xf bank_mask:0xf
v_mul_f32_dpp v37, v37, v37 row_shr:4 row_mask:0xf bank_mask:0xf
v_mul_f32_dpp v36, v36, v36 row_shr:4 row_mask:0xf bank_mask:0xf
v_mul_f32_dpp v39, v39, v39 row_shr:4 row_mask:0xf bank_mask:0xf
v_fmac_f32_dpp v46, v46, v32 row_shr:8 row_mask:0xf bank_mask:0xf
v_fmac_f32_dpp v47, v47, v37 row_shr:8 row_mask:0xf bank_mask:0xf
v_fmac_f32_dpp v44, v44, v36 row_shr:8 row_mask:0xf bank_mask:0xf
v_fmac_f32_dpp v45, v45, v39 row_shr:8 row_mask:0xf bank_mask:0xf
v_mul_f32_dpp v32, v32, v32 row_shr:8 row_mask:0xf bank_mask:0xf
v_mul_f32_dpp v37, v37, v37 row_shr:8 row_mask:0xf bank_mask:0xf
v_mul_f32_dpp v36, v36, v36 row_shr:8 row_mask:0xf bank_mask:0xf
v_mul_f32_dpp v39, v39, v39 row_shr:8 row_mask:0xf bank_mask:0xf

	s_add_i32 s49, s49, 6
	s_waitcnt lgkmcnt(0)
	v_fmac_f32_e32 v50, v104, v33
	v_mul_f32_e32 v92, v104, v34
	v_fmac_f32_e32 v51, v105, v35
	v_mul_f32_e32 v93, v105, v38
	v_fmac_f32_e32 v48, v102, v84
	v_mul_f32_e32 v94, v102, v85
	v_fmac_f32_e32 v49, v103, v86
	v_mul_f32_e32 v95, v103, v87
	ds_bpermute_b32 v33, v112, v50
	ds_bpermute_b32 v34, v112, v92
	ds_bpermute_b32 v35, v112, v51
	ds_bpermute_b32 v38, v112, v93
	ds_bpermute_b32 v84, v112, v48
	ds_bpermute_b32 v85, v112, v94
	ds_bpermute_b32 v87, v112, v49
	ds_bpermute_b32 v89, v112, v95
	s_waitcnt lgkmcnt(0)
	v_fmac_f32_e32 v42, v108, v33
	v_mul_f32_e32 v86, v108, v34
	v_fmac_f32_e32 v43, v109, v35
	v_mul_f32_e32 v88, v109, v38
	v_fmac_f32_e32 v40, v106, v84
	v_mul_f32_e32 v90, v106, v85
	v_fmac_f32_e32 v41, v107, v87
	v_mul_f32_e32 v91, v107, v89
	ds_bpermute_b32 v33, v112, v42
	ds_bpermute_b32 v34, v112, v86
	ds_bpermute_b32 v35, v112, v43
	ds_bpermute_b32 v38, v112, v88
	ds_bpermute_b32 v102, v112, v40
	ds_bpermute_b32 v103, v112, v90
	ds_bpermute_b32 v89, v112, v41
	ds_bpermute_b32 v104, v112, v91
	s_waitcnt lgkmcnt(0)
	v_fmac_f32_e32 v46, v32, v33
	v_mul_f32_e32 v84, v32, v34
	v_fmac_f32_e32 v47, v37, v35
	v_mul_f32_e32 v85, v37, v38
	v_fmac_f32_e32 v44, v36, v102
	v_mul_f32_e32 v87, v36, v103
	v_fmac_f32_e32 v45, v39, v89
	v_mul_f32_e32 v89, v39, v104
	ds_bpermute_b32 v33, v112, v46
	ds_bpermute_b32 v32, v112, v84
	ds_bpermute_b32 v35, v112, v47
	ds_bpermute_b32 v34, v112, v85
	ds_bpermute_b32 v37, v112, v44
	ds_bpermute_b32 v36, v112, v87
	ds_bpermute_b32 v39, v112, v45
	ds_bpermute_b32 v38, v112, v89
	s_and_b64 s[4:5], exec, s[54:55]
	s_cselect_b32 s49, 2, s49
	s_add_i32 s49, s49, s66
	s_and_saveexec_b64 s[54:55], s[10:11]
	s_cbranch_execz .LBB0_443
	s_add_u32 s4, s59, s49
	s_addc_u32 s5, s58, 0
	s_mulk_i32 s5, 0x2800
	s_mul_hi_u32 s10, s4, 0x2800
	s_add_i32 s10, s10, s5
	s_mulk_i32 s4, 0x2800
	s_add_u32 s4, s77, s4
	s_addc_u32 s5, s78, s10
	v_lshl_add_u64 v[102:103], v[176:177], 3, s[4:5]
	s_waitcnt lgkmcnt(0)
	flat_store_dwordx4 v[102:103], v[32:35]
	flat_store_dwordx4 v[102:103], v[36:39] offset:16
.LBB0_443:
	s_or_b64 exec, exec, s[54:55]
	v_pk_fma_f32 v[30:31], v[30:31], s[36:37], v[74:75] op_sel_hi:[1,0,1] neg_lo:[1,0,0] neg_hi:[1,0,0]
	v_pk_fma_f32 v[26:27], v[26:27], s[36:37], v[70:71] op_sel_hi:[1,0,1] neg_lo:[1,0,0] neg_hi:[1,0,0]
	v_exp_f32_e32 v30, v30
	v_exp_f32_e32 v31, v31
	v_exp_f32_e32 v26, v26
	v_exp_f32_e32 v27, v27
	v_pk_fma_f32 v[28:29], v[28:29], s[36:37], v[72:73] op_sel_hi:[1,0,1] neg_lo:[1,0,0] neg_hi:[1,0,0]
	v_pk_add_f32 v[30:31], v[30:31], 1.0 op_sel_hi:[1,0]
	v_exp_f32_e32 v28, v28
	v_rcp_f32_e32 v30, v30
	v_rcp_f32_e32 v31, v31
	v_exp_f32_e32 v29, v29
	v_pk_add_f32 v[26:27], v[26:27], 1.0 op_sel_hi:[1,0]
	v_pk_fma_f32 v[20:21], v[20:21], s[36:37], v[72:73] op_sel_hi:[1,0,1] neg_lo:[1,0,0] neg_hi:[1,0,0]
	s_waitcnt lgkmcnt(0)
	v_rcp_f32_e32 v32, v26
	v_rcp_f32_e32 v33, v27
	v_pk_mul_f32 v[26:27], v[66:67], v[30:31]
	v_pk_add_f32 v[28:29], v[28:29], 1.0 op_sel_hi:[1,0]
	v_exp_f32_e32 v26, v26
	v_exp_f32_e32 v27, v27
	v_rcp_f32_e32 v28, v28
	v_rcp_f32_e32 v29, v29
	v_exp_f32_e32 v20, v20
	v_exp_f32_e32 v21, v21
	v_pk_fma_f32 v[24:25], v[24:25], s[36:37], v[68:69] op_sel_hi:[1,0,1] neg_lo:[1,0,0] neg_hi:[1,0,0]
	v_pk_fma_f32 v[30:31], v[26:27], v[26:27], 1.0 op_sel_hi:[1,1,0] neg_lo:[1,0,0] neg_hi:[1,0,0]
	v_exp_f32_e32 v24, v24
	v_exp_f32_e32 v25, v25
	v_pk_mul_f32 v[28:29], v[64:65], v[28:29]
	v_sqrt_f32_e32 v34, v30
	v_sqrt_f32_e32 v35, v31
	v_exp_f32_e32 v30, v28
	v_exp_f32_e32 v31, v29
	v_pk_add_f32 v[20:21], v[20:21], 1.0 op_sel_hi:[1,0]
	v_pk_add_f32 v[24:25], v[24:25], 1.0 op_sel_hi:[1,0]
	v_rcp_f32_e32 v20, v20
	v_rcp_f32_e32 v21, v21
	v_rcp_f32_e32 v28, v24
	v_rcp_f32_e32 v29, v25
	v_pk_fma_f32 v[24:25], v[30:31], v[30:31], 1.0 op_sel_hi:[1,1,0] neg_lo:[1,0,0] neg_hi:[1,0,0]
	v_pk_fma_f32 v[18:19], v[18:19], s[36:37], v[70:71] op_sel_hi:[1,0,1] neg_lo:[1,0,0] neg_hi:[1,0,0]
	v_pk_fma_f32 v[16:17], v[16:17], s[36:37], v[68:69] op_sel_hi:[1,0,1] neg_lo:[1,0,0] neg_hi:[1,0,0]
	v_pk_fma_f32 v[14:15], v[14:15], s[36:37], v[74:75] op_sel_hi:[1,0,1] neg_lo:[1,0,0] neg_hi:[1,0,0]
	v_sqrt_f32_e32 v36, v24
	v_sqrt_f32_e32 v37, v25
	v_pk_mul_f32 v[24:25], v[32:33], v[80:81]
	v_exp_f32_e32 v18, v18
	v_exp_f32_e32 v19, v19
	v_exp_f32_e32 v16, v16
	v_exp_f32_e32 v17, v17
	v_pk_mul_f32 v[20:21], v[64:65], v[20:21]
	v_exp_f32_e32 v14, v14
	v_exp_f32_e32 v15, v15
	v_pk_mul_f32 v[24:25], v[24:25], v[34:35]
	v_exp_f32_e32 v34, v20
	v_exp_f32_e32 v35, v21
	v_pk_fma_f32 v[12:13], v[12:13], s[36:37], v[72:73] op_sel_hi:[1,0,1] neg_lo:[1,0,0] neg_hi:[1,0,0]
	v_pk_add_f32 v[18:19], v[18:19], 1.0 op_sel_hi:[1,0]
	v_exp_f32_e32 v12, v12
	v_exp_f32_e32 v13, v13
	v_pk_add_f32 v[16:17], v[16:17], 1.0 op_sel_hi:[1,0]
	v_pk_add_f32 v[14:15], v[14:15], 1.0 op_sel_hi:[1,0]
	v_pk_mul_f32 v[28:29], v[28:29], v[78:79]
	v_rcp_f32_e32 v18, v18
	v_rcp_f32_e32 v19, v19
	v_rcp_f32_e32 v20, v16
	v_rcp_f32_e32 v21, v17
	v_pk_fma_f32 v[16:17], v[34:35], v[34:35], 1.0 op_sel_hi:[1,1,0] neg_lo:[1,0,0] neg_hi:[1,0,0]
	v_rcp_f32_e32 v14, v14
	v_rcp_f32_e32 v15, v15
	v_pk_mul_f32 v[28:29], v[28:29], v[36:37]
	v_sqrt_f32_e32 v36, v16
	v_sqrt_f32_e32 v37, v17
	v_pk_add_f32 v[12:13], v[12:13], 1.0 op_sel_hi:[1,0]
	v_pk_fma_f32 v[22:23], v[22:23], s[36:37], v[74:75] op_sel_hi:[1,0,1] neg_lo:[1,0,0] neg_hi:[1,0,0]
	v_pk_fma_f32 v[10:11], v[10:11], s[36:37], v[70:71] op_sel_hi:[1,0,1] neg_lo:[1,0,0] neg_hi:[1,0,0]
	v_rcp_f32_e32 v12, v12
	v_rcp_f32_e32 v13, v13
	v_pk_fma_f32 v[6:7], v[6:7], s[36:37], v[74:75] op_sel_hi:[1,0,1] neg_lo:[1,0,0] neg_hi:[1,0,0]
	v_pk_fma_f32 v[4:5], v[4:5], s[36:37], v[72:73] op_sel_hi:[1,0,1] neg_lo:[1,0,0] neg_hi:[1,0,0]
	v_exp_f32_e32 v22, v22
	v_exp_f32_e32 v23, v23
	v_pk_mul_f32 v[16:17], v[18:19], v[96:97]
	v_pk_mul_f32 v[18:19], v[20:21], v[82:83]
	v_exp_f32_e32 v10, v10
	v_exp_f32_e32 v11, v11
	v_pk_mul_f32 v[14:15], v[66:67], v[14:15]
	v_pk_fma_f32 v[8:9], v[8:9], s[36:37], v[68:69] op_sel_hi:[1,0,1] neg_lo:[1,0,0] neg_hi:[1,0,0]
	v_exp_f32_e32 v6, v6
	v_exp_f32_e32 v7, v7
	v_exp_f32_e32 v4, v4
	v_exp_f32_e32 v5, v5
	v_pk_mul_f32 v[18:19], v[18:19], v[36:37]
	v_exp_f32_e32 v36, v14
	v_exp_f32_e32 v37, v15
	v_exp_f32_e32 v8, v8
	v_exp_f32_e32 v9, v9
	v_pk_mul_f32 v[12:13], v[64:65], v[12:13]
	v_pk_add_f32 v[22:23], v[22:23], 1.0 op_sel_hi:[1,0]
	v_pk_add_f32 v[10:11], v[10:11], 1.0 op_sel_hi:[1,0]
	v_exp_f32_e32 v38, v12
	v_exp_f32_e32 v39, v13
	v_pk_add_f32 v[6:7], v[6:7], 1.0 op_sel_hi:[1,0]
	v_pk_add_f32 v[4:5], v[4:5], 1.0 op_sel_hi:[1,0]
	v_rcp_f32_e32 v22, v22
	v_rcp_f32_e32 v23, v23
	v_rcp_f32_e32 v10, v10
	v_rcp_f32_e32 v11, v11
	v_pk_fma_f32 v[14:15], v[36:37], v[36:37], 1.0 op_sel_hi:[1,1,0] neg_lo:[1,0,0] neg_hi:[1,0,0]
	v_pk_add_f32 v[8:9], v[8:9], 1.0 op_sel_hi:[1,0]
	v_rcp_f32_e32 v6, v6
	v_rcp_f32_e32 v7, v7
	v_rcp_f32_e32 v4, v4
	v_rcp_f32_e32 v5, v5
	v_sqrt_f32_e32 v14, v14
	v_sqrt_f32_e32 v15, v15
	v_rcp_f32_e32 v12, v8
	v_rcp_f32_e32 v13, v9
	v_pk_fma_f32 v[8:9], v[38:39], v[38:39], 1.0 op_sel_hi:[1,1,0] neg_lo:[1,0,0] neg_hi:[1,0,0]
	v_pk_fma_f32 v[2:3], v[2:3], s[36:37], v[70:71] op_sel_hi:[1,0,1] neg_lo:[1,0,0] neg_hi:[1,0,0]
	v_pk_fma_f32 v[0:1], v[0:1], s[36:37], v[68:69] op_sel_hi:[1,0,1] neg_lo:[1,0,0] neg_hi:[1,0,0]
	v_pk_mul_f32 v[22:23], v[66:67], v[22:23]
	v_sqrt_f32_e32 v20, v8
	v_sqrt_f32_e32 v21, v9
	v_pk_mul_f32 v[8:9], v[10:11], v[54:55]
	v_exp_f32_e32 v2, v2
	v_exp_f32_e32 v3, v3
	v_pk_mul_f32 v[6:7], v[66:67], v[6:7]
	v_exp_f32_e32 v0, v0
	v_exp_f32_e32 v1, v1
	v_pk_mul_f32 v[4:5], v[64:65], v[4:5]
	v_exp_f32_e32 v22, v22
	v_exp_f32_e32 v23, v23
	v_pk_mul_f32 v[8:9], v[8:9], v[14:15]
	v_pk_mul_f32 v[10:11], v[12:13], v[52:53]
	v_exp_f32_e32 v12, v6
	v_exp_f32_e32 v13, v7
	v_exp_f32_e32 v14, v4
	v_exp_f32_e32 v15, v5
	v_pk_add_f32 v[2:3], v[2:3], 1.0 op_sel_hi:[1,0]
	v_pk_add_f32 v[0:1], v[0:1], 1.0 op_sel_hi:[1,0]
	v_pk_fma_f32 v[32:33], v[22:23], v[22:23], 1.0 op_sel_hi:[1,1,0] neg_lo:[1,0,0] neg_hi:[1,0,0]
	v_rcp_f32_e32 v2, v2
	v_rcp_f32_e32 v3, v3
	v_pk_fma_f32 v[6:7], v[12:13], v[12:13], 1.0 op_sel_hi:[1,1,0] neg_lo:[1,0,0] neg_hi:[1,0,0]
	v_rcp_f32_e32 v0, v0
	v_rcp_f32_e32 v1, v1
	v_pk_fma_f32 v[4:5], v[14:15], v[14:15], 1.0 op_sel_hi:[1,1,0] neg_lo:[1,0,0] neg_hi:[1,0,0]
	v_sqrt_f32_e32 v32, v32
	v_sqrt_f32_e32 v33, v33
	v_sqrt_f32_e32 v6, v6
	v_sqrt_f32_e32 v7, v7
	v_sqrt_f32_e32 v4, v4
	v_sqrt_f32_e32 v5, v5
	v_pk_mul_f32 v[2:3], v[2:3], v[100:101]
	v_pk_mul_f32 v[0:1], v[0:1], v[98:99]
	v_mov_b32_e32 v78, v26
	v_mov_b32_e32 v79, v31
	v_pk_mul_f32 v[16:17], v[16:17], v[32:33]
	v_mov_b32_e32 v80, v34
	v_mov_b32_e32 v81, v22
	v_pk_mul_f32 v[10:11], v[10:11], v[20:21]
	v_mov_b32_e32 v34, v37
	v_mov_b32_e32 v22, v38
	v_pk_mul_f32 v[20:21], v[2:3], v[6:7]
	v_pk_mul_f32 v[32:33], v[0:1], v[4:5]
	s_nop 1
v_fmac_f32_dpp v28, v28, v30 row_shl:1 row_mask:0xf bank_mask:0xf
v_fmac_f32_dpp v29, v29, v79 row_shl:1 row_mask:0xf bank_mask:0xf
v_fmac_f32_dpp v24, v24, v78 row_shl:1 row_mask:0xf bank_mask:0xf
v_fmac_f32_dpp v25, v25, v27 row_shl:1 row_mask:0xf bank_mask:0xf
v_mul_f32_dpp v30, v30, v30 row_shl:1 row_mask:0xf bank_mask:0xf
v_mul_f32_dpp v79, v79, v79 row_shl:1 row_mask:0xf bank_mask:0xf
v_mul_f32_dpp v78, v78, v78 row_shl:1 row_mask:0xf bank_mask:0xf
v_mul_f32_dpp v27, v27, v27 row_shl:1 row_mask:0xf bank_mask:0xf
v_fmac_f32_dpp v28, v28, v30 row_shl:2 row_mask:0xf bank_mask:0xf
v_fmac_f32_dpp v29, v29, v79 row_shl:2 row_mask:0xf bank_mask:0xf
v_fmac_f32_dpp v24, v24, v78 row_shl:2 row_mask:0xf bank_mask:0xf
v_fmac_f32_dpp v25, v25, v27 row_shl:2 row_mask:0xf bank_mask:0xf
v_mul_f32_dpp v30, v30, v30 row_shl:2 row_mask:0xf bank_mask:0xf
v_mul_f32_dpp v79, v79, v79 row_shl:2 row_mask:0xf bank_mask:0xf
v_mul_f32_dpp v78, v78, v78 row_shl:2 row_mask:0xf bank_mask:0xf
v_mul_f32_dpp v27, v27, v27 row_shl:2 row_mask:0xf bank_mask:0xf
v_fmac_f32_dpp v28, v28, v30 row_shl:4 row_mask:0xf bank_mask:0xf
v_fmac_f32_dpp v29, v29, v79 row_shl:4 row_mask:0xf bank_mask:0xf
v_fmac_f32_dpp v24, v24, v78 row_shl:4 row_mask:0xf bank_mask:0xf
v_fmac_f32_dpp v25, v25, v27 row_shl:4 row_mask:0xf bank_mask:0xf
v_mul_f32_dpp v30, v30, v30 row_shl:4 row_mask:0xf bank_mask:0xf
v_mul_f32_dpp v79, v79, v79 row_shl:4 row_mask:0xf bank_mask:0xf
v_mul_f32_dpp v78, v78, v78 row_shl:4 row_mask:0xf bank_mask:0xf
v_mul_f32_dpp v27, v27, v27 row_shl:4 row_mask:0xf bank_mask:0xf
v_fmac_f32_dpp v28, v28, v30 row_shl:8 row_mask:0xf bank_mask:0xf
v_fmac_f32_dpp v29, v29, v79 row_shl:8 row_mask:0xf bank_mask:0xf
v_fmac_f32_dpp v24, v24, v78 row_shl:8 row_mask:0xf bank_mask:0xf
v_fmac_f32_dpp v25, v25, v27 row_shl:8 row_mask:0xf bank_mask:0xf
v_mul_f32_dpp v30, v30, v30 row_shl:8 row_mask:0xf bank_mask:0xf
v_mul_f32_dpp v79, v79, v79 row_shl:8 row_mask:0xf bank_mask:0xf
v_mul_f32_dpp v78, v78, v78 row_shl:8 row_mask:0xf bank_mask:0xf
v_mul_f32_dpp v27, v27, v27 row_shl:8 row_mask:0xf bank_mask:0xf

	s_nop 1
v_fmac_f32_dpp v18, v18, v80 row_shl:1 row_mask:0xf bank_mask:0xf
v_fmac_f32_dpp v19, v19, v35 row_shl:1 row_mask:0xf bank_mask:0xf
v_fmac_f32_dpp v16, v16, v81 row_shl:1 row_mask:0xf bank_mask:0xf
v_fmac_f32_dpp v17, v17, v23 row_shl:1 row_mask:0xf bank_mask:0xf
v_mul_f32_dpp v80, v80, v80 row_shl:1 row_mask:0xf bank_mask:0xf
v_mul_f32_dpp v35, v35, v35 row_shl:1 row_mask:0xf bank_mask:0xf
v_mul_f32_dpp v81, v81, v81 row_shl:1 row_mask:0xf bank_mask:0xf
v_mul_f32_dpp v23, v23, v23 row_shl:1 row_mask:0xf bank_mask:0xf
v_fmac_f32_dpp v18, v18, v80 row_shl:2 row_mask:0xf bank_mask:0xf
v_fmac_f32_dpp v19, v19, v35 row_shl:2 row_mask:0xf bank_mask:0xf
v_fmac_f32_dpp v16, v16, v81 row_shl:2 row_mask:0xf bank_mask:0xf
v_fmac_f32_dpp v17, v17, v23 row_shl:2 row_mask:0xf bank_mask:0xf
v_mul_f32_dpp v80, v80, v80 row_shl:2 row_mask:0xf bank_mask:0xf
v_mul_f32_dpp v35, v35, v35 row_shl:2 row_mask:0xf bank_mask:0xf
v_mul_f32_dpp v81, v81, v81 row_shl:2 row_mask:0xf bank_mask:0xf
v_mul_f32_dpp v23, v23, v23 row_shl:2 row_mask:0xf bank_mask:0xf
v_fmac_f32_dpp v18, v18, v80 row_shl:4 row_mask:0xf bank_mask:0xf
v_fmac_f32_dpp v19, v19, v35 row_shl:4 row_mask:0xf bank_mask:0xf
v_fmac_f32_dpp v16, v16, v81 row_shl:4 row_mask:0xf bank_mask:0xf
v_fmac_f32_dpp v17, v17, v23 row_shl:4 row_mask:0xf bank_mask:0xf
v_mul_f32_dpp v80, v80, v80 row_shl:4 row_mask:0xf bank_mask:0xf
v_mul_f32_dpp v35, v35, v35 row_shl:4 row_mask:0xf bank_mask:0xf
v_mul_f32_dpp v81, v81, v81 row_shl:4 row_mask:0xf bank_mask:0xf
v_mul_f32_dpp v23, v23, v23 row_shl:4 row_mask:0xf bank_mask:0xf
v_fmac_f32_dpp v18, v18, v80 row_shl:8 row_mask:0xf bank_mask:0xf
v_fmac_f32_dpp v19, v19, v35 row_shl:8 row_mask:0xf bank_mask:0xf
v_fmac_f32_dpp v16, v16, v81 row_shl:8 row_mask:0xf bank_mask:0xf
v_fmac_f32_dpp v17, v17, v23 row_shl:8 row_mask:0xf bank_mask:0xf
v_mul_f32_dpp v80, v80, v80 row_shl:8 row_mask:0xf bank_mask:0xf
v_mul_f32_dpp v35, v35, v35 row_shl:8 row_mask:0xf bank_mask:0xf
v_mul_f32_dpp v81, v81, v81 row_shl:8 row_mask:0xf bank_mask:0xf
v_mul_f32_dpp v23, v23, v23 row_shl:8 row_mask:0xf bank_mask:0xf

	s_nop 1
v_fmac_f32_dpp v10, v10, v22 row_shl:1 row_mask:0xf bank_mask:0xf
v_fmac_f32_dpp v11, v11, v39 row_shl:1 row_mask:0xf bank_mask:0xf
v_fmac_f32_dpp v8, v8, v36 row_shl:1 row_mask:0xf bank_mask:0xf
v_fmac_f32_dpp v9, v9, v34 row_shl:1 row_mask:0xf bank_mask:0xf
v_mul_f32_dpp v22, v22, v22 row_shl:1 row_mask:0xf bank_mask:0xf
v_mul_f32_dpp v39, v39, v39 row_shl:1 row_mask:0xf bank_mask:0xf
v_mul_f32_dpp v36, v36, v36 row_shl:1 row_mask:0xf bank_mask:0xf
v_mul_f32_dpp v34, v34, v34 row_shl:1 row_mask:0xf bank_mask:0xf
v_fmac_f32_dpp v10, v10, v22 row_shl:2 row_mask:0xf bank_mask:0xf
v_fmac_f32_dpp v11, v11, v39 row_shl:2 row_mask:0xf bank_mask:0xf
v_fmac_f32_dpp v8, v8, v36 row_shl:2 row_mask:0xf bank_mask:0xf
v_fmac_f32_dpp v9, v9, v34 row_shl:2 row_mask:0xf bank_mask:0xf
v_mul_f32_dpp v22, v22, v22 row_shl:2 row_mask:0xf bank_mask:0xf
v_mul_f32_dpp v39, v39, v39 row_shl:2 row_mask:0xf bank_mask:0xf
v_mul_f32_dpp v36, v36, v36 row_shl:2 row_mask:0xf bank_mask:0xf
v_mul_f32_dpp v34, v34, v34 row_shl:2 row_mask:0xf bank_mask:0xf
v_fmac_f32_dpp v10, v10, v22 row_shl:4 row_mask:0xf bank_mask:0xf
v_fmac_f32_dpp v11, v11, v39 row_shl:4 row_mask:0xf bank_mask:0xf
v_fmac_f32_dpp v8, v8, v36 row_shl:4 row_mask:0xf bank_mask:0xf
v_fmac_f32_dpp v9, v9, v34 row_shl:4 row_mask:0xf bank_mask:0xf
v_mul_f32_dpp v22, v22, v22 row_shl:4 row_mask:0xf bank_mask:0xf
v_mul_f32_dpp v39, v39, v39 row_shl:4 row_mask:0xf bank_mask:0xf
v_mul_f32_dpp v36, v36, v36 row_shl:4 row_mask:0xf bank_mask:0xf
v_mul_f32_dpp v34, v34, v34 row_shl:4 row_mask:0xf bank_mask:0xf
v_fmac_f32_dpp v10, v10, v22 row_shl:8 row_mask:0xf bank_mask:0xf
v_fmac_f32_dpp v11, v11, v39 row_shl:8 row_mask:0xf bank_mask:0xf
v_fmac_f32_dpp v8, v8, v36 row_shl:8 row_mask:0xf bank_mask:0xf
v_fmac_f32_dpp v9, v9, v34 row_shl:8 row_mask:0xf bank_mask:0xf
v_mul_f32_dpp v22, v22, v22 row_shl:8 row_mask:0xf bank_mask:0xf
v_mul_f32_dpp v39, v39, v39 row_shl:8 row_mask:0xf bank_mask:0xf
v_mul_f32_dpp v36, v36, v36 row_shl:8 row_mask:0xf bank_mask:0xf
v_mul_f32_dpp v34, v34, v34 row_shl:8 row_mask:0xf bank_mask:0xf

	s_nop 0
	s_nop 1
v_fmac_f32_dpp v32, v32, v14 row_shl:1 row_mask:0xf bank_mask:0xf
v_fmac_f32_dpp v33, v33, v15 row_shl:1 row_mask:0xf bank_mask:0xf
v_fmac_f32_dpp v20, v20, v12 row_shl:1 row_mask:0xf bank_mask:0xf
v_fmac_f32_dpp v21, v21, v13 row_shl:1 row_mask:0xf bank_mask:0xf
v_mul_f32_dpp v14, v14, v14 row_shl:1 row_mask:0xf bank_mask:0xf
v_mul_f32_dpp v15, v15, v15 row_shl:1 row_mask:0xf bank_mask:0xf
v_mul_f32_dpp v12, v12, v12 row_shl:1 row_mask:0xf bank_mask:0xf
v_mul_f32_dpp v13, v13, v13 row_shl:1 row_mask:0xf bank_mask:0xf
v_fmac_f32_dpp v32, v32, v14 row_shl:2 row_mask:0xf bank_mask:0xf
v_fmac_f32_dpp v33, v33, v15 row_shl:2 row_mask:0xf bank_mask:0xf
v_fmac_f32_dpp v20, v20, v12 row_shl:2 row_mask:0xf bank_mask:0xf
v_fmac_f32_dpp v21, v21, v13 row_shl:2 row_mask:0xf bank_mask:0xf
v_mul_f32_dpp v14, v14, v14 row_shl:2 row_mask:0xf bank_mask:0xf
v_mul_f32_dpp v15, v15, v15 row_shl:2 row_mask:0xf bank_mask:0xf
v_mul_f32_dpp v12, v12, v12 row_shl:2 row_mask:0xf bank_mask:0xf
v_mul_f32_dpp v13, v13, v13 row_shl:2 row_mask:0xf bank_mask:0xf
v_fmac_f32_dpp v32, v32, v14 row_shl:4 row_mask:0xf bank_mask:0xf
v_fmac_f32_dpp v33, v33, v15 row_shl:4 row_mask:0xf bank_mask:0xf
v_fmac_f32_dpp v20, v20, v12 row_shl:4 row_mask:0xf bank_mask:0xf
v_fmac_f32_dpp v21, v21, v13 row_shl:4 row_mask:0xf bank_mask:0xf
v_mul_f32_dpp v14, v14, v14 row_shl:4 row_mask:0xf bank_mask:0xf
v_mul_f32_dpp v15, v15, v15 row_shl:4 row_mask:0xf bank_mask:0xf
v_mul_f32_dpp v12, v12, v12 row_shl:4 row_mask:0xf bank_mask:0xf
v_mul_f32_dpp v13, v13, v13 row_shl:4 row_mask:0xf bank_mask:0xf
v_fmac_f32_dpp v32, v32, v14 row_shl:8 row_mask:0xf bank_mask:0xf
v_fmac_f32_dpp v33, v33, v15 row_shl:8 row_mask:0xf bank_mask:0xf
v_fmac_f32_dpp v20, v20, v12 row_shl:8 row_mask:0xf bank_mask:0xf
v_fmac_f32_dpp v21, v21, v13 row_shl:8 row_mask:0xf bank_mask:0xf
v_mul_f32_dpp v14, v14, v14 row_shl:8 row_mask:0xf bank_mask:0xf
v_mul_f32_dpp v15, v15, v15 row_shl:8 row_mask:0xf bank_mask:0xf
v_mul_f32_dpp v12, v12, v12 row_shl:8 row_mask:0xf bank_mask:0xf
v_mul_f32_dpp v13, v13, v13 row_shl:8 row_mask:0xf bank_mask:0xf

	ds_bpermute_b32 v1, v144, v14
	v_fmac_f32_e32 v32, 0, v14
	v_fmac_f32_e32 v33, 0, v15
	v_fmac_f32_e32 v20, 0, v12
	v_fmac_f32_e32 v21, 0, v13
	ds_bpermute_b32 v0, v144, v32
	ds_bpermute_b32 v2, v144, v33
	ds_bpermute_b32 v3, v144, v15
	ds_bpermute_b32 v4, v144, v20
	ds_bpermute_b32 v5, v144, v12
	ds_bpermute_b32 v6, v144, v21
	ds_bpermute_b32 v7, v144, v13
	s_waitcnt lgkmcnt(0)
	v_fmac_f32_e32 v10, v22, v0
	v_mul_f32_e32 v22, v22, v1
	v_fmac_f32_e32 v11, v39, v2
	v_mul_f32_e32 v26, v39, v3
	v_fmac_f32_e32 v8, v36, v4
	v_mul_f32_e32 v31, v36, v5
	v_fmac_f32_e32 v9, v34, v6
	v_mul_f32_e32 v34, v34, v7
	ds_bpermute_b32 v0, v144, v10
	ds_bpermute_b32 v1, v144, v22
	ds_bpermute_b32 v2, v144, v11
	ds_bpermute_b32 v3, v144, v26
	ds_bpermute_b32 v4, v144, v8
	ds_bpermute_b32 v5, v144, v31
	ds_bpermute_b32 v6, v144, v9
	ds_bpermute_b32 v7, v144, v34
	s_waitcnt lgkmcnt(0)
	v_fmac_f32_e32 v18, v80, v0
	v_mul_f32_e32 v36, v80, v1
	v_fmac_f32_e32 v19, v35, v2
	v_mul_f32_e32 v35, v35, v3
	v_fmac_f32_e32 v16, v81, v4
	v_mul_f32_e32 v37, v81, v5
	v_fmac_f32_e32 v17, v23, v6
	v_mul_f32_e32 v23, v23, v7
	ds_bpermute_b32 v0, v144, v18
	ds_bpermute_b32 v1, v144, v36
	ds_bpermute_b32 v2, v144, v19
	ds_bpermute_b32 v3, v144, v35
	ds_bpermute_b32 v4, v144, v16
	ds_bpermute_b32 v5, v144, v37
	ds_bpermute_b32 v6, v144, v17
	ds_bpermute_b32 v7, v144, v23
	s_waitcnt lgkmcnt(0)
	v_fmac_f32_e32 v28, v30, v0
	v_mul_f32_e32 v30, v30, v1
	v_fmac_f32_e32 v29, v79, v2
	v_mul_f32_e32 v38, v79, v3
	v_fmac_f32_e32 v24, v78, v4
	v_mul_f32_e32 v39, v78, v5
	v_fmac_f32_e32 v25, v27, v6
	v_mul_f32_e32 v27, v27, v7
	ds_bpermute_b32 v1, v144, v28
	ds_bpermute_b32 v0, v144, v30
	ds_bpermute_b32 v3, v144, v29
	ds_bpermute_b32 v2, v144, v38
	ds_bpermute_b32 v5, v144, v24
	ds_bpermute_b32 v4, v144, v39
	ds_bpermute_b32 v7, v144, v25
	ds_bpermute_b32 v6, v144, v27
	s_and_saveexec_b64 s[10:11], s[12:13]
	s_cbranch_execz .LBB0_445
	s_or_b32 s4, s47, 1
	s_mul_hi_i32 s5, s4, 0x84
	s_mulk_i32 s4, 0x84
	s_add_u32 s4, s4, s49
	s_addc_u32 s5, s5, 0
	s_mulk_i32 s5, 0x2800
	s_mul_hi_u32 s12, s4, 0x2800
	s_add_i32 s12, s12, s5
	s_mulk_i32 s4, 0x2800
	s_add_u32 s4, s77, s4
	s_addc_u32 s5, s78, s12
	v_lshl_add_u64 v[52:53], v[176:177], 3, s[4:5]
	s_waitcnt lgkmcnt(0)
	flat_store_dwordx4 v[52:53], v[0:3]
	flat_store_dwordx4 v[52:53], v[4:7] offset:16
	s_or_b64 exec, exec, s[10:11]
	s_and_b64 vcc, exec, s[14:15]
	s_cbranch_vccnz .LBB0_447
	s_branch .LBB0_446

.LBB0_446:
	s_waitcnt lgkmcnt(0)
	v_lshlrev_b32_e32 v0, 16, v180
	v_and_b32_e32 v1, 0xffff0000, v180
	v_add_f32_e32 v4, v62, v28
	v_add_f32_e32 v5, v63, v29
	v_mul_f32_e32 v4, v4, v0
	v_mul_f32_e32 v5, v5, v1
	v_lshlrev_b32_e32 v2, 16, v181
	v_and_b32_e32 v3, 0xffff0000, v181
	v_cvt_pk_bf16_f32 v4, v4, v5
	v_add_f32_e32 v5, v60, v24
	v_add_f32_e32 v6, v61, v25
	v_mul_f32_e32 v5, v5, v2
	v_mul_f32_e32 v6, v6, v3
	v_cvt_pk_bf16_f32 v5, v5, v6
	v_mul_f32_e32 v6, v56, v0
	v_mul_f32_e32 v7, v57, v1
	v_mul_f32_e32 v0, v30, v0
	v_mul_f32_e32 v1, v38, v1
	v_cvt_pk_bf16_f32 v6, v6, v7
	v_mul_f32_e32 v7, v58, v2
	v_mul_f32_e32 v24, v59, v3
	v_cvt_pk_bf16_f32 v0, v0, v1
	v_mul_f32_e32 v1, v39, v2
	v_mul_f32_e32 v2, v27, v3
	v_cvt_pk_bf16_f32 v7, v7, v24
	v_cvt_pk_bf16_f32 v1, v1, v2
	v_lshlrev_b32_e32 v2, 16, v178
	v_and_b32_e32 v3, 0xffff0000, v178
	v_lshlrev_b32_e32 v24, 16, v179
	v_and_b32_e32 v25, 0xffff0000, v179
	v_add_f32_e32 v18, v50, v18
	v_add_f32_e32 v19, v51, v19
	v_add_f32_e32 v16, v48, v16
	v_add_f32_e32 v17, v49, v17
	v_mul_f32_e32 v18, v18, v2
	v_mul_f32_e32 v19, v19, v3
	v_mul_f32_e32 v16, v16, v24
	v_mul_f32_e32 v17, v17, v25
	v_cvt_pk_bf16_f32 v18, v18, v19
	v_cvt_pk_bf16_f32 v16, v16, v17
	v_mul_f32_e32 v17, v92, v2
	v_mul_f32_e32 v19, v93, v3
	v_mul_f32_e32 v2, v36, v2
	v_mul_f32_e32 v3, v35, v3
	v_cmp_lt_i32_e32 vcc, v111, v116
	v_cvt_pk_bf16_f32 v17, v17, v19
	v_mul_f32_e32 v19, v94, v24
	v_cvt_pk_bf16_f32 v2, v2, v3
	v_mul_f32_e32 v3, v37, v24
	v_mul_f32_e32 v23, v23, v25
	v_cndmask_b32_e64 v29, v0, v2, s[8:9]
	v_cndmask_b32_e64 v30, v2, v0, s[8:9]
	v_cndmask_b32_e32 v0, v214, v111, vcc
	v_mul_f32_e32 v27, v95, v25
	v_cvt_pk_bf16_f32 v19, v19, v27
	v_cvt_pk_bf16_f32 v3, v3, v23
	v_cndmask_b32_e64 v23, v5, v16, s[8:9]
	v_cndmask_b32_e64 v24, v4, v18, s[8:9]
	v_cndmask_b32_e64 v25, v7, v19, s[8:9]
	v_cndmask_b32_e64 v28, v1, v3, s[8:9]
	v_lshlrev_b32_e32 v36, 2, v0
	v_cndmask_b32_e64 v27, v6, v17, s[8:9]
	v_cndmask_b32_e64 v5, v16, v5, s[8:9]
	v_cndmask_b32_e64 v16, v17, v6, s[8:9]
	v_cndmask_b32_e64 v17, v19, v7, s[8:9]
	v_cndmask_b32_e64 v35, v3, v1, s[8:9]
	ds_bpermute_b32 v0, v36, v24
	ds_bpermute_b32 v1, v36, v23
	ds_bpermute_b32 v19, v36, v25
	ds_bpermute_b32 v24, v36, v28
	v_cndmask_b32_e64 v4, v18, v4, s[8:9]
	ds_bpermute_b32 v18, v36, v27
	ds_bpermute_b32 v23, v36, v29
	v_add_u32_e32 v52, 0x80, v110
	s_waitcnt lgkmcnt(0)
	v_cndmask_b32_e64 v3, v5, v1, s[8:9]
	v_cndmask_b32_e64 v1, v1, v5, s[8:9]
	v_cndmask_b32_e64 v7, v17, v19, s[8:9]
	v_cndmask_b32_e64 v5, v19, v17, s[8:9]
	v_cndmask_b32_e64 v19, v35, v24, s[8:9]
	v_cndmask_b32_e64 v17, v24, v35, s[8:9]
	v_mov_b64_e32 v[24:25], s[24:25]
	v_mad_i64_i32 v[28:29], s[4:5], v52, s88, v[24:25]
	v_cndmask_b32_e64 v2, v4, v0, s[8:9]
	v_cndmask_b32_e64 v0, v0, v4, s[8:9]
	v_cndmask_b32_e64 v6, v16, v18, s[8:9]
	v_cndmask_b32_e64 v4, v18, v16, s[8:9]
	v_cndmask_b32_e64 v18, v30, v23, s[8:9]
	v_cndmask_b32_e64 v16, v23, v30, s[8:9]
	v_ashrrev_i32_e32 v23, 31, v52
	v_lshl_add_u64 v[28:29], v[28:29], 0, v[76:77]
	v_cmp_gt_i32_e32 vcc, s85, v52
	flat_store_dwordx4 v[28:29], v[0:3] offset:2560
	flat_store_dwordx4 v[28:29], v[4:7]
	v_mov_b32_e32 v27, s80
	v_add_u32_e32 v0, 0xffff8080, v110
	v_cndmask_b32_e32 v2, 0, v23, vcc
	v_mov_b32_e32 v23, s82
	v_mov_b32_e32 v28, s81
	v_mov_b32_e32 v29, s79
	v_cndmask_b32_e32 v3, v0, v52, vcc
	v_cndmask_b32_e32 v1, v23, v27, vcc
	v_cndmask_b32_e32 v0, v28, v29, vcc
	v_mad_u64_u32 v[0:1], s[4:5], v3, s3, v[0:1]
	v_mad_i32_i24 v1, v2, s3, v1
	v_lshl_add_u64 v[0:1], v[0:1], 0, v[76:77]
	flat_store_dwordx4 v[0:1], v[16:19]
	v_lshlrev_b32_e32 v0, 16, v174
	v_and_b32_e32 v1, 0xffff0000, v174
	v_add_f32_e32 v4, v42, v10
	v_add_f32_e32 v5, v43, v11
	v_mul_f32_e32 v4, v4, v0
	v_mul_f32_e32 v5, v5, v1
	v_lshlrev_b32_e32 v2, 16, v175
	v_and_b32_e32 v3, 0xffff0000, v175
	v_cvt_pk_bf16_f32 v4, v4, v5
	v_add_f32_e32 v5, v40, v8
	v_add_f32_e32 v6, v41, v9
	v_mul_f32_e32 v5, v5, v2
	v_mul_f32_e32 v6, v6, v3
	v_cvt_pk_bf16_f32 v5, v5, v6
	v_mul_f32_e32 v6, v86, v0
	v_mul_f32_e32 v7, v88, v1
	v_mul_f32_e32 v0, v22, v0
	v_mul_f32_e32 v1, v26, v1
	v_cvt_pk_bf16_f32 v6, v6, v7
	v_mul_f32_e32 v7, v90, v2
	v_cvt_pk_bf16_f32 v0, v0, v1
	v_mul_f32_e32 v1, v31, v2
	v_mul_f32_e32 v2, v34, v3
	v_mul_f32_e32 v8, v91, v3
	v_cvt_pk_bf16_f32 v1, v1, v2
	v_lshlrev_b32_e32 v2, 16, v172
	v_and_b32_e32 v3, 0xffff0000, v172
	v_add_f32_e32 v10, v46, v32
	v_add_f32_e32 v11, v47, v33
	v_mul_f32_e32 v10, v10, v2
	v_mul_f32_e32 v11, v11, v3
	v_cvt_pk_bf16_f32 v7, v7, v8
	v_lshlrev_b32_e32 v8, 16, v173
	v_and_b32_e32 v9, 0xffff0000, v173
	v_cvt_pk_bf16_f32 v10, v10, v11
	v_add_f32_e32 v11, v44, v20
	v_add_f32_e32 v16, v45, v21
	v_mul_f32_e32 v11, v11, v8
	v_mul_f32_e32 v16, v16, v9
	v_cvt_pk_bf16_f32 v11, v11, v16
	v_mul_f32_e32 v16, v84, v2
	v_mul_f32_e32 v17, v85, v3
	v_mul_f32_e32 v2, v14, v2
	v_mul_f32_e32 v3, v15, v3
	v_cvt_pk_bf16_f32 v16, v16, v17
	v_mul_f32_e32 v17, v87, v8
	v_mul_f32_e32 v18, v89, v9
	v_cvt_pk_bf16_f32 v2, v2, v3
	v_mul_f32_e32 v3, v12, v8
	v_mul_f32_e32 v8, v13, v9
	v_cvt_pk_bf16_f32 v17, v17, v18
	v_cvt_pk_bf16_f32 v3, v3, v8
	v_cndmask_b32_e64 v8, v5, v11, s[8:9]
	v_cndmask_b32_e64 v9, v4, v10, s[8:9]
	v_cndmask_b32_e64 v12, v7, v17, s[8:9]
	v_cndmask_b32_e64 v13, v6, v16, s[8:9]
	v_cndmask_b32_e64 v15, v1, v3, s[8:9]
	v_cndmask_b32_e64 v18, v0, v2, s[8:9]
	v_cndmask_b32_e64 v4, v10, v4, s[8:9]
	v_cndmask_b32_e64 v5, v11, v5, s[8:9]
	v_cndmask_b32_e64 v10, v16, v6, s[8:9]
	v_cndmask_b32_e64 v11, v17, v7, s[8:9]
	v_cndmask_b32_e64 v16, v2, v0, s[8:9]
	v_cndmask_b32_e64 v17, v3, v1, s[8:9]
	ds_bpermute_b32 v0, v36, v9
	ds_bpermute_b32 v1, v36, v8
	ds_bpermute_b32 v8, v36, v13
	ds_bpermute_b32 v9, v36, v12
	ds_bpermute_b32 v12, v36, v18
	ds_bpermute_b32 v13, v36, v15
	v_add_u32_e32 v14, 0xa0, v110
	s_waitcnt lgkmcnt(0)
	v_cndmask_b32_e64 v3, v5, v1, s[8:9]
	v_cndmask_b32_e64 v2, v4, v0, s[8:9]
	v_cndmask_b32_e64 v1, v1, v5, s[8:9]
	v_cndmask_b32_e64 v0, v0, v4, s[8:9]
	v_cndmask_b32_e64 v7, v11, v9, s[8:9]
	v_cndmask_b32_e64 v6, v10, v8, s[8:9]
	v_cndmask_b32_e64 v5, v9, v11, s[8:9]
	v_cndmask_b32_e64 v4, v8, v10, s[8:9]
	v_cndmask_b32_e64 v11, v17, v13, s[8:9]
	v_cndmask_b32_e64 v10, v16, v12, s[8:9]
	v_cndmask_b32_e64 v9, v13, v17, s[8:9]
	v_cndmask_b32_e64 v8, v12, v16, s[8:9]
	v_mad_i64_i32 v[12:13], s[4:5], v14, s88, v[24:25]
	v_lshl_add_u64 v[12:13], v[12:13], 0, v[76:77]
	flat_store_dwordx4 v[12:13], v[0:3] offset:2560
	flat_store_dwordx4 v[12:13], v[4:7]
	v_cmp_gt_i32_e32 vcc, s85, v14
	v_add_u32_e32 v0, 0xffff80a0, v110
	v_ashrrev_i32_e32 v15, 31, v14
	v_cndmask_b32_e32 v3, v0, v14, vcc
	v_cndmask_b32_e32 v1, v23, v27, vcc
	v_cndmask_b32_e32 v0, v28, v29, vcc
	v_cndmask_b32_e32 v2, 0, v15, vcc
	v_mad_u64_u32 v[0:1], s[4:5], v3, s3, v[0:1]
	v_mad_i32_i24 v1, v2, s3, v1
	v_lshl_add_u64 v[0:1], v[0:1], 0, v[76:77]
	flat_store_dwordx4 v[0:1], v[8:11]
.LBB0_447:
	s_and_b64 vcc, exec, s[6:7]
	s_mov_b64 s[6:7], -1
	s_cbranch_vccnz .LBB0_424
	s_lshl_b32 s4, s46, 6
	s_or_b32 s4, s4, s69
	s_waitcnt lgkmcnt(0)
	v_add_u32_e32 v0, s4, v216
	s_lshl_b32 s4, s89, 8
	s_add_i32 s4, s4, s68
	v_ashrrev_i32_e32 v1, 31, v0
	v_add_u32_e32 v12, s4, v215
	v_mov_b64_e32 v[2:3], s[16:17]
	v_mad_i64_i32 v[4:5], s[4:5], v12, s3, v[2:3]
	v_lshlrev_b64 v[0:1], 1, v[0:1]
	v_add_u32_e32 v6, 16, v12
	v_add_u32_e32 v8, 32, v12
	v_add_u32_e32 v10, 48, v12
	v_lshl_add_u64 v[4:5], v[4:5], 0, v[0:1]
	v_mad_i64_i32 v[6:7], s[4:5], v6, s3, v[2:3]
	v_mad_i64_i32 v[8:9], s[4:5], v8, s3, v[2:3]
	v_mad_i64_i32 v[10:11], s[4:5], v10, s3, v[2:3]
	v_lshl_add_u64 v[6:7], v[6:7], 0, v[0:1]
	v_lshl_add_u64 v[8:9], v[8:9], 0, v[0:1]
	v_lshl_add_u64 v[10:11], v[10:11], 0, v[0:1]
	flat_load_dwordx2 v[188:189], v[4:5]
	flat_load_dwordx2 v[186:187], v[6:7]
	flat_load_dwordx2 v[184:185], v[8:9]
	flat_load_dwordx2 v[182:183], v[10:11]
	v_add_u32_e32 v4, 0x80, v12
	v_mad_i64_i32 v[4:5], s[4:5], v4, s3, v[2:3]
	v_add_u32_e32 v6, 0x90, v12
	v_add_u32_e32 v8, 0xa0, v12
	v_add_u32_e32 v10, 0xb0, v12
	v_lshl_add_u64 v[4:5], v[4:5], 0, v[0:1]
	v_mad_i64_i32 v[6:7], s[4:5], v6, s3, v[2:3]
	v_mad_i64_i32 v[8:9], s[4:5], v8, s3, v[2:3]
	v_mad_i64_i32 v[2:3], s[4:5], v10, s3, v[2:3]
	v_lshl_add_u64 v[6:7], v[6:7], 0, v[0:1]
	v_lshl_add_u64 v[8:9], v[8:9], 0, v[0:1]
	v_lshl_add_u64 v[0:1], v[2:3], 0, v[0:1]
	flat_load_dwordx2 v[170:171], v[4:5]
	flat_load_dwordx2 v[168:169], v[6:7]
	flat_load_dwordx2 v[166:167], v[8:9]
	flat_load_dwordx2 v[164:165], v[0:1]
	s_andn2_b64 vcc, exec, s[22:23]
	s_cbranch_vccnz .LBB0_423
	s_barrier
	s_branch .LBB0_423

.LBB0_501:
	v_lshl_add_u64 v[4:5], v[4:5], 0, s[8:9]
	v_add_co_u32_e32 v8, vcc, 0xa000, v4
	s_nop 1
	v_addc_co_u32_e32 v9, vcc, 0, v5, vcc
	flat_load_dwordx2 v[8:9], v[8:9]
	v_add_co_u32_e32 v10, vcc, 0xc000, v4
	ds_write_b32 v15, v7
	s_nop 0
	v_addc_co_u32_e32 v11, vcc, 0, v5, vcc
	v_add_co_u32_e32 v4, vcc, 0xf000, v4
	flat_load_dwordx2 v[10:11], v[10:11] offset:2048
	s_nop 0
	v_addc_co_u32_e32 v5, vcc, 0, v5, vcc
	s_waitcnt vmcnt(0) lgkmcnt(0)
	v_fmac_f32_e32 v9, v7, v8
	ds_write_b32 v15, v9 offset:5120
	flat_load_dwordx2 v[4:5], v[4:5]
	v_fmac_f32_e32 v11, v9, v10
	s_waitcnt vmcnt(0) lgkmcnt(0)
	v_fmac_f32_e32 v5, v11, v4
	ds_write2st64_b32 v15, v11, v5 offset0:40 offset1:60

.LBB0_503:
	v_lshl_add_u32 v7, s67, 9, v196
	v_mul_hi_u32 v4, v7, s3
	v_lshrrev_b32_e32 v6, 9, v4
	v_mad_i32_i24 v8, v6, s53, v7
	v_add_u32_e32 v4, s66, v6
	v_mad_i64_i32 v[4:5], s[4:5], v4, s54, v[0:1]
	v_ashrrev_i32_e32 v9, 31, v8
	v_lshl_add_u64 v[4:5], v[8:9], 3, v[4:5]
	v_mul_u32_u24_e32 v9, 0x5000, v6
	v_lshlrev_b32_e32 v8, 2, v8
	v_add3_u32 v15, 0, v9, v8
	v_cmp_lt_u32_e32 vcc, s55, v7
	s_and_saveexec_b64 s[4:5], vcc
	s_xor_b64 s[46:47], exec, s[4:5]
	s_cbranch_execz .LBB0_510
	v_add_co_u32_e32 v6, vcc, 0x7000, v4
	s_nop 1
	v_addc_co_u32_e32 v7, vcc, 0, v5, vcc
	v_add_co_u32_e32 v8, vcc, 0x5000, v4
	s_nop 1
	v_addc_co_u32_e32 v9, vcc, 0, v5, vcc
	v_add_co_u32_e32 v10, vcc, 0x2000, v4
	s_nop 1
	v_addc_co_u32_e32 v11, vcc, 0, v5, vcc
	flat_load_dwordx2 v[12:13], v[6:7] offset:2048
	s_nop 0
	flat_load_dwordx2 v[8:9], v[8:9]
	s_nop 0
	flat_load_dwordx2 v[10:11], v[10:11] offset:2048
	s_nop 0
	flat_load_dwordx2 v[6:7], v[4:5]
	s_andn2_b64 vcc, exec, s[24:25]
	s_waitcnt vmcnt(0) lgkmcnt(0)
	v_fmac_f32_e32 v13, 0, v12
	v_fmac_f32_e32 v9, v13, v8
	v_fmac_f32_e32 v11, v9, v10
	v_fmac_f32_e32 v7, v11, v6
	s_cbranch_vccnz .LBB0_509
	s_andn2_b64 vcc, exec, s[28:29]
	s_movk_i32 s4, 0x83
	s_cbranch_vccnz .LBB0_507
.LBB0_506:
	v_mad_u64_u32 v[8:9], s[40:41], s4, v14, v[4:5]
	flat_load_dwordx2 v[8:9], v[8:9]
	s_add_i32 s5, s4, -1
	s_add_i32 s33, s4, -2
	s_add_i32 s44, s4, -3
	s_add_i32 s45, s4, -4
	s_add_i32 s68, s4, -5
	s_add_i32 s69, s4, -6
	s_add_i32 s70, s4, -7
	v_mad_u64_u32 v[10:11], s[40:41], s5, v14, v[4:5]
	v_mad_u64_u32 v[12:13], s[40:41], s33, v14, v[4:5]
	v_mad_u64_u32 v[16:17], s[40:41], s44, v14, v[4:5]
	v_mad_u64_u32 v[18:19], s[40:41], s45, v14, v[4:5]
	v_mad_u64_u32 v[20:21], s[40:41], s68, v14, v[4:5]
	v_mad_u64_u32 v[22:23], s[40:41], s69, v14, v[4:5]
	v_mad_u64_u32 v[24:25], s[40:41], s70, v14, v[4:5]
	flat_load_dwordx2 v[10:11], v[10:11]
	s_nop 0
	flat_load_dwordx2 v[12:13], v[12:13]
	s_nop 0
	flat_load_dwordx2 v[16:17], v[16:17]
	s_nop 0
	flat_load_dwordx2 v[18:19], v[18:19]
	s_nop 0
	flat_load_dwordx2 v[20:21], v[20:21]
	s_nop 0
	flat_load_dwordx2 v[22:23], v[22:23]
	s_add_i32 s4, s4, -8
	s_add_i32 s5, s65, s4
	s_cmpk_eq_i32 s5, 0x83
	s_waitcnt vmcnt(0) lgkmcnt(0)
	v_fmac_f32_e32 v9, v7, v8
	flat_load_dwordx2 v[6:7], v[24:25]
	v_fmac_f32_e32 v11, v9, v10
	v_fmac_f32_e32 v13, v11, v12
	v_fmac_f32_e32 v17, v13, v16
	v_fmac_f32_e32 v19, v17, v18
	v_fmac_f32_e32 v21, v19, v20
	v_fmac_f32_e32 v23, v21, v22
	s_waitcnt vmcnt(0) lgkmcnt(0)
	v_fmac_f32_e32 v7, v23, v6
	s_cbranch_scc0 .LBB0_506

.LBB0_508:
	v_mov_b32_e32 v8, v7
	v_mad_u64_u32 v[6:7], s[40:41], s4, v14, v[4:5]
	flat_load_dwordx2 v[6:7], v[6:7]
	s_add_i32 s4, s4, -1
	s_add_i32 s5, s5, -1
	s_cmp_lg_u32 s5, 0
	s_waitcnt vmcnt(0) lgkmcnt(0)
	v_fmac_f32_e32 v7, v8, v6
	s_cbranch_scc1 .LBB0_508
.LBB0_509:
	v_lshl_add_u64 v[4:5], v[4:5], 0, s[26:27]
	v_add_co_u32_e32 v8, vcc, 0x11000, v4
	s_nop 1
	v_addc_co_u32_e32 v9, vcc, 0, v5, vcc
	flat_load_dwordx2 v[8:9], v[8:9] offset:2048
	v_add_co_u32_e32 v10, vcc, 0xf000, v4
	ds_write_b32 v15, v7 offset:15360
	s_nop 0
	v_addc_co_u32_e32 v11, vcc, 0, v5, vcc
	v_add_co_u32_e32 v4, vcc, 0xc000, v4
	flat_load_dwordx2 v[10:11], v[10:11]
	s_nop 0
	v_addc_co_u32_e32 v5, vcc, 0, v5, vcc
	s_waitcnt vmcnt(0) lgkmcnt(0)
	v_fmac_f32_e32 v9, v7, v8
	ds_write_b32 v15, v9 offset:10240
	flat_load_dwordx2 v[4:5], v[4:5] offset:2048
	v_fmac_f32_e32 v11, v9, v10
	s_waitcnt vmcnt(0) lgkmcnt(0)
	v_fmac_f32_e32 v5, v11, v4
	ds_write2st64_b32 v15, v5, v11 offset1:20

.LBB0_513:
	v_add_co_u32_e32 v16, vcc, 0xfffee7fc, v12
	s_add_i32 s4, s4, 8
	s_nop 0
	v_addc_co_u32_e32 v17, vcc, -1, v13, vcc
	flat_load_dwordx2 v[16:17], v[16:17]
	v_add_co_u32_e32 v18, vcc, -4, v12
	s_cmp_lg_u32 s63, s4
	s_nop 0
	v_addc_co_u32_e32 v19, vcc, -1, v13, vcc
	v_add_co_u32_e32 v20, vcc, 0xffff0ffc, v12
	s_nop 1
	v_addc_co_u32_e32 v21, vcc, -1, v13, vcc
	v_add_co_u32_e32 v22, vcc, 0xffff37fc, v12
	flat_load_dwordx2 v[20:21], v[20:21]
	s_nop 0
	v_addc_co_u32_e32 v23, vcc, -1, v13, vcc
	v_add_co_u32_e32 v24, vcc, 0xffff5ffc, v12
	s_waitcnt vmcnt(0) lgkmcnt(0)
	v_fmac_f32_e32 v17, v7, v16
	v_addc_co_u32_e32 v25, vcc, -1, v13, vcc
	v_add_co_u32_e32 v26, vcc, 0xffff87fc, v12
	flat_load_dwordx2 v[22:23], v[22:23]
	s_nop 0
	flat_load_dwordx2 v[24:25], v[24:25]
	v_addc_co_u32_e32 v27, vcc, -1, v13, vcc
	v_add_co_u32_e32 v28, vcc, 0xffffaffc, v12
	flat_load_dwordx2 v[26:27], v[26:27]
	s_nop 0
	v_addc_co_u32_e32 v29, vcc, -1, v13, vcc
	v_add_co_u32_e32 v30, vcc, 0xffffd7fc, v12
	v_fmac_f32_e32 v21, v17, v20
	s_nop 0
	v_addc_co_u32_e32 v31, vcc, -1, v13, vcc
	flat_load_dwordx2 v[28:29], v[28:29]
	s_nop 0
	flat_load_dwordx2 v[30:31], v[30:31]
	v_lshl_add_u64 v[12:13], v[12:13], 0, s[16:17]
	flat_load_dwordx2 v[6:7], v[18:19]
	s_waitcnt vmcnt(0) lgkmcnt(0)
	v_fmac_f32_e32 v23, v21, v22
	v_fmac_f32_e32 v25, v23, v24
	v_fmac_f32_e32 v27, v25, v26
	v_fmac_f32_e32 v29, v27, v28
	v_fmac_f32_e32 v31, v29, v30
	v_fmac_f32_e32 v7, v31, v6
	s_cbranch_scc1 .LBB0_513
	s_mov_b32 s4, s63
	s_andn2_b64 vcc, exec, s[36:37]
	s_cbranch_vccnz .LBB0_501
	s_branch .LBB0_516

.LBB0_517:
	v_add_co_u32_e32 v10, vcc, -4, v8
	v_mov_b32_e32 v6, v7
	s_nop 0
	v_addc_co_u32_e32 v11, vcc, -1, v9, vcc
	flat_load_dwordx2 v[10:11], v[10:11]
	s_add_i32 s4, s4, -1
	v_lshl_add_u64 v[8:9], v[8:9], 0, s[18:19]
	s_cmp_lg_u32 s4, 0
	s_waitcnt vmcnt(0) lgkmcnt(0)
	v_mov_b32_e32 v7, v11
	v_fmac_f32_e32 v7, v6, v10
	s_cbranch_scc1 .LBB0_517
	s_branch .LBB0_501

.LBB0_519:
	v_mul_u32_u24_e32 v5, 0xcccd, v4
	v_lshrrev_b32_e32 v2, 23, v5
	v_lshl_add_u64 v[8:9], s[26:27], 0, v[2:3]
	v_mov_b32_e32 v11, s50
	v_mov_b32_e32 v12, s48
	v_mov_b32_e32 v15, s49
	v_mov_b32_e32 v16, s39
	v_mad_i32_i24 v20, v2, s57, v4
	v_cmp_gt_u64_e32 vcc, s[20:21], v[8:9]
	v_mov_b64_e32 v[6:7], s[10:11]
	v_lshlrev_b32_e32 v10, 3, v20
	v_cndmask_b32_e32 v13, v11, v12, vcc
	v_cndmask_b32_e32 v12, v15, v16, vcc
	v_mad_u64_u32 v[6:7], s[4:5], v8, s58, v[6:7]
	v_ashrrev_i32_e32 v11, 31, v10
	v_mad_u64_u32 v[18:19], s[4:5], v8, s59, v[12:13]
	v_mad_i32_i24 v7, v9, s58, v7
	v_lshlrev_b64 v[16:17], 1, v[10:11]
	v_mad_i32_i24 v19, v9, s59, v19
	v_lshl_add_u64 v[36:37], v[6:7], 0, v[16:17]
	v_lshl_add_u64 v[16:17], v[18:19], 0, v[16:17]
	flat_load_dwordx4 v[6:9], v[36:37] offset:2560
	flat_load_dwordx4 v[10:13], v[36:37]
	v_add_u32_e32 v2, 0x200, v4
	flat_load_dwordx4 v[16:19], v[16:17]
	v_cmp_lt_u32_e32 vcc, s60, v4
	v_lshrrev_b32_e32 v4, 29, v5
	v_mul_u32_u24_e32 v5, 0x1400, v4
	v_mov_b32_e32 v4, v2
	v_lshlrev_b32_e32 v2, 5, v20
	v_add3_u32 v2, 0, v5, v2
	ds_read_b128 v[20:23], v2
	ds_read_b128 v[24:27], v2 offset:20480
	ds_read_b128 v[28:31], v2 offset:16
	ds_read_b128 v[32:35], v2 offset:20496
	s_or_b64 s[24:25], vcc, s[24:25]
	s_waitcnt lgkmcnt(0)
	v_mov_b32_e32 v38, v20
	v_mov_b32_e32 v39, v24
	v_mov_b32_e32 v24, v21
	v_mov_b32_e32 v20, v22
	v_mov_b32_e32 v21, v26
	v_mov_b32_e32 v26, v23
	v_mov_b32_e32 v22, v28
	v_mov_b32_e32 v23, v32
	v_mov_b32_e32 v32, v29
	v_mov_b32_e32 v28, v30
	v_mov_b32_e32 v29, v34
	v_mov_b32_e32 v34, v31
	s_waitcnt vmcnt(0)
	v_lshlrev_b32_e32 v2, 16, v6
	v_lshlrev_b32_e32 v30, 16, v10
	v_and_b32_e32 v5, 0xffff0000, v6
	v_and_b32_e32 v6, 0xffff0000, v10
	v_lshlrev_b32_e32 v15, 16, v7
	v_lshlrev_b32_e32 v10, 16, v11
	v_and_b32_e32 v46, 0xffff0000, v7
	v_and_b32_e32 v40, 0xffff0000, v11
	v_lshlrev_b32_e32 v47, 16, v8
	v_lshlrev_b32_e32 v42, 16, v12
	v_and_b32_e32 v48, 0xffff0000, v8
	v_and_b32_e32 v8, 0xffff0000, v12
	v_lshlrev_b32_e32 v49, 16, v9
	v_lshlrev_b32_e32 v12, 16, v13
	v_and_b32_e32 v50, 0xffff0000, v9
	v_and_b32_e32 v44, 0xffff0000, v13
	v_and_b32_e32 v7, 0xffff0000, v16
	v_lshlrev_b32_e32 v11, 16, v17
	v_and_b32_e32 v9, 0xffff0000, v18
	v_lshlrev_b32_e32 v13, 16, v19
	v_lshlrev_b32_e32 v31, 16, v16
	v_and_b32_e32 v41, 0xffff0000, v17
	v_lshlrev_b32_e32 v43, 16, v18
	v_and_b32_e32 v45, 0xffff0000, v19
	v_pk_mul_f32 v[6:7], v[24:25], v[6:7]
	v_pk_mul_f32 v[10:11], v[20:21], v[10:11]
	v_pk_mul_f32 v[8:9], v[32:33], v[8:9]
	v_pk_mul_f32 v[12:13], v[28:29], v[12:13]
	v_pk_mul_f32 v[16:17], v[38:39], v[30:31]
	v_pk_mul_f32 v[18:19], v[26:27], v[40:41]
	v_pk_mul_f32 v[20:21], v[22:23], v[42:43]
	v_pk_mul_f32 v[22:23], v[34:35], v[44:45]
	v_add_f32_e32 v5, v6, v5
	v_add_f32_e32 v6, v10, v15
	v_add_f32_e32 v8, v8, v48
	v_add_f32_e32 v12, v12, v49
	v_add_f32_e32 v2, v16, v2
	v_add_f32_e32 v10, v18, v46
	v_add_f32_e32 v15, v20, v47
	v_add_f32_e32 v16, v22, v50
	v_add_f32_e32 v5, v5, v7
	v_add_f32_e32 v7, v6, v11
	v_add_f32_e32 v8, v8, v9
	v_add_f32_e32 v9, v12, v13
	v_add_f32_e32 v2, v2, v17
	v_add_f32_e32 v10, v10, v19
	v_add_f32_e32 v11, v15, v21
	v_add_f32_e32 v12, v16, v23
	v_cvt_pk_bf16_f32 v6, v2, v5
	v_cvt_pk_bf16_f32 v7, v7, v10
	v_cvt_pk_bf16_f32 v8, v11, v8
	v_cvt_pk_bf16_f32 v9, v9, v12
	flat_store_dwordx4 v[36:37], v[6:9] offset:2560
	s_andn2_b64 exec, exec, s[24:25]
	s_cbranch_execnz .LBB0_519
	s_or_b64 exec, exec, s[24:25]
	s_add_i32 s22, s22, s38
	s_add_i32 s62, s62, 1
	s_add_i32 s61, s61, s52
	s_cmpk_gt_i32 s22, 0xff
	s_cbranch_scc0 .LBB0_500

.LBB0_590:
	v_mov_b32_e32 v2, v225
	v_mov_b32_e32 v1, v224
	s_lshl_b32 s27, s65, 8
	v_add_u32_e32 v1, s52, v1
	v_lshl_add_u32 v229, v2, 3, s53
	v_add_u32_e32 v228, s27, v1
	s_lshl_b32 s64, s64, 8
	v_mov_b64_e32 v[132:133], s[16:17]
	v_add_u32_e32 v2, s64, v229
	v_mad_i64_i32 v[218:219], s[4:5], v228, s58, v[132:133]
	v_lshl_add_u64 v[132:133], v[218:219], 0, s[22:23]
	v_ashrrev_i32_e32 v3, 31, v2
	v_lshl_add_u64 v[134:135], v[2:3], 1, v[132:133]
	flat_load_dwordx4 v[192:195], v[134:135]
	s_cmp_eq_u32 s66, 0
	s_cselect_b64 s[8:9], -1, 0
	s_cmp_lg_u32 s66, 0
	s_cselect_b64 s[34:35], -1, 0
	v_lshl_add_u64 v[134:135], v[218:219], 0, s[24:25]
	s_and_b64 vcc, exec, s[34:35]
	s_cbranch_vccnz .LBB0_592
	v_lshl_add_u64 v[136:137], v[2:3], 1, v[134:135]
	flat_load_dwordx4 v[160:163], v[136:137]
.LBB0_592:
	v_add_u32_e32 v216, 0x80, v2
	v_ashrrev_i32_e32 v217, 31, v216
	v_lshl_add_u64 v[132:133], v[216:217], 1, v[132:133]
	flat_load_dwordx4 v[188:191], v[132:133]
	v_cndmask_b32_e64 v132, 0, 1, s[8:9]
	v_cmp_ne_u32_e64 s[10:11], 1, v132
	s_andn2_b64 vcc, exec, s[8:9]
	s_cbranch_vccnz .LBB0_594
	v_lshl_add_u64 v[132:133], v[216:217], 1, v[134:135]
	flat_load_dwordx4 v[156:159], v[132:133]
.LBB0_594:
	v_add_u32_e32 v134, 16, v228
	v_mov_b64_e32 v[132:133], s[16:17]
	v_mad_i64_i32 v[132:133], s[4:5], v134, s58, v[132:133]
	v_lshl_add_u64 v[134:135], v[132:133], 0, s[22:23]
	v_lshl_add_u64 v[136:137], v[2:3], 1, v[134:135]
	flat_load_dwordx4 v[184:187], v[136:137]
	s_and_b64 vcc, exec, s[10:11]
	v_lshl_add_u64 v[132:133], v[132:133], 0, s[24:25]
	s_cbranch_vccz .LBB0_677
	v_lshl_add_u64 v[134:135], v[216:217], 1, v[134:135]
	flat_load_dwordx4 v[180:183], v[134:135]
	s_and_b64 vcc, exec, s[10:11]
	s_cbranch_vccz .LBB0_678
.LBB0_596:
	v_add_u32_e32 v134, 32, v228
	v_mov_b64_e32 v[132:133], s[16:17]
	v_mad_i64_i32 v[132:133], s[4:5], v134, s58, v[132:133]
	v_lshl_add_u64 v[134:135], v[132:133], 0, s[22:23]
	v_lshl_add_u64 v[136:137], v[2:3], 1, v[134:135]
	flat_load_dwordx4 v[176:179], v[136:137]
	s_and_b64 vcc, exec, s[10:11]
	v_lshl_add_u64 v[132:133], v[132:133], 0, s[24:25]
	s_cbranch_vccz .LBB0_679
	v_lshl_add_u64 v[134:135], v[216:217], 1, v[134:135]
	flat_load_dwordx4 v[172:175], v[134:135]
	s_and_b64 vcc, exec, s[10:11]
	s_cbranch_vccz .LBB0_680
.LBB0_598:
	v_add_u32_e32 v134, 48, v228
	v_mov_b64_e32 v[132:133], s[16:17]
	v_mad_i64_i32 v[134:135], s[4:5], v134, s58, v[132:133]
	v_lshl_add_u64 v[132:133], v[134:135], 0, s[22:23]
	v_lshl_add_u64 v[136:137], v[2:3], 1, v[132:133]
	flat_load_dwordx4 v[168:171], v[136:137]
	s_and_b64 vcc, exec, s[10:11]
	v_lshl_add_u64 v[214:215], v[134:135], 0, s[24:25]
	s_cbranch_vccz .LBB0_681
	v_lshl_add_u64 v[132:133], v[216:217], 1, v[132:133]
	flat_load_dwordx4 v[164:167], v[132:133]
	s_and_b64 vcc, exec, s[10:11]
	s_cbranch_vccz .LBB0_682
.LBB0_600:
	s_waitcnt vmcnt(0) lgkmcnt(0)
	v_lshlrev_b32_e32 v214, 16, v192
	v_lshlrev_b32_e32 v230, 16, v194
	v_and_b32_e32 v215, 0xffff0000, v192
	v_max_f32_e32 v192, v214, v214
	v_max_f32_e32 v214, v230, v230
	v_max_f32_e32 v214, 0xc2700000, v214
	v_and_b32_e32 v231, 0xffff0000, v194
	v_mul_f32_e32 v214, 0xbfb8aa3b, v214
	v_exp_f32_e32 v230, v214
	v_max_f32_e32 v214, v231, v231
	v_max_f32_e32 v214, 0xc2700000, v214
	v_lshlrev_b32_e32 v232, 16, v195
	v_mul_f32_e32 v214, 0xbfb8aa3b, v214
	v_exp_f32_e32 v231, v214
	v_max_f32_e32 v214, v232, v232
	v_max_f32_e32 v214, 0xc2700000, v214
	v_lshlrev_b32_e32 v220, 16, v193
	v_and_b32_e32 v221, 0xffff0000, v193
	v_and_b32_e32 v233, 0xffff0000, v195
	v_max_f32_e32 v193, v215, v215
	v_mul_f32_e32 v214, 0xbfb8aa3b, v214
	v_max_f32_e32 v192, 0xc2700000, v192
	v_max_f32_e32 v193, 0xc2700000, v193
	v_max_f32_e32 v194, v220, v220
	v_max_f32_e32 v195, v221, v221
	v_exp_f32_e32 v232, v214
	v_max_f32_e32 v214, v233, v233
	v_mul_f32_e32 v192, 0xbfb8aa3b, v192
	v_mul_f32_e32 v193, 0xbfb8aa3b, v193
	v_max_f32_e32 v194, 0xc2700000, v194
	v_max_f32_e32 v195, 0xc2700000, v195
	v_max_f32_e32 v214, 0xc2700000, v214
	v_exp_f32_e32 v192, v192
	v_exp_f32_e32 v193, v193
	v_mul_f32_e32 v194, 0xbfb8aa3b, v194
	v_mul_f32_e32 v195, 0xbfb8aa3b, v195
	v_mul_f32_e32 v214, 0xbfb8aa3b, v214
	v_exp_f32_e32 v194, v194
	v_exp_f32_e32 v195, v195
	v_exp_f32_e32 v233, v214
	v_pk_add_f32 v[220:221], v[192:193], 1.0 op_sel_hi:[1,0]
	v_pk_add_f32 v[192:193], v[230:231], 1.0 op_sel_hi:[1,0]
	v_cndmask_b32_e64 v230, 0, 1, s[34:35]
	v_pk_add_f32 v[214:215], v[194:195], 1.0 op_sel_hi:[1,0]
	v_pk_add_f32 v[194:195], v[232:233], 1.0 op_sel_hi:[1,0]
	v_cmp_ne_u32_e64 s[8:9], 1, v230
	s_andn2_b64 vcc, exec, s[34:35]
	s_mov_b64 s[34:35], -1
	s_cbranch_vccnz .LBB0_602
	v_rcp_f32_e32 v230, v220
	v_rcp_f32_e32 v231, v221
	v_rcp_f32_e32 v232, v214
	v_rcp_f32_e32 v234, v192
	v_rcp_f32_e32 v235, v193
	v_rcp_f32_e32 v233, v215
	v_rcp_f32_e32 v236, v194
	v_rcp_f32_e32 v237, v195
	v_mul_f32_e32 v230, v128, v230
	v_mul_f32_e32 v231, v129, v231
	v_mul_f32_e32 v232, v130, v232
	v_mul_f32_e32 v234, v124, v234
	v_mul_f32_e32 v235, v125, v235
	v_mul_f32_e32 v233, v131, v233
	v_cvt_pk_bf16_f32 v230, v230, v231
	v_cvt_pk_bf16_f32 v231, v232, v233
	v_cvt_pk_bf16_f32 v232, v234, v235
	v_lshl_add_u64 v[234:235], v[2:3], 1, v[218:219]
	s_mov_b64 s[34:35], 0
	v_mul_f32_e32 v236, v126, v236
	v_mul_f32_e32 v237, v127, v237
	v_cvt_pk_bf16_f32 v233, v236, v237
	flat_store_dwordx4 v[234:235], v[230:233]

.LBB0_604:
	v_lshlrev_b32_e32 v192, 16, v188
	v_lshlrev_b32_e32 v214, 16, v190
	v_and_b32_e32 v193, 0xffff0000, v188
	v_max_f32_e32 v188, v192, v192
	v_max_f32_e32 v192, v214, v214
	v_max_f32_e32 v192, 0xc2700000, v192
	v_and_b32_e32 v215, 0xffff0000, v190
	v_mul_f32_e32 v192, 0xbfb8aa3b, v192
	v_exp_f32_e32 v214, v192
	v_max_f32_e32 v192, v215, v215
	v_max_f32_e32 v192, 0xc2700000, v192
	v_lshlrev_b32_e32 v220, 16, v191
	v_mul_f32_e32 v192, 0xbfb8aa3b, v192
	v_exp_f32_e32 v215, v192
	v_max_f32_e32 v192, v220, v220
	v_max_f32_e32 v192, 0xc2700000, v192
	v_lshlrev_b32_e32 v194, 16, v189
	v_and_b32_e32 v195, 0xffff0000, v189
	v_and_b32_e32 v221, 0xffff0000, v191
	v_max_f32_e32 v189, v193, v193
	v_mul_f32_e32 v192, 0xbfb8aa3b, v192
	v_max_f32_e32 v188, 0xc2700000, v188
	v_max_f32_e32 v189, 0xc2700000, v189
	v_max_f32_e32 v190, v194, v194
	v_max_f32_e32 v191, v195, v195
	v_exp_f32_e32 v220, v192
	v_max_f32_e32 v192, v221, v221
	v_mul_f32_e32 v188, 0xbfb8aa3b, v188
	v_mul_f32_e32 v189, 0xbfb8aa3b, v189
	v_max_f32_e32 v190, 0xc2700000, v190
	v_max_f32_e32 v191, 0xc2700000, v191
	v_max_f32_e32 v192, 0xc2700000, v192
	v_exp_f32_e32 v188, v188
	v_exp_f32_e32 v189, v189
	v_mul_f32_e32 v190, 0xbfb8aa3b, v190
	v_mul_f32_e32 v191, 0xbfb8aa3b, v191
	v_mul_f32_e32 v192, 0xbfb8aa3b, v192
	v_exp_f32_e32 v190, v190
	v_exp_f32_e32 v191, v191
	v_exp_f32_e32 v221, v192
	v_add_u32_e32 v229, 0x80, v229
	v_pk_add_f32 v[194:195], v[188:189], 1.0 op_sel_hi:[1,0]
	v_pk_add_f32 v[188:189], v[214:215], 1.0 op_sel_hi:[1,0]
	v_add_u32_e32 v214, s64, v229
	v_pk_add_f32 v[192:193], v[190:191], 1.0 op_sel_hi:[1,0]
	v_pk_add_f32 v[190:191], v[220:221], 1.0 op_sel_hi:[1,0]
	s_mov_b64 s[34:35], -1
	s_and_b64 vcc, exec, s[8:9]
	v_ashrrev_i32_e32 v215, 31, v214
	s_cbranch_vccnz .LBB0_606
	v_rcp_f32_e32 v230, v193
	v_rcp_f32_e32 v232, v189
	v_rcp_f32_e32 v233, v190
	v_rcp_f32_e32 v220, v194
	v_rcp_f32_e32 v221, v195
	v_rcp_f32_e32 v229, v192
	v_mul_f32_e32 v231, v99, v230
	v_rcp_f32_e32 v230, v188
	v_rcp_f32_e32 v234, v191
	v_mul_f32_e32 v232, v93, v232
	v_mul_f32_e32 v233, v94, v233
	v_lshl_add_u64 v[218:219], v[214:215], 1, v[218:219]
	s_mov_b64 s[34:35], 0
	v_mul_f32_e32 v220, v96, v220
	v_mul_f32_e32 v221, v97, v221
	v_mul_f32_e32 v229, v98, v229
	v_mul_f32_e32 v235, v92, v230
	v_mul_f32_e32 v234, v95, v234
	v_cvt_pk_bf16_f32 v230, v220, v221
	v_cvt_pk_bf16_f32 v231, v229, v231
	v_cvt_pk_bf16_f32 v232, v235, v232
	v_cvt_pk_bf16_f32 v233, v233, v234
	flat_store_dwordx4 v[218:219], v[230:233]

.LBB0_608:
	v_lshlrev_b32_e32 v188, 16, v184
	v_lshlrev_b32_e32 v192, 16, v186
	v_and_b32_e32 v189, 0xffff0000, v184
	v_max_f32_e32 v184, v188, v188
	v_max_f32_e32 v188, v192, v192
	v_max_f32_e32 v188, 0xc2700000, v188
	v_and_b32_e32 v193, 0xffff0000, v186
	v_mul_f32_e32 v188, 0xbfb8aa3b, v188
	v_exp_f32_e32 v192, v188
	v_max_f32_e32 v188, v193, v193
	v_max_f32_e32 v188, 0xc2700000, v188
	v_lshlrev_b32_e32 v194, 16, v187
	v_mul_f32_e32 v188, 0xbfb8aa3b, v188
	v_exp_f32_e32 v193, v188
	v_max_f32_e32 v188, v194, v194
	v_max_f32_e32 v188, 0xc2700000, v188
	v_lshlrev_b32_e32 v190, 16, v185
	v_and_b32_e32 v191, 0xffff0000, v185
	v_and_b32_e32 v195, 0xffff0000, v187
	v_mul_f32_e32 v188, 0xbfb8aa3b, v188
	v_max_f32_e32 v185, v189, v189
	v_max_f32_e32 v186, v190, v190
	v_max_f32_e32 v187, v191, v191
	v_exp_f32_e32 v194, v188
	v_max_f32_e32 v188, v195, v195
	v_max_f32_e32 v184, 0xc2700000, v184
	v_max_f32_e32 v185, 0xc2700000, v185
	v_max_f32_e32 v186, 0xc2700000, v186
	v_max_f32_e32 v187, 0xc2700000, v187
	v_max_f32_e32 v188, 0xc2700000, v188
	v_mul_f32_e32 v184, 0xbfb8aa3b, v184
	v_mul_f32_e32 v185, 0xbfb8aa3b, v185
	v_mul_f32_e32 v186, 0xbfb8aa3b, v186
	v_mul_f32_e32 v187, 0xbfb8aa3b, v187
	v_mul_f32_e32 v188, 0xbfb8aa3b, v188
	v_exp_f32_e32 v184, v184
	v_exp_f32_e32 v185, v185
	v_exp_f32_e32 v186, v186
	v_exp_f32_e32 v187, v187
	v_exp_f32_e32 v195, v188
	v_add_u32_e32 v218, 16, v1
	v_pk_add_f32 v[190:191], v[184:185], 1.0 op_sel_hi:[1,0]
	v_pk_add_f32 v[188:189], v[186:187], 1.0 op_sel_hi:[1,0]
	v_pk_add_f32 v[184:185], v[192:193], 1.0 op_sel_hi:[1,0]
	v_pk_add_f32 v[186:187], v[194:195], 1.0 op_sel_hi:[1,0]
	s_mov_b64 s[34:35], -1
	s_and_b64 vcc, exec, s[8:9]
	v_add_u32_e32 v192, s27, v218
	s_cbranch_vccnz .LBB0_610
	v_rcp_f32_e32 v218, v189
	v_rcp_f32_e32 v194, v191
	v_rcp_f32_e32 v195, v188
	v_rcp_f32_e32 v193, v190
	v_mul_f32_e32 v219, v123, v218
	v_rcp_f32_e32 v218, v184
	v_rcp_f32_e32 v220, v185
	v_rcp_f32_e32 v221, v186
	v_mul_f32_e32 v194, v121, v194
	v_mul_f32_e32 v195, v122, v195
	v_rcp_f32_e32 v229, v187
	v_mul_f32_e32 v193, v120, v193
	v_mul_f32_e32 v230, v116, v218
	v_cvt_pk_bf16_f32 v218, v193, v194
	v_cvt_pk_bf16_f32 v219, v195, v219
	v_mov_b64_e32 v[194:195], s[16:17]
	v_mad_i64_i32 v[194:195], s[4:5], v192, s58, v[194:195]
	v_mul_f32_e32 v220, v117, v220
	v_mul_f32_e32 v221, v118, v221
	v_lshl_add_u64 v[194:195], v[2:3], 1, v[194:195]
	s_mov_b64 s[34:35], 0
	v_mul_f32_e32 v229, v119, v229
	v_cvt_pk_bf16_f32 v220, v230, v220
	v_cvt_pk_bf16_f32 v221, v221, v229
	flat_store_dwordx4 v[194:195], v[218:221]

.LBB0_612:
	v_lshlrev_b32_e32 v184, 16, v180
	v_lshlrev_b32_e32 v188, 16, v182
	v_and_b32_e32 v185, 0xffff0000, v180
	v_max_f32_e32 v180, v184, v184
	v_max_f32_e32 v184, v188, v188
	v_max_f32_e32 v184, 0xc2700000, v184
	v_and_b32_e32 v189, 0xffff0000, v182
	v_mul_f32_e32 v184, 0xbfb8aa3b, v184
	v_exp_f32_e32 v188, v184
	v_max_f32_e32 v184, v189, v189
	v_max_f32_e32 v184, 0xc2700000, v184
	v_lshlrev_b32_e32 v190, 16, v183
	v_mul_f32_e32 v184, 0xbfb8aa3b, v184
	v_exp_f32_e32 v189, v184
	v_max_f32_e32 v184, v190, v190
	v_max_f32_e32 v184, 0xc2700000, v184
	v_lshlrev_b32_e32 v186, 16, v181
	v_and_b32_e32 v187, 0xffff0000, v181
	v_and_b32_e32 v191, 0xffff0000, v183
	v_mul_f32_e32 v184, 0xbfb8aa3b, v184
	v_max_f32_e32 v181, v185, v185
	v_max_f32_e32 v182, v186, v186
	v_max_f32_e32 v183, v187, v187
	v_exp_f32_e32 v190, v184
	v_max_f32_e32 v184, v191, v191
	v_max_f32_e32 v180, 0xc2700000, v180
	v_max_f32_e32 v181, 0xc2700000, v181
	v_max_f32_e32 v182, 0xc2700000, v182
	v_max_f32_e32 v183, 0xc2700000, v183
	v_max_f32_e32 v184, 0xc2700000, v184
	v_mul_f32_e32 v180, 0xbfb8aa3b, v180
	v_mul_f32_e32 v181, 0xbfb8aa3b, v181
	v_mul_f32_e32 v182, 0xbfb8aa3b, v182
	v_mul_f32_e32 v183, 0xbfb8aa3b, v183
	v_mul_f32_e32 v184, 0xbfb8aa3b, v184
	v_exp_f32_e32 v180, v180
	v_exp_f32_e32 v181, v181
	v_exp_f32_e32 v182, v182
	v_exp_f32_e32 v183, v183
	v_exp_f32_e32 v191, v184
	v_pk_add_f32 v[186:187], v[180:181], 1.0 op_sel_hi:[1,0]
	v_pk_add_f32 v[180:181], v[188:189], 1.0 op_sel_hi:[1,0]
	v_pk_add_f32 v[184:185], v[182:183], 1.0 op_sel_hi:[1,0]
	v_pk_add_f32 v[182:183], v[190:191], 1.0 op_sel_hi:[1,0]
	s_and_b64 vcc, exec, s[8:9]
	s_mov_b64 s[34:35], -1
	s_cbranch_vccnz .LBB0_614
	v_rcp_f32_e32 v188, v186
	v_rcp_f32_e32 v189, v187
	v_rcp_f32_e32 v190, v184
	v_rcp_f32_e32 v191, v185
	v_rcp_f32_e32 v194, v181
	v_rcp_f32_e32 v195, v182
	v_rcp_f32_e32 v193, v180
	v_rcp_f32_e32 v218, v183
	v_mul_f32_e32 v188, v88, v188
	v_mul_f32_e32 v189, v89, v189
	v_mul_f32_e32 v190, v90, v190
	v_mul_f32_e32 v191, v91, v191
	v_mul_f32_e32 v194, v85, v194
	v_mul_f32_e32 v195, v86, v195
	v_mul_f32_e32 v193, v84, v193
	v_mul_f32_e32 v218, v87, v218
	v_cvt_pk_bf16_f32 v188, v188, v189
	v_cvt_pk_bf16_f32 v189, v190, v191
	v_cvt_pk_bf16_f32 v190, v193, v194
	v_cvt_pk_bf16_f32 v191, v195, v218
	v_mov_b64_e32 v[194:195], s[16:17]
	v_mad_i64_i32 v[192:193], s[4:5], v192, s58, v[194:195]
	v_lshl_add_u64 v[192:193], v[214:215], 1, v[192:193]
	s_mov_b64 s[34:35], 0
	flat_store_dwordx4 v[192:193], v[188:191]

.LBB0_616:
	v_lshlrev_b32_e32 v180, 16, v176
	v_lshlrev_b32_e32 v184, 16, v178
	v_and_b32_e32 v181, 0xffff0000, v176
	v_max_f32_e32 v176, v180, v180
	v_max_f32_e32 v180, v184, v184
	v_max_f32_e32 v180, 0xc2700000, v180
	v_and_b32_e32 v185, 0xffff0000, v178
	v_mul_f32_e32 v180, 0xbfb8aa3b, v180
	v_exp_f32_e32 v184, v180
	v_max_f32_e32 v180, v185, v185
	v_max_f32_e32 v180, 0xc2700000, v180
	v_lshlrev_b32_e32 v186, 16, v179
	v_mul_f32_e32 v180, 0xbfb8aa3b, v180
	v_exp_f32_e32 v185, v180
	v_max_f32_e32 v180, v186, v186
	v_max_f32_e32 v180, 0xc2700000, v180
	v_lshlrev_b32_e32 v182, 16, v177
	v_and_b32_e32 v183, 0xffff0000, v177
	v_and_b32_e32 v187, 0xffff0000, v179
	v_mul_f32_e32 v180, 0xbfb8aa3b, v180
	v_max_f32_e32 v177, v181, v181
	v_max_f32_e32 v178, v182, v182
	v_max_f32_e32 v179, v183, v183
	v_exp_f32_e32 v186, v180
	v_max_f32_e32 v180, v187, v187
	v_max_f32_e32 v176, 0xc2700000, v176
	v_max_f32_e32 v177, 0xc2700000, v177
	v_max_f32_e32 v178, 0xc2700000, v178
	v_max_f32_e32 v179, 0xc2700000, v179
	v_max_f32_e32 v180, 0xc2700000, v180
	v_mul_f32_e32 v176, 0xbfb8aa3b, v176
	v_mul_f32_e32 v177, 0xbfb8aa3b, v177
	v_mul_f32_e32 v178, 0xbfb8aa3b, v178
	v_mul_f32_e32 v179, 0xbfb8aa3b, v179
	v_mul_f32_e32 v180, 0xbfb8aa3b, v180
	v_exp_f32_e32 v176, v176
	v_exp_f32_e32 v177, v177
	v_exp_f32_e32 v178, v178
	v_exp_f32_e32 v179, v179
	v_exp_f32_e32 v187, v180
	v_add_u32_e32 v188, 32, v1
	v_pk_add_f32 v[182:183], v[176:177], 1.0 op_sel_hi:[1,0]
	v_pk_add_f32 v[180:181], v[178:179], 1.0 op_sel_hi:[1,0]
	v_pk_add_f32 v[176:177], v[184:185], 1.0 op_sel_hi:[1,0]
	v_pk_add_f32 v[178:179], v[186:187], 1.0 op_sel_hi:[1,0]
	s_mov_b64 s[34:35], -1
	s_and_b64 vcc, exec, s[8:9]
	v_add_u32_e32 v184, s27, v188
	s_cbranch_vccnz .LBB0_618
	v_rcp_f32_e32 v187, v180
	v_rcp_f32_e32 v188, v181
	v_rcp_f32_e32 v189, v176
	v_rcp_f32_e32 v190, v177
	v_rcp_f32_e32 v191, v178
	v_rcp_f32_e32 v192, v179
	v_rcp_f32_e32 v186, v183
	v_rcp_f32_e32 v185, v182
	v_mul_f32_e32 v187, v114, v187
	v_mul_f32_e32 v188, v115, v188
	v_mul_f32_e32 v189, v108, v189
	v_mul_f32_e32 v190, v109, v190
	v_mul_f32_e32 v191, v110, v191
	v_mul_f32_e32 v192, v111, v192
	v_cvt_pk_bf16_f32 v187, v187, v188
	v_cvt_pk_bf16_f32 v188, v189, v190
	v_cvt_pk_bf16_f32 v189, v191, v192
	v_mov_b64_e32 v[190:191], s[16:17]
	v_mad_i64_i32 v[190:191], s[4:5], v184, s58, v[190:191]
	v_mul_f32_e32 v186, v113, v186
	v_lshl_add_u64 v[190:191], v[2:3], 1, v[190:191]
	s_mov_b64 s[34:35], 0
	v_mul_f32_e32 v185, v112, v185
	v_cvt_pk_bf16_f32 v186, v185, v186
	flat_store_dwordx4 v[190:191], v[186:189]

.LBB0_620:
	v_lshlrev_b32_e32 v176, 16, v172
	v_lshlrev_b32_e32 v180, 16, v174
	v_and_b32_e32 v177, 0xffff0000, v172
	v_max_f32_e32 v172, v176, v176
	v_max_f32_e32 v176, v180, v180
	v_max_f32_e32 v176, 0xc2700000, v176
	v_and_b32_e32 v181, 0xffff0000, v174
	v_mul_f32_e32 v176, 0xbfb8aa3b, v176
	v_exp_f32_e32 v180, v176
	v_max_f32_e32 v176, v181, v181
	v_max_f32_e32 v176, 0xc2700000, v176
	v_lshlrev_b32_e32 v182, 16, v175
	v_mul_f32_e32 v176, 0xbfb8aa3b, v176
	v_exp_f32_e32 v181, v176
	v_max_f32_e32 v176, v182, v182
	v_max_f32_e32 v176, 0xc2700000, v176
	v_lshlrev_b32_e32 v178, 16, v173
	v_and_b32_e32 v179, 0xffff0000, v173
	v_and_b32_e32 v183, 0xffff0000, v175
	v_mul_f32_e32 v176, 0xbfb8aa3b, v176
	v_max_f32_e32 v173, v177, v177
	v_max_f32_e32 v174, v178, v178
	v_max_f32_e32 v175, v179, v179
	v_exp_f32_e32 v182, v176
	v_max_f32_e32 v176, v183, v183
	v_max_f32_e32 v172, 0xc2700000, v172
	v_max_f32_e32 v173, 0xc2700000, v173
	v_max_f32_e32 v174, 0xc2700000, v174
	v_max_f32_e32 v175, 0xc2700000, v175
	v_max_f32_e32 v176, 0xc2700000, v176
	v_mul_f32_e32 v172, 0xbfb8aa3b, v172
	v_mul_f32_e32 v173, 0xbfb8aa3b, v173
	v_mul_f32_e32 v174, 0xbfb8aa3b, v174
	v_mul_f32_e32 v175, 0xbfb8aa3b, v175
	v_mul_f32_e32 v176, 0xbfb8aa3b, v176
	v_exp_f32_e32 v172, v172
	v_exp_f32_e32 v173, v173
	v_exp_f32_e32 v174, v174
	v_exp_f32_e32 v175, v175
	v_exp_f32_e32 v183, v176
	v_pk_add_f32 v[178:179], v[172:173], 1.0 op_sel_hi:[1,0]
	v_pk_add_f32 v[172:173], v[180:181], 1.0 op_sel_hi:[1,0]
	v_pk_add_f32 v[176:177], v[174:175], 1.0 op_sel_hi:[1,0]
	v_pk_add_f32 v[174:175], v[182:183], 1.0 op_sel_hi:[1,0]
	s_and_b64 vcc, exec, s[8:9]
	s_mov_b64 s[34:35], -1
	s_cbranch_vccnz .LBB0_622
	v_rcp_f32_e32 v180, v178
	v_rcp_f32_e32 v181, v179
	v_rcp_f32_e32 v182, v176
	v_rcp_f32_e32 v183, v177
	v_rcp_f32_e32 v186, v173
	v_rcp_f32_e32 v187, v174
	v_rcp_f32_e32 v185, v172
	v_rcp_f32_e32 v188, v175
	v_mul_f32_e32 v180, v80, v180
	v_mul_f32_e32 v181, v81, v181
	v_mul_f32_e32 v182, v82, v182
	v_mul_f32_e32 v183, v83, v183
	v_mul_f32_e32 v186, v77, v186
	v_mul_f32_e32 v187, v78, v187
	v_mul_f32_e32 v185, v76, v185
	v_mul_f32_e32 v188, v79, v188
	v_cvt_pk_bf16_f32 v180, v180, v181
	v_cvt_pk_bf16_f32 v181, v182, v183
	v_cvt_pk_bf16_f32 v182, v185, v186
	v_cvt_pk_bf16_f32 v183, v187, v188
	v_mov_b64_e32 v[186:187], s[16:17]
	v_mad_i64_i32 v[184:185], s[4:5], v184, s58, v[186:187]
	v_lshl_add_u64 v[184:185], v[214:215], 1, v[184:185]
	s_mov_b64 s[34:35], 0
	flat_store_dwordx4 v[184:185], v[180:183]

.LBB0_624:
	v_lshlrev_b32_e32 v172, 16, v168
	v_lshlrev_b32_e32 v176, 16, v170
	v_and_b32_e32 v173, 0xffff0000, v168
	v_max_f32_e32 v168, v172, v172
	v_max_f32_e32 v172, v176, v176
	v_max_f32_e32 v172, 0xc2700000, v172
	v_and_b32_e32 v177, 0xffff0000, v170
	v_mul_f32_e32 v172, 0xbfb8aa3b, v172
	v_exp_f32_e32 v176, v172
	v_max_f32_e32 v172, v177, v177
	v_max_f32_e32 v172, 0xc2700000, v172
	v_lshlrev_b32_e32 v178, 16, v171
	v_mul_f32_e32 v172, 0xbfb8aa3b, v172
	v_exp_f32_e32 v177, v172
	v_max_f32_e32 v172, v178, v178
	v_max_f32_e32 v172, 0xc2700000, v172
	v_lshlrev_b32_e32 v174, 16, v169
	v_and_b32_e32 v175, 0xffff0000, v169
	v_and_b32_e32 v179, 0xffff0000, v171
	v_mul_f32_e32 v172, 0xbfb8aa3b, v172
	v_max_f32_e32 v169, v173, v173
	v_max_f32_e32 v170, v174, v174
	v_max_f32_e32 v171, v175, v175
	v_exp_f32_e32 v178, v172
	v_max_f32_e32 v172, v179, v179
	v_max_f32_e32 v168, 0xc2700000, v168
	v_max_f32_e32 v169, 0xc2700000, v169
	v_max_f32_e32 v170, 0xc2700000, v170
	v_max_f32_e32 v171, 0xc2700000, v171
	v_max_f32_e32 v172, 0xc2700000, v172
	v_mul_f32_e32 v168, 0xbfb8aa3b, v168
	v_mul_f32_e32 v169, 0xbfb8aa3b, v169
	v_mul_f32_e32 v170, 0xbfb8aa3b, v170
	v_mul_f32_e32 v171, 0xbfb8aa3b, v171
	v_mul_f32_e32 v172, 0xbfb8aa3b, v172
	v_exp_f32_e32 v168, v168
	v_exp_f32_e32 v169, v169
	v_exp_f32_e32 v170, v170
	v_exp_f32_e32 v171, v171
	v_exp_f32_e32 v179, v172
	v_add_u32_e32 v180, 48, v1
	v_pk_add_f32 v[174:175], v[168:169], 1.0 op_sel_hi:[1,0]
	v_pk_add_f32 v[172:173], v[170:171], 1.0 op_sel_hi:[1,0]
	v_pk_add_f32 v[168:169], v[176:177], 1.0 op_sel_hi:[1,0]
	v_pk_add_f32 v[170:171], v[178:179], 1.0 op_sel_hi:[1,0]
	s_mov_b64 s[34:35], -1
	s_and_b64 vcc, exec, s[8:9]
	v_add_u32_e32 v176, s27, v180
	s_cbranch_vccnz .LBB0_626
	v_rcp_f32_e32 v179, v172
	v_rcp_f32_e32 v180, v173
	v_rcp_f32_e32 v181, v168
	v_rcp_f32_e32 v182, v169
	v_rcp_f32_e32 v183, v170
	v_rcp_f32_e32 v184, v171
	v_rcp_f32_e32 v178, v175
	v_rcp_f32_e32 v177, v174
	v_mul_f32_e32 v179, v106, v179
	v_mul_f32_e32 v180, v107, v180
	v_mul_f32_e32 v181, v100, v181
	v_mul_f32_e32 v182, v101, v182
	v_mul_f32_e32 v183, v102, v183
	v_mul_f32_e32 v184, v103, v184
	v_cvt_pk_bf16_f32 v179, v179, v180
	v_cvt_pk_bf16_f32 v180, v181, v182
	v_cvt_pk_bf16_f32 v181, v183, v184
	v_mov_b64_e32 v[182:183], s[16:17]
	v_mad_i64_i32 v[182:183], s[4:5], v176, s58, v[182:183]
	v_mul_f32_e32 v178, v105, v178
	v_lshl_add_u64 v[182:183], v[2:3], 1, v[182:183]
	s_mov_b64 s[34:35], 0
	v_mul_f32_e32 v177, v104, v177
	v_cvt_pk_bf16_f32 v178, v177, v178
	flat_store_dwordx4 v[182:183], v[178:181]

.LBB0_628:
	v_lshlrev_b32_e32 v168, 16, v164
	v_lshlrev_b32_e32 v172, 16, v166
	v_and_b32_e32 v169, 0xffff0000, v164
	v_max_f32_e32 v164, v168, v168
	v_max_f32_e32 v168, v172, v172
	v_max_f32_e32 v168, 0xc2700000, v168
	v_and_b32_e32 v173, 0xffff0000, v166
	v_mul_f32_e32 v168, 0xbfb8aa3b, v168
	v_exp_f32_e32 v172, v168
	v_max_f32_e32 v168, v173, v173
	v_max_f32_e32 v168, 0xc2700000, v168
	v_lshlrev_b32_e32 v174, 16, v167
	v_mul_f32_e32 v168, 0xbfb8aa3b, v168
	v_exp_f32_e32 v173, v168
	v_max_f32_e32 v168, v174, v174
	v_max_f32_e32 v168, 0xc2700000, v168
	v_lshlrev_b32_e32 v170, 16, v165
	v_and_b32_e32 v171, 0xffff0000, v165
	v_and_b32_e32 v175, 0xffff0000, v167
	v_mul_f32_e32 v168, 0xbfb8aa3b, v168
	v_max_f32_e32 v165, v169, v169
	v_max_f32_e32 v166, v170, v170
	v_max_f32_e32 v167, v171, v171
	v_exp_f32_e32 v174, v168
	v_max_f32_e32 v168, v175, v175
	v_max_f32_e32 v164, 0xc2700000, v164
	v_max_f32_e32 v165, 0xc2700000, v165
	v_max_f32_e32 v166, 0xc2700000, v166
	v_max_f32_e32 v167, 0xc2700000, v167
	v_max_f32_e32 v168, 0xc2700000, v168
	v_mul_f32_e32 v164, 0xbfb8aa3b, v164
	v_mul_f32_e32 v165, 0xbfb8aa3b, v165
	v_mul_f32_e32 v166, 0xbfb8aa3b, v166
	v_mul_f32_e32 v167, 0xbfb8aa3b, v167
	v_mul_f32_e32 v168, 0xbfb8aa3b, v168
	v_exp_f32_e32 v164, v164
	v_exp_f32_e32 v165, v165
	v_exp_f32_e32 v166, v166
	v_exp_f32_e32 v167, v167
	v_exp_f32_e32 v175, v168
	v_pk_add_f32 v[170:171], v[164:165], 1.0 op_sel_hi:[1,0]
	v_pk_add_f32 v[164:165], v[172:173], 1.0 op_sel_hi:[1,0]
	v_pk_add_f32 v[168:169], v[166:167], 1.0 op_sel_hi:[1,0]
	v_pk_add_f32 v[166:167], v[174:175], 1.0 op_sel_hi:[1,0]
	s_and_b64 vcc, exec, s[8:9]
	s_mov_b64 s[34:35], -1
	s_cbranch_vccnz .LBB0_630
	v_rcp_f32_e32 v172, v170
	v_rcp_f32_e32 v173, v171
	v_rcp_f32_e32 v174, v168
	v_rcp_f32_e32 v175, v169
	v_rcp_f32_e32 v178, v165
	v_rcp_f32_e32 v179, v166
	v_rcp_f32_e32 v177, v164
	v_rcp_f32_e32 v180, v167
	v_mul_f32_e32 v172, v72, v172
	v_mul_f32_e32 v173, v73, v173
	v_mul_f32_e32 v174, v74, v174
	v_mul_f32_e32 v175, v75, v175
	v_mul_f32_e32 v178, v69, v178
	v_mul_f32_e32 v179, v70, v179
	v_mul_f32_e32 v177, v68, v177
	v_mul_f32_e32 v180, v71, v180
	v_cvt_pk_bf16_f32 v172, v172, v173
	v_cvt_pk_bf16_f32 v173, v174, v175
	v_cvt_pk_bf16_f32 v174, v177, v178
	v_cvt_pk_bf16_f32 v175, v179, v180
	v_mov_b64_e32 v[178:179], s[16:17]
	v_mad_i64_i32 v[176:177], s[4:5], v176, s58, v[178:179]
	v_lshl_add_u64 v[176:177], v[214:215], 1, v[176:177]
	s_mov_b64 s[34:35], 0
	flat_store_dwordx4 v[176:177], v[172:175]

.LBB0_632:
	v_add_u32_e32 v166, 0x80, v228
	v_mov_b64_e32 v[164:165], s[16:17]
	v_mad_i64_i32 v[218:219], s[4:5], v166, s58, v[164:165]
	v_lshl_add_u64 v[166:167], v[218:219], 0, s[22:23]
	v_lshl_add_u64 v[164:165], v[2:3], 1, v[166:167]
	flat_load_dwordx4 v[192:195], v[164:165]
	s_and_b64 vcc, exec, s[10:11]
	v_lshl_add_u64 v[164:165], v[218:219], 0, s[24:25]
	s_cbranch_vccz .LBB0_683
	v_lshl_add_u64 v[166:167], v[216:217], 1, v[166:167]
	flat_load_dwordx4 v[188:191], v[166:167]
	s_and_b64 vcc, exec, s[10:11]
	s_cbranch_vccz .LBB0_684
.LBB0_634:
	v_add_u32_e32 v166, 0x90, v228
	v_mov_b64_e32 v[164:165], s[16:17]
	v_mad_i64_i32 v[164:165], s[4:5], v166, s58, v[164:165]
	v_lshl_add_u64 v[166:167], v[164:165], 0, s[22:23]
	v_lshl_add_u64 v[168:169], v[2:3], 1, v[166:167]
	flat_load_dwordx4 v[184:187], v[168:169]
	s_and_b64 vcc, exec, s[10:11]
	v_lshl_add_u64 v[164:165], v[164:165], 0, s[24:25]
	s_cbranch_vccz .LBB0_685
	v_lshl_add_u64 v[166:167], v[216:217], 1, v[166:167]
	flat_load_dwordx4 v[180:183], v[166:167]
	s_and_b64 vcc, exec, s[10:11]
	s_cbranch_vccz .LBB0_686
.LBB0_636:
	v_add_u32_e32 v166, 0xa0, v228
	v_mov_b64_e32 v[164:165], s[16:17]
	v_mad_i64_i32 v[164:165], s[4:5], v166, s58, v[164:165]
	v_lshl_add_u64 v[166:167], v[164:165], 0, s[22:23]
	v_lshl_add_u64 v[168:169], v[2:3], 1, v[166:167]
	flat_load_dwordx4 v[176:179], v[168:169]
	s_and_b64 vcc, exec, s[10:11]
	v_lshl_add_u64 v[164:165], v[164:165], 0, s[24:25]
	s_cbranch_vccz .LBB0_687
	v_lshl_add_u64 v[166:167], v[216:217], 1, v[166:167]
	flat_load_dwordx4 v[172:175], v[166:167]
	s_and_b64 vcc, exec, s[10:11]
	s_cbranch_vccz .LBB0_688
.LBB0_638:
	v_add_u32_e32 v166, 0xb0, v228
	v_mov_b64_e32 v[164:165], s[16:17]
	v_mad_i64_i32 v[166:167], s[4:5], v166, s58, v[164:165]
	v_lshl_add_u64 v[164:165], v[166:167], 0, s[22:23]
	v_lshl_add_u64 v[168:169], v[2:3], 1, v[164:165]
	flat_load_dwordx4 v[168:171], v[168:169]
	s_and_b64 vcc, exec, s[10:11]
	v_lshl_add_u64 v[220:221], v[166:167], 0, s[24:25]
	s_cbranch_vccz .LBB0_689
	v_lshl_add_u64 v[164:165], v[216:217], 1, v[164:165]
	flat_load_dwordx4 v[164:167], v[164:165]
	s_and_b64 vcc, exec, s[10:11]
	s_cbranch_vccz .LBB0_690
.LBB0_640:
	s_waitcnt vmcnt(0) lgkmcnt(0)
	v_lshlrev_b32_e32 v216, 16, v192
	v_lshlrev_b32_e32 v228, 16, v194
	v_and_b32_e32 v217, 0xffff0000, v192
	v_max_f32_e32 v192, v216, v216
	v_max_f32_e32 v216, v228, v228
	v_max_f32_e32 v216, 0xc2700000, v216
	v_and_b32_e32 v229, 0xffff0000, v194
	v_mul_f32_e32 v216, 0xbfb8aa3b, v216
	v_exp_f32_e32 v228, v216
	v_max_f32_e32 v216, v229, v229
	v_max_f32_e32 v216, 0xc2700000, v216
	v_lshlrev_b32_e32 v230, 16, v195
	v_mul_f32_e32 v216, 0xbfb8aa3b, v216
	v_exp_f32_e32 v229, v216
	v_max_f32_e32 v216, v230, v230
	v_max_f32_e32 v216, 0xc2700000, v216
	v_lshlrev_b32_e32 v220, 16, v193
	v_and_b32_e32 v221, 0xffff0000, v193
	v_and_b32_e32 v231, 0xffff0000, v195
	v_mul_f32_e32 v216, 0xbfb8aa3b, v216
	v_max_f32_e32 v193, v217, v217
	v_max_f32_e32 v194, v220, v220
	v_max_f32_e32 v195, v221, v221
	v_exp_f32_e32 v230, v216
	v_max_f32_e32 v216, v231, v231
	v_max_f32_e32 v192, 0xc2700000, v192
	v_max_f32_e32 v193, 0xc2700000, v193
	v_max_f32_e32 v194, 0xc2700000, v194
	v_max_f32_e32 v195, 0xc2700000, v195
	v_max_f32_e32 v216, 0xc2700000, v216
	v_mul_f32_e32 v192, 0xbfb8aa3b, v192
	v_mul_f32_e32 v193, 0xbfb8aa3b, v193
	v_mul_f32_e32 v194, 0xbfb8aa3b, v194
	v_mul_f32_e32 v195, 0xbfb8aa3b, v195
	v_mul_f32_e32 v216, 0xbfb8aa3b, v216
	v_exp_f32_e32 v192, v192
	v_exp_f32_e32 v193, v193
	v_exp_f32_e32 v194, v194
	v_exp_f32_e32 v195, v195
	v_exp_f32_e32 v231, v216
	v_pk_add_f32 v[220:221], v[192:193], 1.0 op_sel_hi:[1,0]
	v_pk_add_f32 v[192:193], v[228:229], 1.0 op_sel_hi:[1,0]
	v_pk_add_f32 v[216:217], v[194:195], 1.0 op_sel_hi:[1,0]
	v_pk_add_f32 v[194:195], v[230:231], 1.0 op_sel_hi:[1,0]
	s_and_b64 vcc, exec, s[8:9]
	s_mov_b64 s[10:11], -1
	s_cbranch_vccnz .LBB0_642
	v_rcp_f32_e32 v228, v220
	v_rcp_f32_e32 v229, v221
	v_rcp_f32_e32 v230, v216
	v_rcp_f32_e32 v232, v192
	v_rcp_f32_e32 v233, v193
	v_rcp_f32_e32 v231, v217
	v_rcp_f32_e32 v234, v194
	v_rcp_f32_e32 v235, v195
	v_mul_f32_e32 v228, v64, v228
	v_mul_f32_e32 v229, v65, v229
	v_mul_f32_e32 v230, v66, v230
	v_mul_f32_e32 v232, v60, v232
	v_mul_f32_e32 v233, v61, v233
	v_mul_f32_e32 v231, v67, v231
	v_cvt_pk_bf16_f32 v228, v228, v229
	v_cvt_pk_bf16_f32 v229, v230, v231
	v_cvt_pk_bf16_f32 v230, v232, v233
	v_lshl_add_u64 v[232:233], v[2:3], 1, v[218:219]
	s_mov_b64 s[10:11], 0
	v_mul_f32_e32 v234, v62, v234
	v_mul_f32_e32 v235, v63, v235
	v_cvt_pk_bf16_f32 v231, v234, v235
	flat_store_dwordx4 v[232:233], v[228:231]

.LBB0_644:
	v_lshlrev_b32_e32 v160, 16, v188
	v_and_b32_e32 v161, 0xffff0000, v188
	v_lshlrev_b32_e32 v188, 16, v190
	v_max_f32_e32 v188, v188, v188
	v_max_f32_e32 v188, 0xc2700000, v188
	v_lshlrev_b32_e32 v162, 16, v189
	v_and_b32_e32 v163, 0xffff0000, v189
	v_and_b32_e32 v189, 0xffff0000, v190
	v_mul_f32_e32 v188, 0xbfb8aa3b, v188
	v_exp_f32_e32 v192, v188
	v_max_f32_e32 v188, v189, v189
	v_max_f32_e32 v188, 0xc2700000, v188
	v_lshlrev_b32_e32 v190, 16, v191
	v_mul_f32_e32 v188, 0xbfb8aa3b, v188
	v_exp_f32_e32 v193, v188
	v_max_f32_e32 v188, v190, v190
	v_max_f32_e32 v188, 0xc2700000, v188
	v_and_b32_e32 v191, 0xffff0000, v191
	v_mul_f32_e32 v188, 0xbfb8aa3b, v188
	v_max_f32_e32 v160, v160, v160
	v_max_f32_e32 v161, v161, v161
	v_max_f32_e32 v162, v162, v162
	v_max_f32_e32 v163, v163, v163
	v_exp_f32_e32 v194, v188
	v_max_f32_e32 v188, v191, v191
	v_max_f32_e32 v160, 0xc2700000, v160
	v_max_f32_e32 v161, 0xc2700000, v161
	v_max_f32_e32 v162, 0xc2700000, v162
	v_max_f32_e32 v163, 0xc2700000, v163
	v_max_f32_e32 v188, 0xc2700000, v188
	v_mul_f32_e32 v160, 0xbfb8aa3b, v160
	v_mul_f32_e32 v161, 0xbfb8aa3b, v161
	v_mul_f32_e32 v162, 0xbfb8aa3b, v162
	v_mul_f32_e32 v163, 0xbfb8aa3b, v163
	v_mul_f32_e32 v188, 0xbfb8aa3b, v188
	v_exp_f32_e32 v160, v160
	v_exp_f32_e32 v161, v161
	v_exp_f32_e32 v162, v162
	v_exp_f32_e32 v163, v163
	v_exp_f32_e32 v195, v188
	v_pk_add_f32 v[190:191], v[160:161], 1.0 op_sel_hi:[1,0]
	v_pk_add_f32 v[160:161], v[192:193], 1.0 op_sel_hi:[1,0]
	v_pk_add_f32 v[188:189], v[162:163], 1.0 op_sel_hi:[1,0]
	v_pk_add_f32 v[162:163], v[194:195], 1.0 op_sel_hi:[1,0]
	s_and_b64 vcc, exec, s[8:9]
	s_mov_b64 s[10:11], -1
	s_cbranch_vccnz .LBB0_646
	v_rcp_f32_e32 v192, v190
	v_rcp_f32_e32 v193, v191
	v_rcp_f32_e32 v194, v188
	v_rcp_f32_e32 v216, v160
	v_rcp_f32_e32 v217, v161
	v_rcp_f32_e32 v195, v189
	v_rcp_f32_e32 v220, v162
	v_rcp_f32_e32 v221, v163
	v_mul_f32_e32 v192, v32, v192
	v_mul_f32_e32 v193, v33, v193
	v_mul_f32_e32 v194, v34, v194
	v_mul_f32_e32 v216, v28, v216
	v_mul_f32_e32 v217, v29, v217
	v_mul_f32_e32 v195, v35, v195
	v_cvt_pk_bf16_f32 v192, v192, v193
	v_cvt_pk_bf16_f32 v193, v194, v195
	v_cvt_pk_bf16_f32 v194, v216, v217
	v_lshl_add_u64 v[216:217], v[214:215], 1, v[218:219]
	s_mov_b64 s[10:11], 0
	v_mul_f32_e32 v220, v30, v220
	v_mul_f32_e32 v221, v31, v221
	v_cvt_pk_bf16_f32 v195, v220, v221
	flat_store_dwordx4 v[216:217], v[192:195]

.LBB0_648:
	v_lshlrev_b32_e32 v160, 16, v186
	v_max_f32_e32 v160, v160, v160
	v_max_f32_e32 v160, 0xc2700000, v160
	v_and_b32_e32 v161, 0xffff0000, v186
	v_mul_f32_e32 v160, 0xbfb8aa3b, v160
	v_lshlrev_b32_e32 v156, 16, v184
	v_and_b32_e32 v157, 0xffff0000, v184
	v_exp_f32_e32 v184, v160
	v_max_f32_e32 v160, v161, v161
	v_max_f32_e32 v160, 0xc2700000, v160
	v_lshlrev_b32_e32 v162, 16, v187
	v_mul_f32_e32 v160, 0xbfb8aa3b, v160
	v_lshlrev_b32_e32 v158, 16, v185
	v_and_b32_e32 v159, 0xffff0000, v185
	v_exp_f32_e32 v185, v160
	v_max_f32_e32 v160, v162, v162
	v_max_f32_e32 v160, 0xc2700000, v160
	v_and_b32_e32 v163, 0xffff0000, v187
	v_mul_f32_e32 v160, 0xbfb8aa3b, v160
	v_max_f32_e32 v156, v156, v156
	v_max_f32_e32 v157, v157, v157
	v_max_f32_e32 v158, v158, v158
	v_max_f32_e32 v159, v159, v159
	v_exp_f32_e32 v186, v160
	v_max_f32_e32 v160, v163, v163
	v_max_f32_e32 v156, 0xc2700000, v156
	v_max_f32_e32 v157, 0xc2700000, v157
	v_max_f32_e32 v158, 0xc2700000, v158
	v_max_f32_e32 v159, 0xc2700000, v159
	v_max_f32_e32 v160, 0xc2700000, v160
	v_mul_f32_e32 v156, 0xbfb8aa3b, v156
	v_mul_f32_e32 v157, 0xbfb8aa3b, v157
	v_mul_f32_e32 v158, 0xbfb8aa3b, v158
	v_mul_f32_e32 v159, 0xbfb8aa3b, v159
	v_mul_f32_e32 v160, 0xbfb8aa3b, v160
	v_exp_f32_e32 v156, v156
	v_exp_f32_e32 v157, v157
	v_exp_f32_e32 v158, v158
	v_exp_f32_e32 v159, v159
	v_exp_f32_e32 v187, v160
	v_add_u32_e32 v188, 0x90, v1
	v_pk_add_f32 v[162:163], v[156:157], 1.0 op_sel_hi:[1,0]
	v_pk_add_f32 v[160:161], v[158:159], 1.0 op_sel_hi:[1,0]
	v_pk_add_f32 v[156:157], v[184:185], 1.0 op_sel_hi:[1,0]
	v_pk_add_f32 v[158:159], v[186:187], 1.0 op_sel_hi:[1,0]
	s_mov_b64 s[10:11], -1
	s_and_b64 vcc, exec, s[8:9]
	v_add_u32_e32 v184, s27, v188
	s_cbranch_vccnz .LBB0_650
	v_rcp_f32_e32 v187, v160
	v_rcp_f32_e32 v188, v161
	v_rcp_f32_e32 v189, v156
	v_rcp_f32_e32 v190, v157
	v_rcp_f32_e32 v191, v158
	v_rcp_f32_e32 v192, v159
	v_rcp_f32_e32 v186, v163
	v_rcp_f32_e32 v185, v162
	v_mul_f32_e32 v187, v58, v187
	v_mul_f32_e32 v188, v59, v188
	v_mul_f32_e32 v189, v52, v189
	v_mul_f32_e32 v190, v53, v190
	v_mul_f32_e32 v191, v54, v191
	v_mul_f32_e32 v192, v55, v192
	v_cvt_pk_bf16_f32 v187, v187, v188
	v_cvt_pk_bf16_f32 v188, v189, v190
	v_cvt_pk_bf16_f32 v189, v191, v192
	v_mov_b64_e32 v[190:191], s[16:17]
	v_mad_i64_i32 v[190:191], s[4:5], v184, s58, v[190:191]
	v_mul_f32_e32 v186, v57, v186
	v_lshl_add_u64 v[190:191], v[2:3], 1, v[190:191]
	s_mov_b64 s[10:11], 0
	v_mul_f32_e32 v185, v56, v185
	v_cvt_pk_bf16_f32 v186, v185, v186
	flat_store_dwordx4 v[190:191], v[186:189]

.LBB0_652:
	v_lshlrev_b32_e32 v156, 16, v182
	v_max_f32_e32 v156, v156, v156
	v_max_f32_e32 v156, 0xc2700000, v156
	v_and_b32_e32 v157, 0xffff0000, v182
	v_mul_f32_e32 v156, 0xbfb8aa3b, v156
	v_exp_f32_e32 v160, v156
	v_max_f32_e32 v156, v157, v157
	v_max_f32_e32 v156, 0xc2700000, v156
	v_lshlrev_b32_e32 v158, 16, v183
	v_mul_f32_e32 v156, 0xbfb8aa3b, v156
	v_exp_f32_e32 v161, v156
	v_max_f32_e32 v156, v158, v158
	v_max_f32_e32 v156, 0xc2700000, v156
	v_lshlrev_b32_e32 v152, 16, v180
	v_and_b32_e32 v153, 0xffff0000, v180
	v_lshlrev_b32_e32 v154, 16, v181
	v_and_b32_e32 v155, 0xffff0000, v181
	v_and_b32_e32 v159, 0xffff0000, v183
	v_mul_f32_e32 v156, 0xbfb8aa3b, v156
	v_max_f32_e32 v152, v152, v152
	v_max_f32_e32 v153, v153, v153
	v_max_f32_e32 v154, v154, v154
	v_max_f32_e32 v155, v155, v155
	v_exp_f32_e32 v162, v156
	v_max_f32_e32 v156, v159, v159
	v_max_f32_e32 v152, 0xc2700000, v152
	v_max_f32_e32 v153, 0xc2700000, v153
	v_max_f32_e32 v154, 0xc2700000, v154
	v_max_f32_e32 v155, 0xc2700000, v155
	v_max_f32_e32 v156, 0xc2700000, v156
	v_mul_f32_e32 v152, 0xbfb8aa3b, v152
	v_mul_f32_e32 v153, 0xbfb8aa3b, v153
	v_mul_f32_e32 v154, 0xbfb8aa3b, v154
	v_mul_f32_e32 v155, 0xbfb8aa3b, v155
	v_mul_f32_e32 v156, 0xbfb8aa3b, v156
	v_exp_f32_e32 v152, v152
	v_exp_f32_e32 v153, v153
	v_exp_f32_e32 v154, v154
	v_exp_f32_e32 v155, v155
	v_exp_f32_e32 v163, v156
	v_pk_add_f32 v[158:159], v[152:153], 1.0 op_sel_hi:[1,0]
	v_pk_add_f32 v[152:153], v[160:161], 1.0 op_sel_hi:[1,0]
	v_pk_add_f32 v[156:157], v[154:155], 1.0 op_sel_hi:[1,0]
	v_pk_add_f32 v[154:155], v[162:163], 1.0 op_sel_hi:[1,0]
	s_and_b64 vcc, exec, s[8:9]
	s_mov_b64 s[10:11], -1
	s_cbranch_vccnz .LBB0_654
	v_rcp_f32_e32 v160, v158
	v_rcp_f32_e32 v161, v159
	v_rcp_f32_e32 v162, v156
	v_rcp_f32_e32 v180, v152
	v_rcp_f32_e32 v181, v153
	v_rcp_f32_e32 v163, v157
	v_mul_f32_e32 v160, v24, v160
	v_mul_f32_e32 v161, v25, v161
	v_mul_f32_e32 v162, v26, v162
	v_rcp_f32_e32 v182, v154
	v_rcp_f32_e32 v183, v155
	v_mul_f32_e32 v180, v20, v180
	v_mul_f32_e32 v181, v21, v181
	v_mul_f32_e32 v163, v27, v163
	v_cvt_pk_bf16_f32 v160, v160, v161
	v_cvt_pk_bf16_f32 v161, v162, v163
	v_cvt_pk_bf16_f32 v162, v180, v181
	v_mov_b64_e32 v[180:181], s[16:17]
	v_mad_i64_i32 v[180:181], s[4:5], v184, s58, v[180:181]
	v_lshl_add_u64 v[180:181], v[214:215], 1, v[180:181]
	s_mov_b64 s[10:11], 0
	v_mul_f32_e32 v182, v22, v182
	v_mul_f32_e32 v183, v23, v183
	v_cvt_pk_bf16_f32 v163, v182, v183
	flat_store_dwordx4 v[180:181], v[160:163]

.LBB0_656:
	v_lshlrev_b32_e32 v152, 16, v178
	v_max_f32_e32 v152, v152, v152
	v_max_f32_e32 v152, 0xc2700000, v152
	v_and_b32_e32 v153, 0xffff0000, v178
	v_mul_f32_e32 v152, 0xbfb8aa3b, v152
	v_exp_f32_e32 v156, v152
	v_max_f32_e32 v152, v153, v153
	v_max_f32_e32 v152, 0xc2700000, v152
	v_lshlrev_b32_e32 v154, 16, v179
	v_mul_f32_e32 v152, 0xbfb8aa3b, v152
	v_exp_f32_e32 v157, v152
	v_max_f32_e32 v152, v154, v154
	v_max_f32_e32 v152, 0xc2700000, v152
	v_lshlrev_b32_e32 v148, 16, v176
	v_and_b32_e32 v149, 0xffff0000, v176
	v_lshlrev_b32_e32 v150, 16, v177
	v_and_b32_e32 v151, 0xffff0000, v177
	v_and_b32_e32 v155, 0xffff0000, v179
	v_mul_f32_e32 v152, 0xbfb8aa3b, v152
	v_max_f32_e32 v148, v148, v148
	v_max_f32_e32 v149, v149, v149
	v_max_f32_e32 v150, v150, v150
	v_max_f32_e32 v151, v151, v151
	v_exp_f32_e32 v158, v152
	v_max_f32_e32 v152, v155, v155
	v_max_f32_e32 v148, 0xc2700000, v148
	v_max_f32_e32 v149, 0xc2700000, v149
	v_max_f32_e32 v150, 0xc2700000, v150
	v_max_f32_e32 v151, 0xc2700000, v151
	v_max_f32_e32 v152, 0xc2700000, v152
	v_mul_f32_e32 v148, 0xbfb8aa3b, v148
	v_mul_f32_e32 v149, 0xbfb8aa3b, v149
	v_mul_f32_e32 v150, 0xbfb8aa3b, v150
	v_mul_f32_e32 v151, 0xbfb8aa3b, v151
	v_mul_f32_e32 v152, 0xbfb8aa3b, v152
	v_exp_f32_e32 v148, v148
	v_exp_f32_e32 v149, v149
	v_exp_f32_e32 v150, v150
	v_exp_f32_e32 v151, v151
	v_exp_f32_e32 v159, v152
	v_add_u32_e32 v160, 0xa0, v1
	v_pk_add_f32 v[154:155], v[148:149], 1.0 op_sel_hi:[1,0]
	v_pk_add_f32 v[152:153], v[150:151], 1.0 op_sel_hi:[1,0]
	v_pk_add_f32 v[148:149], v[156:157], 1.0 op_sel_hi:[1,0]
	v_pk_add_f32 v[150:151], v[158:159], 1.0 op_sel_hi:[1,0]
	s_mov_b64 s[10:11], -1
	s_and_b64 vcc, exec, s[8:9]
	v_add_u32_e32 v156, s27, v160
	s_cbranch_vccnz .LBB0_658
	v_rcp_f32_e32 v159, v152
	v_rcp_f32_e32 v160, v153
	v_rcp_f32_e32 v161, v148
	v_rcp_f32_e32 v162, v149
	v_rcp_f32_e32 v163, v150
	v_rcp_f32_e32 v176, v151
	v_rcp_f32_e32 v158, v155
	v_rcp_f32_e32 v157, v154
	v_mul_f32_e32 v159, v50, v159
	v_mul_f32_e32 v160, v51, v160
	v_mul_f32_e32 v161, v44, v161
	v_mul_f32_e32 v162, v45, v162
	v_mul_f32_e32 v163, v46, v163
	v_mul_f32_e32 v176, v47, v176
	v_cvt_pk_bf16_f32 v159, v159, v160
	v_cvt_pk_bf16_f32 v160, v161, v162
	v_cvt_pk_bf16_f32 v161, v163, v176
	v_mov_b64_e32 v[162:163], s[16:17]
	v_mad_i64_i32 v[162:163], s[4:5], v156, s58, v[162:163]
	v_mul_f32_e32 v158, v49, v158
	v_lshl_add_u64 v[162:163], v[2:3], 1, v[162:163]
	s_mov_b64 s[10:11], 0
	v_mul_f32_e32 v157, v48, v157
	v_cvt_pk_bf16_f32 v158, v157, v158
	flat_store_dwordx4 v[162:163], v[158:161]

.LBB0_660:
	v_lshlrev_b32_e32 v148, 16, v174
	v_max_f32_e32 v148, v148, v148
	v_max_f32_e32 v148, 0xc2700000, v148
	v_and_b32_e32 v149, 0xffff0000, v174
	v_mul_f32_e32 v148, 0xbfb8aa3b, v148
	v_exp_f32_e32 v152, v148
	v_max_f32_e32 v148, v149, v149
	v_max_f32_e32 v148, 0xc2700000, v148
	v_lshlrev_b32_e32 v150, 16, v175
	v_mul_f32_e32 v148, 0xbfb8aa3b, v148
	v_exp_f32_e32 v153, v148
	v_max_f32_e32 v148, v150, v150
	v_max_f32_e32 v148, 0xc2700000, v148
	v_lshlrev_b32_e32 v144, 16, v172
	v_and_b32_e32 v145, 0xffff0000, v172
	v_lshlrev_b32_e32 v146, 16, v173
	v_and_b32_e32 v147, 0xffff0000, v173
	v_and_b32_e32 v151, 0xffff0000, v175
	v_mul_f32_e32 v148, 0xbfb8aa3b, v148
	v_max_f32_e32 v144, v144, v144
	v_max_f32_e32 v145, v145, v145
	v_max_f32_e32 v146, v146, v146
	v_max_f32_e32 v147, v147, v147
	v_exp_f32_e32 v154, v148
	v_max_f32_e32 v148, v151, v151
	v_max_f32_e32 v144, 0xc2700000, v144
	v_max_f32_e32 v145, 0xc2700000, v145
	v_max_f32_e32 v146, 0xc2700000, v146
	v_max_f32_e32 v147, 0xc2700000, v147
	v_max_f32_e32 v148, 0xc2700000, v148
	v_mul_f32_e32 v144, 0xbfb8aa3b, v144
	v_mul_f32_e32 v145, 0xbfb8aa3b, v145
	v_mul_f32_e32 v146, 0xbfb8aa3b, v146
	v_mul_f32_e32 v147, 0xbfb8aa3b, v147
	v_mul_f32_e32 v148, 0xbfb8aa3b, v148
	v_exp_f32_e32 v144, v144
	v_exp_f32_e32 v145, v145
	v_exp_f32_e32 v146, v146
	v_exp_f32_e32 v147, v147
	v_exp_f32_e32 v155, v148
	v_pk_add_f32 v[150:151], v[144:145], 1.0 op_sel_hi:[1,0]
	v_pk_add_f32 v[144:145], v[152:153], 1.0 op_sel_hi:[1,0]
	v_pk_add_f32 v[148:149], v[146:147], 1.0 op_sel_hi:[1,0]
	v_pk_add_f32 v[146:147], v[154:155], 1.0 op_sel_hi:[1,0]
	s_and_b64 vcc, exec, s[8:9]
	s_mov_b64 s[10:11], -1
	s_cbranch_vccnz .LBB0_662
	v_rcp_f32_e32 v152, v150
	v_rcp_f32_e32 v153, v151
	v_rcp_f32_e32 v154, v148
	v_rcp_f32_e32 v155, v149
	v_rcp_f32_e32 v158, v145
	v_rcp_f32_e32 v159, v146
	v_rcp_f32_e32 v157, v144
	v_rcp_f32_e32 v160, v147
	v_mul_f32_e32 v152, v16, v152
	v_mul_f32_e32 v153, v17, v153
	v_mul_f32_e32 v154, v18, v154
	v_mul_f32_e32 v155, v19, v155
	v_mul_f32_e32 v158, v13, v158
	v_mul_f32_e32 v159, v14, v159
	v_mul_f32_e32 v157, v12, v157
	v_mul_f32_e32 v160, v15, v160
	v_cvt_pk_bf16_f32 v152, v152, v153
	v_cvt_pk_bf16_f32 v153, v154, v155
	v_cvt_pk_bf16_f32 v154, v157, v158
	v_cvt_pk_bf16_f32 v155, v159, v160
	v_mov_b64_e32 v[158:159], s[16:17]
	v_mad_i64_i32 v[156:157], s[4:5], v156, s58, v[158:159]
	v_lshl_add_u64 v[156:157], v[214:215], 1, v[156:157]
	s_mov_b64 s[10:11], 0
	flat_store_dwordx4 v[156:157], v[152:155]

.LBB0_664:
	v_lshlrev_b32_e32 v144, 16, v170
	v_max_f32_e32 v144, v144, v144
	v_max_f32_e32 v144, 0xc2700000, v144
	v_and_b32_e32 v145, 0xffff0000, v170
	v_mul_f32_e32 v144, 0xbfb8aa3b, v144
	v_exp_f32_e32 v148, v144
	v_max_f32_e32 v144, v145, v145
	v_max_f32_e32 v144, 0xc2700000, v144
	v_lshlrev_b32_e32 v146, 16, v171
	v_mul_f32_e32 v144, 0xbfb8aa3b, v144
	v_exp_f32_e32 v149, v144
	v_max_f32_e32 v144, v146, v146
	v_max_f32_e32 v144, 0xc2700000, v144
	v_lshlrev_b32_e32 v140, 16, v168
	v_and_b32_e32 v141, 0xffff0000, v168
	v_lshlrev_b32_e32 v142, 16, v169
	v_and_b32_e32 v143, 0xffff0000, v169
	v_and_b32_e32 v147, 0xffff0000, v171
	v_mul_f32_e32 v144, 0xbfb8aa3b, v144
	v_max_f32_e32 v140, v140, v140
	v_max_f32_e32 v141, v141, v141
	v_max_f32_e32 v142, v142, v142
	v_max_f32_e32 v143, v143, v143
	v_exp_f32_e32 v150, v144
	v_max_f32_e32 v144, v147, v147
	v_max_f32_e32 v140, 0xc2700000, v140
	v_max_f32_e32 v141, 0xc2700000, v141
	v_max_f32_e32 v142, 0xc2700000, v142
	v_max_f32_e32 v143, 0xc2700000, v143
	v_max_f32_e32 v144, 0xc2700000, v144
	v_mul_f32_e32 v140, 0xbfb8aa3b, v140
	v_mul_f32_e32 v141, 0xbfb8aa3b, v141
	v_mul_f32_e32 v142, 0xbfb8aa3b, v142
	v_mul_f32_e32 v143, 0xbfb8aa3b, v143
	v_mul_f32_e32 v144, 0xbfb8aa3b, v144
	v_exp_f32_e32 v140, v140
	v_exp_f32_e32 v141, v141
	v_exp_f32_e32 v142, v142
	v_exp_f32_e32 v143, v143
	v_exp_f32_e32 v151, v144
	v_add_u32_e32 v1, 0xb0, v1
	v_pk_add_f32 v[146:147], v[140:141], 1.0 op_sel_hi:[1,0]
	v_pk_add_f32 v[144:145], v[142:143], 1.0 op_sel_hi:[1,0]
	v_pk_add_f32 v[140:141], v[148:149], 1.0 op_sel_hi:[1,0]
	v_pk_add_f32 v[142:143], v[150:151], 1.0 op_sel_hi:[1,0]
	s_mov_b64 s[10:11], -1
	s_and_b64 vcc, exec, s[8:9]
	v_add_u32_e32 v1, s27, v1
	s_cbranch_vccnz .LBB0_666
	v_rcp_f32_e32 v148, v146
	v_rcp_f32_e32 v149, v147
	v_rcp_f32_e32 v150, v144
	v_rcp_f32_e32 v152, v140
	v_rcp_f32_e32 v153, v141
	v_rcp_f32_e32 v151, v145
	v_mul_f32_e32 v148, v40, v148
	v_mul_f32_e32 v149, v41, v149
	v_mul_f32_e32 v150, v42, v150
	v_rcp_f32_e32 v154, v142
	v_rcp_f32_e32 v155, v143
	v_mul_f32_e32 v152, v36, v152
	v_mul_f32_e32 v153, v37, v153
	v_mul_f32_e32 v151, v43, v151
	v_cvt_pk_bf16_f32 v148, v148, v149
	v_cvt_pk_bf16_f32 v149, v150, v151
	v_cvt_pk_bf16_f32 v150, v152, v153
	v_mov_b64_e32 v[152:153], s[16:17]
	v_mad_i64_i32 v[152:153], s[4:5], v1, s58, v[152:153]
	v_lshl_add_u64 v[2:3], v[2:3], 1, v[152:153]
	s_mov_b64 s[10:11], 0
	v_mul_f32_e32 v154, v38, v154
	v_mul_f32_e32 v155, v39, v155
	v_cvt_pk_bf16_f32 v151, v154, v155
	flat_store_dwordx4 v[2:3], v[148:151]

.LBB0_668:
	v_lshlrev_b32_e32 v138, 16, v166
	v_max_f32_e32 v138, v138, v138
	v_max_f32_e32 v138, 0xc2700000, v138
	v_and_b32_e32 v139, 0xffff0000, v166
	v_mul_f32_e32 v138, 0xbfb8aa3b, v138
	v_exp_f32_e32 v142, v138
	v_max_f32_e32 v138, v139, v139
	v_max_f32_e32 v138, 0xc2700000, v138
	v_lshlrev_b32_e32 v140, 16, v167
	v_mul_f32_e32 v138, 0xbfb8aa3b, v138
	v_exp_f32_e32 v143, v138
	v_max_f32_e32 v138, v140, v140
	v_max_f32_e32 v138, 0xc2700000, v138
	v_lshlrev_b32_e32 v2, 16, v164
	v_and_b32_e32 v3, 0xffff0000, v164
	v_lshlrev_b32_e32 v136, 16, v165
	v_and_b32_e32 v137, 0xffff0000, v165
	v_and_b32_e32 v141, 0xffff0000, v167
	v_mul_f32_e32 v138, 0xbfb8aa3b, v138
	v_max_f32_e32 v2, v2, v2
	v_max_f32_e32 v3, v3, v3
	v_max_f32_e32 v136, v136, v136
	v_max_f32_e32 v137, v137, v137
	v_exp_f32_e32 v144, v138
	v_max_f32_e32 v138, v141, v141
	v_max_f32_e32 v2, 0xc2700000, v2
	v_max_f32_e32 v3, 0xc2700000, v3
	v_max_f32_e32 v136, 0xc2700000, v136
	v_max_f32_e32 v137, 0xc2700000, v137
	v_max_f32_e32 v138, 0xc2700000, v138
	v_mul_f32_e32 v2, 0xbfb8aa3b, v2
	v_mul_f32_e32 v3, 0xbfb8aa3b, v3
	v_mul_f32_e32 v136, 0xbfb8aa3b, v136
	v_mul_f32_e32 v137, 0xbfb8aa3b, v137
	v_mul_f32_e32 v138, 0xbfb8aa3b, v138
	v_exp_f32_e32 v2, v2
	v_exp_f32_e32 v3, v3
	v_exp_f32_e32 v136, v136
	v_exp_f32_e32 v137, v137
	v_exp_f32_e32 v145, v138
	v_pk_add_f32 v[140:141], v[2:3], 1.0 op_sel_hi:[1,0]
	v_pk_add_f32 v[2:3], v[142:143], 1.0 op_sel_hi:[1,0]
	v_pk_add_f32 v[138:139], v[136:137], 1.0 op_sel_hi:[1,0]
	v_pk_add_f32 v[136:137], v[144:145], 1.0 op_sel_hi:[1,0]
	s_and_b64 vcc, exec, s[8:9]
	s_mov_b64 s[10:11], -1
	s_cbranch_vccnz .LBB0_671
	v_rcp_f32_e32 v142, v140
	v_rcp_f32_e32 v143, v141
	v_rcp_f32_e32 v144, v138
	v_rcp_f32_e32 v146, v2
	v_rcp_f32_e32 v147, v3
	v_rcp_f32_e32 v145, v139
	v_mul_f32_e32 v142, v8, v142
	v_mul_f32_e32 v143, v9, v143
	v_mul_f32_e32 v144, v10, v144
	v_rcp_f32_e32 v148, v136
	v_rcp_f32_e32 v149, v137
	v_mul_f32_e32 v146, v4, v146
	v_mul_f32_e32 v147, v5, v147
	v_mul_f32_e32 v145, v11, v145
	v_cvt_pk_bf16_f32 v142, v142, v143
	v_cvt_pk_bf16_f32 v143, v144, v145
	v_cvt_pk_bf16_f32 v144, v146, v147
	v_mov_b64_e32 v[146:147], s[16:17]
	v_mad_i64_i32 v[146:147], s[4:5], v1, s58, v[146:147]
	v_lshl_add_u64 v[146:147], v[214:215], 1, v[146:147]
	v_mul_f32_e32 v148, v6, v148
	v_mul_f32_e32 v149, v7, v149
	v_cvt_pk_bf16_f32 v145, v148, v149
	flat_store_dwordx4 v[146:147], v[142:145]
	s_cbranch_execz .LBB0_672

.LBB0_677:
	v_lshl_add_u64 v[136:137], v[2:3], 1, v[132:133]
	flat_load_dwordx4 v[152:155], v[136:137]
	v_lshl_add_u64 v[134:135], v[216:217], 1, v[134:135]
	flat_load_dwordx4 v[180:183], v[134:135]
	s_and_b64 vcc, exec, s[10:11]
	s_cbranch_vccnz .LBB0_596
.LBB0_678:
	v_lshl_add_u64 v[132:133], v[216:217], 1, v[132:133]
	flat_load_dwordx4 v[148:151], v[132:133]
	s_branch .LBB0_596
.LBB0_679:
	v_lshl_add_u64 v[136:137], v[2:3], 1, v[132:133]
	flat_load_dwordx4 v[144:147], v[136:137]
	v_lshl_add_u64 v[134:135], v[216:217], 1, v[134:135]
	flat_load_dwordx4 v[172:175], v[134:135]
	s_and_b64 vcc, exec, s[10:11]
	s_cbranch_vccnz .LBB0_598
.LBB0_680:
	v_lshl_add_u64 v[132:133], v[216:217], 1, v[132:133]
	flat_load_dwordx4 v[140:143], v[132:133]
	s_branch .LBB0_598
.LBB0_681:
	v_lshl_add_u64 v[134:135], v[2:3], 1, v[214:215]
	flat_load_dwordx4 v[136:139], v[134:135]
	v_lshl_add_u64 v[132:133], v[216:217], 1, v[132:133]
	flat_load_dwordx4 v[164:167], v[132:133]
	s_and_b64 vcc, exec, s[10:11]
	s_cbranch_vccnz .LBB0_600
.LBB0_682:
	v_lshl_add_u64 v[132:133], v[216:217], 1, v[214:215]
	flat_load_dwordx4 v[132:135], v[132:133]
	s_branch .LBB0_600
.LBB0_683:
	v_lshl_add_u64 v[160:161], v[2:3], 1, v[164:165]
	flat_load_dwordx4 v[160:163], v[160:161]
	v_lshl_add_u64 v[166:167], v[216:217], 1, v[166:167]
	flat_load_dwordx4 v[188:191], v[166:167]
	s_and_b64 vcc, exec, s[10:11]
	s_cbranch_vccnz .LBB0_634
.LBB0_684:
	v_lshl_add_u64 v[156:157], v[216:217], 1, v[164:165]
	flat_load_dwordx4 v[156:159], v[156:157]
	s_branch .LBB0_634
.LBB0_685:
	v_lshl_add_u64 v[152:153], v[2:3], 1, v[164:165]
	flat_load_dwordx4 v[152:155], v[152:153]
	v_lshl_add_u64 v[166:167], v[216:217], 1, v[166:167]
	flat_load_dwordx4 v[180:183], v[166:167]
	s_and_b64 vcc, exec, s[10:11]
	s_cbranch_vccnz .LBB0_636
.LBB0_686:
	v_lshl_add_u64 v[148:149], v[216:217], 1, v[164:165]
	flat_load_dwordx4 v[148:151], v[148:149]
	s_branch .LBB0_636
.LBB0_687:
	v_lshl_add_u64 v[144:145], v[2:3], 1, v[164:165]
	flat_load_dwordx4 v[144:147], v[144:145]
	v_lshl_add_u64 v[166:167], v[216:217], 1, v[166:167]
	flat_load_dwordx4 v[172:175], v[166:167]
	s_and_b64 vcc, exec, s[10:11]
	s_cbranch_vccnz .LBB0_638
.LBB0_688:
	v_lshl_add_u64 v[140:141], v[216:217], 1, v[164:165]
	flat_load_dwordx4 v[140:143], v[140:141]
	s_branch .LBB0_638
.LBB0_689:
	v_lshl_add_u64 v[136:137], v[2:3], 1, v[220:221]
	flat_load_dwordx4 v[136:139], v[136:137]
	v_lshl_add_u64 v[164:165], v[216:217], 1, v[164:165]
	flat_load_dwordx4 v[164:167], v[164:165]
	s_and_b64 vcc, exec, s[10:11]
	s_cbranch_vccnz .LBB0_640
.LBB0_690:
	v_lshl_add_u64 v[132:133], v[216:217], 1, v[220:221]
	flat_load_dwordx4 v[132:135], v[132:133]
	s_branch .LBB0_640

.LBB0_757:
	s_ashr_i32 s4, s16, 5
	s_mul_hi_i32 s5, s4, 0x6000
	s_mulk_i32 s4, 0x6000
	s_add_u32 s23, s51, s4
	s_addc_u32 s28, s52, s5
	s_lshl_b32 s8, s63, 8
	s_ashr_i32 s9, s8, 31
	s_lshl_b64 s[4:5], s[8:9], 2
	s_add_u32 s23, s23, s4
	s_addc_u32 s29, s28, s5
	s_lshl_b32 s28, s54, 2
	s_add_u32 s28, s23, s28
	v_mov_b32_e32 v132, v166
	v_mov_b32_e32 v128, v167
	s_addc_u32 s29, s29, 0
	s_lshl_b32 s16, s16, 8
	s_add_i32 s16, s16, s53
	v_lshlrev_b32_e32 v160, 3, v128
	v_ashrrev_i32_e32 v161, 31, v160
	v_add_u32_e32 v164, s16, v132
	s_add_u32 s4, s57, s4
	v_lshlrev_b64 v[128:129], 2, v[160:161]
	s_addc_u32 s5, s58, s5
	v_ashrrev_i32_e32 v165, 31, v164
	v_lshl_add_u64 v[130:131], s[28:29], 0, v[128:129]
	v_lshl_add_u64 v[162:163], s[4:5], 0, v[128:129]
	v_lshlrev_b64 v[128:129], 12, v[164:165]
	v_lshl_add_u64 v[184:185], v[162:163], 0, v[128:129]
	v_add_u32_e32 v232, 16, v164
	flat_load_dwordx4 v[172:175], v[184:185]
	flat_load_dwordx4 v[140:143], v[130:131]
	flat_load_dwordx4 v[136:139], v[130:131] offset:16
	flat_load_dwordx4 v[176:179], v[184:185] offset:16
	flat_load_dwordx4 v[180:183], v[184:185] offset:512
	flat_load_dwordx4 v[132:135], v[130:131] offset:512
	s_nop 0
	flat_load_dwordx4 v[128:131], v[130:131] offset:528
	s_nop 0
	flat_load_dwordx4 v[184:187], v[184:185] offset:528
	v_ashrrev_i32_e32 v233, 31, v232
	v_lshlrev_b64 v[188:189], 12, v[232:233]
	v_lshl_add_u64 v[202:203], v[162:163], 0, v[188:189]
	flat_load_dwordx4 v[188:191], v[202:203]
	flat_load_dwordx4 v[192:195], v[202:203] offset:16
	flat_load_dwordx4 v[198:201], v[202:203] offset:512
	s_nop 0
	flat_load_dwordx4 v[202:205], v[202:203] offset:528
	v_add_u32_e32 v240, 32, v164
	v_ashrrev_i32_e32 v241, 31, v240
	v_lshlrev_b64 v[206:207], 12, v[240:241]
	v_lshl_add_u64 v[218:219], v[162:163], 0, v[206:207]
	flat_load_dwordx4 v[206:209], v[218:219]
	flat_load_dwordx4 v[210:213], v[218:219] offset:16
	flat_load_dwordx4 v[214:217], v[218:219] offset:512
	s_nop 0
	flat_load_dwordx4 v[218:221], v[218:219] offset:528
	v_add_u32_e32 v242, 48, v164
	v_ashrrev_i32_e32 v243, 31, v242
	v_lshlrev_b64 v[224:225], 12, v[242:243]
	v_lshl_add_u64 v[236:237], v[162:163], 0, v[224:225]
	v_lshlrev_b64 v[234:235], 11, v[164:165]
	flat_load_dwordx4 v[224:227], v[236:237]
	flat_load_dwordx4 v[228:231], v[236:237] offset:16
	s_lshl_b64 s[8:9], s[8:9], 1
	v_lshl_add_u64 v[234:235], s[12:13], 0, v[234:235]
	v_lshlrev_b64 v[232:233], 11, v[232:233]
	v_lshl_add_u64 v[244:245], v[234:235], 0, s[8:9]
	v_lshl_add_u64 v[246:247], s[12:13], 0, v[232:233]
	flat_load_dwordx4 v[232:235], v[236:237] offset:512
	s_nop 0
	flat_load_dwordx4 v[236:239], v[236:237] offset:528
	s_lshl_b32 s16, s54, 1
	v_lshlrev_b64 v[160:161], 1, v[160:161]
	v_lshl_add_u64 v[244:245], v[244:245], 0, s[16:17]
	v_lshl_add_u64 v[246:247], v[246:247], 0, s[8:9]
	v_lshl_add_u64 v[244:245], v[244:245], 0, v[160:161]
	s_and_b64 vcc, exec, s[6:7]
	s_mov_b64 s[6:7], -1
	s_waitcnt vmcnt(0) lgkmcnt(0)
	v_pk_fma_f32 v[126:127], v[126:127], v[142:143], v[174:175]
	v_pk_fma_f32 v[124:125], v[124:125], v[140:141], v[172:173]
	v_pk_fma_f32 v[122:123], v[122:123], v[138:139], v[178:179]
	v_pk_fma_f32 v[120:121], v[120:121], v[136:137], v[176:177]
	v_pk_fma_f32 v[108:109], v[108:109], v[132:133], v[180:181]
	v_pk_fma_f32 v[110:111], v[110:111], v[134:135], v[182:183]
	v_pk_fma_f32 v[172:173], v[106:107], v[130:131], v[186:187]
	v_pk_fma_f32 v[174:175], v[104:105], v[128:129], v[184:185]
	v_cvt_pk_bf16_f32 v104, v124, v125
	v_cvt_pk_bf16_f32 v105, v126, v127
	v_cvt_pk_bf16_f32 v106, v120, v121
	v_cvt_pk_bf16_f32 v107, v122, v123
	v_cvt_pk_bf16_f32 v108, v108, v109
	v_cvt_pk_bf16_f32 v109, v110, v111
	s_nop 0
	v_cvt_pk_bf16_f32 v110, v174, v175
	v_cvt_pk_bf16_f32 v111, v172, v173
	flat_store_dwordx4 v[244:245], v[104:107]
	flat_store_dwordx4 v[244:245], v[108:111] offset:256
	v_pk_fma_f32 v[118:119], v[118:119], v[142:143], v[190:191]
	v_pk_fma_f32 v[116:117], v[116:117], v[140:141], v[188:189]
	v_lshl_add_u64 v[108:109], v[246:247], 0, s[16:17]
	v_cvt_pk_bf16_f32 v104, v116, v117
	v_cvt_pk_bf16_f32 v105, v118, v119
	v_lshl_add_u64 v[108:109], v[108:109], 0, v[160:161]
	v_pk_fma_f32 v[114:115], v[114:115], v[138:139], v[194:195]
	v_pk_fma_f32 v[112:113], v[112:113], v[136:137], v[192:193]
	v_cvt_pk_bf16_f32 v107, v114, v115
	v_pk_fma_f32 v[102:103], v[102:103], v[134:135], v[200:201]
	v_cvt_pk_bf16_f32 v106, v112, v113
	flat_store_dwordx4 v[108:109], v[104:107]
	v_pk_fma_f32 v[100:101], v[100:101], v[132:133], v[198:199]
	v_pk_fma_f32 v[96:97], v[96:97], v[140:141], v[206:207]
	v_pk_fma_f32 v[104:105], v[94:95], v[130:131], v[204:205]
	v_pk_fma_f32 v[94:95], v[92:93], v[128:129], v[202:203]
	v_cvt_pk_bf16_f32 v92, v100, v101
	v_cvt_pk_bf16_f32 v93, v102, v103
	v_pk_fma_f32 v[86:87], v[86:87], v[134:135], v[216:217]
	v_cvt_pk_bf16_f32 v94, v94, v95
	v_cvt_pk_bf16_f32 v95, v104, v105
	flat_store_dwordx4 v[108:109], v[92:95] offset:256
	v_pk_fma_f32 v[84:85], v[84:85], v[132:133], v[214:215]
	v_pk_fma_f32 v[80:81], v[80:81], v[140:141], v[224:225]
	v_lshlrev_b64 v[92:93], 11, v[240:241]
	v_lshl_add_u64 v[92:93], s[12:13], 0, v[92:93]
	v_lshl_add_u64 v[92:93], v[92:93], 0, s[8:9]
	v_lshl_add_u64 v[92:93], v[92:93], 0, s[16:17]
	v_pk_fma_f32 v[94:95], v[98:99], v[142:143], v[208:209]
	v_pk_fma_f32 v[98:99], v[90:91], v[138:139], v[212:213]
	v_pk_fma_f32 v[90:91], v[88:89], v[136:137], v[210:211]
	v_cvt_pk_bf16_f32 v88, v96, v97
	v_cvt_pk_bf16_f32 v89, v94, v95
	v_lshl_add_u64 v[92:93], v[92:93], 0, v[160:161]
	v_cvt_pk_bf16_f32 v90, v90, v91
	v_cvt_pk_bf16_f32 v91, v98, v99
	flat_store_dwordx4 v[92:93], v[88:91]
	v_add_u32_e32 v172, 0x80, v164
	v_pk_fma_f32 v[70:71], v[70:71], v[134:135], v[234:235]
	v_pk_fma_f32 v[88:89], v[78:79], v[130:131], v[220:221]
	v_pk_fma_f32 v[78:79], v[76:77], v[128:129], v[218:219]
	v_cvt_pk_bf16_f32 v76, v84, v85
	v_cvt_pk_bf16_f32 v77, v86, v87
	v_pk_fma_f32 v[68:69], v[68:69], v[132:133], v[232:233]
	v_cvt_pk_bf16_f32 v78, v78, v79
	v_cvt_pk_bf16_f32 v79, v88, v89
	flat_store_dwordx4 v[92:93], v[76:79] offset:256
	v_ashrrev_i32_e32 v173, 31, v172
	v_add_u32_e32 v174, 0x90, v164
	v_lshlrev_b64 v[76:77], 11, v[242:243]
	v_lshl_add_u64 v[76:77], s[12:13], 0, v[76:77]
	v_lshl_add_u64 v[76:77], v[76:77], 0, s[8:9]
	v_lshl_add_u64 v[76:77], v[76:77], 0, s[16:17]
	v_pk_fma_f32 v[78:79], v[82:83], v[142:143], v[226:227]
	v_pk_fma_f32 v[82:83], v[74:75], v[138:139], v[230:231]
	v_pk_fma_f32 v[74:75], v[72:73], v[136:137], v[228:229]
	v_cvt_pk_bf16_f32 v72, v80, v81
	v_cvt_pk_bf16_f32 v73, v78, v79
	v_lshl_add_u64 v[76:77], v[76:77], 0, v[160:161]
	v_cvt_pk_bf16_f32 v74, v74, v75
	v_cvt_pk_bf16_f32 v75, v82, v83
	flat_store_dwordx4 v[76:77], v[72:75]
	v_ashrrev_i32_e32 v175, 31, v174
	v_lshlrev_b64 v[80:81], 12, v[174:175]
	v_pk_fma_f32 v[72:73], v[66:67], v[130:131], v[238:239]
	v_pk_fma_f32 v[66:67], v[64:65], v[128:129], v[236:237]
	v_cvt_pk_bf16_f32 v64, v68, v69
	v_cvt_pk_bf16_f32 v65, v70, v71
	v_lshl_add_u64 v[92:93], v[162:163], 0, v[80:81]
	v_cvt_pk_bf16_f32 v66, v66, v67
	v_cvt_pk_bf16_f32 v67, v72, v73
	flat_store_dwordx4 v[76:77], v[64:67] offset:256
	v_add_u32_e32 v176, 0xa0, v164
	v_ashrrev_i32_e32 v177, 31, v176
	v_lshlrev_b64 v[64:65], 12, v[172:173]
	v_lshl_add_u64 v[76:77], v[162:163], 0, v[64:65]
	flat_load_dwordx4 v[64:67], v[76:77]
	flat_load_dwordx4 v[68:71], v[76:77] offset:16
	flat_load_dwordx4 v[72:75], v[76:77] offset:512
	s_nop 0
	flat_load_dwordx4 v[76:79], v[76:77] offset:528
	s_nop 0
	flat_load_dwordx4 v[80:83], v[92:93]
	flat_load_dwordx4 v[84:87], v[92:93] offset:16
	flat_load_dwordx4 v[88:91], v[92:93] offset:512
	s_nop 0
	flat_load_dwordx4 v[92:95], v[92:93] offset:528
	v_lshlrev_b64 v[96:97], 12, v[176:177]
	v_lshl_add_u64 v[108:109], v[162:163], 0, v[96:97]
	flat_load_dwordx4 v[96:99], v[108:109]
	flat_load_dwordx4 v[100:103], v[108:109] offset:16
	flat_load_dwordx4 v[104:107], v[108:109] offset:512
	s_nop 0
	flat_load_dwordx4 v[108:111], v[108:109] offset:528
	v_add_u32_e32 v164, 0xb0, v164
	v_ashrrev_i32_e32 v165, 31, v164
	v_lshlrev_b64 v[112:113], 12, v[164:165]
	v_lshl_add_u64 v[124:125], v[162:163], 0, v[112:113]
	flat_load_dwordx4 v[112:115], v[124:125]
	flat_load_dwordx4 v[116:119], v[124:125] offset:16
	flat_load_dwordx4 v[120:123], v[124:125] offset:512
	s_nop 0
	flat_load_dwordx4 v[124:127], v[124:125] offset:528
	v_lshlrev_b64 v[162:163], 11, v[172:173]
	s_waitcnt vmcnt(0) lgkmcnt(0)
	v_pk_fma_f32 v[60:61], v[60:61], v[140:141], v[64:65]
	v_pk_fma_f32 v[64:65], v[58:59], v[138:139], v[70:71]
	v_pk_fma_f32 v[58:59], v[56:57], v[136:137], v[68:69]
	v_cvt_pk_bf16_f32 v56, v60, v61
	v_lshl_add_u64 v[60:61], s[12:13], 0, v[162:163]
	v_lshl_add_u64 v[60:61], v[60:61], 0, s[8:9]
	v_lshl_add_u64 v[60:61], v[60:61], 0, s[16:17]
	v_pk_fma_f32 v[62:63], v[62:63], v[142:143], v[66:67]
	v_lshl_add_u64 v[60:61], v[60:61], 0, v[160:161]
	v_cvt_pk_bf16_f32 v57, v62, v63
	v_cvt_pk_bf16_f32 v58, v58, v59
	v_cvt_pk_bf16_f32 v59, v64, v65
	flat_store_dwordx4 v[60:61], v[56:59]
	v_pk_fma_f32 v[54:55], v[54:55], v[134:135], v[74:75]
	v_pk_fma_f32 v[52:53], v[52:53], v[132:133], v[72:73]
	v_pk_fma_f32 v[56:57], v[46:47], v[130:131], v[78:79]
	v_pk_fma_f32 v[46:47], v[44:45], v[128:129], v[76:77]
	v_cvt_pk_bf16_f32 v44, v52, v53
	v_cvt_pk_bf16_f32 v45, v54, v55
	v_pk_fma_f32 v[48:49], v[48:49], v[140:141], v[80:81]
	v_cvt_pk_bf16_f32 v46, v46, v47
	v_cvt_pk_bf16_f32 v47, v56, v57
	flat_store_dwordx4 v[60:61], v[44:47] offset:256
	v_pk_fma_f32 v[38:39], v[38:39], v[134:135], v[90:91]
	v_pk_fma_f32 v[36:37], v[36:37], v[132:133], v[88:89]
	v_lshlrev_b64 v[44:45], 11, v[174:175]
	v_lshl_add_u64 v[44:45], s[12:13], 0, v[44:45]
	v_lshl_add_u64 v[44:45], v[44:45], 0, s[8:9]
	v_lshl_add_u64 v[44:45], v[44:45], 0, s[16:17]
	v_pk_fma_f32 v[46:47], v[50:51], v[142:143], v[82:83]
	v_pk_fma_f32 v[50:51], v[42:43], v[138:139], v[86:87]
	v_pk_fma_f32 v[42:43], v[40:41], v[136:137], v[84:85]
	v_cvt_pk_bf16_f32 v40, v48, v49
	v_cvt_pk_bf16_f32 v41, v46, v47
	v_lshl_add_u64 v[44:45], v[44:45], 0, v[160:161]
	v_cvt_pk_bf16_f32 v42, v42, v43
	v_cvt_pk_bf16_f32 v43, v50, v51
	flat_store_dwordx4 v[44:45], v[40:43]
	v_pk_fma_f32 v[32:33], v[32:33], v[140:141], v[96:97]
	v_pk_fma_f32 v[22:23], v[22:23], v[134:135], v[106:107]
	v_pk_fma_f32 v[40:41], v[30:31], v[130:131], v[94:95]
	v_pk_fma_f32 v[30:31], v[28:29], v[128:129], v[92:93]
	v_cvt_pk_bf16_f32 v28, v36, v37
	v_cvt_pk_bf16_f32 v29, v38, v39
	v_pk_fma_f32 v[20:21], v[20:21], v[132:133], v[104:105]
	v_cvt_pk_bf16_f32 v30, v30, v31
	v_cvt_pk_bf16_f32 v31, v40, v41
	flat_store_dwordx4 v[44:45], v[28:31] offset:256
	v_pk_fma_f32 v[16:17], v[16:17], v[140:141], v[112:113]
	v_pk_fma_f32 v[6:7], v[6:7], v[134:135], v[122:123]
	v_lshlrev_b64 v[28:29], 11, v[176:177]
	v_lshl_add_u64 v[28:29], s[12:13], 0, v[28:29]
	v_lshl_add_u64 v[28:29], v[28:29], 0, s[8:9]
	v_lshl_add_u64 v[28:29], v[28:29], 0, s[16:17]
	v_pk_fma_f32 v[30:31], v[34:35], v[142:143], v[98:99]
	v_pk_fma_f32 v[34:35], v[26:27], v[138:139], v[102:103]
	v_pk_fma_f32 v[26:27], v[24:25], v[136:137], v[100:101]
	v_cvt_pk_bf16_f32 v24, v32, v33
	v_cvt_pk_bf16_f32 v25, v30, v31
	v_lshl_add_u64 v[28:29], v[28:29], 0, v[160:161]
	v_cvt_pk_bf16_f32 v26, v26, v27
	v_cvt_pk_bf16_f32 v27, v34, v35
	flat_store_dwordx4 v[28:29], v[24:27]
	v_pk_fma_f32 v[4:5], v[4:5], v[132:133], v[120:121]
	s_nop 0
	v_pk_fma_f32 v[24:25], v[14:15], v[130:131], v[110:111]
	v_pk_fma_f32 v[14:15], v[12:13], v[128:129], v[108:109]
	v_cvt_pk_bf16_f32 v12, v20, v21
	v_cvt_pk_bf16_f32 v13, v22, v23
	s_nop 0
	v_cvt_pk_bf16_f32 v14, v14, v15
	v_cvt_pk_bf16_f32 v15, v24, v25
	flat_store_dwordx4 v[28:29], v[12:15] offset:256
	s_nop 1
	v_lshlrev_b64 v[12:13], 11, v[164:165]
	v_lshl_add_u64 v[12:13], s[12:13], 0, v[12:13]
	v_lshl_add_u64 v[12:13], v[12:13], 0, s[8:9]
	v_lshl_add_u64 v[12:13], v[12:13], 0, s[16:17]
	v_pk_fma_f32 v[14:15], v[18:19], v[142:143], v[114:115]
	v_pk_fma_f32 v[18:19], v[10:11], v[138:139], v[118:119]
	v_pk_fma_f32 v[10:11], v[8:9], v[136:137], v[116:117]
	v_cvt_pk_bf16_f32 v8, v16, v17
	v_cvt_pk_bf16_f32 v9, v14, v15
	v_lshl_add_u64 v[12:13], v[12:13], 0, v[160:161]
	v_cvt_pk_bf16_f32 v10, v10, v11
	v_cvt_pk_bf16_f32 v11, v18, v19
	flat_store_dwordx4 v[12:13], v[8:11]
	s_nop 1
	v_pk_fma_f32 v[8:9], v[2:3], v[130:131], v[126:127]
	v_pk_fma_f32 v[2:3], v[0:1], v[128:129], v[124:125]
	v_cvt_pk_bf16_f32 v0, v4, v5
	v_cvt_pk_bf16_f32 v1, v6, v7
	s_nop 0
	v_cvt_pk_bf16_f32 v2, v2, v3
	v_cvt_pk_bf16_f32 v3, v8, v9
	flat_store_dwordx4 v[12:13], v[0:3] offset:256
	s_cbranch_vccnz .LBB0_744
	s_andn2_b64 vcc, exec, s[18:19]
	s_cbranch_vccnz .LBB0_743
	s_barrier
	s_branch .LBB0_743

.LBB0_812:
	flat_load_dword v4, v[0:1]
	v_cmp_lt_u32_e32 vcc, s3, v3
	s_and_saveexec_b64 s[4:5], vcc
	s_xor_b64 s[16:17], exec, s[4:5]
	s_cbranch_execz .LBB0_814
	v_add_u32_e32 v16, 0xfffffc00, v3
	v_lshl_add_u64 v[6:7], v[16:17], 2, s[12:13]
	flat_load_dword v5, v[6:7]
	s_waitcnt vmcnt(0) lgkmcnt(0)
	v_add_f32_e32 v4, 1.0, v4
	v_mul_f32_e32 v4, v4, v5
	ds_write_b32 v2, v4

.LBB0_817:
	v_lshl_add_u64 v[42:43], v[22:23], 0, s[14:15]
	flat_load_dwordx4 v[34:37], v[42:43]
	flat_load_dwordx4 v[38:41], v[42:43] offset:1024
	v_lshl_add_u64 v[58:59], v[20:21], 0, s[14:15]
	v_add_co_u32_e32 v60, vcc, s20, v58
	ds_read_b128 v[42:45], v24 offset:2048
	ds_read_b128 v[46:49], v24 offset:2064
	ds_read_b128 v[50:53], v24 offset:6144
	ds_read_b128 v[54:57], v24 offset:6160
	v_addc_co_u32_e32 v61, vcc, 0, v59, vcc
	v_add_co_u32_e32 v58, vcc, 0x5201000, v58
	s_add_u32 s14, s14, 0x800
	s_nop 0
	v_addc_co_u32_e32 v59, vcc, 0, v59, vcc
	s_addc_u32 s15, s15, 0
	s_cmp_eq_u32 s14, 0x10000
	s_waitcnt vmcnt(0) lgkmcnt(0)
	v_and_b32_e32 v65, 0xffff0000, v36
	v_and_b32_e32 v64, 0xffff0000, v34
	v_lshlrev_b32_e32 v63, 16, v36
	v_lshlrev_b32_e32 v62, 16, v34
	v_lshlrev_b32_e32 v66, 16, v35
	v_and_b32_e32 v36, 0xffff0000, v35
	v_lshlrev_b32_e32 v35, 16, v38
	v_lshlrev_b32_e32 v34, 16, v40
	v_and_b32_e32 v69, 0xffff0000, v38
	v_and_b32_e32 v68, 0xffff0000, v40
	v_lshlrev_b32_e32 v70, 16, v41
	v_and_b32_e32 v38, 0xffff0000, v41
	v_pk_mul_f32 v[40:41], v[64:65], v[64:65]
	v_lshlrev_b32_e32 v67, 16, v37
	v_pk_mul_f32 v[72:73], v[68:69], v[68:69]
	v_pk_fma_f32 v[40:41], v[62:63], v[62:63], v[40:41]
	v_and_b32_e32 v37, 0xffff0000, v37
	v_lshlrev_b32_e32 v71, 16, v39
	v_mov_b32_e32 v74, v62
	v_mov_b32_e32 v75, v64
	v_mov_b32_e32 v64, v63
	v_pk_fma_f32 v[62:63], v[34:35], v[34:35], v[72:73]
	v_pk_fma_f32 v[40:41], v[66:67], v[66:67], v[40:41]
	v_and_b32_e32 v39, 0xffff0000, v39
	v_pk_fma_f32 v[62:63], v[70:71], v[70:71], v[62:63]
	v_pk_fma_f32 v[40:41], v[36:37], v[36:37], v[40:41]
	v_mov_b32_e32 v80, v71
	v_mov_b32_e32 v81, v39
	v_mov_b32_e32 v71, v38
	v_pk_fma_f32 v[38:39], v[38:39], v[38:39], v[62:63]
	v_add_f32_e32 v16, v40, v41
	v_add_f32_e32 v16, v16, v39
	v_add_f32_e32 v16, v38, v16
	ds_bpermute_b32 v38, v25, v16
	v_mov_b32_e32 v77, v36
	v_mov_b32_e32 v36, v67
	v_mov_b32_e32 v76, v66
	v_mov_b32_e32 v78, v35
	s_waitcnt lgkmcnt(0)
	v_add_f32_e32 v16, v16, v38
	ds_bpermute_b32 v38, v26, v16
	v_mov_b32_e32 v35, v68
	v_mov_b32_e32 v79, v69
	s_waitcnt lgkmcnt(0)
	v_add_f32_e32 v16, v16, v38
	ds_bpermute_b32 v38, v27, v16
	s_waitcnt lgkmcnt(0)
	v_add_f32_e32 v16, v16, v38
	ds_bpermute_b32 v38, v28, v16
	s_waitcnt lgkmcnt(0)
	v_add_f32_e32 v16, v16, v38
	ds_bpermute_b32 v38, v29, v16
	s_waitcnt lgkmcnt(0)
	v_add_f32_e32 v16, v16, v38
	ds_bpermute_b32 v38, v30, v16
	s_waitcnt lgkmcnt(0)
	v_add_f32_e32 v16, v16, v38
	v_fmamk_f32 v16, v16, 0x3a800000, v33
	v_mul_f32_e32 v38, 0x4b800000, v16
	v_cmp_gt_f32_e32 vcc, s19, v16
	s_nop 1
	v_cndmask_b32_e32 v16, v16, v38, vcc
	v_rsq_f32_e32 v16, v16
	s_nop 0
	v_mul_f32_e32 v38, 0x45800000, v16
	v_cndmask_b32_e32 v16, v16, v38, vcc
	v_pk_mul_f32 v[62:63], v[64:65], v[16:17] op_sel_hi:[1,0]
	v_pk_mul_f32 v[36:37], v[36:37], v[16:17] op_sel_hi:[1,0]
	v_pk_mul_f32 v[38:39], v[74:75], v[16:17] op_sel_hi:[1,0]
	v_pk_mul_f32 v[40:41], v[76:77], v[16:17] op_sel_hi:[1,0]
	v_pk_mul_f32 v[34:35], v[34:35], v[16:17] op_sel_hi:[1,0]
	v_pk_mul_f32 v[68:69], v[70:71], v[16:17] op_sel_hi:[1,0]
	v_pk_fma_f32 v[70:71], v[6:7], v[36:37], v[14:15]
	v_pk_fma_f32 v[36:37], v[4:5], v[62:63], v[12:13]
	v_pk_mul_f32 v[64:65], v[78:79], v[16:17] op_sel_hi:[1,0]
	v_pk_mul_f32 v[66:67], v[80:81], v[16:17] op_sel_hi:[1,0]
	v_pk_fma_f32 v[40:41], v[2:3], v[40:41], v[10:11]
	v_pk_fma_f32 v[38:39], v[0:1], v[38:39], v[8:9]
	v_pk_fma_f32 v[46:47], v[46:47], v[34:35], v[54:55]
	v_cvt_pk_bf16_f32 v34, v38, v39
	v_cvt_pk_bf16_f32 v35, v40, v41
	v_cvt_pk_bf16_f32 v36, v36, v37
	v_cvt_pk_bf16_f32 v37, v70, v71
	v_pk_fma_f32 v[44:45], v[44:45], v[66:67], v[52:53]
	v_pk_fma_f32 v[42:43], v[42:43], v[64:65], v[50:51]
	v_pk_fma_f32 v[48:49], v[48:49], v[68:69], v[56:57]
	v_cvt_pk_bf16_f32 v38, v42, v43
	v_cvt_pk_bf16_f32 v39, v44, v45
	v_cvt_pk_bf16_f32 v40, v46, v47
	s_nop 0
	v_cvt_pk_bf16_f32 v41, v48, v49
	flat_store_dwordx4 v[60:61], v[34:37] offset:3584
	flat_store_dwordx4 v[58:59], v[38:41] offset:512
	s_cbranch_scc0 .LBB0_817
	s_add_i32 s21, s21, s38
	v_lshl_add_u64 v[20:21], v[20:21], 0, s[10:11]
	s_cmpk_gt_i32 s21, 0xff
	v_lshl_add_u64 v[22:23], v[22:23], 0, s[10:11]
	s_cbranch_scc0 .LBB0_810

.LBB0_878:
	s_lshl_b32 s4, s62, 8
	s_add_i32 s5, s4, 0xfffff500
	s_cmp_lt_i32 s62, 11
	s_cselect_b32 s19, s60, 0x23200e00
	s_cselect_b32 s21, s4, s5
	s_add_u32 s4, s10, s19
	s_addc_u32 s5, s11, 0
	s_lshl_b32 s19, s26, 8
	v_mov_b32_e32 v144, v146
	v_mov_b32_e32 v145, v147
	s_add_i32 s19, s19, s54
	v_cvt_pk_bf16_f32 v68, v68, v69
	v_cvt_pk_bf16_f32 v69, v70, v71
	v_cvt_pk_bf16_f32 v70, v64, v65
	v_cvt_pk_bf16_f32 v124, v124, v125
	v_cvt_pk_bf16_f32 v125, v126, v127
	s_nop 0
	v_add_u32_e32 v156, s19, v144
	s_or_b32 s19, s21, s55
	v_lshl_add_u32 v152, v145, 3, s19
	v_mov_b64_e32 v[144:145], s[4:5]
	v_ashrrev_i32_e32 v153, 31, v152
	v_add_u32_e32 v64, 0x80, v156
	v_mad_i64_i32 v[154:155], s[4:5], v156, s61, v[144:145]
	v_cvt_pk_bf16_f32 v126, v120, v121
	v_lshlrev_b64 v[120:121], 1, v[152:153]
	v_mad_i64_i32 v[64:65], s[4:5], v64, s61, v[144:145]
	v_cvt_pk_bf16_f32 v127, v122, v123
	v_lshl_add_u64 v[122:123], v[154:155], 0, v[120:121]
	v_cvt_pk_bf16_f32 v112, v112, v113
	v_cvt_pk_bf16_f32 v113, v114, v115
	v_cvt_pk_bf16_f32 v114, v104, v105
	v_add_u32_e32 v104, 16, v156
	v_cvt_pk_bf16_f32 v60, v60, v61
	v_cvt_pk_bf16_f32 v61, v62, v63
	v_cvt_pk_bf16_f32 v62, v56, v57
	v_lshl_add_u64 v[56:57], v[64:65], 0, v[120:121]
	v_cvt_pk_bf16_f32 v48, v48, v49
	v_cvt_pk_bf16_f32 v49, v50, v51
	v_cvt_pk_bf16_f32 v50, v40, v41
	v_add_u32_e32 v40, 0x90, v156
	v_cvt_pk_bf16_f32 v115, v106, v107
	flat_store_dwordx4 v[122:123], v[112:115] offset:256
	v_cvt_pk_bf16_f32 v51, v42, v43
	flat_store_dwordx4 v[56:57], v[48:51] offset:256
	v_cvt_pk_bf16_f32 v106, v108, v109
	v_cvt_pk_bf16_f32 v96, v96, v97
	v_cvt_pk_bf16_f32 v97, v98, v99
	s_nop 0
	v_mad_i64_i32 v[112:113], s[4:5], v104, s61, v[144:145]
	v_mad_i64_i32 v[48:49], s[4:5], v40, s61, v[144:145]
	v_lshl_add_u64 v[108:109], v[112:113], 0, v[120:121]
	v_cvt_pk_bf16_f32 v98, v88, v89
	v_add_u32_e32 v88, 32, v156
	v_cvt_pk_bf16_f32 v42, v44, v45
	v_lshl_add_u64 v[44:45], v[48:49], 0, v[120:121]
	v_cvt_pk_bf16_f32 v32, v32, v33
	v_cvt_pk_bf16_f32 v33, v34, v35
	v_cvt_pk_bf16_f32 v34, v24, v25
	v_add_u32_e32 v24, 0xa0, v156
	v_cvt_pk_bf16_f32 v99, v90, v91
	flat_store_dwordx4 v[108:109], v[96:99] offset:256
	v_cvt_pk_bf16_f32 v35, v26, v27
	flat_store_dwordx4 v[44:45], v[32:35] offset:256
	v_cvt_pk_bf16_f32 v90, v92, v93
	v_cvt_pk_bf16_f32 v80, v80, v81
	v_cvt_pk_bf16_f32 v81, v82, v83
	s_nop 0
	v_mad_i64_i32 v[96:97], s[4:5], v88, s61, v[144:145]
	v_mad_i64_i32 v[32:33], s[4:5], v24, s61, v[144:145]
	v_lshl_add_u64 v[92:93], v[96:97], 0, v[120:121]
	v_cvt_pk_bf16_f32 v82, v72, v73
	v_add_u32_e32 v72, 48, v156
	v_cvt_pk_bf16_f32 v26, v28, v29
	v_lshl_add_u64 v[28:29], v[32:33], 0, v[120:121]
	v_cvt_pk_bf16_f32 v16, v16, v17
	v_cvt_pk_bf16_f32 v17, v18, v19
	v_cvt_pk_bf16_f32 v18, v8, v9
	v_add_u32_e32 v8, 0xb0, v156
	v_cvt_pk_bf16_f32 v83, v74, v75
	flat_store_dwordx4 v[92:93], v[80:83] offset:256
	v_cvt_pk_bf16_f32 v19, v10, v11
	flat_store_dwordx4 v[28:29], v[16:19] offset:256
	v_cvt_pk_bf16_f32 v74, v76, v77
	v_cvt_pk_bf16_f32 v10, v12, v13
	s_andn2_b64 vcc, exec, s[6:7]
	v_mad_i64_i32 v[80:81], s[4:5], v72, s61, v[144:145]
	v_mad_i64_i32 v[16:17], s[4:5], v8, s61, v[144:145]
	v_lshl_add_u64 v[76:77], v[80:81], 0, v[120:121]
	v_lshl_add_u64 v[12:13], v[16:17], 0, v[120:121]
	s_mov_b64 s[6:7], -1
	flat_store_dwordx4 v[122:123], v[124:127]
	v_cvt_pk_bf16_f32 v104, v116, v117
	v_cvt_pk_bf16_f32 v105, v118, v119
	v_cvt_pk_bf16_f32 v107, v110, v111
	flat_store_dwordx4 v[108:109], v[104:107]
	v_cvt_pk_bf16_f32 v88, v100, v101
	v_cvt_pk_bf16_f32 v89, v102, v103
	v_cvt_pk_bf16_f32 v91, v94, v95
	flat_store_dwordx4 v[92:93], v[88:91]
	v_cvt_pk_bf16_f32 v72, v84, v85
	v_cvt_pk_bf16_f32 v73, v86, v87
	v_cvt_pk_bf16_f32 v75, v78, v79
	flat_store_dwordx4 v[76:77], v[72:75]
	v_cvt_pk_bf16_f32 v71, v66, v67
	flat_store_dwordx4 v[76:77], v[68:71] offset:256
	v_cvt_pk_bf16_f32 v63, v58, v59
	flat_store_dwordx4 v[56:57], v[60:63]
	v_cvt_pk_bf16_f32 v40, v52, v53
	v_cvt_pk_bf16_f32 v41, v54, v55
	v_cvt_pk_bf16_f32 v43, v46, v47
	flat_store_dwordx4 v[44:45], v[40:43]
	v_cvt_pk_bf16_f32 v24, v36, v37
	v_cvt_pk_bf16_f32 v25, v38, v39
	v_cvt_pk_bf16_f32 v27, v30, v31
	flat_store_dwordx4 v[28:29], v[24:27]
	v_cvt_pk_bf16_f32 v8, v20, v21
	v_cvt_pk_bf16_f32 v9, v22, v23
	v_cvt_pk_bf16_f32 v11, v14, v15
	flat_store_dwordx4 v[12:13], v[8:11]
	v_cvt_pk_bf16_f32 v4, v4, v5
	v_cvt_pk_bf16_f32 v5, v6, v7
	v_cvt_pk_bf16_f32 v6, v0, v1
	v_cvt_pk_bf16_f32 v7, v2, v3
	flat_store_dwordx4 v[12:13], v[4:7] offset:256
	s_cbranch_vccnz .LBB0_871
	s_andn2_b64 vcc, exec, s[12:13]
	s_cbranch_vccnz .LBB0_870
	s_barrier
	s_branch .LBB0_870

.LBB0_928:
	s_cmp_lt_i32 s76, 12
	s_cselect_b64 s[16:17], -1, 0
	s_and_b64 s[4:5], s[16:17], s[46:47]
	s_andn2_b64 vcc, exec, s[4:5]
	s_cbranch_vccnz .LBB0_979
	s_and_b32 s4, s2, 7
	s_mulk_i32 s4, 0x2c0
	s_and_b32 s5, s2, -8
	s_and_b32 s3, s38, 7
	s_lshl_b32 s10, s2, 3
	s_add_i32 s11, s4, s5
	s_add_i32 s12, s4, 0x2c0
	s_cmp_eq_u32 s3, 0
	s_cselect_b64 s[6:7], -1, 0
	s_and_b64 s[4:5], s[6:7], exec
	s_cselect_b32 s3, s11, s10
	s_waitcnt vmcnt(0)
	v_add_u32_e32 v166, s3, v197
	s_cselect_b32 s27, s12, 0x1600
	s_mov_b64 s[8:9], s[0:1]
	s_movk_i32 s3, 0x1600
	v_cmp_gt_i32_e32 vcc, s27, v166
	s_and_saveexec_b64 s[18:19], vcc
	s_cbranch_execz .LBB0_978
	s_load_dwordx4 s[12:15], s[8:9], 0xb8
	s_load_dwordx2 s[20:21], s[8:9], 0xe0
	s_and_b32 s10, s38, -8
	s_lshl_b32 s11, s38, 3
	s_and_b64 s[4:5], s[6:7], exec
	s_cselect_b32 s29, s10, s11
	s_waitcnt lgkmcnt(0)
	s_add_u32 s22, s20, 0xd200e00
	v_lshlrev_b32_e32 v0, 2, v196
	s_addc_u32 s23, s21, 0
	v_and_b32_e32 v167, 0xfc, v0
	s_mov_b64 s[24:25], 0
	s_mov_b32 s39, 0x2e8ba2e9
	s_movk_i32 s48, 0x2000
	s_movk_i32 s49, 0x5000
	s_mov_b32 s50, 0x8000
	s_mov_b32 s51, 0xb000
	s_mov_b32 s52, 0xd000
	s_mov_b32 s53, 0x10000
	s_mov_b32 s54, 0x13000
	s_mov_b32 s55, 0x16000
	s_movk_i32 s56, 0x7c
	s_mov_b32 s57, 0x2c00000
	v_mov_b64_e32 v[40:41], s[22:23]
	s_movk_i32 s58, 0x80
	v_mov_b32_e32 v42, 0
	s_movk_i32 s59, 0x100
	s_mov_b32 s60, 0x160000
	s_mov_b32 s61, 0x23200000
	s_mov_b32 s26, 0x3dd2d3e7
	s_mov_b32 s28, 0xc0135761
	s_mov_b32 s62, 0x23202000
	s_mov_b32 s63, 0x23203000
	s_mov_b32 s98, s61
	s_mov_b32 s99, 0
	s_mov_b32 s100, s63
	s_mov_b32 s101, 0
	s_branch .LBB0_932

.LBB0_932:
	v_mul_hi_i32 v0, v166, s39
	v_lshrrev_b32_e32 v1, 31, v0
	v_ashrrev_i32_e32 v0, 1, v0
	v_add_u32_e32 v104, v0, v1
	v_mul_lo_u32 v0, v104, 11
	v_sub_u32_e32 v0, v166, v0
	v_lshl_or_b32 v46, v0, 8, v167
	v_ashrrev_i32_e32 v47, 31, v46
	v_lshlrev_b64 v[36:37], 2, v[46:47]
	v_lshl_add_u64 v[32:33], s[12:13], 0, v[36:37]
	v_add_co_u32_e32 v4, vcc, s48, v32
	v_lshl_add_u64 v[36:37], s[14:15], 0, v[36:37]
	s_nop 0
	v_addc_co_u32_e32 v5, vcc, 0, v33, vcc
	v_add_co_u32_e32 v8, vcc, s49, v32
	flat_load_dwordx4 v[0:3], v[32:33]
	s_nop 0
	flat_load_dwordx4 v[4:7], v[4:5] offset:3072
	v_addc_co_u32_e32 v9, vcc, 0, v33, vcc
	v_add_co_u32_e32 v12, vcc, s50, v32
	v_lshlrev_b32_e32 v43, 1, v104
	s_nop 0
	v_addc_co_u32_e32 v13, vcc, 0, v33, vcc
	v_add_co_u32_e32 v16, vcc, s51, v32
	flat_load_dwordx4 v[8:11], v[8:9] offset:2048
	s_nop 0
	flat_load_dwordx4 v[12:15], v[12:13] offset:1024
	v_addc_co_u32_e32 v17, vcc, 0, v33, vcc
	v_add_co_u32_e32 v20, vcc, s52, v32
	v_lshlrev_b32_e32 v44, 5, v104
	s_nop 0
	v_addc_co_u32_e32 v21, vcc, 0, v33, vcc
	v_add_co_u32_e32 v24, vcc, s53, v32
	flat_load_dwordx4 v[16:19], v[16:17]
	s_nop 0
	flat_load_dwordx4 v[20:23], v[20:21] offset:3072
	v_addc_co_u32_e32 v25, vcc, 0, v33, vcc
	v_add_co_u32_e32 v28, vcc, s54, v32
	v_and_b32_e32 v60, 0x7c, v43
	s_nop 0
	v_addc_co_u32_e32 v29, vcc, 0, v33, vcc
	v_add_co_u32_e32 v32, vcc, s55, v32
	flat_load_dwordx4 v[24:27], v[24:25] offset:2048
	s_nop 0
	flat_load_dwordx4 v[28:31], v[28:29] offset:1024
	v_addc_co_u32_e32 v33, vcc, 0, v33, vcc
	flat_load_dwordx4 v[32:35], v[32:33]
	v_and_b32_e32 v168, 32, v44
	flat_load_dwordx4 v[36:39], v[36:37]
	v_ashrrev_i32_e32 v105, 6, v104
	v_add_u32_e32 v43, -1, v168
	v_add_u32_e32 v62, -1, v60
	v_mad_i64_i32 v[44:45], s[4:5], v105, s57, v[40:41]
	v_cmp_gt_u32_e64 s[10:11], 64, v43
	v_cmp_gt_u32_e64 s[6:7], s58, v62
	v_lshl_add_u64 v[44:45], v[46:47], 1, v[44:45]
	s_and_b64 s[4:5], s[10:11], s[6:7]
	v_mov_b32_e32 v48, v42
	v_mov_b32_e32 v49, v42
	s_and_saveexec_b64 s[8:9], s[4:5]
	s_cbranch_execz .LBB0_934
	v_lshl_or_b32 v48, v62, 6, v43
	v_mul_i32_i24_e32 v48, 0x1600, v48
	v_mov_b32_e32 v49, v42
	v_lshl_add_u64 v[48:49], v[44:45], 0, v[48:49]
	flat_load_dwordx2 v[48:49], v[48:49]
.LBB0_934:
	s_or_b64 exec, exec, s[8:9]
	v_lshl_or_b32 v51, v60, 6, v43
	v_mov_b32_e32 v50, 0
	v_mul_i32_i24_e32 v58, 0x1600, v51
	v_mov_b32_e32 v52, 0
	v_mov_b32_e32 v53, 0
	v_mov_b32_e32 v54, 0
	v_mov_b32_e32 v55, 0
	s_and_saveexec_b64 s[8:9], s[10:11]
	s_cbranch_execz .LBB0_936
	v_mov_b32_e32 v59, v42
	v_lshl_add_u64 v[52:53], v[44:45], 0, v[58:59]
	v_add_co_u32_e32 v54, vcc, 0x58000, v52
	s_nop 1
	v_addc_co_u32_e32 v55, vcc, 0, v53, vcc
	flat_load_dwordx2 v[52:53], v[52:53]
	s_nop 0
	flat_load_dwordx2 v[54:55], v[54:55]
.LBB0_936:
	s_or_b64 exec, exec, s[8:9]
	v_mov_b32_e32 v51, 0
	v_mov_b32_e32 v56, 0
	v_mov_b32_e32 v57, 0
	s_and_saveexec_b64 s[8:9], s[10:11]
	s_cbranch_execz .LBB0_938
	v_mov_b32_e32 v59, v42
	v_lshl_add_u64 v[50:51], v[44:45], 0, v[58:59]
	v_add_co_u32_e32 v56, vcc, 0xb0000, v50
	s_nop 1
	v_addc_co_u32_e32 v57, vcc, 0, v51, vcc
	v_add_co_u32_e32 v58, vcc, 0x108000, v50
	s_nop 1
	v_addc_co_u32_e32 v59, vcc, 0, v51, vcc
	flat_load_dwordx2 v[50:51], v[56:57]
	s_nop 0
	flat_load_dwordx2 v[56:57], v[58:59]
.LBB0_938:
	s_or_b64 exec, exec, s[8:9]
	v_cmp_ne_u32_e64 s[8:9], s56, v60
	s_and_b64 s[4:5], s[8:9], s[10:11]
	v_mov_b32_e32 v58, 0
	v_lshlrev_b32_e32 v110, 6, v60
	v_mov_b32_e32 v60, 0
	v_mov_b32_e32 v61, 0
	s_and_saveexec_b64 s[10:11], s[4:5]
	s_cbranch_execz .LBB0_940
	v_add3_u32 v43, v110, v43, s59
	v_mul_i32_i24_e32 v60, 0x1600, v43
	v_mov_b32_e32 v61, v42
	v_lshl_add_u64 v[60:61], v[44:45], 0, v[60:61]
	flat_load_dwordx2 v[60:61], v[60:61]
.LBB0_940:
	s_or_b64 exec, exec, s[10:11]
	v_mov_b32_e32 v59, 0
	s_and_saveexec_b64 s[10:11], s[6:7]
	s_cbranch_execz .LBB0_942
	v_lshl_or_b32 v43, v62, 6, v168
	v_mul_i32_i24_e32 v58, 0x1600, v43
	v_mov_b32_e32 v59, v42
	v_lshl_add_u64 v[58:59], v[44:45], 0, v[58:59]
	flat_load_dwordx2 v[58:59], v[58:59]
.LBB0_942:
	s_or_b64 exec, exec, s[10:11]
	v_or_b32_e32 v43, v110, v168
	v_or_b32_e32 v63, 64, v110
	v_mul_u32_u24_e32 v64, 0x1600, v43
	v_mov_b32_e32 v65, v42
	v_or_b32_e32 v43, v63, v168
	v_lshl_add_u64 v[66:67], v[44:45], 0, v[64:65]
	v_mul_u32_u24_e32 v64, 0x1600, v43
	v_lshl_add_u64 v[70:71], v[44:45], 0, v[64:65]
	v_or_b32_e32 v64, 0x80, v110
	v_or_b32_e32 v43, v64, v168
	v_or_b32_e32 v65, 0xc0, v110
	v_mul_u32_u24_e32 v68, 0x1600, v43
	v_mov_b32_e32 v69, v42
	v_or_b32_e32 v43, v65, v168
	v_lshl_add_u64 v[72:73], v[44:45], 0, v[68:69]
	v_mul_u32_u24_e32 v68, 0x1600, v43
	v_lshl_add_u64 v[76:77], v[44:45], 0, v[68:69]
	flat_load_dwordx2 v[68:69], v[66:67]
	flat_load_dwordx2 v[74:75], v[70:71]
	flat_load_dwordx2 v[88:89], v[72:73]
	flat_load_dwordx2 v[96:97], v[76:77]
	v_mov_b32_e32 v100, 0
	v_mov_b32_e32 v101, 0
	s_and_saveexec_b64 s[10:11], s[8:9]
	s_cbranch_execz .LBB0_944
	v_add3_u32 v43, v110, v168, s59
	v_mul_u32_u24_e32 v66, 0x1600, v43
	v_mov_b32_e32 v67, v42
	v_lshl_add_u64 v[66:67], v[44:45], 0, v[66:67]
	flat_load_dwordx2 v[100:101], v[66:67]
.LBB0_944:
	s_or_b64 exec, exec, s[10:11]
	v_mov_b32_e32 v43, v42
	v_or_b32_e32 v66, 1, v168
	v_mov_b64_e32 v[118:119], v[42:43]
	s_and_saveexec_b64 s[10:11], s[6:7]
	s_cbranch_execz .LBB0_946
	v_lshl_or_b32 v62, v62, 6, v66
	v_mul_i32_i24_e32 v70, 0x1600, v62
	v_mov_b32_e32 v71, v42
	v_lshl_add_u64 v[70:71], v[44:45], 0, v[70:71]
	flat_load_dwordx2 v[118:119], v[70:71]
.LBB0_946:
	s_or_b64 exec, exec, s[10:11]
	v_or_b32_e32 v62, v110, v66
	v_or_b32_e32 v64, v64, v66
	v_mul_u32_u24_e32 v70, 0x1600, v62
	v_mov_b32_e32 v71, v42
	v_or_b32_e32 v62, v63, v66
	v_mul_u32_u24_e32 v72, 0x1600, v64
	v_or_b32_e32 v64, v65, v66
	v_lshl_add_u64 v[70:71], v[44:45], 0, v[70:71]
	v_mul_u32_u24_e32 v62, 0x1600, v62
	v_mov_b32_e32 v63, v42
	v_mov_b32_e32 v73, v42
	v_mul_u32_u24_e32 v64, 0x1600, v64
	v_mov_b32_e32 v65, v42
	v_lshl_add_u64 v[62:63], v[44:45], 0, v[62:63]
	v_lshl_add_u64 v[72:73], v[44:45], 0, v[72:73]
	v_lshl_add_u64 v[64:65], v[44:45], 0, v[64:65]
	flat_load_dwordx2 v[122:123], v[70:71]
	flat_load_dwordx2 v[126:127], v[62:63]
	flat_load_dwordx2 v[120:121], v[72:73]
	flat_load_dwordx2 v[132:133], v[64:65]
	v_mov_b32_e32 v111, 0x2000
	v_mov_b64_e32 v[140:141], v[42:43]
	s_and_saveexec_b64 s[10:11], s[8:9]
	s_cbranch_execz .LBB0_948
	v_add_u32_e32 v111, 0x100, v110
	v_or_b32_e32 v43, v111, v66
	v_mul_u32_u24_e32 v62, 0x1600, v43
	v_mov_b32_e32 v63, v42
	v_lshl_add_u64 v[62:63], v[44:45], 0, v[62:63]
	flat_load_dwordx2 v[140:141], v[62:63]

.LBB0_949:
	s_or_b64 exec, exec, s[10:11]
	v_add_co_u32_e32 v86, vcc, s63, v128
	v_pk_mul_f32 v[94:95], v[6:7], v[76:77]
	s_nop 0
	v_addc_co_u32_e32 v87, vcc, 0, v129, vcc
	flat_load_dwordx2 v[88:89], v[86:87] offset:2560
	v_lshl_add_u64 v[178:179], v[116:117], 0, s[100:101]
	v_lshl_add_u64 v[180:181], v[110:111], 0, s[100:101]
	v_lshl_add_u64 v[182:183], v[100:101], 0, s[100:101]
	global_load_dwordx2 v[184:185], v[178:179], off offset:2560
	global_load_dwordx2 v[186:187], v[180:181], off offset:2560
	global_load_dwordx2 v[188:189], v[182:183], off offset:2560
	v_pk_mul_f32 v[96:97], v[4:5], v[72:73]
	v_lshlrev_b32_e32 v62, 16, v148
	v_and_b32_e32 v63, 0xffff0000, v148
	v_lshlrev_b32_e32 v64, 16, v149
	v_and_b32_e32 v65, 0xffff0000, v149
	v_pk_mul_f32 v[106:107], v[18:19], v[80:81]
	v_pk_mul_f32 v[108:109], v[16:17], v[78:79]
	v_pk_fma_f32 v[94:95], v[2:3], v[144:145], v[94:95]
	v_pk_fma_f32 v[96:97], v[0:1], v[142:143], v[96:97]
	v_lshlrev_b32_e32 v66, 16, v152
	v_and_b32_e32 v67, 0xffff0000, v152
	v_lshlrev_b32_e32 v68, 16, v153
	v_and_b32_e32 v69, 0xffff0000, v153
	v_lshlrev_b32_e32 v70, 16, v150
	v_and_b32_e32 v71, 0xffff0000, v150
	v_lshlrev_b32_e32 v74, 16, v151
	v_and_b32_e32 v75, 0xffff0000, v151
	v_pk_mul_f32 v[148:149], v[30:31], v[84:85]
	v_pk_mul_f32 v[150:151], v[28:29], v[82:83]
	v_pk_fma_f32 v[106:107], v[14:15], v[136:137], v[106:107]
	v_pk_fma_f32 v[108:109], v[12:13], v[134:135], v[108:109]
	v_pk_fma_f32 v[94:95], v[10:11], v[64:65], v[94:95]
	v_pk_fma_f32 v[96:97], v[8:9], v[62:63], v[96:97]
	v_pk_fma_f32 v[142:143], v[26:27], v[126:127], v[148:149]
	v_pk_fma_f32 v[144:145], v[24:25], v[122:123], v[150:151]
	v_pk_fma_f32 v[106:107], v[22:23], v[68:69], v[106:107]
	v_pk_fma_f32 v[108:109], v[20:21], v[66:67], v[108:109]
	v_pk_add_f32 v[94:95], v[38:39], v[94:95]
	v_pk_add_f32 v[96:97], v[36:37], v[96:97]
	v_pk_fma_f32 v[142:143], v[34:35], v[74:75], v[142:143]
	v_pk_fma_f32 v[144:145], v[32:33], v[70:71], v[144:145]
	v_pk_add_f32 v[94:95], v[106:107], v[94:95]
	v_pk_add_f32 v[96:97], v[108:109], v[96:97]
	v_pk_add_f32 v[94:95], v[142:143], v[94:95]
	v_pk_add_f32 v[96:97], v[144:145], v[96:97]
	v_mov_b64_e32 v[128:129], s[28:29]
	v_pk_mul_f32 v[106:107], v[94:95], v[94:95]
	v_pk_mul_f32 v[108:109], v[96:97], v[96:97]
	v_pk_fma_f32 v[106:107], v[106:107], s[26:27], v[128:129] op_sel_hi:[1,0,0] neg_lo:[1,0,0] neg_hi:[1,0,0]
	v_pk_fma_f32 v[108:109], v[108:109], s[26:27], v[128:129] op_sel_hi:[1,0,0] neg_lo:[1,0,0] neg_hi:[1,0,0]
	v_pk_mul_f32 v[106:107], v[94:95], v[106:107]
	v_pk_mul_f32 v[108:109], v[96:97], v[108:109]
	v_exp_f32_e32 v106, v106
	v_exp_f32_e32 v108, v108
	v_exp_f32_e32 v109, v109
	v_exp_f32_e32 v107, v107
	v_add_co_u32_e32 v116, vcc, s63, v116
	v_pk_add_f32 v[108:109], v[108:109], 1.0 op_sel_hi:[1,0]
	v_pk_add_f32 v[106:107], v[106:107], 1.0 op_sel_hi:[1,0]
	v_rcp_f32_e32 v108, v108
	v_rcp_f32_e32 v109, v109
	v_rcp_f32_e32 v106, v106
	v_rcp_f32_e32 v107, v107
	v_addc_co_u32_e32 v117, vcc, 0, v117, vcc
	v_pk_mul_f32 v[96:97], v[96:97], v[108:109]
	v_pk_mul_f32 v[94:95], v[94:95], v[106:107]
	v_pk_mul_f32 v[108:109], v[18:19], v[84:85]
	v_pk_mul_f32 v[142:143], v[16:17], v[82:83]
	v_pk_mul_f32 v[144:145], v[30:31], v[92:93]
	v_pk_fma_f32 v[108:109], v[14:15], v[126:127], v[108:109]
	v_add_co_u32_e32 v110, vcc, s63, v110
	v_pk_fma_f32 v[108:109], v[22:23], v[74:75], v[108:109]
	s_nop 0
	v_addc_co_u32_e32 v111, vcc, 0, v111, vcc
	v_add_co_u32_e32 v100, vcc, s63, v100
	s_waitcnt vmcnt(0) lgkmcnt(0)
	v_mov_b64_e32 v[148:149], v[158:159]
	v_addc_co_u32_e32 v101, vcc, 0, v101, vcc
	v_mov_b64_e32 v[152:153], v[154:155]
	v_mov_b64_e32 v[150:151], v[156:157]
	v_lshlrev_b32_e32 v43, 16, v88
	v_and_b32_e32 v88, 0xffff0000, v88
	v_lshlrev_b32_e32 v106, 16, v89
	v_and_b32_e32 v89, 0xffff0000, v89
	v_mul_f32_e32 v88, v97, v88
	v_mul_f32_e32 v89, v95, v89
	v_mul_f32_e32 v43, v96, v43
	v_mul_f32_e32 v94, v94, v106
	v_cvt_pk_bf16_f32 v88, v43, v88
	v_cvt_pk_bf16_f32 v89, v94, v89
	flat_store_dwordx2 v[86:87], v[88:89] offset:2560
	v_mov_b64_e32 v[94:95], v[184:185]
	v_pk_mul_f32 v[96:97], v[6:7], v[80:81]
	v_pk_mul_f32 v[106:107], v[4:5], v[78:79]
	v_pk_fma_f32 v[96:97], v[2:3], v[136:137], v[96:97]
	v_pk_fma_f32 v[106:107], v[0:1], v[134:135], v[106:107]
	v_lshlrev_b32_e32 v86, 16, v146
	v_and_b32_e32 v87, 0xffff0000, v146
	v_lshlrev_b32_e32 v88, 16, v147
	v_and_b32_e32 v89, 0xffff0000, v147
	v_pk_mul_f32 v[146:147], v[28:29], v[90:91]
	v_pk_fma_f32 v[134:135], v[12:13], v[122:123], v[142:143]
	v_pk_fma_f32 v[96:97], v[10:11], v[68:69], v[96:97]
	v_pk_fma_f32 v[106:107], v[8:9], v[66:67], v[106:107]
	v_pk_fma_f32 v[136:137], v[26:27], v[120:121], v[144:145]
	v_pk_fma_f32 v[142:143], v[24:25], v[118:119], v[146:147]
	v_pk_fma_f32 v[134:135], v[20:21], v[70:71], v[134:135]
	v_pk_add_f32 v[96:97], v[38:39], v[96:97]
	v_pk_add_f32 v[106:107], v[36:37], v[106:107]
	v_pk_fma_f32 v[136:137], v[34:35], v[88:89], v[136:137]
	v_pk_fma_f32 v[142:143], v[32:33], v[86:87], v[142:143]
	v_pk_add_f32 v[96:97], v[108:109], v[96:97]
	v_pk_add_f32 v[106:107], v[134:135], v[106:107]
	v_pk_add_f32 v[96:97], v[136:137], v[96:97]
	v_pk_add_f32 v[106:107], v[142:143], v[106:107]
	v_pk_mul_f32 v[108:109], v[96:97], v[96:97]
	v_pk_mul_f32 v[134:135], v[106:107], v[106:107]
	v_pk_fma_f32 v[108:109], v[108:109], s[26:27], v[128:129] op_sel_hi:[1,0,0] neg_lo:[1,0,0] neg_hi:[1,0,0]
	v_pk_fma_f32 v[134:135], v[134:135], s[26:27], v[128:129] op_sel_hi:[1,0,0] neg_lo:[1,0,0] neg_hi:[1,0,0]
	v_pk_mul_f32 v[108:109], v[96:97], v[108:109]
	v_pk_mul_f32 v[134:135], v[106:107], v[134:135]
	v_exp_f32_e32 v108, v108
	v_exp_f32_e32 v134, v134
	v_exp_f32_e32 v135, v135
	v_exp_f32_e32 v109, v109
	v_pk_mul_f32 v[136:137], v[30:31], v[102:103]
	v_pk_mul_f32 v[142:143], v[28:29], v[98:99]
	v_pk_add_f32 v[134:135], v[134:135], 1.0 op_sel_hi:[1,0]
	v_pk_add_f32 v[108:109], v[108:109], 1.0 op_sel_hi:[1,0]
	v_rcp_f32_e32 v134, v134
	v_rcp_f32_e32 v135, v135
	v_rcp_f32_e32 v108, v108
	v_rcp_f32_e32 v109, v109
	v_mov_b64_e32 v[146:147], v[160:161]
	v_pk_mul_f32 v[106:107], v[106:107], v[134:135]
	v_pk_mul_f32 v[134:135], v[16:17], v[90:91]
	v_pk_mul_f32 v[96:97], v[96:97], v[108:109]
	s_nop 0
	v_lshlrev_b32_e32 v43, 16, v94
	v_and_b32_e32 v94, 0xffff0000, v94
	v_lshlrev_b32_e32 v108, 16, v95
	v_and_b32_e32 v95, 0xffff0000, v95
	v_mul_f32_e32 v94, v107, v94
	v_mul_f32_e32 v95, v97, v95
	v_mul_f32_e32 v43, v106, v43
	v_mul_f32_e32 v96, v96, v108
	v_cvt_pk_bf16_f32 v94, v43, v94
	v_cvt_pk_bf16_f32 v95, v96, v95
	flat_store_dwordx2 v[116:117], v[94:95] offset:2560
	v_mov_b64_e32 v[106:107], v[186:187]
	v_pk_mul_f32 v[108:109], v[6:7], v[84:85]
	v_pk_mul_f32 v[116:117], v[4:5], v[82:83]
	v_lshlrev_b32_e32 v94, 16, v124
	v_and_b32_e32 v95, 0xffff0000, v124
	v_lshlrev_b32_e32 v96, 16, v125
	v_and_b32_e32 v97, 0xffff0000, v125
	v_pk_mul_f32 v[124:125], v[18:19], v[92:93]
	v_pk_fma_f32 v[108:109], v[2:3], v[126:127], v[108:109]
	v_pk_fma_f32 v[116:117], v[0:1], v[122:123], v[116:117]
	v_pk_fma_f32 v[122:123], v[14:15], v[120:121], v[124:125]
	v_pk_fma_f32 v[124:125], v[12:13], v[118:119], v[134:135]
	v_pk_fma_f32 v[108:109], v[10:11], v[74:75], v[108:109]
	v_pk_fma_f32 v[116:117], v[8:9], v[70:71], v[116:117]
	v_pk_fma_f32 v[126:127], v[26:27], v[132:133], v[136:137]
	v_pk_fma_f32 v[134:135], v[24:25], v[130:131], v[142:143]
	v_pk_fma_f32 v[122:123], v[22:23], v[88:89], v[122:123]
	v_pk_fma_f32 v[124:125], v[20:21], v[86:87], v[124:125]
	v_pk_add_f32 v[108:109], v[38:39], v[108:109]
	v_pk_add_f32 v[116:117], v[36:37], v[116:117]
	v_pk_fma_f32 v[126:127], v[34:35], v[96:97], v[126:127]
	v_pk_fma_f32 v[134:135], v[32:33], v[94:95], v[134:135]
	v_pk_add_f32 v[108:109], v[122:123], v[108:109]
	v_pk_add_f32 v[116:117], v[124:125], v[116:117]
	v_pk_add_f32 v[108:109], v[126:127], v[108:109]
	v_pk_add_f32 v[116:117], v[134:135], v[116:117]
	v_pk_mul_f32 v[122:123], v[108:109], v[108:109]
	v_pk_mul_f32 v[124:125], v[116:117], v[116:117]
	v_pk_fma_f32 v[122:123], v[122:123], s[26:27], v[128:129] op_sel_hi:[1,0,0] neg_lo:[1,0,0] neg_hi:[1,0,0]
	v_pk_fma_f32 v[124:125], v[124:125], s[26:27], v[128:129] op_sel_hi:[1,0,0] neg_lo:[1,0,0] neg_hi:[1,0,0]
	v_pk_mul_f32 v[122:123], v[108:109], v[122:123]
	v_pk_mul_f32 v[124:125], v[116:117], v[124:125]
	v_exp_f32_e32 v122, v122
	v_exp_f32_e32 v124, v124
	v_exp_f32_e32 v125, v125
	v_exp_f32_e32 v123, v123
	v_pk_mul_f32 v[126:127], v[30:31], v[114:115]
	v_pk_mul_f32 v[134:135], v[28:29], v[112:113]
	v_pk_add_f32 v[124:125], v[124:125], 1.0 op_sel_hi:[1,0]
	v_pk_add_f32 v[122:123], v[122:123], 1.0 op_sel_hi:[1,0]
	v_rcp_f32_e32 v124, v124
	v_rcp_f32_e32 v125, v125
	v_rcp_f32_e32 v122, v122
	v_rcp_f32_e32 v123, v123
	v_pk_mul_f32 v[116:117], v[116:117], v[124:125]
	v_pk_mul_f32 v[124:125], v[16:17], v[98:99]
	v_pk_mul_f32 v[108:109], v[108:109], v[122:123]
	s_nop 0
	v_lshlrev_b32_e32 v43, 16, v106
	v_and_b32_e32 v106, 0xffff0000, v106
	v_lshlrev_b32_e32 v122, 16, v107
	v_and_b32_e32 v107, 0xffff0000, v107
	v_mul_f32_e32 v106, v117, v106
	v_mul_f32_e32 v107, v109, v107
	v_mul_f32_e32 v43, v116, v43
	v_mul_f32_e32 v108, v108, v122
	v_cvt_pk_bf16_f32 v106, v43, v106
	v_cvt_pk_bf16_f32 v107, v108, v107
	flat_store_dwordx2 v[110:111], v[106:107] offset:2560
	v_mov_b64_e32 v[110:111], v[188:189]
	v_lshlrev_b32_e32 v106, 16, v104
	v_and_b32_e32 v107, 0xffff0000, v104
	v_lshlrev_b32_e32 v108, 16, v105
	v_and_b32_e32 v109, 0xffff0000, v105
	v_pk_mul_f32 v[104:105], v[6:7], v[92:93]
	v_pk_mul_f32 v[116:117], v[4:5], v[90:91]
	v_pk_mul_f32 v[122:123], v[18:19], v[102:103]
	v_pk_fma_f32 v[104:105], v[2:3], v[120:121], v[104:105]
	v_pk_fma_f32 v[116:117], v[0:1], v[118:119], v[116:117]
	v_pk_fma_f32 v[118:119], v[14:15], v[132:133], v[122:123]
	v_pk_fma_f32 v[104:105], v[10:11], v[88:89], v[104:105]
	v_pk_fma_f32 v[120:121], v[12:13], v[130:131], v[124:125]
	v_pk_fma_f32 v[122:123], v[26:27], v[140:141], v[126:127]
	v_pk_fma_f32 v[116:117], v[8:9], v[86:87], v[116:117]
	v_pk_fma_f32 v[118:119], v[22:23], v[96:97], v[118:119]
	v_pk_add_f32 v[104:105], v[38:39], v[104:105]
	v_pk_fma_f32 v[124:125], v[24:25], v[138:139], v[134:135]
	v_pk_fma_f32 v[120:121], v[20:21], v[94:95], v[120:121]
	v_pk_fma_f32 v[122:123], v[34:35], v[108:109], v[122:123]
	v_pk_add_f32 v[116:117], v[36:37], v[116:117]
	v_pk_add_f32 v[104:105], v[118:119], v[104:105]
	v_pk_fma_f32 v[124:125], v[32:33], v[106:107], v[124:125]
	v_pk_add_f32 v[116:117], v[120:121], v[116:117]
	v_pk_add_f32 v[104:105], v[122:123], v[104:105]
	v_pk_add_f32 v[116:117], v[124:125], v[116:117]
	v_pk_mul_f32 v[118:119], v[104:105], v[104:105]
	v_pk_mul_f32 v[120:121], v[116:117], v[116:117]
	v_pk_fma_f32 v[118:119], v[118:119], s[26:27], v[128:129] op_sel_hi:[1,0,0] neg_lo:[1,0,0] neg_hi:[1,0,0]
	v_pk_fma_f32 v[120:121], v[120:121], s[26:27], v[128:129] op_sel_hi:[1,0,0] neg_lo:[1,0,0] neg_hi:[1,0,0]
	v_pk_mul_f32 v[118:119], v[104:105], v[118:119]
	v_pk_mul_f32 v[120:121], v[116:117], v[120:121]
	v_exp_f32_e32 v118, v118
	v_exp_f32_e32 v119, v119
	v_exp_f32_e32 v120, v120
	v_exp_f32_e32 v121, v121
	v_mov_b64_e32 v[124:125], v[162:163]
	v_pk_add_f32 v[118:119], v[118:119], 1.0 op_sel_hi:[1,0]
	v_pk_add_f32 v[120:121], v[120:121], 1.0 op_sel_hi:[1,0]
	v_rcp_f32_e32 v118, v118
	v_rcp_f32_e32 v119, v119
	v_rcp_f32_e32 v120, v120
	v_rcp_f32_e32 v121, v121
	v_pk_mul_f32 v[104:105], v[104:105], v[118:119]
	v_pk_mul_f32 v[116:117], v[116:117], v[120:121]
	s_nop 0
	v_lshlrev_b32_e32 v118, 16, v111
	v_and_b32_e32 v111, 0xffff0000, v111
	v_lshlrev_b32_e32 v43, 16, v110
	v_and_b32_e32 v110, 0xffff0000, v110
	v_mul_f32_e32 v105, v105, v111
	v_mul_f32_e32 v43, v116, v43
	v_mul_f32_e32 v110, v117, v110
	v_mul_f32_e32 v116, v104, v118
	v_cvt_pk_bf16_f32 v104, v43, v110
	v_cvt_pk_bf16_f32 v105, v116, v105
	flat_store_dwordx2 v[100:101], v[104:105] offset:2560
	v_mov_b64_e32 v[104:105], v[164:165]

.LBB0_951:
	v_cmp_gt_u32_e64 s[10:11], 62, v168
	v_mov_b32_e32 v43, v42
	s_and_b64 s[4:5], s[6:7], s[10:11]
	v_mov_b64_e32 v[148:149], v[42:43]
	s_and_saveexec_b64 s[36:37], s[4:5]
	s_cbranch_execz .LBB0_953
	v_add_u32_e32 v100, s34, v52
	v_add_u32_e32 v100, 0xfffaac00, v100
	v_mov_b32_e32 v101, v42
	v_lshl_add_u64 v[100:101], v[44:45], 0, v[100:101]
	flat_load_dwordx2 v[148:149], v[100:101]
.LBB0_953:
	s_or_b64 exec, exec, s[36:37]
	v_lshl_add_u64 v[128:129], v[48:49], 0, s[34:35]
	v_lshl_add_u64 v[116:117], v[54:55], 0, s[34:35]
	v_mov_b64_e32 v[152:153], v[42:43]
	v_mov_b64_e32 v[150:151], v[42:43]
	s_and_saveexec_b64 s[36:37], s[10:11]
	s_cbranch_execz .LBB0_955
	v_add_co_u32_e32 v100, vcc, 0xd203000, v128
	s_nop 1
	v_addc_co_u32_e32 v101, vcc, 0, v129, vcc
	v_add_co_u32_e32 v104, vcc, 0xd203000, v116
	s_nop 1
	v_addc_co_u32_e32 v105, vcc, 0, v117, vcc
	flat_load_dwordx2 v[152:153], v[100:101] offset:2560
	flat_load_dwordx2 v[150:151], v[104:105] offset:2560
.LBB0_955:
	s_or_b64 exec, exec, s[36:37]
	v_mov_b32_e32 v43, v42
	v_lshl_add_u64 v[110:111], v[46:47], 0, s[34:35]
	v_lshl_add_u64 v[100:101], v[56:57], 0, s[34:35]
	v_mov_b64_e32 v[146:147], v[42:43]
	v_mov_b64_e32 v[124:125], v[42:43]
	s_and_saveexec_b64 s[36:37], s[10:11]
	s_cbranch_execz .LBB0_957
	v_add_co_u32_e32 v104, vcc, 0xd203000, v110
	s_nop 1
	v_addc_co_u32_e32 v105, vcc, 0, v111, vcc
	v_add_co_u32_e32 v124, vcc, 0xd203000, v100
	s_nop 1
	v_addc_co_u32_e32 v125, vcc, 0, v101, vcc
	flat_load_dwordx2 v[146:147], v[104:105] offset:2560
	s_nop 0
	flat_load_dwordx2 v[124:125], v[124:125] offset:2560
.LBB0_957:
	s_or_b64 exec, exec, s[36:37]
	s_and_b64 s[4:5], s[8:9], s[10:11]
	v_mov_b64_e32 v[104:105], v[42:43]
	s_and_saveexec_b64 s[10:11], s[4:5]
	s_cbranch_execz .LBB0_959
	v_lshl_add_u64 v[104:105], v[60:61], 0, s[34:35]
	flat_load_dwordx2 v[104:105], v[104:105]
.LBB0_959:
	s_or_b64 exec, exec, s[10:11]
	v_add_co_u32_e32 v130, vcc, s61, v128
	v_lshlrev_b32_e32 v142, 16, v118
	s_nop 0
	v_addc_co_u32_e32 v131, vcc, 0, v129, vcc
	flat_load_dwordx2 v[138:139], v[130:131] offset:3584
	v_lshl_add_u64 v[178:179], v[116:117], 0, s[98:99]
	v_lshl_add_u64 v[180:181], v[110:111], 0, s[98:99]
	v_lshl_add_u64 v[182:183], v[100:101], 0, s[98:99]
	global_load_dwordx2 v[184:185], v[178:179], off offset:3584
	global_load_dwordx2 v[186:187], v[180:181], off offset:3584
	global_load_dwordx2 v[188:189], v[182:183], off offset:3584
	v_and_b32_e32 v143, 0xffff0000, v118
	v_lshlrev_b32_e32 v144, 16, v119
	v_and_b32_e32 v145, 0xffff0000, v119
	v_pk_mul_f32 v[118:119], v[6:7], v[64:65]
	v_pk_mul_f32 v[156:157], v[4:5], v[62:63]
	v_pk_mul_f32 v[158:159], v[18:19], v[68:69]
	v_pk_fma_f32 v[118:119], v[2:3], v[76:77], v[118:119]
	v_lshlrev_b32_e32 v136, 16, v123
	v_and_b32_e32 v137, 0xffff0000, v123
	v_pk_mul_f32 v[160:161], v[16:17], v[66:67]
	v_pk_mul_f32 v[162:163], v[30:31], v[74:75]
	v_pk_fma_f32 v[156:157], v[0:1], v[72:73], v[156:157]
	v_pk_fma_f32 v[158:159], v[14:15], v[80:81], v[158:159]
	v_pk_fma_f32 v[118:119], v[10:11], v[144:145], v[118:119]
	v_lshlrev_b32_e32 v134, 16, v122
	v_and_b32_e32 v135, 0xffff0000, v122
	v_lshlrev_b32_e32 v122, 16, v126
	v_and_b32_e32 v123, 0xffff0000, v126
	v_lshlrev_b32_e32 v126, 16, v127
	v_and_b32_e32 v127, 0xffff0000, v127
	v_pk_mul_f32 v[164:165], v[28:29], v[70:71]
	v_pk_fma_f32 v[160:161], v[12:13], v[78:79], v[160:161]
	v_pk_fma_f32 v[162:163], v[26:27], v[84:85], v[162:163]
	v_pk_fma_f32 v[156:157], v[8:9], v[142:143], v[156:157]
	v_pk_fma_f32 v[158:159], v[22:23], v[136:137], v[158:159]
	v_pk_add_f32 v[118:119], v[38:39], v[118:119]
	v_pk_fma_f32 v[164:165], v[24:25], v[82:83], v[164:165]
	v_pk_fma_f32 v[160:161], v[20:21], v[134:135], v[160:161]
	v_pk_fma_f32 v[162:163], v[34:35], v[126:127], v[162:163]
	v_pk_add_f32 v[156:157], v[36:37], v[156:157]
	v_pk_add_f32 v[118:119], v[118:119], v[158:159]
	v_pk_fma_f32 v[164:165], v[32:33], v[122:123], v[164:165]
	v_pk_add_f32 v[156:157], v[156:157], v[160:161]
	v_pk_add_f32 v[118:119], v[118:119], v[162:163]
	v_mov_b64_e32 v[154:155], s[28:29]
	v_pk_add_f32 v[156:157], v[156:157], v[164:165]
	v_pk_mul_f32 v[158:159], v[118:119], v[118:119]
	v_pk_mul_f32 v[160:161], v[156:157], v[156:157]
	v_pk_fma_f32 v[158:159], v[158:159], s[26:27], v[154:155] op_sel_hi:[1,0,0] neg_lo:[1,0,0] neg_hi:[1,0,0]
	v_pk_fma_f32 v[160:161], v[160:161], s[26:27], v[154:155] op_sel_hi:[1,0,0] neg_lo:[1,0,0] neg_hi:[1,0,0]
	v_pk_mul_f32 v[158:159], v[118:119], v[158:159]
	v_pk_mul_f32 v[160:161], v[156:157], v[160:161]
	v_exp_f32_e32 v158, v158
	v_exp_f32_e32 v159, v159
	v_exp_f32_e32 v160, v160
	v_exp_f32_e32 v161, v161
	v_add_co_u32_e32 v162, vcc, s61, v116
	v_pk_add_f32 v[158:159], v[158:159], 1.0 op_sel_hi:[1,0]
	v_pk_add_f32 v[160:161], v[160:161], 1.0 op_sel_hi:[1,0]
	v_rcp_f32_e32 v158, v158
	v_rcp_f32_e32 v159, v159
	v_rcp_f32_e32 v160, v160
	v_rcp_f32_e32 v161, v161
	v_addc_co_u32_e32 v163, vcc, 0, v117, vcc
	v_pk_mul_f32 v[118:119], v[118:119], v[158:159]
	v_pk_mul_f32 v[156:157], v[156:157], v[160:161]
	v_pk_mul_f32 v[160:161], v[16:17], v[70:71]
	v_pk_mul_f32 v[164:165], v[30:31], v[88:89]
	v_pk_mul_f32 v[170:171], v[28:29], v[86:87]
	v_pk_fma_f32 v[160:161], v[12:13], v[82:83], v[160:161]
	v_pk_fma_f32 v[170:171], v[24:25], v[90:91], v[170:171]
	v_pk_fma_f32 v[164:165], v[26:27], v[92:93], v[164:165]
	v_pk_fma_f32 v[160:161], v[20:21], v[122:123], v[160:161]
	v_pk_mul_f32 v[172:173], v[28:29], v[94:95]
	v_pk_mul_f32 v[174:175], v[28:29], v[106:107]
	v_pk_fma_f32 v[172:173], v[24:25], v[98:99], v[172:173]
	v_pk_fma_f32 v[174:175], v[24:25], v[112:113], v[174:175]
	s_waitcnt vmcnt(0) lgkmcnt(0)
	v_lshlrev_b32_e32 v158, 16, v139
	v_and_b32_e32 v139, 0xffff0000, v139
	v_lshlrev_b32_e32 v43, 16, v138
	v_and_b32_e32 v138, 0xffff0000, v138
	v_mul_f32_e32 v119, v119, v139
	v_mul_f32_e32 v43, v156, v43
	v_mul_f32_e32 v138, v157, v138
	v_mul_f32_e32 v156, v118, v158
	v_cvt_pk_bf16_f32 v118, v43, v138
	v_cvt_pk_bf16_f32 v119, v156, v119
	flat_store_dwordx2 v[130:131], v[118:119] offset:3584
	v_mov_b64_e32 v[130:131], v[184:185]
	v_pk_mul_f32 v[138:139], v[6:7], v[68:69]
	v_pk_mul_f32 v[156:157], v[4:5], v[66:67]
	v_pk_mul_f32 v[158:159], v[18:19], v[74:75]
	v_pk_fma_f32 v[156:157], v[0:1], v[78:79], v[156:157]
	v_pk_fma_f32 v[138:139], v[2:3], v[80:81], v[138:139]
	v_pk_fma_f32 v[158:159], v[14:15], v[84:85], v[158:159]
	v_pk_fma_f32 v[138:139], v[10:11], v[136:137], v[138:139]
	v_pk_fma_f32 v[156:157], v[8:9], v[134:135], v[156:157]
	v_lshlrev_b32_e32 v118, 16, v120
	v_and_b32_e32 v119, 0xffff0000, v120
	v_lshlrev_b32_e32 v120, 16, v121
	v_and_b32_e32 v121, 0xffff0000, v121
	v_pk_fma_f32 v[158:159], v[22:23], v[126:127], v[158:159]
	v_pk_add_f32 v[156:157], v[36:37], v[156:157]
	v_pk_add_f32 v[138:139], v[38:39], v[138:139]
	v_pk_fma_f32 v[164:165], v[34:35], v[120:121], v[164:165]
	v_pk_fma_f32 v[170:171], v[32:33], v[118:119], v[170:171]
	v_pk_add_f32 v[138:139], v[138:139], v[158:159]
	v_pk_add_f32 v[156:157], v[156:157], v[160:161]
	v_pk_add_f32 v[138:139], v[138:139], v[164:165]
	v_pk_add_f32 v[156:157], v[156:157], v[170:171]
	v_pk_mul_f32 v[158:159], v[138:139], v[138:139]
	v_pk_mul_f32 v[160:161], v[156:157], v[156:157]
	v_pk_fma_f32 v[158:159], v[158:159], s[26:27], v[154:155] op_sel_hi:[1,0,0] neg_lo:[1,0,0] neg_hi:[1,0,0]
	v_pk_fma_f32 v[160:161], v[160:161], s[26:27], v[154:155] op_sel_hi:[1,0,0] neg_lo:[1,0,0] neg_hi:[1,0,0]
	v_pk_mul_f32 v[158:159], v[138:139], v[158:159]
	v_pk_mul_f32 v[160:161], v[156:157], v[160:161]
	v_exp_f32_e32 v158, v158
	v_exp_f32_e32 v160, v160
	v_exp_f32_e32 v161, v161
	v_exp_f32_e32 v159, v159
	v_add_co_u32_e32 v164, vcc, s61, v110
	v_pk_add_f32 v[160:161], v[160:161], 1.0 op_sel_hi:[1,0]
	v_pk_add_f32 v[158:159], v[158:159], 1.0 op_sel_hi:[1,0]
	v_rcp_f32_e32 v160, v160
	v_rcp_f32_e32 v161, v161
	v_rcp_f32_e32 v158, v158
	v_rcp_f32_e32 v159, v159
	v_addc_co_u32_e32 v165, vcc, 0, v111, vcc
	v_pk_mul_f32 v[156:157], v[156:157], v[160:161]
	v_pk_mul_f32 v[138:139], v[138:139], v[158:159]
	v_pk_mul_f32 v[160:161], v[18:19], v[88:89]
	v_pk_mul_f32 v[170:171], v[30:31], v[96:97]
	v_pk_fma_f32 v[160:161], v[14:15], v[92:93], v[160:161]
	v_pk_fma_f32 v[170:171], v[26:27], v[102:103], v[170:171]
	v_pk_fma_f32 v[160:161], v[22:23], v[120:121], v[160:161]
	s_nop 0
	v_lshlrev_b32_e32 v43, 16, v130
	v_and_b32_e32 v130, 0xffff0000, v130
	v_lshlrev_b32_e32 v158, 16, v131
	v_and_b32_e32 v131, 0xffff0000, v131
	v_mul_f32_e32 v130, v157, v130
	v_mul_f32_e32 v131, v139, v131
	v_mul_f32_e32 v43, v156, v43
	v_mul_f32_e32 v138, v138, v158
	v_cvt_pk_bf16_f32 v130, v43, v130
	v_cvt_pk_bf16_f32 v131, v138, v131
	flat_store_dwordx2 v[162:163], v[130:131] offset:3584
	v_mov_b64_e32 v[138:139], v[186:187]
	v_pk_mul_f32 v[156:157], v[6:7], v[74:75]
	v_pk_mul_f32 v[158:159], v[4:5], v[70:71]
	v_pk_mul_f32 v[162:163], v[16:17], v[86:87]
	v_pk_fma_f32 v[158:159], v[0:1], v[82:83], v[158:159]
	v_pk_fma_f32 v[156:157], v[2:3], v[84:85], v[156:157]
	v_pk_fma_f32 v[162:163], v[12:13], v[90:91], v[162:163]
	v_pk_fma_f32 v[156:157], v[10:11], v[126:127], v[156:157]
	v_pk_fma_f32 v[158:159], v[8:9], v[122:123], v[158:159]
	v_lshlrev_b32_e32 v130, 16, v132
	v_and_b32_e32 v131, 0xffff0000, v132
	v_lshlrev_b32_e32 v132, 16, v133
	v_and_b32_e32 v133, 0xffff0000, v133
	v_pk_fma_f32 v[162:163], v[20:21], v[118:119], v[162:163]
	v_pk_add_f32 v[158:159], v[36:37], v[158:159]
	v_pk_add_f32 v[156:157], v[38:39], v[156:157]
	v_pk_fma_f32 v[170:171], v[34:35], v[132:133], v[170:171]
	v_pk_fma_f32 v[172:173], v[32:33], v[130:131], v[172:173]
	v_pk_add_f32 v[156:157], v[156:157], v[160:161]
	v_pk_add_f32 v[158:159], v[158:159], v[162:163]
	v_pk_add_f32 v[156:157], v[156:157], v[170:171]
	v_pk_add_f32 v[158:159], v[158:159], v[172:173]
	v_pk_mul_f32 v[160:161], v[156:157], v[156:157]
	v_pk_mul_f32 v[162:163], v[158:159], v[158:159]
	v_pk_fma_f32 v[160:161], v[160:161], s[26:27], v[154:155] op_sel_hi:[1,0,0] neg_lo:[1,0,0] neg_hi:[1,0,0]
	v_pk_fma_f32 v[162:163], v[162:163], s[26:27], v[154:155] op_sel_hi:[1,0,0] neg_lo:[1,0,0] neg_hi:[1,0,0]
	v_pk_mul_f32 v[160:161], v[156:157], v[160:161]
	v_pk_mul_f32 v[162:163], v[158:159], v[162:163]
	v_exp_f32_e32 v160, v160
	v_exp_f32_e32 v162, v162
	v_exp_f32_e32 v163, v163
	v_exp_f32_e32 v161, v161
	v_add_co_u32_e32 v170, vcc, s61, v100
	v_pk_add_f32 v[162:163], v[162:163], 1.0 op_sel_hi:[1,0]
	v_pk_add_f32 v[160:161], v[160:161], 1.0 op_sel_hi:[1,0]
	v_rcp_f32_e32 v162, v162
	v_rcp_f32_e32 v163, v163
	v_rcp_f32_e32 v160, v160
	v_rcp_f32_e32 v161, v161
	v_addc_co_u32_e32 v171, vcc, 0, v101, vcc
	v_pk_mul_f32 v[158:159], v[158:159], v[162:163]
	v_pk_mul_f32 v[156:157], v[156:157], v[160:161]
	v_pk_mul_f32 v[162:163], v[18:19], v[96:97]
	v_pk_mul_f32 v[172:173], v[30:31], v[108:109]
	v_pk_fma_f32 v[162:163], v[14:15], v[102:103], v[162:163]
	v_pk_fma_f32 v[172:173], v[26:27], v[114:115], v[172:173]
	v_pk_fma_f32 v[162:163], v[22:23], v[132:133], v[162:163]
	s_nop 0
	v_lshlrev_b32_e32 v43, 16, v138
	v_and_b32_e32 v138, 0xffff0000, v138
	v_lshlrev_b32_e32 v160, 16, v139
	v_and_b32_e32 v139, 0xffff0000, v139
	v_mul_f32_e32 v138, v159, v138
	v_mul_f32_e32 v139, v157, v139
	v_mul_f32_e32 v43, v158, v43
	v_mul_f32_e32 v156, v156, v160
	v_cvt_pk_bf16_f32 v138, v43, v138
	v_cvt_pk_bf16_f32 v139, v156, v139
	flat_store_dwordx2 v[164:165], v[138:139] offset:3584
	v_mov_b64_e32 v[156:157], v[188:189]
	v_pk_mul_f32 v[158:159], v[6:7], v[88:89]
	v_pk_mul_f32 v[160:161], v[4:5], v[86:87]
	v_pk_mul_f32 v[164:165], v[16:17], v[94:95]
	v_pk_fma_f32 v[160:161], v[0:1], v[90:91], v[160:161]
	v_pk_fma_f32 v[158:159], v[2:3], v[92:93], v[158:159]
	v_pk_fma_f32 v[164:165], v[12:13], v[98:99], v[164:165]
	v_pk_fma_f32 v[158:159], v[10:11], v[120:121], v[158:159]
	v_pk_fma_f32 v[160:161], v[8:9], v[118:119], v[160:161]
	v_lshlrev_b32_e32 v138, 16, v140
	v_and_b32_e32 v139, 0xffff0000, v140
	v_lshlrev_b32_e32 v140, 16, v141
	v_and_b32_e32 v141, 0xffff0000, v141
	v_pk_fma_f32 v[164:165], v[20:21], v[130:131], v[164:165]
	v_pk_add_f32 v[160:161], v[36:37], v[160:161]
	v_pk_add_f32 v[158:159], v[38:39], v[158:159]
	v_pk_fma_f32 v[172:173], v[34:35], v[140:141], v[172:173]
	v_pk_fma_f32 v[174:175], v[32:33], v[138:139], v[174:175]
	v_pk_add_f32 v[158:159], v[158:159], v[162:163]
	v_pk_add_f32 v[160:161], v[160:161], v[164:165]
	v_pk_add_f32 v[158:159], v[158:159], v[172:173]
	v_pk_add_f32 v[160:161], v[160:161], v[174:175]
	v_pk_mul_f32 v[162:163], v[158:159], v[158:159]
	v_pk_mul_f32 v[164:165], v[160:161], v[160:161]
	v_add_u32_e32 v43, 1, v168
	v_pk_fma_f32 v[164:165], v[164:165], s[26:27], v[154:155] op_sel_hi:[1,0,0] neg_lo:[1,0,0] neg_hi:[1,0,0]
	v_pk_fma_f32 v[154:155], v[162:163], s[26:27], v[154:155] op_sel_hi:[1,0,0] neg_lo:[1,0,0] neg_hi:[1,0,0]
	v_pk_mul_f32 v[162:163], v[160:161], v[164:165]
	v_pk_mul_f32 v[154:155], v[158:159], v[154:155]
	v_exp_f32_e32 v162, v162
	v_exp_f32_e32 v154, v154
	v_exp_f32_e32 v155, v155
	v_exp_f32_e32 v163, v163
	v_cmp_lt_u32_e32 vcc, v43, v53
	v_pk_add_f32 v[154:155], v[154:155], 1.0 op_sel_hi:[1,0]
	v_pk_add_f32 v[162:163], v[162:163], 1.0 op_sel_hi:[1,0]
	v_rcp_f32_e32 v154, v154
	v_rcp_f32_e32 v155, v155
	v_rcp_f32_e32 v162, v162
	v_rcp_f32_e32 v163, v163
	v_pk_mul_f32 v[154:155], v[158:159], v[154:155]
	v_pk_mul_f32 v[160:161], v[160:161], v[162:163]
	s_nop 0
	v_lshlrev_b32_e32 v159, 16, v157
	v_and_b32_e32 v157, 0xffff0000, v157
	v_lshlrev_b32_e32 v158, 16, v156
	v_and_b32_e32 v156, 0xffff0000, v156
	v_mul_f32_e32 v155, v155, v157
	v_mul_f32_e32 v158, v160, v158
	v_mul_f32_e32 v156, v161, v156
	v_mul_f32_e32 v159, v154, v159
	v_cvt_pk_bf16_f32 v154, v158, v156
	v_cvt_pk_bf16_f32 v155, v159, v155
	flat_store_dwordx2 v[170:171], v[154:155] offset:3584
	s_and_saveexec_b64 s[36:37], vcc
	s_cbranch_execz .LBB0_969
	v_cmp_gt_u32_e64 s[10:11], 61, v168
	v_mov_b32_e32 v154, v42
	v_mov_b32_e32 v155, v42
	s_and_b64 s[4:5], s[6:7], s[10:11]
	v_mov_b64_e32 v[158:159], v[154:155]
	s_and_saveexec_b64 s[46:47], s[4:5]
	s_cbranch_execz .LBB0_962
	v_add_u32_e32 v43, s34, v52
	v_add_u32_e32 v72, 0xfffac200, v43
	v_mov_b32_e32 v73, v42
	v_lshl_add_u64 v[72:73], v[44:45], 0, v[72:73]
	flat_load_dwordx2 v[158:159], v[72:73]
.LBB0_962:
	s_or_b64 exec, exec, s[46:47]
	v_mov_b64_e32 v[156:157], v[154:155]
	s_and_saveexec_b64 s[46:47], s[10:11]
	s_cbranch_execz .LBB0_964
	v_add_co_u32_e32 v72, vcc, 0xd205000, v128
	s_nop 1
	v_addc_co_u32_e32 v73, vcc, 0, v129, vcc
	v_add_co_u32_e32 v76, vcc, 0xd205000, v116
	s_nop 1
	v_addc_co_u32_e32 v77, vcc, 0, v117, vcc
	flat_load_dwordx2 v[154:155], v[72:73]
	flat_load_dwordx2 v[156:157], v[76:77]
.LBB0_964:
	s_or_b64 exec, exec, s[46:47]
	v_mov_b32_e32 v43, v42
	v_mov_b64_e32 v[160:161], v[42:43]
	v_mov_b64_e32 v[162:163], v[42:43]
	s_and_saveexec_b64 s[46:47], s[10:11]
	s_cbranch_execz .LBB0_966
	v_add_co_u32_e32 v72, vcc, 0xd205000, v110
	s_nop 1
	v_addc_co_u32_e32 v73, vcc, 0, v111, vcc
	v_add_co_u32_e32 v76, vcc, 0xd205000, v100
	s_nop 1
	v_addc_co_u32_e32 v77, vcc, 0, v101, vcc
	flat_load_dwordx2 v[160:161], v[72:73]
	flat_load_dwordx2 v[162:163], v[76:77]
.LBB0_966:
	s_or_b64 exec, exec, s[46:47]
	s_and_b64 s[4:5], s[8:9], s[10:11]
	v_mov_b64_e32 v[164:165], v[42:43]
	s_and_saveexec_b64 s[10:11], s[4:5]
	s_cbranch_execz .LBB0_968
	v_lshl_add_u64 v[72:73], v[50:51], 0, s[34:35]
	flat_load_dwordx2 v[164:165], v[72:73]
.LBB0_968:
	s_or_b64 exec, exec, s[10:11]
	v_add_co_u32_e32 v90, vcc, s62, v128
	v_pk_mul_f32 v[98:99], v[2:3], v[64:65]
	s_nop 0
	v_addc_co_u32_e32 v91, vcc, 0, v129, vcc
	flat_load_dwordx2 v[92:93], v[90:91] offset:1024
	v_lshl_add_u64 v[178:179], v[116:117], 0, s[100:101]
	v_lshl_add_u64 v[180:181], v[110:111], 0, s[100:101]
	v_lshl_add_u64 v[182:183], v[100:101], 0, s[100:101]
	global_load_dwordx2 v[184:185], v[178:179], off offset:-3072
	global_load_dwordx2 v[186:187], v[180:181], off offset:-3072
	global_load_dwordx2 v[188:189], v[182:183], off offset:-3072
	v_pk_mul_f32 v[102:103], v[0:1], v[62:63]
	v_lshlrev_b32_e32 v72, 16, v148
	v_and_b32_e32 v73, 0xffff0000, v148
	v_lshlrev_b32_e32 v76, 16, v149
	v_and_b32_e32 v77, 0xffff0000, v149
	v_pk_mul_f32 v[112:113], v[14:15], v[68:69]
	v_pk_mul_f32 v[114:115], v[12:13], v[66:67]
	v_pk_fma_f32 v[98:99], v[6:7], v[144:145], v[98:99]
	v_pk_fma_f32 v[102:103], v[4:5], v[142:143], v[102:103]
	v_lshlrev_b32_e32 v78, 16, v152
	v_and_b32_e32 v79, 0xffff0000, v152
	v_lshlrev_b32_e32 v80, 16, v153
	v_and_b32_e32 v81, 0xffff0000, v153
	v_pk_mul_f32 v[148:149], v[26:27], v[74:75]
	v_pk_mul_f32 v[152:153], v[24:25], v[70:71]
	v_pk_fma_f32 v[112:113], v[18:19], v[136:137], v[112:113]
	v_pk_fma_f32 v[114:115], v[16:17], v[134:135], v[114:115]
	v_pk_fma_f32 v[98:99], v[10:11], v[76:77], v[98:99]
	v_pk_fma_f32 v[102:103], v[8:9], v[72:73], v[102:103]
	v_lshlrev_b32_e32 v82, 16, v150
	v_and_b32_e32 v83, 0xffff0000, v150
	v_lshlrev_b32_e32 v84, 16, v151
	v_and_b32_e32 v85, 0xffff0000, v151
	v_pk_fma_f32 v[148:149], v[30:31], v[126:127], v[148:149]
	v_pk_fma_f32 v[152:153], v[28:29], v[122:123], v[152:153]
	v_pk_fma_f32 v[112:113], v[22:23], v[80:81], v[112:113]
	v_pk_fma_f32 v[114:115], v[20:21], v[78:79], v[114:115]
	v_pk_add_f32 v[98:99], v[38:39], v[98:99]
	v_pk_add_f32 v[102:103], v[36:37], v[102:103]
	v_pk_fma_f32 v[148:149], v[34:35], v[84:85], v[148:149]
	v_pk_fma_f32 v[152:153], v[32:33], v[82:83], v[152:153]
	v_pk_add_f32 v[98:99], v[98:99], v[112:113]
	v_pk_add_f32 v[102:103], v[102:103], v[114:115]
	v_pk_add_f32 v[98:99], v[98:99], v[148:149]
	v_pk_add_f32 v[102:103], v[102:103], v[152:153]
	v_mov_b64_e32 v[150:151], s[28:29]
	v_pk_mul_f32 v[112:113], v[98:99], v[98:99]
	v_pk_mul_f32 v[114:115], v[102:103], v[102:103]
	v_pk_fma_f32 v[112:113], v[112:113], s[26:27], v[150:151] op_sel_hi:[1,0,0] neg_lo:[1,0,0] neg_hi:[1,0,0]
	v_pk_fma_f32 v[114:115], v[114:115], s[26:27], v[150:151] op_sel_hi:[1,0,0] neg_lo:[1,0,0] neg_hi:[1,0,0]
	v_pk_mul_f32 v[112:113], v[98:99], v[112:113]
	v_pk_mul_f32 v[114:115], v[102:103], v[114:115]
	v_exp_f32_e32 v112, v112
	v_exp_f32_e32 v114, v114
	v_exp_f32_e32 v115, v115
	v_exp_f32_e32 v113, v113
	v_add_co_u32_e32 v148, vcc, s62, v116
	v_pk_add_f32 v[114:115], v[114:115], 1.0 op_sel_hi:[1,0]
	v_pk_add_f32 v[112:113], v[112:113], 1.0 op_sel_hi:[1,0]
	v_rcp_f32_e32 v114, v114
	v_rcp_f32_e32 v115, v115
	v_rcp_f32_e32 v112, v112
	v_rcp_f32_e32 v113, v113
	v_addc_co_u32_e32 v149, vcc, 0, v117, vcc
	v_pk_mul_f32 v[102:103], v[102:103], v[114:115]
	v_pk_mul_f32 v[98:99], v[98:99], v[112:113]
	v_pk_mul_f32 v[114:115], v[14:15], v[74:75]
	v_pk_mul_f32 v[152:153], v[26:27], v[88:89]
	v_pk_mul_f32 v[170:171], v[24:25], v[86:87]
	v_pk_fma_f32 v[114:115], v[18:19], v[126:127], v[114:115]
	v_pk_fma_f32 v[152:153], v[30:31], v[120:121], v[152:153]
	v_pk_fma_f32 v[170:171], v[28:29], v[118:119], v[170:171]
	v_pk_fma_f32 v[114:115], v[22:23], v[84:85], v[114:115]
	v_pk_mul_f32 v[172:173], v[24:25], v[94:95]
	v_pk_mul_f32 v[174:175], v[26:27], v[108:109]
	v_pk_fma_f32 v[172:173], v[28:29], v[130:131], v[172:173]
	v_pk_mul_f32 v[176:177], v[24:25], v[106:107]
	s_waitcnt vmcnt(0) lgkmcnt(0)
	v_lshlrev_b32_e32 v43, 16, v92
	v_and_b32_e32 v92, 0xffff0000, v92
	v_lshlrev_b32_e32 v112, 16, v93
	v_and_b32_e32 v93, 0xffff0000, v93
	v_mul_f32_e32 v92, v103, v92
	v_mul_f32_e32 v93, v99, v93
	v_mul_f32_e32 v43, v102, v43
	v_mul_f32_e32 v98, v98, v112
	v_cvt_pk_bf16_f32 v92, v43, v92
	v_cvt_pk_bf16_f32 v93, v98, v93
	flat_store_dwordx2 v[90:91], v[92:93] offset:1024
	v_mov_b64_e32 v[98:99], v[184:185]
	v_pk_mul_f32 v[102:103], v[2:3], v[68:69]
	v_pk_mul_f32 v[112:113], v[0:1], v[66:67]
	v_lshlrev_b32_e32 v90, 16, v146
	v_and_b32_e32 v91, 0xffff0000, v146
	v_lshlrev_b32_e32 v92, 16, v147
	v_and_b32_e32 v93, 0xffff0000, v147
	v_pk_mul_f32 v[146:147], v[12:13], v[70:71]
	v_pk_fma_f32 v[102:103], v[6:7], v[136:137], v[102:103]
	v_pk_fma_f32 v[112:113], v[4:5], v[134:135], v[112:113]
	v_pk_fma_f32 v[146:147], v[16:17], v[122:123], v[146:147]
	v_pk_fma_f32 v[102:103], v[10:11], v[80:81], v[102:103]
	v_pk_fma_f32 v[112:113], v[8:9], v[78:79], v[112:113]
	v_pk_fma_f32 v[146:147], v[20:21], v[82:83], v[146:147]
	v_pk_add_f32 v[102:103], v[38:39], v[102:103]
	v_pk_add_f32 v[112:113], v[36:37], v[112:113]
	v_pk_fma_f32 v[152:153], v[34:35], v[92:93], v[152:153]
	v_pk_fma_f32 v[170:171], v[32:33], v[90:91], v[170:171]
	v_pk_add_f32 v[102:103], v[102:103], v[114:115]
	v_pk_add_f32 v[112:113], v[112:113], v[146:147]
	v_pk_add_f32 v[102:103], v[102:103], v[152:153]
	v_pk_add_f32 v[112:113], v[112:113], v[170:171]
	v_pk_mul_f32 v[114:115], v[102:103], v[102:103]
	v_pk_mul_f32 v[146:147], v[112:113], v[112:113]
	v_pk_fma_f32 v[114:115], v[114:115], s[26:27], v[150:151] op_sel_hi:[1,0,0] neg_lo:[1,0,0] neg_hi:[1,0,0]
	v_pk_fma_f32 v[146:147], v[146:147], s[26:27], v[150:151] op_sel_hi:[1,0,0] neg_lo:[1,0,0] neg_hi:[1,0,0]
	v_pk_mul_f32 v[114:115], v[102:103], v[114:115]
	v_pk_mul_f32 v[146:147], v[112:113], v[146:147]
	v_exp_f32_e32 v114, v114
	v_exp_f32_e32 v146, v146
	v_exp_f32_e32 v147, v147
	v_exp_f32_e32 v115, v115
	v_add_co_u32_e32 v152, vcc, s62, v110
	v_pk_add_f32 v[146:147], v[146:147], 1.0 op_sel_hi:[1,0]
	v_pk_add_f32 v[114:115], v[114:115], 1.0 op_sel_hi:[1,0]
	v_rcp_f32_e32 v146, v146
	v_rcp_f32_e32 v147, v147
	v_rcp_f32_e32 v114, v114
	v_rcp_f32_e32 v115, v115
	v_addc_co_u32_e32 v153, vcc, 0, v111, vcc
	v_pk_mul_f32 v[112:113], v[112:113], v[146:147]
	v_pk_mul_f32 v[102:103], v[102:103], v[114:115]
	v_pk_mul_f32 v[146:147], v[14:15], v[88:89]
	v_pk_mul_f32 v[170:171], v[26:27], v[96:97]
	v_pk_fma_f32 v[146:147], v[18:19], v[120:121], v[146:147]
	v_pk_fma_f32 v[170:171], v[30:31], v[132:133], v[170:171]
	v_pk_fma_f32 v[146:147], v[22:23], v[92:93], v[146:147]
	s_nop 0
	v_lshlrev_b32_e32 v43, 16, v98
	v_and_b32_e32 v98, 0xffff0000, v98
	v_lshlrev_b32_e32 v114, 16, v99
	v_and_b32_e32 v99, 0xffff0000, v99
	v_mul_f32_e32 v98, v113, v98
	v_mul_f32_e32 v99, v103, v99
	v_mul_f32_e32 v43, v112, v43
	v_mul_f32_e32 v102, v102, v114
	v_cvt_pk_bf16_f32 v98, v43, v98
	v_cvt_pk_bf16_f32 v99, v102, v99
	flat_store_dwordx2 v[148:149], v[98:99] offset:1024
	v_mov_b64_e32 v[112:113], v[186:187]
	v_lshlrev_b32_e32 v98, 16, v124
	v_and_b32_e32 v99, 0xffff0000, v124
	v_lshlrev_b32_e32 v102, 16, v125
	v_and_b32_e32 v103, 0xffff0000, v125
	v_pk_mul_f32 v[114:115], v[2:3], v[74:75]
	v_pk_mul_f32 v[124:125], v[0:1], v[70:71]
	v_pk_mul_f32 v[148:149], v[12:13], v[86:87]
	v_pk_fma_f32 v[114:115], v[6:7], v[126:127], v[114:115]
	v_pk_fma_f32 v[124:125], v[4:5], v[122:123], v[124:125]
	v_pk_fma_f32 v[148:149], v[16:17], v[118:119], v[148:149]
	v_pk_fma_f32 v[114:115], v[10:11], v[84:85], v[114:115]
	v_pk_fma_f32 v[124:125], v[8:9], v[82:83], v[124:125]
	v_pk_fma_f32 v[148:149], v[20:21], v[90:91], v[148:149]
	v_pk_add_f32 v[114:115], v[38:39], v[114:115]
	v_pk_add_f32 v[124:125], v[36:37], v[124:125]
	v_pk_fma_f32 v[170:171], v[34:35], v[102:103], v[170:171]
	v_pk_fma_f32 v[172:173], v[32:33], v[98:99], v[172:173]
	v_pk_add_f32 v[114:115], v[114:115], v[146:147]
	v_pk_add_f32 v[124:125], v[124:125], v[148:149]
	v_pk_add_f32 v[114:115], v[114:115], v[170:171]
	v_pk_add_f32 v[124:125], v[124:125], v[172:173]
	v_pk_mul_f32 v[146:147], v[114:115], v[114:115]
	v_pk_mul_f32 v[148:149], v[124:125], v[124:125]
	v_pk_fma_f32 v[146:147], v[146:147], s[26:27], v[150:151] op_sel_hi:[1,0,0] neg_lo:[1,0,0] neg_hi:[1,0,0]
	v_pk_fma_f32 v[148:149], v[148:149], s[26:27], v[150:151] op_sel_hi:[1,0,0] neg_lo:[1,0,0] neg_hi:[1,0,0]
	v_pk_mul_f32 v[146:147], v[114:115], v[146:147]
	v_pk_mul_f32 v[148:149], v[124:125], v[148:149]
	v_exp_f32_e32 v146, v146
	v_exp_f32_e32 v148, v148
	v_exp_f32_e32 v149, v149
	v_exp_f32_e32 v147, v147
	v_add_co_u32_e32 v170, vcc, s62, v100
	v_pk_add_f32 v[148:149], v[148:149], 1.0 op_sel_hi:[1,0]
	v_pk_add_f32 v[146:147], v[146:147], 1.0 op_sel_hi:[1,0]
	v_rcp_f32_e32 v148, v148
	v_rcp_f32_e32 v149, v149
	v_rcp_f32_e32 v146, v146
	v_rcp_f32_e32 v147, v147
	v_addc_co_u32_e32 v171, vcc, 0, v101, vcc
	v_pk_mul_f32 v[124:125], v[124:125], v[148:149]
	v_pk_mul_f32 v[114:115], v[114:115], v[146:147]
	v_mov_b64_e32 v[148:149], v[158:159]
	v_pk_fma_f32 v[158:159], v[30:31], v[140:141], v[174:175]
	v_pk_fma_f32 v[174:175], v[28:29], v[138:139], v[176:177]
	s_nop 0
	v_lshlrev_b32_e32 v43, 16, v112
	v_and_b32_e32 v112, 0xffff0000, v112
	v_lshlrev_b32_e32 v146, 16, v113
	v_and_b32_e32 v113, 0xffff0000, v113
	v_mul_f32_e32 v112, v125, v112
	v_mul_f32_e32 v113, v115, v113
	v_mul_f32_e32 v43, v124, v43
	v_mul_f32_e32 v114, v114, v146
	v_cvt_pk_bf16_f32 v112, v43, v112
	v_cvt_pk_bf16_f32 v113, v114, v113
	flat_store_dwordx2 v[152:153], v[112:113] offset:1024
	v_mov_b64_e32 v[172:173], v[188:189]
	v_lshlrev_b32_e32 v112, 16, v104
	v_and_b32_e32 v113, 0xffff0000, v104
	v_lshlrev_b32_e32 v114, 16, v105
	v_and_b32_e32 v115, 0xffff0000, v105
	v_pk_mul_f32 v[104:105], v[2:3], v[88:89]
	v_pk_mul_f32 v[124:125], v[0:1], v[86:87]
	v_pk_mul_f32 v[146:147], v[14:15], v[96:97]
	v_pk_mul_f32 v[152:153], v[12:13], v[94:95]
	v_pk_fma_f32 v[104:105], v[6:7], v[120:121], v[104:105]
	v_pk_fma_f32 v[124:125], v[4:5], v[118:119], v[124:125]
	v_pk_fma_f32 v[146:147], v[18:19], v[132:133], v[146:147]
	v_pk_fma_f32 v[152:153], v[16:17], v[130:131], v[152:153]
	v_pk_fma_f32 v[104:105], v[10:11], v[92:93], v[104:105]
	v_pk_fma_f32 v[124:125], v[8:9], v[90:91], v[124:125]
	v_pk_fma_f32 v[146:147], v[22:23], v[102:103], v[146:147]
	v_pk_fma_f32 v[152:153], v[20:21], v[98:99], v[152:153]
	v_pk_add_f32 v[104:105], v[38:39], v[104:105]
	v_pk_add_f32 v[124:125], v[36:37], v[124:125]
	v_pk_fma_f32 v[158:159], v[34:35], v[114:115], v[158:159]
	v_pk_fma_f32 v[174:175], v[32:33], v[112:113], v[174:175]
	v_pk_add_f32 v[104:105], v[104:105], v[146:147]
	v_pk_add_f32 v[124:125], v[124:125], v[152:153]
	v_pk_add_f32 v[104:105], v[104:105], v[158:159]
	v_pk_add_f32 v[158:159], v[124:125], v[174:175]
	v_pk_mul_f32 v[124:125], v[104:105], v[104:105]
	v_pk_mul_f32 v[146:147], v[158:159], v[158:159]
	v_pk_fma_f32 v[124:125], v[124:125], s[26:27], v[150:151] op_sel_hi:[1,0,0] neg_lo:[1,0,0] neg_hi:[1,0,0]
	v_pk_fma_f32 v[146:147], v[146:147], s[26:27], v[150:151] op_sel_hi:[1,0,0] neg_lo:[1,0,0] neg_hi:[1,0,0]
	v_pk_mul_f32 v[124:125], v[104:105], v[124:125]
	v_pk_mul_f32 v[146:147], v[158:159], v[146:147]
	v_exp_f32_e32 v124, v124
	v_exp_f32_e32 v146, v146
	v_exp_f32_e32 v147, v147
	v_exp_f32_e32 v125, v125
	v_mov_b64_e32 v[152:153], v[154:155]
	v_mov_b64_e32 v[150:151], v[156:157]
	v_pk_add_f32 v[146:147], v[146:147], 1.0 op_sel_hi:[1,0]
	v_pk_add_f32 v[124:125], v[124:125], 1.0 op_sel_hi:[1,0]
	v_rcp_f32_e32 v154, v146
	v_rcp_f32_e32 v155, v147
	v_rcp_f32_e32 v156, v124
	v_rcp_f32_e32 v157, v125
	v_mov_b64_e32 v[146:147], v[160:161]
	v_pk_mul_f32 v[154:155], v[158:159], v[154:155]
	v_mov_b64_e32 v[124:125], v[162:163]
	v_pk_mul_f32 v[104:105], v[104:105], v[156:157]
	s_nop 0
	v_and_b32_e32 v158, 0xffff0000, v173
	v_lshlrev_b32_e32 v43, 16, v172
	v_and_b32_e32 v156, 0xffff0000, v172
	v_lshlrev_b32_e32 v157, 16, v173
	v_mul_f32_e32 v105, v105, v158
	v_mul_f32_e32 v43, v154, v43
	v_mul_f32_e32 v154, v155, v156
	v_mul_f32_e32 v155, v104, v157
	v_cvt_pk_bf16_f32 v104, v43, v154
	v_cvt_pk_bf16_f32 v105, v155, v105
	flat_store_dwordx2 v[170:171], v[104:105] offset:1024
	v_mov_b64_e32 v[104:105], v[164:165]
.LBB0_969:
	s_or_b64 exec, exec, s[36:37]
	v_add_u32_e32 v43, 2, v168
	v_cmp_lt_u32_e32 vcc, v43, v53
	s_and_saveexec_b64 s[36:37], vcc
	s_cbranch_execz .LBB0_950
	v_cmp_gt_u32_e64 s[10:11], 60, v168
	v_mov_b32_e32 v154, v42
	v_mov_b32_e32 v155, v42
	s_and_b64 s[4:5], s[6:7], s[10:11]
	v_mov_b64_e32 v[158:159], v[154:155]
	s_and_saveexec_b64 s[46:47], s[4:5]
	s_cbranch_execz .LBB0_972
	v_add_u32_e32 v43, s34, v52
	v_add_u32_e32 v62, 0xfffad800, v43
	v_mov_b32_e32 v63, v42
	v_lshl_add_u64 v[62:63], v[44:45], 0, v[62:63]
	flat_load_dwordx2 v[158:159], v[62:63]
.LBB0_972:
	s_or_b64 exec, exec, s[46:47]
	v_mov_b64_e32 v[156:157], v[154:155]
	s_and_saveexec_b64 s[46:47], s[10:11]
	s_cbranch_execz .LBB0_974
	v_add_co_u32_e32 v62, vcc, 0xd206000, v128
	s_nop 1
	v_addc_co_u32_e32 v63, vcc, 0, v129, vcc
	v_add_co_u32_e32 v64, vcc, 0xd206000, v116
	s_nop 1
	v_addc_co_u32_e32 v65, vcc, 0, v117, vcc
	flat_load_dwordx2 v[154:155], v[62:63] offset:1536
	flat_load_dwordx2 v[156:157], v[64:65] offset:1536
.LBB0_974:
	s_or_b64 exec, exec, s[46:47]
	v_mov_b32_e32 v43, v42
	v_mov_b64_e32 v[160:161], v[42:43]
	v_mov_b64_e32 v[162:163], v[42:43]
	s_and_saveexec_b64 s[46:47], s[10:11]
	s_cbranch_execz .LBB0_976
	v_add_co_u32_e32 v62, vcc, 0xd206000, v110
	s_nop 1
	v_addc_co_u32_e32 v63, vcc, 0, v111, vcc
	v_add_co_u32_e32 v64, vcc, 0xd206000, v100
	s_nop 1
	v_addc_co_u32_e32 v65, vcc, 0, v101, vcc
	flat_load_dwordx2 v[160:161], v[62:63] offset:1536
	flat_load_dwordx2 v[162:163], v[64:65] offset:1536
.LBB0_976:
	s_or_b64 exec, exec, s[46:47]
	s_and_b64 s[4:5], s[8:9], s[10:11]
	v_mov_b64_e32 v[164:165], v[42:43]
	s_and_saveexec_b64 s[10:11], s[4:5]
	s_cbranch_execz .LBB0_949
	v_lshl_add_u64 v[62:63], v[58:59], 0, s[34:35]
	flat_load_dwordx2 v[164:165], v[62:63]
	s_branch .LBB0_949

.LBB0_1046:
	s_ashr_i32 s4, s14, 5
	s_mul_hi_i32 s5, s4, 0x6000
	s_mulk_i32 s4, 0x6000
	s_add_u32 s26, s49, s4
	s_addc_u32 s27, s50, s5
	s_lshl_b32 s4, s62, 8
	s_ashr_i32 s5, s4, 31
	s_lshl_b64 s[24:25], s[4:5], 2
	s_add_u32 s24, s26, s24
	s_addc_u32 s25, s27, s25
	s_lshl_b32 s26, s52, 2
	v_mov_b32_e32 v130, v214
	v_mov_b32_e32 v128, v215
	s_add_u32 s26, s24, s26
	s_addc_u32 s27, s25, 0
	s_lshl_b32 s14, s14, 8
	v_lshlrev_b32_e32 v128, 3, v128
	s_add_i32 s14, s14, s51
	s_lshl_b64 s[24:25], s[4:5], 1
	v_ashrrev_i32_e32 v129, 31, v128
	v_add_u32_e32 v144, s14, v130
	s_add_u32 s4, s55, s24
	s_addc_u32 s5, s56, s25
	v_lshlrev_b64 v[202:203], 1, v[128:129]
	v_ashrrev_i32_e32 v145, 31, v144
	v_lshl_add_u64 v[146:147], s[4:5], 0, v[202:203]
	v_lshlrev_b64 v[148:149], 11, v[144:145]
	v_lshl_add_u64 v[130:131], v[146:147], 0, v[148:149]
	flat_load_dwordx4 v[220:223], v[130:131]
	v_add_u32_e32 v150, 16, v144
	v_ashrrev_i32_e32 v151, 31, v150
	v_lshl_add_u64 v[128:129], v[128:129], 2, s[26:27]
	v_lshlrev_b64 v[244:245], 11, v[150:151]
	flat_load_dwordx4 v[140:143], v[128:129]
	flat_load_dwordx4 v[136:139], v[128:129] offset:16
	flat_load_dwordx4 v[224:227], v[130:131] offset:256
	flat_load_dwordx4 v[132:135], v[128:129] offset:512
	s_nop 0
	flat_load_dwordx4 v[128:131], v[128:129] offset:528
	v_lshl_add_u64 v[150:151], v[146:147], 0, v[244:245]
	flat_load_dwordx4 v[228:231], v[150:151]
	flat_load_dwordx4 v[232:235], v[150:151] offset:256
	v_add_u32_e32 v152, 32, v144
	v_add_u32_e32 v154, 48, v144
	v_add_u32_e32 v156, 0x80, v144
	v_add_u32_e32 v158, 0x90, v144
	v_add_u32_e32 v160, 0xa0, v144
	v_add_u32_e32 v144, 0xb0, v144
	v_ashrrev_i32_e32 v153, 31, v152
	v_ashrrev_i32_e32 v155, 31, v154
	v_ashrrev_i32_e32 v157, 31, v156
	v_ashrrev_i32_e32 v159, 31, v158
	v_ashrrev_i32_e32 v161, 31, v160
	v_ashrrev_i32_e32 v145, 31, v144
	v_lshlrev_b64 v[246:247], 11, v[152:153]
	v_lshlrev_b64 v[212:213], 11, v[154:155]
	v_lshlrev_b64 v[210:211], 11, v[156:157]
	v_lshlrev_b64 v[208:209], 11, v[158:159]
	v_lshlrev_b64 v[206:207], 11, v[160:161]
	v_lshlrev_b64 v[204:205], 11, v[144:145]
	v_lshl_add_u64 v[144:145], s[18:19], 0, v[148:149]
	v_lshl_add_u64 v[148:149], v[146:147], 0, v[246:247]
	v_lshl_add_u64 v[150:151], v[146:147], 0, v[212:213]
	v_lshl_add_u64 v[152:153], v[146:147], 0, v[210:211]
	v_lshl_add_u64 v[154:155], v[146:147], 0, v[208:209]
	v_lshl_add_u64 v[248:249], v[146:147], 0, v[206:207]
	v_lshl_add_u64 v[146:147], v[146:147], 0, v[204:205]
	v_lshl_add_u64 v[250:251], v[144:145], 0, s[24:25]
	flat_load_dwordx4 v[236:239], v[148:149]
	flat_load_dwordx4 v[240:243], v[148:149] offset:256
	flat_load_dwordx4 v[180:183], v[150:151]
	flat_load_dwordx4 v[176:179], v[150:151] offset:256
	flat_load_dwordx4 v[172:175], v[152:153]
	flat_load_dwordx4 v[168:171], v[152:153] offset:256
	flat_load_dwordx4 v[164:167], v[154:155]
	flat_load_dwordx4 v[160:163], v[154:155] offset:256
	flat_load_dwordx4 v[156:159], v[248:249]
	s_nop 0
	flat_load_dwordx4 v[152:155], v[248:249] offset:256
	flat_load_dwordx4 v[148:151], v[146:147]
	s_nop 0
	flat_load_dwordx4 v[144:147], v[146:147] offset:256
	s_lshl_b32 s14, s52, 1
	v_lshl_add_u64 v[248:249], v[250:251], 0, s[14:15]
	s_and_b64 vcc, exec, s[6:7]
	s_mov_b64 s[6:7], -1
	s_waitcnt vmcnt(0) lgkmcnt(0)
	v_lshlrev_b32_e32 v250, 16, v220
	v_and_b32_e32 v251, 0xffff0000, v220
	v_lshlrev_b32_e32 v220, 16, v221
	v_and_b32_e32 v221, 0xffff0000, v221
	v_lshlrev_b32_e32 v252, 16, v222
	v_and_b32_e32 v253, 0xffff0000, v222
	v_lshlrev_b32_e32 v222, 16, v223
	v_and_b32_e32 v223, 0xffff0000, v223
	v_pk_fma_f32 v[126:127], v[126:127], v[142:143], v[220:221]
	v_pk_fma_f32 v[124:125], v[124:125], v[140:141], v[250:251]
	v_pk_fma_f32 v[220:221], v[122:123], v[138:139], v[222:223]
	v_pk_fma_f32 v[122:123], v[120:121], v[136:137], v[252:253]
	v_cvt_pk_bf16_f32 v120, v124, v125
	v_cvt_pk_bf16_f32 v121, v126, v127
	v_lshl_add_u64 v[124:125], v[248:249], 0, v[202:203]
	v_cvt_pk_bf16_f32 v122, v122, v123
	v_cvt_pk_bf16_f32 v123, v220, v221
	flat_store_dwordx4 v[124:125], v[120:123]
	v_lshlrev_b32_e32 v126, 16, v226
	v_and_b32_e32 v127, 0xffff0000, v226
	v_lshlrev_b32_e32 v120, 16, v224
	v_and_b32_e32 v121, 0xffff0000, v224
	v_lshlrev_b32_e32 v122, 16, v225
	v_and_b32_e32 v123, 0xffff0000, v225
	v_lshlrev_b32_e32 v220, 16, v227
	v_and_b32_e32 v221, 0xffff0000, v227
	v_pk_fma_f32 v[118:119], v[118:119], v[134:135], v[122:123]
	v_pk_fma_f32 v[116:117], v[116:117], v[132:133], v[120:121]
	v_pk_fma_f32 v[120:121], v[114:115], v[130:131], v[220:221]
	v_pk_fma_f32 v[114:115], v[112:113], v[128:129], v[126:127]
	v_cvt_pk_bf16_f32 v112, v116, v117
	v_cvt_pk_bf16_f32 v113, v118, v119
	v_lshlrev_b32_e32 v116, 16, v230
	v_cvt_pk_bf16_f32 v114, v114, v115
	v_cvt_pk_bf16_f32 v115, v120, v121
	flat_store_dwordx4 v[124:125], v[112:115] offset:256
	v_and_b32_e32 v117, 0xffff0000, v230
	v_lshlrev_b32_e32 v118, 16, v231
	v_lshlrev_b32_e32 v112, 16, v228
	v_and_b32_e32 v113, 0xffff0000, v228
	v_and_b32_e32 v119, 0xffff0000, v231
	v_pk_fma_f32 v[108:109], v[108:109], v[140:141], v[112:113]
	v_pk_fma_f32 v[112:113], v[106:107], v[138:139], v[118:119]
	v_pk_fma_f32 v[106:107], v[104:105], v[136:137], v[116:117]
	v_cvt_pk_bf16_f32 v104, v108, v109
	v_lshl_add_u64 v[108:109], s[18:19], 0, v[244:245]
	v_lshl_add_u64 v[108:109], v[108:109], 0, s[24:25]
	v_lshlrev_b32_e32 v114, 16, v229
	v_and_b32_e32 v115, 0xffff0000, v229
	v_lshl_add_u64 v[108:109], v[108:109], 0, s[14:15]
	v_pk_fma_f32 v[110:111], v[110:111], v[142:143], v[114:115]
	v_cvt_pk_bf16_f32 v106, v106, v107
	v_cvt_pk_bf16_f32 v107, v112, v113
	v_lshl_add_u64 v[108:109], v[108:109], 0, v[202:203]
	v_cvt_pk_bf16_f32 v105, v110, v111
	flat_store_dwordx4 v[108:109], v[104:107]
	v_lshlrev_b32_e32 v110, 16, v234
	v_and_b32_e32 v111, 0xffff0000, v234
	v_lshlrev_b32_e32 v104, 16, v232
	v_and_b32_e32 v105, 0xffff0000, v232
	v_lshlrev_b32_e32 v106, 16, v233
	v_and_b32_e32 v107, 0xffff0000, v233
	v_lshlrev_b32_e32 v112, 16, v235
	v_and_b32_e32 v113, 0xffff0000, v235
	v_pk_fma_f32 v[102:103], v[102:103], v[134:135], v[106:107]
	v_pk_fma_f32 v[100:101], v[100:101], v[132:133], v[104:105]
	v_pk_fma_f32 v[104:105], v[98:99], v[130:131], v[112:113]
	v_pk_fma_f32 v[98:99], v[96:97], v[128:129], v[110:111]
	v_cvt_pk_bf16_f32 v96, v100, v101
	v_cvt_pk_bf16_f32 v97, v102, v103
	v_lshlrev_b32_e32 v100, 16, v238
	v_cvt_pk_bf16_f32 v98, v98, v99
	v_cvt_pk_bf16_f32 v99, v104, v105
	flat_store_dwordx4 v[108:109], v[96:99] offset:256
	v_and_b32_e32 v101, 0xffff0000, v238
	v_lshlrev_b32_e32 v102, 16, v239
	v_lshlrev_b32_e32 v96, 16, v236
	v_and_b32_e32 v97, 0xffff0000, v236
	v_and_b32_e32 v103, 0xffff0000, v239
	v_pk_fma_f32 v[92:93], v[92:93], v[140:141], v[96:97]
	v_pk_fma_f32 v[96:97], v[90:91], v[138:139], v[102:103]
	v_pk_fma_f32 v[90:91], v[88:89], v[136:137], v[100:101]
	v_cvt_pk_bf16_f32 v88, v92, v93
	v_lshl_add_u64 v[92:93], s[18:19], 0, v[246:247]
	v_lshl_add_u64 v[92:93], v[92:93], 0, s[24:25]
	v_lshlrev_b32_e32 v98, 16, v237
	v_and_b32_e32 v99, 0xffff0000, v237
	v_lshl_add_u64 v[92:93], v[92:93], 0, s[14:15]
	v_pk_fma_f32 v[94:95], v[94:95], v[142:143], v[98:99]
	v_cvt_pk_bf16_f32 v90, v90, v91
	v_cvt_pk_bf16_f32 v91, v96, v97
	v_lshl_add_u64 v[92:93], v[92:93], 0, v[202:203]
	v_cvt_pk_bf16_f32 v89, v94, v95
	flat_store_dwordx4 v[92:93], v[88:91]
	v_lshlrev_b32_e32 v94, 16, v242
	v_and_b32_e32 v95, 0xffff0000, v242
	v_lshlrev_b32_e32 v88, 16, v240
	v_and_b32_e32 v89, 0xffff0000, v240
	v_lshlrev_b32_e32 v90, 16, v241
	v_and_b32_e32 v91, 0xffff0000, v241
	v_lshlrev_b32_e32 v96, 16, v243
	v_and_b32_e32 v97, 0xffff0000, v243
	v_pk_fma_f32 v[86:87], v[86:87], v[134:135], v[90:91]
	v_pk_fma_f32 v[84:85], v[84:85], v[132:133], v[88:89]
	v_pk_fma_f32 v[88:89], v[82:83], v[130:131], v[96:97]
	v_pk_fma_f32 v[82:83], v[80:81], v[128:129], v[94:95]
	v_cvt_pk_bf16_f32 v80, v84, v85
	v_cvt_pk_bf16_f32 v81, v86, v87
	v_lshlrev_b32_e32 v84, 16, v182
	v_cvt_pk_bf16_f32 v82, v82, v83
	v_cvt_pk_bf16_f32 v83, v88, v89
	flat_store_dwordx4 v[92:93], v[80:83] offset:256
	v_and_b32_e32 v85, 0xffff0000, v182
	v_lshlrev_b32_e32 v86, 16, v183
	v_lshlrev_b32_e32 v80, 16, v180
	v_and_b32_e32 v81, 0xffff0000, v180
	v_and_b32_e32 v87, 0xffff0000, v183
	v_pk_fma_f32 v[76:77], v[76:77], v[140:141], v[80:81]
	v_pk_fma_f32 v[80:81], v[74:75], v[138:139], v[86:87]
	v_pk_fma_f32 v[74:75], v[72:73], v[136:137], v[84:85]
	v_cvt_pk_bf16_f32 v72, v76, v77
	v_lshl_add_u64 v[76:77], s[18:19], 0, v[212:213]
	v_lshl_add_u64 v[76:77], v[76:77], 0, s[24:25]
	v_lshlrev_b32_e32 v82, 16, v181
	v_and_b32_e32 v83, 0xffff0000, v181
	v_lshl_add_u64 v[76:77], v[76:77], 0, s[14:15]
	v_pk_fma_f32 v[78:79], v[78:79], v[142:143], v[82:83]
	v_cvt_pk_bf16_f32 v74, v74, v75
	v_cvt_pk_bf16_f32 v75, v80, v81
	v_lshl_add_u64 v[76:77], v[76:77], 0, v[202:203]
	v_cvt_pk_bf16_f32 v73, v78, v79
	flat_store_dwordx4 v[76:77], v[72:75]
	v_lshlrev_b32_e32 v78, 16, v178
	v_and_b32_e32 v79, 0xffff0000, v178
	v_lshlrev_b32_e32 v72, 16, v176
	v_and_b32_e32 v73, 0xffff0000, v176
	v_lshlrev_b32_e32 v74, 16, v177
	v_and_b32_e32 v75, 0xffff0000, v177
	v_lshlrev_b32_e32 v80, 16, v179
	v_and_b32_e32 v81, 0xffff0000, v179
	v_pk_fma_f32 v[70:71], v[70:71], v[134:135], v[74:75]
	v_pk_fma_f32 v[68:69], v[68:69], v[132:133], v[72:73]
	v_pk_fma_f32 v[72:73], v[66:67], v[130:131], v[80:81]
	v_pk_fma_f32 v[66:67], v[64:65], v[128:129], v[78:79]
	v_cvt_pk_bf16_f32 v64, v68, v69
	v_cvt_pk_bf16_f32 v65, v70, v71
	v_lshlrev_b32_e32 v68, 16, v174
	v_cvt_pk_bf16_f32 v66, v66, v67
	v_cvt_pk_bf16_f32 v67, v72, v73
	flat_store_dwordx4 v[76:77], v[64:67] offset:256
	v_and_b32_e32 v69, 0xffff0000, v174
	v_lshlrev_b32_e32 v70, 16, v175
	v_lshlrev_b32_e32 v64, 16, v172
	v_and_b32_e32 v65, 0xffff0000, v172
	v_and_b32_e32 v71, 0xffff0000, v175
	v_pk_fma_f32 v[60:61], v[60:61], v[140:141], v[64:65]
	v_pk_fma_f32 v[64:65], v[58:59], v[138:139], v[70:71]
	v_pk_fma_f32 v[58:59], v[56:57], v[136:137], v[68:69]
	v_cvt_pk_bf16_f32 v56, v60, v61
	v_lshl_add_u64 v[60:61], s[18:19], 0, v[210:211]
	v_lshl_add_u64 v[60:61], v[60:61], 0, s[24:25]
	v_lshlrev_b32_e32 v66, 16, v173
	v_and_b32_e32 v67, 0xffff0000, v173
	v_lshl_add_u64 v[60:61], v[60:61], 0, s[14:15]
	v_pk_fma_f32 v[62:63], v[62:63], v[142:143], v[66:67]
	v_cvt_pk_bf16_f32 v58, v58, v59
	v_cvt_pk_bf16_f32 v59, v64, v65
	v_lshl_add_u64 v[60:61], v[60:61], 0, v[202:203]
	v_cvt_pk_bf16_f32 v57, v62, v63
	flat_store_dwordx4 v[60:61], v[56:59]
	v_lshlrev_b32_e32 v62, 16, v170
	v_and_b32_e32 v63, 0xffff0000, v170
	v_lshlrev_b32_e32 v56, 16, v168
	v_and_b32_e32 v57, 0xffff0000, v168
	v_lshlrev_b32_e32 v58, 16, v169
	v_and_b32_e32 v59, 0xffff0000, v169
	v_lshlrev_b32_e32 v64, 16, v171
	v_and_b32_e32 v65, 0xffff0000, v171
	v_pk_fma_f32 v[54:55], v[54:55], v[134:135], v[58:59]
	v_pk_fma_f32 v[52:53], v[52:53], v[132:133], v[56:57]
	v_pk_fma_f32 v[56:57], v[50:51], v[130:131], v[64:65]
	v_pk_fma_f32 v[50:51], v[48:49], v[128:129], v[62:63]
	v_cvt_pk_bf16_f32 v48, v52, v53
	v_cvt_pk_bf16_f32 v49, v54, v55
	v_lshlrev_b32_e32 v52, 16, v166
	v_cvt_pk_bf16_f32 v50, v50, v51
	v_cvt_pk_bf16_f32 v51, v56, v57
	flat_store_dwordx4 v[60:61], v[48:51] offset:256
	v_and_b32_e32 v53, 0xffff0000, v166
	v_lshlrev_b32_e32 v54, 16, v167
	v_lshlrev_b32_e32 v48, 16, v164
	v_and_b32_e32 v49, 0xffff0000, v164
	v_and_b32_e32 v55, 0xffff0000, v167
	v_pk_fma_f32 v[44:45], v[44:45], v[140:141], v[48:49]
	v_pk_fma_f32 v[48:49], v[42:43], v[138:139], v[54:55]
	v_pk_fma_f32 v[42:43], v[40:41], v[136:137], v[52:53]
	v_cvt_pk_bf16_f32 v40, v44, v45
	v_lshl_add_u64 v[44:45], s[18:19], 0, v[208:209]
	v_lshl_add_u64 v[44:45], v[44:45], 0, s[24:25]
	v_lshlrev_b32_e32 v50, 16, v165
	v_and_b32_e32 v51, 0xffff0000, v165
	v_lshl_add_u64 v[44:45], v[44:45], 0, s[14:15]
	v_pk_fma_f32 v[46:47], v[46:47], v[142:143], v[50:51]
	v_cvt_pk_bf16_f32 v42, v42, v43
	v_cvt_pk_bf16_f32 v43, v48, v49
	v_lshl_add_u64 v[44:45], v[44:45], 0, v[202:203]
	v_cvt_pk_bf16_f32 v41, v46, v47
	flat_store_dwordx4 v[44:45], v[40:43]
	v_lshlrev_b32_e32 v46, 16, v162
	v_and_b32_e32 v47, 0xffff0000, v162
	v_lshlrev_b32_e32 v40, 16, v160
	v_and_b32_e32 v41, 0xffff0000, v160
	v_lshlrev_b32_e32 v42, 16, v161
	v_and_b32_e32 v43, 0xffff0000, v161
	v_lshlrev_b32_e32 v48, 16, v163
	v_and_b32_e32 v49, 0xffff0000, v163
	v_pk_fma_f32 v[38:39], v[38:39], v[134:135], v[42:43]
	v_pk_fma_f32 v[36:37], v[36:37], v[132:133], v[40:41]
	v_pk_fma_f32 v[40:41], v[34:35], v[130:131], v[48:49]
	v_pk_fma_f32 v[34:35], v[32:33], v[128:129], v[46:47]
	v_cvt_pk_bf16_f32 v32, v36, v37
	v_cvt_pk_bf16_f32 v33, v38, v39
	v_lshlrev_b32_e32 v36, 16, v158
	v_cvt_pk_bf16_f32 v34, v34, v35
	v_cvt_pk_bf16_f32 v35, v40, v41
	flat_store_dwordx4 v[44:45], v[32:35] offset:256
	v_and_b32_e32 v37, 0xffff0000, v158
	v_lshlrev_b32_e32 v38, 16, v159
	v_lshlrev_b32_e32 v32, 16, v156
	v_and_b32_e32 v33, 0xffff0000, v156
	v_and_b32_e32 v39, 0xffff0000, v159
	v_pk_fma_f32 v[28:29], v[28:29], v[140:141], v[32:33]
	v_pk_fma_f32 v[32:33], v[26:27], v[138:139], v[38:39]
	v_pk_fma_f32 v[26:27], v[24:25], v[136:137], v[36:37]
	v_cvt_pk_bf16_f32 v24, v28, v29
	v_lshl_add_u64 v[28:29], s[18:19], 0, v[206:207]
	v_lshl_add_u64 v[28:29], v[28:29], 0, s[24:25]
	v_lshlrev_b32_e32 v34, 16, v157
	v_and_b32_e32 v35, 0xffff0000, v157
	v_lshl_add_u64 v[28:29], v[28:29], 0, s[14:15]
	v_pk_fma_f32 v[30:31], v[30:31], v[142:143], v[34:35]
	v_cvt_pk_bf16_f32 v26, v26, v27
	v_cvt_pk_bf16_f32 v27, v32, v33
	v_lshl_add_u64 v[28:29], v[28:29], 0, v[202:203]
	v_cvt_pk_bf16_f32 v25, v30, v31
	flat_store_dwordx4 v[28:29], v[24:27]
	v_lshlrev_b32_e32 v30, 16, v154
	v_and_b32_e32 v31, 0xffff0000, v154
	v_lshlrev_b32_e32 v24, 16, v152
	v_and_b32_e32 v25, 0xffff0000, v152
	v_lshlrev_b32_e32 v26, 16, v153
	v_and_b32_e32 v27, 0xffff0000, v153
	v_lshlrev_b32_e32 v32, 16, v155
	v_and_b32_e32 v33, 0xffff0000, v155
	v_pk_fma_f32 v[22:23], v[22:23], v[134:135], v[26:27]
	v_pk_fma_f32 v[20:21], v[20:21], v[132:133], v[24:25]
	v_pk_fma_f32 v[24:25], v[18:19], v[130:131], v[32:33]
	v_pk_fma_f32 v[18:19], v[16:17], v[128:129], v[30:31]
	v_cvt_pk_bf16_f32 v16, v20, v21
	v_cvt_pk_bf16_f32 v17, v22, v23
	v_lshlrev_b32_e32 v20, 16, v150
	v_cvt_pk_bf16_f32 v18, v18, v19
	v_cvt_pk_bf16_f32 v19, v24, v25
	flat_store_dwordx4 v[28:29], v[16:19] offset:256
	v_and_b32_e32 v21, 0xffff0000, v150
	v_lshlrev_b32_e32 v22, 16, v151
	v_lshlrev_b32_e32 v16, 16, v148
	v_and_b32_e32 v17, 0xffff0000, v148
	v_and_b32_e32 v23, 0xffff0000, v151
	v_pk_fma_f32 v[12:13], v[12:13], v[140:141], v[16:17]
	v_pk_fma_f32 v[16:17], v[10:11], v[138:139], v[22:23]
	v_pk_fma_f32 v[10:11], v[8:9], v[136:137], v[20:21]
	v_cvt_pk_bf16_f32 v8, v12, v13
	v_lshl_add_u64 v[12:13], s[18:19], 0, v[204:205]
	v_lshl_add_u64 v[12:13], v[12:13], 0, s[24:25]
	v_lshlrev_b32_e32 v18, 16, v149
	v_and_b32_e32 v19, 0xffff0000, v149
	v_lshl_add_u64 v[12:13], v[12:13], 0, s[14:15]
	v_pk_fma_f32 v[14:15], v[14:15], v[142:143], v[18:19]
	v_lshl_add_u64 v[12:13], v[12:13], 0, v[202:203]
	v_cvt_pk_bf16_f32 v9, v14, v15
	v_cvt_pk_bf16_f32 v10, v10, v11
	v_cvt_pk_bf16_f32 v11, v16, v17
	flat_store_dwordx4 v[12:13], v[8:11]
	v_lshlrev_b32_e32 v14, 16, v146
	v_and_b32_e32 v15, 0xffff0000, v146
	v_lshlrev_b32_e32 v8, 16, v144
	v_and_b32_e32 v9, 0xffff0000, v144
	v_lshlrev_b32_e32 v16, 16, v147
	v_and_b32_e32 v17, 0xffff0000, v147
	v_lshlrev_b32_e32 v10, 16, v145
	v_and_b32_e32 v11, 0xffff0000, v145
	v_pk_fma_f32 v[4:5], v[4:5], v[132:133], v[8:9]
	v_pk_fma_f32 v[8:9], v[2:3], v[130:131], v[16:17]
	v_pk_fma_f32 v[2:3], v[0:1], v[128:129], v[14:15]
	v_pk_fma_f32 v[6:7], v[6:7], v[134:135], v[10:11]
	v_cvt_pk_bf16_f32 v0, v4, v5
	v_cvt_pk_bf16_f32 v2, v2, v3
	v_cvt_pk_bf16_f32 v3, v8, v9
	s_nop 0
	v_cvt_pk_bf16_f32 v1, v6, v7
	flat_store_dwordx4 v[12:13], v[0:3] offset:256
	s_cbranch_vccnz .LBB0_1031
	s_andn2_b64 vcc, exec, s[16:17]
	s_cbranch_vccnz .LBB0_1030
	s_barrier
	s_branch .LBB0_1030

.LBB0_1096:
	s_cmp_lt_i32 s76, 14
	s_cselect_b64 s[4:5], -1, 0
	s_and_b64 s[4:5], s[4:5], s[36:37]
	s_andn2_b64 vcc, exec, s[4:5]
	s_cbranch_vccnz .LBB0_1100
	v_lshl_add_u32 v16, s2, 3, v197
	s_mov_b32 s2, 0x10000
	v_cmp_gt_i32_e32 vcc, s2, v16
	s_and_saveexec_b64 s[2:3], vcc
	s_cbranch_execz .LBB0_1100
	s_load_dwordx4 s[4:7], s[0:1], 0xd0
	v_and_b32_e32 v17, 63, v196
	v_mov_b32_e32 v21, 0
	v_lshlrev_b32_e32 v20, 5, v17
	s_load_dwordx2 s[0:1], s[0:1], 0xe0
	s_waitcnt lgkmcnt(0)
	v_lshl_add_u64 v[18:19], s[4:5], 0, v[20:21]
	flat_load_dwordx4 v[0:3], v[18:19]
	flat_load_dwordx4 v[4:7], v[18:19] offset:16
	flat_load_dwordx4 v[8:11], v[18:19] offset:2048
	flat_load_dwordx4 v[12:15], v[18:19] offset:2064
	v_lshlrev_b32_e32 v18, 4, v17
	v_mbcnt_lo_u32_b32 v17, -1, 0
	v_mbcnt_hi_u32_b32 v17, -1, v17
	v_and_b32_e32 v22, 64, v17
	v_add_u32_e32 v27, 64, v22
	v_xor_b32_e32 v22, 32, v17
	v_cmp_lt_i32_e32 vcc, v22, v27
	v_xor_b32_e32 v23, 16, v17
	v_xor_b32_e32 v24, 8, v17
	v_cndmask_b32_e32 v22, v17, v22, vcc
	v_cmp_lt_i32_e32 vcc, v23, v27
	v_xor_b32_e32 v25, 4, v17
	v_xor_b32_e32 v26, 2, v17
	v_cndmask_b32_e32 v23, v17, v23, vcc
	v_cmp_lt_i32_e32 vcc, v24, v27
	v_xor_b32_e32 v28, 1, v17
	v_mov_b32_e32 v19, v21
	v_cndmask_b32_e32 v24, v17, v24, vcc
	v_cmp_lt_i32_e32 vcc, v25, v27
	v_lshl_add_u64 v[18:19], s[0:1], 0, v[18:19]
	s_mov_b64 s[0:1], 0x5200e00
	v_cndmask_b32_e32 v25, v17, v25, vcc
	v_cmp_lt_i32_e32 vcc, v26, v27
	s_lshl_b32 s2, s38, 3
	v_lshl_add_u64 v[18:19], v[18:19], 0, s[0:1]
	v_cndmask_b32_e32 v26, v17, v26, vcc
	v_cmp_lt_i32_e32 vcc, v28, v27
	v_lshlrev_b32_e32 v22, 2, v22
	v_lshlrev_b32_e32 v23, 2, v23
	v_cndmask_b32_e32 v17, v17, v28, vcc
	v_lshlrev_b32_e32 v24, 2, v24
	v_lshlrev_b32_e32 v25, 2, v25
	v_lshlrev_b32_e32 v26, 2, v26
	v_lshlrev_b32_e32 v27, 2, v17
	v_lshl_add_u64 v[20:21], s[6:7], 0, v[20:21]
	s_mov_b64 s[0:1], 0
	v_mov_b32_e32 v28, 0x358637bd
	s_mov_b32 s3, 0x800000
	s_mov_b32 s4, 0xffff
.LBB0_1099:
	v_ashrrev_i32_e32 v17, 31, v16
	v_lshlrev_b64 v[30:31], 11, v[16:17]
	v_lshl_add_u64 v[38:39], v[18:19], 0, v[30:31]
	flat_load_dwordx4 v[30:33], v[38:39]
	flat_load_dwordx4 v[34:37], v[38:39] offset:1024
	s_waitcnt vmcnt(0) lgkmcnt(0)
	v_and_b32_e32 v41, 0xffff0000, v32
	v_and_b32_e32 v40, 0xffff0000, v30
	v_lshlrev_b32_e32 v39, 16, v32
	v_lshlrev_b32_e32 v38, 16, v30
	v_lshlrev_b32_e32 v42, 16, v31
	v_and_b32_e32 v32, 0xffff0000, v31
	v_lshlrev_b32_e32 v31, 16, v34
	v_lshlrev_b32_e32 v30, 16, v36
	v_and_b32_e32 v45, 0xffff0000, v34
	v_and_b32_e32 v44, 0xffff0000, v36
	v_lshlrev_b32_e32 v46, 16, v37
	v_and_b32_e32 v34, 0xffff0000, v37
	v_pk_mul_f32 v[36:37], v[40:41], v[40:41]
	v_lshlrev_b32_e32 v43, 16, v33
	v_pk_mul_f32 v[48:49], v[44:45], v[44:45]
	v_pk_fma_f32 v[36:37], v[38:39], v[38:39], v[36:37]
	v_and_b32_e32 v33, 0xffff0000, v33
	v_lshlrev_b32_e32 v47, 16, v35
	v_pk_fma_f32 v[48:49], v[30:31], v[30:31], v[48:49]
	v_pk_fma_f32 v[36:37], v[42:43], v[42:43], v[36:37]
	v_and_b32_e32 v35, 0xffff0000, v35
	v_pk_fma_f32 v[48:49], v[46:47], v[46:47], v[48:49]
	v_pk_fma_f32 v[36:37], v[32:33], v[32:33], v[36:37]
	v_pk_fma_f32 v[48:49], v[34:35], v[34:35], v[48:49]
	v_add_f32_e32 v29, v36, v37
	v_add_f32_e32 v29, v29, v49
	v_add_f32_e32 v29, v48, v29
	ds_bpermute_b32 v36, v22, v29
	v_mov_b32_e32 v50, v42
	v_mov_b32_e32 v51, v32
	v_mov_b32_e32 v52, v47
	v_mov_b32_e32 v47, v34
	s_waitcnt lgkmcnt(0)
	v_add_f32_e32 v29, v29, v36
	ds_bpermute_b32 v36, v23, v29
	v_mov_b32_e32 v53, v35
	v_mov_b32_e32 v32, v43
	s_waitcnt lgkmcnt(0)
	v_add_f32_e32 v29, v29, v36
	ds_bpermute_b32 v48, v24, v29
	v_lshlrev_b64 v[36:37], 12, v[16:17]
	v_add_u32_e32 v16, s2, v16
	v_cmp_lt_i32_e32 vcc, s4, v16
	s_or_b64 s[0:1], vcc, s[0:1]
	s_waitcnt lgkmcnt(0)
	v_add_f32_e32 v17, v29, v48
	ds_bpermute_b32 v29, v25, v17
	v_lshl_add_u64 v[48:49], v[20:21], 0, v[36:37]
	v_mov_b32_e32 v36, v38
	v_mov_b32_e32 v37, v40
	v_mov_b32_e32 v40, v39
	s_waitcnt lgkmcnt(0)
	v_add_f32_e32 v17, v17, v29
	ds_bpermute_b32 v29, v26, v17
	v_mov_b32_e32 v38, v31
	v_mov_b32_e32 v39, v45
	v_mov_b32_e32 v31, v44
	s_waitcnt lgkmcnt(0)
	v_add_f32_e32 v17, v17, v29
	ds_bpermute_b32 v29, v27, v17
	s_waitcnt lgkmcnt(0)
	v_add_f32_e32 v17, v17, v29
	v_fmamk_f32 v17, v17, 0x3a800000, v28
	v_mul_f32_e32 v29, 0x4b800000, v17
	v_cmp_gt_f32_e32 vcc, s3, v17
	s_nop 1
	v_cndmask_b32_e32 v17, v17, v29, vcc
	v_rsq_f32_e32 v17, v17
	s_nop 0
	v_mul_f32_e32 v29, 0x45800000, v17
	v_cndmask_b32_e32 v34, v17, v29, vcc
	v_pk_mul_f32 v[36:37], v[36:37], v[34:35] op_sel_hi:[1,0]
	v_pk_mul_f32 v[42:43], v[50:51], v[34:35] op_sel_hi:[1,0]
	v_pk_mul_f32 v[40:41], v[40:41], v[34:35] op_sel_hi:[1,0]
	v_pk_mul_f32 v[44:45], v[32:33], v[34:35] op_sel_hi:[1,0]
	v_pk_mul_f32 v[38:39], v[38:39], v[34:35] op_sel_hi:[1,0]
	v_pk_mul_f32 v[50:51], v[52:53], v[34:35] op_sel_hi:[1,0]
	v_pk_mul_f32 v[52:53], v[30:31], v[34:35] op_sel_hi:[1,0]
	v_pk_mul_f32 v[46:47], v[46:47], v[34:35] op_sel_hi:[1,0]
	v_pk_mul_f32 v[32:33], v[2:3], v[42:43]
	v_pk_mul_f32 v[30:31], v[0:1], v[36:37]
	v_pk_mul_f32 v[36:37], v[6:7], v[44:45]
	v_pk_mul_f32 v[34:35], v[4:5], v[40:41]
	v_pk_mul_f32 v[40:41], v[10:11], v[50:51]
	v_pk_mul_f32 v[38:39], v[8:9], v[38:39]
	v_pk_mul_f32 v[44:45], v[14:15], v[46:47]
	v_pk_mul_f32 v[42:43], v[12:13], v[52:53]
	flat_store_dwordx4 v[48:49], v[30:33] nt
	flat_store_dwordx4 v[48:49], v[34:37] offset:16 nt
	flat_store_dwordx4 v[48:49], v[38:41] offset:2048 nt
	flat_store_dwordx4 v[48:49], v[42:45] offset:2064 nt
	s_andn2_b64 exec, exec, s[0:1]
	s_cbranch_execnz .LBB0_1099

	.amdhsa_kernel _Z4mega6Params
		.amdhsa_group_segment_fixed_size 0
		.amdhsa_private_segment_fixed_size 0
		.amdhsa_kernarg_size 496
		.amdhsa_user_sgpr_count 2
		.amdhsa_user_sgpr_dispatch_ptr 0
		.amdhsa_user_sgpr_queue_ptr 0
		.amdhsa_user_sgpr_kernarg_segment_ptr 1
		.amdhsa_user_sgpr_dispatch_id 0
		.amdhsa_user_sgpr_kernarg_preload_length 0
		.amdhsa_user_sgpr_kernarg_preload_offset 0
		.amdhsa_user_sgpr_private_segment_size 0
		.amdhsa_uses_dynamic_stack 0
		.amdhsa_enable_private_segment 0
		.amdhsa_system_sgpr_workgroup_id_x 1
		.amdhsa_system_sgpr_workgroup_id_y 0
		.amdhsa_system_sgpr_workgroup_id_z 0
		.amdhsa_system_sgpr_workgroup_info 0
		.amdhsa_system_vgpr_workitem_id 2
		.amdhsa_next_free_vgpr 255
		.amdhsa_next_free_sgpr 102
		.amdhsa_accum_offset 256
		.amdhsa_reserve_vcc 1
		.amdhsa_float_round_mode_32 0
		.amdhsa_float_round_mode_16_64 0
		.amdhsa_float_denorm_mode_32 3
		.amdhsa_float_denorm_mode_16_64 3
		.amdhsa_dx10_clamp 1
		.amdhsa_ieee_mode 1
		.amdhsa_fp16_overflow 0
		.amdhsa_tg_split 0
		.amdhsa_exception_fp_ieee_invalid_op 0
		.amdhsa_exception_fp_denorm_src 0
		.amdhsa_exception_fp_ieee_div_zero 0
		.amdhsa_exception_fp_ieee_overflow 0
		.amdhsa_exception_fp_ieee_underflow 0
		.amdhsa_exception_fp_ieee_inexact 0
		.amdhsa_exception_int_div_zero 0
	.end_amdhsa_kernel

amdhsa.kernels:
  - .agpr_count:     0
    .args:
      - .offset:         0
        .size:           240
        .value_kind:     by_value
      - .offset:         240
        .size:           4
        .value_kind:     hidden_block_count_x
      - .offset:         244
        .size:           4
        .value_kind:     hidden_block_count_y
      - .offset:         248
        .size:           4
        .value_kind:     hidden_block_count_z
      - .offset:         252
        .size:           2
        .value_kind:     hidden_group_size_x
      - .offset:         254
        .size:           2
        .value_kind:     hidden_group_size_y
      - .offset:         256
        .size:           2
        .value_kind:     hidden_group_size_z
      - .offset:         258
        .size:           2
        .value_kind:     hidden_remainder_x
      - .offset:         260
        .size:           2
        .value_kind:     hidden_remainder_y
      - .offset:         262
        .size:           2
        .value_kind:     hidden_remainder_z
      - .offset:         280
        .size:           8
        .value_kind:     hidden_global_offset_x
      - .offset:         288
        .size:           8
        .value_kind:     hidden_global_offset_y
      - .offset:         296
        .size:           8
        .value_kind:     hidden_global_offset_z
      - .offset:         304
        .size:           2
        .value_kind:     hidden_grid_dims
      - .offset:         328
        .size:           8
        .value_kind:     hidden_multigrid_sync_arg
      - .offset:         360
        .size:           4
        .value_kind:     hidden_dynamic_lds_size
    .group_segment_fixed_size: 0
    .kernarg_segment_align: 8
    .kernarg_segment_size: 496
    .language:       OpenCL C
    .language_version:
      - 2
      - 0
    .max_flat_workgroup_size: 512
    .name:           _Z4mega6Params
    .private_segment_fixed_size: 0
    .sgpr_count:     108
    .sgpr_spill_count: 11
    .symbol:         _Z4mega6Params.kd
    .uniform_work_group_size: 1
    .uses_dynamic_stack: false
    .vgpr_count:     255
    .vgpr_spill_count: 0
    .wavefront_size: 64
